# all RMS-norm scale factors: 33-instruction IEEE sqrt+div sequence for 1/sqrt(x) replaced by one f32 v_rsq_f32 (102 sites, f32 throughout), on top of v6
# speedup vs baseline: 1.0173x; 1.0049x over previous
.LBB0_77:
	s_ashr_i32 s1, s0, 31
	s_lshl_b64 s[0:1], s[0:1], 8
	v_mov_b32_e32 v134, v1
	v_mov_b32_e32 v132, v203
	s_add_u32 s0, s0, s92
	s_addc_u32 s1, s1, s95
	v_ashrrev_i32_e32 v135, 31, v134
	v_lshlrev_b32_e32 v130, 2, v132
	v_readlane_b32 s8, v251, 0
	v_lshl_add_u64 v[188:189], s[0:1], 0, v[134:135]
	v_ashrrev_i32_e32 v131, 31, v130
	v_readlane_b32 s10, v251, 2
	v_readlane_b32 s11, v251, 3
	v_lshlrev_b64 v[192:193], 6, v[188:189]
	v_lshlrev_b32_e32 v133, 2, v134
	v_lshl_add_u64 v[130:131], v[130:131], 2, s[10:11]
	v_lshl_add_u64 v[134:135], v[130:131], 0, v[192:193]
	global_load_dwordx4 v[134:137], v[134:135], off
	v_lshl_add_u32 v133, v132, 6, v133
	v_xor_b32_e32 v232, 64, v133
	v_xor_b32_e32 v231, 0x80, v133
	v_lshl_add_u64 v[184:185], v[188:189], 0, 16
	v_lshlrev_b64 v[186:187], 6, v[184:185]
	v_lshl_add_u64 v[180:181], v[188:189], 0, 32
	v_lshlrev_b64 v[182:183], 6, v[180:181]
	v_lshl_add_u64 v[176:177], v[188:189], 0, 48
	v_lshlrev_b64 v[178:179], 6, v[176:177]
	v_lshl_add_u64 v[172:173], v[188:189], 0, s[28:29]
	v_lshlrev_b64 v[174:175], 6, v[172:173]
	s_cmp_gt_i32 s4, 2
	v_lshlrev_b32_e32 v162, 3, v132
	s_mov_b64 s[10:11], -1
	v_readlane_b32 s9, v251, 1
	s_waitcnt vmcnt(0)
	v_add_f32_e32 v133, v134, v135
	v_add_f32_e32 v134, v136, v137
	v_add_f32_e32 v133, v133, v134
	ds_bpermute_b32 v134, v232, v133
	s_waitcnt lgkmcnt(0)
	v_add_f32_e32 v133, v133, v134
	ds_bpermute_b32 v134, v231, v133
	s_waitcnt lgkmcnt(0)
	v_add_f32_e32 v133, v133, v134
	v_fmamk_f32 v133, v133, 0x3a800000, v243
	s_nop 1
	v_cmp_eq_u32_e64 s[42:43], 0, v132
	s_nop 0
	s_nop 1
	s_mov_b64 s[0:1], 0x90
	v_lshl_add_u64 v[168:169], v[188:189], 0, s[0:1]
	v_lshlrev_b64 v[170:171], 6, v[168:169]
	v_rsq_f32_e32 v190, v133
	s_nop 0
	v_lshl_add_u64 v[134:135], v[130:131], 0, v[186:187]
	global_load_dwordx4 v[134:137], v[134:135], off
	s_mov_b64 s[0:1], 0xa0
	v_lshl_add_u64 v[164:165], v[188:189], 0, s[0:1]
	v_lshlrev_b64 v[166:167], 6, v[164:165]
	s_mov_b64 s[0:1], 0xb0
	v_lshl_add_u64 v[158:159], v[188:189], 0, s[0:1]
	v_lshlrev_b64 v[160:161], 6, v[158:159]
	s_cselect_b64 s[0:1], -1, 0
	s_cmp_eq_u32 s4, 2
	s_cselect_b64 s[44:45], -1, 0
	s_cmp_lg_u32 s4, 2
	s_cselect_b64 s[80:81], -1, 0
	s_and_b64 vcc, exec, s[0:1]
	s_waitcnt vmcnt(0)
	v_add_f32_e32 v133, v134, v135
	v_add_f32_e32 v134, v136, v137
	v_add_f32_e32 v133, v133, v134
	ds_bpermute_b32 v134, v232, v133
	s_waitcnt lgkmcnt(0)
	v_add_f32_e32 v191, v133, v134
	v_lshl_add_u64 v[134:135], v[130:131], 0, v[182:183]
	global_load_dwordx4 v[134:137], v[134:135], off
	ds_bpermute_b32 v208, v231, v191
	s_waitcnt vmcnt(0)
	v_add_f32_e32 v133, v134, v135
	v_add_f32_e32 v134, v136, v137
	v_add_f32_e32 v133, v133, v134
	ds_bpermute_b32 v134, v232, v133
	s_waitcnt lgkmcnt(0)
	v_add_f32_e32 v206, v133, v134
	v_lshl_add_u64 v[134:135], v[130:131], 0, v[178:179]
	global_load_dwordx4 v[134:137], v[134:135], off
	ds_bpermute_b32 v207, v231, v206
	s_waitcnt vmcnt(0)
	v_add_f32_e32 v133, v134, v135
	v_add_f32_e32 v134, v136, v137
	v_add_f32_e32 v133, v133, v134
	ds_bpermute_b32 v134, v232, v133
	s_waitcnt lgkmcnt(0)
	v_add_f32_e32 v204, v133, v134
	v_lshl_add_u64 v[134:135], v[130:131], 0, v[174:175]
	global_load_dwordx4 v[134:137], v[134:135], off
	ds_bpermute_b32 v205, v231, v204
	s_waitcnt vmcnt(0)
	v_add_f32_e32 v133, v134, v135
	v_add_f32_e32 v134, v136, v137
	v_add_f32_e32 v133, v133, v134
	ds_bpermute_b32 v134, v232, v133
	s_waitcnt lgkmcnt(0)
	v_add_f32_e32 v239, v133, v134
	v_lshl_add_u64 v[134:135], v[130:131], 0, v[170:171]
	global_load_dwordx4 v[134:137], v[134:135], off
	ds_bpermute_b32 v240, v231, v239
	s_waitcnt vmcnt(0)
	v_add_f32_e32 v133, v134, v135
	v_add_f32_e32 v134, v136, v137
	v_add_f32_e32 v133, v133, v134
	ds_bpermute_b32 v134, v232, v133
	s_waitcnt lgkmcnt(0)
	v_add_f32_e32 v237, v133, v134
	v_lshl_add_u64 v[134:135], v[130:131], 0, v[166:167]
	global_load_dwordx4 v[134:137], v[134:135], off
	v_lshl_add_u64 v[130:131], v[130:131], 0, v[160:161]
	ds_bpermute_b32 v238, v231, v237
	s_waitcnt vmcnt(0)
	v_add_f32_e32 v133, v134, v135
	v_add_f32_e32 v134, v136, v137
	v_add_f32_e32 v133, v133, v134
	ds_bpermute_b32 v134, v232, v133
	s_waitcnt lgkmcnt(0)
	v_add_f32_e32 v235, v133, v134
	global_load_dwordx4 v[134:137], v[130:131], off
	ds_bpermute_b32 v236, v231, v235
	s_waitcnt vmcnt(0)
	v_add_f32_e32 v130, v134, v135
	v_add_f32_e32 v131, v136, v137
	v_add_f32_e32 v130, v130, v131
	ds_bpermute_b32 v131, v232, v130
	s_waitcnt lgkmcnt(0)
	v_add_f32_e32 v233, v130, v131
	ds_bpermute_b32 v234, v231, v233
	v_cndmask_b32_e64 v130, 0, 1, s[70:71]
	v_cmp_ne_u32_e64 s[46:47], 1, v130
	s_cbranch_vccz .LBB0_81
	s_and_b64 vcc, exec, s[46:47]
	s_cbranch_vccnz .LBB0_80
	v_pk_mul_f32 v[218:219], v[128:129], v[190:191] op_sel_hi:[1,0]
	v_pk_mul_f32 v[220:221], v[126:127], v[190:191] op_sel_hi:[1,0]
	v_pk_mul_f32 v[130:131], v[218:219], v[218:219]
	v_pk_mul_f32 v[132:133], v[220:221], v[220:221]
	v_pk_mul_f32 v[194:195], v[124:125], v[190:191] op_sel_hi:[1,0]
	v_pk_mov_b32 v[134:135], v[132:133], v[130:131] op_sel:[1,0]
	v_mov_b32_e32 v133, v131
	v_pk_add_f32 v[130:131], v[134:135], v[132:133]
	v_pk_mul_f32 v[196:197], v[122:123], v[190:191] op_sel_hi:[1,0]
	v_pk_add_f32 v[130:131], v[130:131], v[130:131] op_sel_hi:[0,1]
	v_pk_mul_f32 v[132:133], v[194:195], v[194:195]
	v_pk_mul_f32 v[134:135], v[196:197], v[196:197]
	v_mov_b64_e32 v[212:213], v[224:225]
	v_pk_mul_f32 v[224:225], v[118:119], v[190:191] op_sel_hi:[1,0]
	v_pk_mov_b32 v[136:137], v[134:135], v[132:133] op_sel:[1,0]
	v_mov_b32_e32 v135, v133
	v_pk_mul_f32 v[222:223], v[120:121], v[190:191] op_sel_hi:[1,0]
	v_mul_f32_e32 v130, v224, v224
	v_pk_add_f32 v[132:133], v[136:137], v[134:135]
	v_pk_fma_f32 v[134:135], v[224:225], v[224:225], v[130:131] op_sel_hi:[1,1,0]
	v_mul_f32_e32 v130, v222, v222
	v_pk_add_f32 v[132:133], v[132:133], v[132:133] op_sel_hi:[0,1]
	v_pk_fma_f32 v[136:137], v[222:223], v[222:223], v[130:131] op_sel_hi:[1,1,0]
	v_pk_mul_f32 v[198:199], v[116:117], v[190:191] op_sel_hi:[1,0]
	v_pk_mul_f32 v[200:201], v[114:115], v[190:191] op_sel_hi:[1,0]
	v_mul_f32_e32 v130, v198, v198
	v_mul_f32_e32 v134, v200, v200
	v_mul_f32_e32 v136, v201, v201
	v_mul_f32_e32 v132, v199, v199
	v_pk_add_f32 v[134:135], v[134:135], v[136:137]
	v_pk_add_f32 v[130:131], v[130:131], v[132:133]
	v_ashrrev_i32_e32 v163, 31, v162
	v_pk_add_f32 v[130:131], v[134:135], v[130:131]
	v_lshl_add_u64 v[226:227], v[162:163], 2, s[58:59]
	v_add_f32_e32 v130, v130, v131
	ds_bpermute_b32 v131, v232, v130
	s_waitcnt lgkmcnt(0)
	v_add_f32_e32 v130, v130, v131
	ds_bpermute_b32 v131, v231, v130
	s_waitcnt lgkmcnt(0)
	v_add_f32_e32 v130, v130, v131
	v_fmamk_f32 v130, v130, 0x3c800000, v243
	s_nop 1
	v_readlane_b32 s6, v251, 47
	v_readlane_b32 s7, v251, 48
	v_rsq_f32_e32 v202, v130
	s_nop 0
	v_lshlrev_b64 v[130:131], 8, v[188:189]
	v_lshl_add_u64 v[130:131], s[6:7], 0, v[130:131]
	global_load_dwordx4 v[142:145], v[226:227], off
	global_load_dwordx4 v[134:137], v[226:227], off offset:128
	v_lshl_add_u64 v[228:229], v[162:163], 3, v[130:131]
	global_load_dwordx4 v[130:133], v[228:229], off
	global_load_dwordx4 v[138:141], v[228:229], off offset:16
	v_readlane_b32 s6, v251, 53
	v_readlane_b32 s7, v251, 54
	s_waitcnt vmcnt(3)
	v_pk_mul_f32 v[144:145], v[218:219], v[144:145]
	s_waitcnt vmcnt(2)
	v_pk_mul_f32 v[136:137], v[222:223], v[136:137]
	v_pk_mul_f32 v[134:135], v[224:225], v[134:135]
	v_pk_mul_f32 v[142:143], v[220:221], v[142:143]
	v_mov_b64_e32 v[224:225], v[212:213]
	v_pk_mul_f32 v[136:137], v[136:137], v[202:203] op_sel_hi:[1,0]
	v_pk_mul_f32 v[134:135], v[134:135], v[202:203] op_sel_hi:[1,0]
	s_waitcnt vmcnt(1)
	v_mov_b32_e32 v212, v131
	v_mov_b32_e32 v213, v133
	s_waitcnt vmcnt(0)
	v_mov_b32_e32 v216, v139
	v_mov_b32_e32 v217, v141
	v_pk_mul_f32 v[142:143], v[142:143], v[202:203] op_sel_hi:[1,0]
	v_pk_mul_f32 v[144:145], v[144:145], v[202:203] op_sel_hi:[1,0]
	v_pk_mul_f32 v[214:215], v[212:213], v[134:135]
	v_pk_mul_f32 v[218:219], v[216:217], v[136:137]
	v_mov_b32_e32 v139, v140
	v_mov_b32_e32 v131, v132
	v_lshl_add_u64 v[192:193], v[192:193], 1, s[6:7]
	v_pk_fma_f32 v[140:141], v[138:139], v[144:145], v[218:219] neg_lo:[0,0,1] neg_hi:[0,0,1]
	v_pk_fma_f32 v[132:133], v[130:131], v[142:143], v[214:215] neg_lo:[0,0,1] neg_hi:[0,0,1]
	v_lshl_add_u64 v[192:193], v[162:163], 1, v[192:193]
	v_cvt_pk_bf16_f32 v132, v132, v133
	v_cvt_pk_bf16_f32 v133, v140, v141
	global_store_dwordx2 v[192:193], v[132:133], off
	v_pk_mul_f32 v[130:131], v[130:131], v[134:135]
	v_pk_mul_f32 v[132:133], v[138:139], v[136:137]
	v_pk_fma_f32 v[130:131], v[212:213], v[142:143], v[130:131]
	v_pk_fma_f32 v[132:133], v[216:217], v[144:145], v[132:133]
	v_cvt_pk_bf16_f32 v130, v130, v131
	v_cvt_pk_bf16_f32 v131, v132, v133
	global_store_dwordx2 v[192:193], v[130:131], off offset:64
	global_load_dwordx4 v[130:133], v[226:227], off offset:16
	s_nop 0
	global_load_dwordx4 v[134:137], v[226:227], off offset:144
	global_load_dwordx4 v[138:141], v[228:229], off offset:32
	global_load_dwordx4 v[142:145], v[228:229], off offset:48
	s_waitcnt vmcnt(3)
	v_pk_mul_f32 v[132:133], v[194:195], v[132:133]
	s_waitcnt vmcnt(2)
	v_pk_mul_f32 v[136:137], v[198:199], v[136:137]
	v_pk_mul_f32 v[134:135], v[200:201], v[134:135]
	v_pk_mul_f32 v[130:131], v[196:197], v[130:131]
	v_pk_mul_f32 v[136:137], v[202:203], v[136:137] op_sel_hi:[0,1]
	v_pk_mul_f32 v[134:135], v[202:203], v[134:135] op_sel_hi:[0,1]
	s_waitcnt vmcnt(1)
	v_mov_b32_e32 v194, v139
	v_mov_b32_e32 v195, v141
	s_waitcnt vmcnt(0)
	v_mov_b32_e32 v198, v143
	v_mov_b32_e32 v199, v145
	v_mov_b32_e32 v143, v144
	v_mov_b32_e32 v139, v140
	v_pk_mul_f32 v[130:131], v[202:203], v[130:131] op_sel_hi:[0,1]
	v_pk_mul_f32 v[132:133], v[202:203], v[132:133] op_sel_hi:[0,1]
	v_pk_mul_f32 v[196:197], v[134:135], v[194:195]
	v_pk_mul_f32 v[200:201], v[136:137], v[198:199]
	v_pk_mul_f32 v[134:135], v[134:135], v[138:139]
	v_pk_mul_f32 v[136:137], v[136:137], v[142:143]
	v_pk_fma_f32 v[144:145], v[132:133], v[142:143], v[200:201] neg_lo:[0,0,1] neg_hi:[0,0,1]
	v_pk_fma_f32 v[140:141], v[130:131], v[138:139], v[196:197] neg_lo:[0,0,1] neg_hi:[0,0,1]
	v_pk_fma_f32 v[132:133], v[132:133], v[198:199], v[136:137]
	v_pk_fma_f32 v[130:131], v[130:131], v[194:195], v[134:135]
	v_cvt_pk_bf16_f32 v140, v140, v141
	v_cvt_pk_bf16_f32 v141, v144, v145
	v_cvt_pk_bf16_f32 v130, v130, v131
	v_cvt_pk_bf16_f32 v131, v132, v133
	global_store_dwordx2 v[192:193], v[140:141], off offset:8
	global_store_dwordx2 v[192:193], v[130:131], off offset:72

.LBB0_88:
	v_add_f32_e32 v114, v191, v208
	v_fmamk_f32 v114, v114, 0x3a800000, v243
	s_waitcnt lgkmcnt(0)
	v_rsq_f32_e32 v132, v114
	s_nop 0
	v_cndmask_b32_e64 v114, 0, 1, s[0:1]
	v_cmp_ne_u32_e64 s[48:49], 1, v114
	s_andn2_b64 vcc, exec, s[0:1]
	s_mov_b64 s[0:1], -1
	s_cbranch_vccnz .LBB0_92
	s_and_b64 vcc, exec, s[46:47]
	s_cbranch_vccnz .LBB0_91
	v_pk_mul_f32 v[144:145], v[112:113], v[132:133] op_sel_hi:[1,0]
	v_pk_mul_f32 v[188:189], v[110:111], v[132:133] op_sel_hi:[1,0]
	v_pk_mul_f32 v[114:115], v[144:145], v[144:145]
	v_pk_mul_f32 v[116:117], v[188:189], v[188:189]
	v_pk_mul_f32 v[134:135], v[108:109], v[132:133] op_sel_hi:[1,0]
	v_pk_mov_b32 v[118:119], v[116:117], v[114:115] op_sel:[1,0]
	v_mov_b32_e32 v117, v115
	v_pk_add_f32 v[114:115], v[118:119], v[116:117]
	v_pk_mul_f32 v[136:137], v[106:107], v[132:133] op_sel_hi:[1,0]
	v_pk_add_f32 v[114:115], v[114:115], v[114:115] op_sel_hi:[0,1]
	v_pk_mul_f32 v[116:117], v[134:135], v[134:135]
	v_pk_mul_f32 v[118:119], v[136:137], v[136:137]
	v_pk_mul_f32 v[192:193], v[102:103], v[132:133] op_sel_hi:[1,0]
	v_pk_mov_b32 v[120:121], v[118:119], v[116:117] op_sel:[1,0]
	v_mov_b32_e32 v119, v117
	v_pk_mul_f32 v[190:191], v[104:105], v[132:133] op_sel_hi:[1,0]
	v_mul_f32_e32 v114, v192, v192
	v_pk_add_f32 v[116:117], v[120:121], v[118:119]
	v_pk_fma_f32 v[118:119], v[192:193], v[192:193], v[114:115] op_sel_hi:[1,1,0]
	v_mul_f32_e32 v114, v190, v190
	v_pk_add_f32 v[116:117], v[116:117], v[116:117] op_sel_hi:[0,1]
	v_pk_fma_f32 v[120:121], v[190:191], v[190:191], v[114:115] op_sel_hi:[1,1,0]
	v_pk_mul_f32 v[138:139], v[100:101], v[132:133] op_sel_hi:[1,0]
	v_pk_mul_f32 v[140:141], v[98:99], v[132:133] op_sel_hi:[1,0]
	v_mul_f32_e32 v114, v138, v138
	v_mul_f32_e32 v118, v140, v140
	v_mul_f32_e32 v120, v141, v141
	v_mul_f32_e32 v116, v139, v139
	v_pk_add_f32 v[118:119], v[118:119], v[120:121]
	v_pk_add_f32 v[114:115], v[114:115], v[116:117]
	v_ashrrev_i32_e32 v163, 31, v162
	v_pk_add_f32 v[114:115], v[118:119], v[114:115]
	v_lshl_add_u64 v[194:195], v[162:163], 2, s[58:59]
	v_add_f32_e32 v114, v114, v115
	ds_bpermute_b32 v115, v232, v114
	s_waitcnt lgkmcnt(0)
	v_add_f32_e32 v114, v114, v115
	ds_bpermute_b32 v115, v231, v114
	s_waitcnt lgkmcnt(0)
	v_add_f32_e32 v114, v114, v115
	v_fmamk_f32 v114, v114, 0x3c800000, v243
	s_nop 1
	v_readlane_b32 s0, v251, 47
	v_readlane_b32 s1, v251, 48
	v_rsq_f32_e32 v142, v114
	s_nop 0
	v_lshlrev_b64 v[114:115], 8, v[184:185]
	v_lshl_add_u64 v[114:115], s[0:1], 0, v[114:115]
	global_load_dwordx4 v[126:129], v[194:195], off
	global_load_dwordx4 v[118:121], v[194:195], off offset:128
	v_lshl_add_u64 v[196:197], v[162:163], 3, v[114:115]
	global_load_dwordx4 v[114:117], v[196:197], off
	global_load_dwordx4 v[122:125], v[196:197], off offset:16
	v_readlane_b32 s0, v251, 53
	v_readlane_b32 s1, v251, 54
	s_waitcnt vmcnt(3)
	v_pk_mul_f32 v[128:129], v[144:145], v[128:129]
	s_waitcnt vmcnt(2)
	v_pk_mul_f32 v[120:121], v[190:191], v[120:121]
	v_pk_mul_f32 v[118:119], v[192:193], v[118:119]
	v_pk_mul_f32 v[126:127], v[188:189], v[126:127]
	v_pk_mul_f32 v[120:121], v[120:121], v[142:143] op_sel_hi:[1,0]
	v_pk_mul_f32 v[118:119], v[118:119], v[142:143] op_sel_hi:[1,0]
	v_lshl_add_u64 v[144:145], v[186:187], 1, s[0:1]
	s_waitcnt vmcnt(1)
	v_mov_b32_e32 v186, v115
	v_mov_b32_e32 v187, v117
	s_waitcnt vmcnt(0)
	v_mov_b32_e32 v190, v123
	v_mov_b32_e32 v191, v125
	v_pk_mul_f32 v[126:127], v[126:127], v[142:143] op_sel_hi:[1,0]
	v_pk_mul_f32 v[128:129], v[128:129], v[142:143] op_sel_hi:[1,0]
	v_pk_mul_f32 v[188:189], v[186:187], v[118:119]
	v_pk_mul_f32 v[192:193], v[190:191], v[120:121]
	v_mov_b32_e32 v123, v124
	v_mov_b32_e32 v115, v116
	v_pk_fma_f32 v[124:125], v[122:123], v[128:129], v[192:193] neg_lo:[0,0,1] neg_hi:[0,0,1]
	v_pk_fma_f32 v[116:117], v[114:115], v[126:127], v[188:189] neg_lo:[0,0,1] neg_hi:[0,0,1]
	v_lshl_add_u64 v[144:145], v[162:163], 1, v[144:145]
	v_cvt_pk_bf16_f32 v116, v116, v117
	v_cvt_pk_bf16_f32 v117, v124, v125
	global_store_dwordx2 v[144:145], v[116:117], off
	v_pk_mul_f32 v[114:115], v[114:115], v[118:119]
	v_pk_mul_f32 v[116:117], v[122:123], v[120:121]
	v_pk_fma_f32 v[114:115], v[186:187], v[126:127], v[114:115]
	v_pk_fma_f32 v[116:117], v[190:191], v[128:129], v[116:117]
	v_cvt_pk_bf16_f32 v114, v114, v115
	v_cvt_pk_bf16_f32 v115, v116, v117
	global_store_dwordx2 v[144:145], v[114:115], off offset:64
	global_load_dwordx4 v[114:117], v[194:195], off offset:16
	s_nop 0
	global_load_dwordx4 v[118:121], v[194:195], off offset:144
	global_load_dwordx4 v[122:125], v[196:197], off offset:32
	global_load_dwordx4 v[126:129], v[196:197], off offset:48
	s_waitcnt vmcnt(3)
	v_pk_mul_f32 v[116:117], v[134:135], v[116:117]
	s_waitcnt vmcnt(2)
	v_pk_mul_f32 v[120:121], v[138:139], v[120:121]
	v_pk_mul_f32 v[118:119], v[140:141], v[118:119]
	v_pk_mul_f32 v[114:115], v[136:137], v[114:115]
	v_pk_mul_f32 v[120:121], v[142:143], v[120:121] op_sel_hi:[0,1]
	v_pk_mul_f32 v[118:119], v[142:143], v[118:119] op_sel_hi:[0,1]
	s_waitcnt vmcnt(1)
	v_mov_b32_e32 v134, v123
	v_mov_b32_e32 v135, v125
	s_waitcnt vmcnt(0)
	v_mov_b32_e32 v138, v127
	v_mov_b32_e32 v139, v129
	v_mov_b32_e32 v127, v128
	v_mov_b32_e32 v123, v124
	v_pk_mul_f32 v[114:115], v[142:143], v[114:115] op_sel_hi:[0,1]
	v_pk_mul_f32 v[116:117], v[142:143], v[116:117] op_sel_hi:[0,1]
	v_pk_mul_f32 v[136:137], v[118:119], v[134:135]
	v_pk_mul_f32 v[140:141], v[120:121], v[138:139]
	v_pk_mul_f32 v[118:119], v[118:119], v[122:123]
	v_pk_mul_f32 v[120:121], v[120:121], v[126:127]
	v_pk_fma_f32 v[128:129], v[116:117], v[126:127], v[140:141] neg_lo:[0,0,1] neg_hi:[0,0,1]
	v_pk_fma_f32 v[124:125], v[114:115], v[122:123], v[136:137] neg_lo:[0,0,1] neg_hi:[0,0,1]
	v_pk_fma_f32 v[116:117], v[116:117], v[138:139], v[120:121]
	v_pk_fma_f32 v[114:115], v[114:115], v[134:135], v[118:119]
	v_cvt_pk_bf16_f32 v124, v124, v125
	v_cvt_pk_bf16_f32 v125, v128, v129
	v_cvt_pk_bf16_f32 v114, v114, v115
	v_cvt_pk_bf16_f32 v115, v116, v117
	global_store_dwordx2 v[144:145], v[124:125], off offset:8
	global_store_dwordx2 v[144:145], v[114:115], off offset:72

.LBB0_99:
	v_add_f32_e32 v98, v206, v207
	v_fmamk_f32 v98, v98, 0x3a800000, v243
	s_waitcnt lgkmcnt(0)
	s_nop 1
	s_mov_b64 s[0:1], -1
	v_rsq_f32_e32 v114, v98
	s_nop 0
	s_and_b64 vcc, exec, s[48:49]
	s_cbranch_vccnz .LBB0_103
	s_and_b64 vcc, exec, s[46:47]
	s_cbranch_vccnz .LBB0_102
	v_pk_mul_f32 v[126:127], v[96:97], v[114:115] op_sel_hi:[1,0]
	v_pk_mul_f32 v[128:129], v[94:95], v[114:115] op_sel_hi:[1,0]
	v_pk_mul_f32 v[98:99], v[126:127], v[126:127]
	v_pk_mul_f32 v[100:101], v[128:129], v[128:129]
	v_pk_mul_f32 v[116:117], v[92:93], v[114:115] op_sel_hi:[1,0]
	v_pk_mov_b32 v[102:103], v[100:101], v[98:99] op_sel:[1,0]
	v_mov_b32_e32 v101, v99
	v_pk_add_f32 v[98:99], v[102:103], v[100:101]
	v_pk_mul_f32 v[118:119], v[90:91], v[114:115] op_sel_hi:[1,0]
	v_pk_add_f32 v[98:99], v[98:99], v[98:99] op_sel_hi:[0,1]
	v_pk_mul_f32 v[100:101], v[116:117], v[116:117]
	v_pk_mul_f32 v[102:103], v[118:119], v[118:119]
	v_pk_mul_f32 v[134:135], v[86:87], v[114:115] op_sel_hi:[1,0]
	v_pk_mov_b32 v[104:105], v[102:103], v[100:101] op_sel:[1,0]
	v_mov_b32_e32 v103, v101
	v_pk_mul_f32 v[132:133], v[88:89], v[114:115] op_sel_hi:[1,0]
	v_mul_f32_e32 v98, v134, v134
	v_pk_add_f32 v[100:101], v[104:105], v[102:103]
	v_pk_fma_f32 v[102:103], v[134:135], v[134:135], v[98:99] op_sel_hi:[1,1,0]
	v_mul_f32_e32 v98, v132, v132
	v_pk_add_f32 v[100:101], v[100:101], v[100:101] op_sel_hi:[0,1]
	v_pk_fma_f32 v[104:105], v[132:133], v[132:133], v[98:99] op_sel_hi:[1,1,0]
	v_pk_mul_f32 v[120:121], v[84:85], v[114:115] op_sel_hi:[1,0]
	v_pk_mul_f32 v[122:123], v[82:83], v[114:115] op_sel_hi:[1,0]
	v_mul_f32_e32 v98, v120, v120
	v_mul_f32_e32 v102, v122, v122
	v_mul_f32_e32 v104, v123, v123
	v_mul_f32_e32 v100, v121, v121
	v_pk_add_f32 v[102:103], v[102:103], v[104:105]
	v_pk_add_f32 v[98:99], v[98:99], v[100:101]
	v_ashrrev_i32_e32 v163, 31, v162
	v_pk_add_f32 v[98:99], v[102:103], v[98:99]
	v_lshl_add_u64 v[136:137], v[162:163], 2, s[58:59]
	v_add_f32_e32 v98, v98, v99
	ds_bpermute_b32 v99, v232, v98
	s_waitcnt lgkmcnt(0)
	v_add_f32_e32 v98, v98, v99
	ds_bpermute_b32 v99, v231, v98
	s_waitcnt lgkmcnt(0)
	v_add_f32_e32 v98, v98, v99
	v_fmamk_f32 v98, v98, 0x3c800000, v243
	s_nop 1
	v_readlane_b32 s0, v251, 47
	v_readlane_b32 s1, v251, 48
	v_rsq_f32_e32 v124, v98
	s_nop 0
	v_lshlrev_b64 v[98:99], 8, v[180:181]
	v_lshl_add_u64 v[98:99], s[0:1], 0, v[98:99]
	global_load_dwordx4 v[110:113], v[136:137], off
	global_load_dwordx4 v[102:105], v[136:137], off offset:128
	v_lshl_add_u64 v[138:139], v[162:163], 3, v[98:99]
	global_load_dwordx4 v[98:101], v[138:139], off
	global_load_dwordx4 v[106:109], v[138:139], off offset:16
	v_readlane_b32 s0, v251, 53
	v_readlane_b32 s1, v251, 54
	s_waitcnt vmcnt(3)
	v_pk_mul_f32 v[112:113], v[126:127], v[112:113]
	s_waitcnt vmcnt(2)
	v_pk_mul_f32 v[104:105], v[132:133], v[104:105]
	v_pk_mul_f32 v[102:103], v[134:135], v[102:103]
	v_pk_mul_f32 v[110:111], v[128:129], v[110:111]
	v_pk_mul_f32 v[104:105], v[104:105], v[124:125] op_sel_hi:[1,0]
	v_pk_mul_f32 v[102:103], v[102:103], v[124:125] op_sel_hi:[1,0]
	s_waitcnt vmcnt(1)
	v_mov_b32_e32 v128, v99
	v_mov_b32_e32 v129, v101
	s_waitcnt vmcnt(0)
	v_mov_b32_e32 v134, v107
	v_mov_b32_e32 v135, v109
	v_pk_mul_f32 v[110:111], v[110:111], v[124:125] op_sel_hi:[1,0]
	v_pk_mul_f32 v[112:113], v[112:113], v[124:125] op_sel_hi:[1,0]
	v_pk_mul_f32 v[132:133], v[128:129], v[102:103]
	v_pk_mul_f32 v[140:141], v[134:135], v[104:105]
	v_mov_b32_e32 v107, v108
	v_mov_b32_e32 v99, v100
	v_lshl_add_u64 v[126:127], v[182:183], 1, s[0:1]
	v_pk_fma_f32 v[108:109], v[106:107], v[112:113], v[140:141] neg_lo:[0,0,1] neg_hi:[0,0,1]
	v_pk_fma_f32 v[100:101], v[98:99], v[110:111], v[132:133] neg_lo:[0,0,1] neg_hi:[0,0,1]
	v_lshl_add_u64 v[126:127], v[162:163], 1, v[126:127]
	v_cvt_pk_bf16_f32 v100, v100, v101
	v_cvt_pk_bf16_f32 v101, v108, v109
	global_store_dwordx2 v[126:127], v[100:101], off
	v_pk_mul_f32 v[98:99], v[98:99], v[102:103]
	v_pk_mul_f32 v[100:101], v[106:107], v[104:105]
	v_pk_fma_f32 v[98:99], v[128:129], v[110:111], v[98:99]
	v_pk_fma_f32 v[100:101], v[134:135], v[112:113], v[100:101]
	v_cvt_pk_bf16_f32 v98, v98, v99
	v_cvt_pk_bf16_f32 v99, v100, v101
	global_store_dwordx2 v[126:127], v[98:99], off offset:64
	global_load_dwordx4 v[98:101], v[136:137], off offset:16
	s_nop 0
	global_load_dwordx4 v[102:105], v[136:137], off offset:144
	global_load_dwordx4 v[106:109], v[138:139], off offset:32
	global_load_dwordx4 v[110:113], v[138:139], off offset:48
	s_waitcnt vmcnt(3)
	v_pk_mul_f32 v[100:101], v[116:117], v[100:101]
	s_waitcnt vmcnt(2)
	v_pk_mul_f32 v[104:105], v[120:121], v[104:105]
	v_pk_mul_f32 v[102:103], v[122:123], v[102:103]
	v_pk_mul_f32 v[98:99], v[118:119], v[98:99]
	v_pk_mul_f32 v[104:105], v[124:125], v[104:105] op_sel_hi:[0,1]
	v_pk_mul_f32 v[102:103], v[124:125], v[102:103] op_sel_hi:[0,1]
	s_waitcnt vmcnt(1)
	v_mov_b32_e32 v116, v107
	v_mov_b32_e32 v117, v109
	s_waitcnt vmcnt(0)
	v_mov_b32_e32 v120, v111
	v_mov_b32_e32 v121, v113
	v_mov_b32_e32 v111, v112
	v_mov_b32_e32 v107, v108
	v_pk_mul_f32 v[98:99], v[124:125], v[98:99] op_sel_hi:[0,1]
	v_pk_mul_f32 v[100:101], v[124:125], v[100:101] op_sel_hi:[0,1]
	v_pk_mul_f32 v[118:119], v[102:103], v[116:117]
	v_pk_mul_f32 v[122:123], v[104:105], v[120:121]
	v_pk_mul_f32 v[102:103], v[102:103], v[106:107]
	v_pk_mul_f32 v[104:105], v[104:105], v[110:111]
	v_pk_fma_f32 v[112:113], v[100:101], v[110:111], v[122:123] neg_lo:[0,0,1] neg_hi:[0,0,1]
	v_pk_fma_f32 v[108:109], v[98:99], v[106:107], v[118:119] neg_lo:[0,0,1] neg_hi:[0,0,1]
	v_pk_fma_f32 v[100:101], v[100:101], v[120:121], v[104:105]
	v_pk_fma_f32 v[98:99], v[98:99], v[116:117], v[102:103]
	v_cvt_pk_bf16_f32 v108, v108, v109
	v_cvt_pk_bf16_f32 v109, v112, v113
	v_cvt_pk_bf16_f32 v98, v98, v99
	v_cvt_pk_bf16_f32 v99, v100, v101
	global_store_dwordx2 v[126:127], v[108:109], off offset:8
	global_store_dwordx2 v[126:127], v[98:99], off offset:72

.LBB0_110:
	v_add_f32_e32 v82, v204, v205
	v_fmamk_f32 v82, v82, 0x3a800000, v243
	s_waitcnt lgkmcnt(0)
	s_nop 1
	s_mov_b64 s[0:1], -1
	v_rsq_f32_e32 v98, v82
	s_nop 0
	s_and_b64 vcc, exec, s[48:49]
	s_cbranch_vccnz .LBB0_114
	s_and_b64 vcc, exec, s[46:47]
	s_cbranch_vccnz .LBB0_113
	v_pk_mul_f32 v[110:111], v[80:81], v[98:99] op_sel_hi:[1,0]
	v_pk_mul_f32 v[112:113], v[78:79], v[98:99] op_sel_hi:[1,0]
	v_pk_mul_f32 v[82:83], v[110:111], v[110:111]
	v_pk_mul_f32 v[84:85], v[112:113], v[112:113]
	v_pk_mul_f32 v[100:101], v[76:77], v[98:99] op_sel_hi:[1,0]
	v_pk_mov_b32 v[86:87], v[84:85], v[82:83] op_sel:[1,0]
	v_mov_b32_e32 v85, v83
	v_pk_add_f32 v[82:83], v[86:87], v[84:85]
	v_pk_mul_f32 v[102:103], v[74:75], v[98:99] op_sel_hi:[1,0]
	v_pk_add_f32 v[82:83], v[82:83], v[82:83] op_sel_hi:[0,1]
	v_pk_mul_f32 v[84:85], v[100:101], v[100:101]
	v_pk_mul_f32 v[86:87], v[102:103], v[102:103]
	v_pk_mul_f32 v[116:117], v[70:71], v[98:99] op_sel_hi:[1,0]
	v_pk_mov_b32 v[88:89], v[86:87], v[84:85] op_sel:[1,0]
	v_mov_b32_e32 v87, v85
	v_pk_mul_f32 v[114:115], v[72:73], v[98:99] op_sel_hi:[1,0]
	v_mul_f32_e32 v82, v116, v116
	v_pk_add_f32 v[84:85], v[88:89], v[86:87]
	v_pk_fma_f32 v[86:87], v[116:117], v[116:117], v[82:83] op_sel_hi:[1,1,0]
	v_mul_f32_e32 v82, v114, v114
	v_pk_add_f32 v[84:85], v[84:85], v[84:85] op_sel_hi:[0,1]
	v_pk_fma_f32 v[88:89], v[114:115], v[114:115], v[82:83] op_sel_hi:[1,1,0]
	v_pk_mul_f32 v[104:105], v[68:69], v[98:99] op_sel_hi:[1,0]
	v_pk_mul_f32 v[106:107], v[66:67], v[98:99] op_sel_hi:[1,0]
	v_mul_f32_e32 v82, v104, v104
	v_mul_f32_e32 v86, v106, v106
	v_mul_f32_e32 v88, v107, v107
	v_mul_f32_e32 v84, v105, v105
	v_pk_add_f32 v[86:87], v[86:87], v[88:89]
	v_pk_add_f32 v[82:83], v[82:83], v[84:85]
	v_ashrrev_i32_e32 v163, 31, v162
	v_pk_add_f32 v[82:83], v[86:87], v[82:83]
	v_lshl_add_u64 v[118:119], v[162:163], 2, s[58:59]
	v_add_f32_e32 v82, v82, v83
	ds_bpermute_b32 v83, v232, v82
	s_waitcnt lgkmcnt(0)
	v_add_f32_e32 v82, v82, v83
	ds_bpermute_b32 v83, v231, v82
	s_waitcnt lgkmcnt(0)
	v_add_f32_e32 v82, v82, v83
	v_fmamk_f32 v82, v82, 0x3c800000, v243
	s_nop 1
	v_readlane_b32 s0, v251, 47
	v_readlane_b32 s1, v251, 48
	v_rsq_f32_e32 v108, v82
	s_nop 0
	v_lshlrev_b64 v[82:83], 8, v[176:177]
	v_lshl_add_u64 v[82:83], s[0:1], 0, v[82:83]
	global_load_dwordx4 v[94:97], v[118:119], off
	global_load_dwordx4 v[86:89], v[118:119], off offset:128
	v_lshl_add_u64 v[120:121], v[162:163], 3, v[82:83]
	global_load_dwordx4 v[82:85], v[120:121], off
	global_load_dwordx4 v[90:93], v[120:121], off offset:16
	v_readlane_b32 s0, v251, 53
	v_readlane_b32 s1, v251, 54
	s_waitcnt vmcnt(3)
	v_pk_mul_f32 v[96:97], v[110:111], v[96:97]
	s_waitcnt vmcnt(2)
	v_pk_mul_f32 v[88:89], v[114:115], v[88:89]
	v_pk_mul_f32 v[86:87], v[116:117], v[86:87]
	v_pk_mul_f32 v[94:95], v[112:113], v[94:95]
	v_pk_mul_f32 v[88:89], v[88:89], v[108:109] op_sel_hi:[1,0]
	v_pk_mul_f32 v[86:87], v[86:87], v[108:109] op_sel_hi:[1,0]
	s_waitcnt vmcnt(1)
	v_mov_b32_e32 v112, v83
	v_mov_b32_e32 v113, v85
	s_waitcnt vmcnt(0)
	v_mov_b32_e32 v116, v91
	v_mov_b32_e32 v117, v93
	v_pk_mul_f32 v[94:95], v[94:95], v[108:109] op_sel_hi:[1,0]
	v_pk_mul_f32 v[96:97], v[96:97], v[108:109] op_sel_hi:[1,0]
	v_pk_mul_f32 v[114:115], v[112:113], v[86:87]
	v_pk_mul_f32 v[122:123], v[116:117], v[88:89]
	v_mov_b32_e32 v91, v92
	v_mov_b32_e32 v83, v84
	v_lshl_add_u64 v[110:111], v[178:179], 1, s[0:1]
	v_pk_fma_f32 v[92:93], v[90:91], v[96:97], v[122:123] neg_lo:[0,0,1] neg_hi:[0,0,1]
	v_pk_fma_f32 v[84:85], v[82:83], v[94:95], v[114:115] neg_lo:[0,0,1] neg_hi:[0,0,1]
	v_lshl_add_u64 v[110:111], v[162:163], 1, v[110:111]
	v_cvt_pk_bf16_f32 v84, v84, v85
	v_cvt_pk_bf16_f32 v85, v92, v93
	global_store_dwordx2 v[110:111], v[84:85], off
	v_pk_mul_f32 v[82:83], v[82:83], v[86:87]
	v_pk_mul_f32 v[84:85], v[90:91], v[88:89]
	v_pk_fma_f32 v[82:83], v[112:113], v[94:95], v[82:83]
	v_pk_fma_f32 v[84:85], v[116:117], v[96:97], v[84:85]
	v_cvt_pk_bf16_f32 v82, v82, v83
	v_cvt_pk_bf16_f32 v83, v84, v85
	global_store_dwordx2 v[110:111], v[82:83], off offset:64
	global_load_dwordx4 v[82:85], v[118:119], off offset:16
	s_nop 0
	global_load_dwordx4 v[86:89], v[118:119], off offset:144
	global_load_dwordx4 v[90:93], v[120:121], off offset:32
	global_load_dwordx4 v[94:97], v[120:121], off offset:48
	s_waitcnt vmcnt(3)
	v_pk_mul_f32 v[84:85], v[100:101], v[84:85]
	s_waitcnt vmcnt(2)
	v_pk_mul_f32 v[88:89], v[104:105], v[88:89]
	v_pk_mul_f32 v[86:87], v[106:107], v[86:87]
	v_pk_mul_f32 v[82:83], v[102:103], v[82:83]
	v_pk_mul_f32 v[88:89], v[108:109], v[88:89] op_sel_hi:[0,1]
	v_pk_mul_f32 v[86:87], v[108:109], v[86:87] op_sel_hi:[0,1]
	s_waitcnt vmcnt(1)
	v_mov_b32_e32 v100, v91
	v_mov_b32_e32 v101, v93
	s_waitcnt vmcnt(0)
	v_mov_b32_e32 v104, v95
	v_mov_b32_e32 v105, v97
	v_mov_b32_e32 v95, v96
	v_mov_b32_e32 v91, v92
	v_pk_mul_f32 v[82:83], v[108:109], v[82:83] op_sel_hi:[0,1]
	v_pk_mul_f32 v[84:85], v[108:109], v[84:85] op_sel_hi:[0,1]
	v_pk_mul_f32 v[102:103], v[86:87], v[100:101]
	v_pk_mul_f32 v[106:107], v[88:89], v[104:105]
	v_pk_mul_f32 v[86:87], v[86:87], v[90:91]
	v_pk_mul_f32 v[88:89], v[88:89], v[94:95]
	v_pk_fma_f32 v[96:97], v[84:85], v[94:95], v[106:107] neg_lo:[0,0,1] neg_hi:[0,0,1]
	v_pk_fma_f32 v[92:93], v[82:83], v[90:91], v[102:103] neg_lo:[0,0,1] neg_hi:[0,0,1]
	v_pk_fma_f32 v[84:85], v[84:85], v[104:105], v[88:89]
	v_pk_fma_f32 v[82:83], v[82:83], v[100:101], v[86:87]
	v_cvt_pk_bf16_f32 v92, v92, v93
	v_cvt_pk_bf16_f32 v93, v96, v97
	v_cvt_pk_bf16_f32 v82, v82, v83
	v_cvt_pk_bf16_f32 v83, v84, v85
	global_store_dwordx2 v[110:111], v[92:93], off offset:8
	global_store_dwordx2 v[110:111], v[82:83], off offset:72

.LBB0_121:
	v_add_f32_e32 v66, v239, v240
	v_fmamk_f32 v66, v66, 0x3a800000, v243
	s_waitcnt lgkmcnt(0)
	s_nop 1
	s_mov_b64 s[0:1], -1
	v_rsq_f32_e32 v82, v66
	s_nop 0
	s_and_b64 vcc, exec, s[48:49]
	s_cbranch_vccnz .LBB0_125
	s_and_b64 vcc, exec, s[46:47]
	s_cbranch_vccnz .LBB0_124
	v_pk_mul_f32 v[94:95], v[64:65], v[82:83] op_sel_hi:[1,0]
	v_pk_mul_f32 v[96:97], v[62:63], v[82:83] op_sel_hi:[1,0]
	v_pk_mul_f32 v[66:67], v[94:95], v[94:95]
	v_pk_mul_f32 v[68:69], v[96:97], v[96:97]
	v_pk_mul_f32 v[84:85], v[60:61], v[82:83] op_sel_hi:[1,0]
	v_pk_mov_b32 v[70:71], v[68:69], v[66:67] op_sel:[1,0]
	v_mov_b32_e32 v69, v67
	v_pk_add_f32 v[66:67], v[70:71], v[68:69]
	v_pk_mul_f32 v[86:87], v[58:59], v[82:83] op_sel_hi:[1,0]
	v_pk_add_f32 v[66:67], v[66:67], v[66:67] op_sel_hi:[0,1]
	v_pk_mul_f32 v[68:69], v[84:85], v[84:85]
	v_pk_mul_f32 v[70:71], v[86:87], v[86:87]
	v_pk_mul_f32 v[100:101], v[54:55], v[82:83] op_sel_hi:[1,0]
	v_pk_mov_b32 v[72:73], v[70:71], v[68:69] op_sel:[1,0]
	v_mov_b32_e32 v71, v69
	v_pk_mul_f32 v[98:99], v[56:57], v[82:83] op_sel_hi:[1,0]
	v_mul_f32_e32 v66, v100, v100
	v_pk_add_f32 v[68:69], v[72:73], v[70:71]
	v_pk_fma_f32 v[70:71], v[100:101], v[100:101], v[66:67] op_sel_hi:[1,1,0]
	v_mul_f32_e32 v66, v98, v98
	v_pk_add_f32 v[68:69], v[68:69], v[68:69] op_sel_hi:[0,1]
	v_pk_fma_f32 v[72:73], v[98:99], v[98:99], v[66:67] op_sel_hi:[1,1,0]
	v_pk_mul_f32 v[88:89], v[52:53], v[82:83] op_sel_hi:[1,0]
	v_pk_mul_f32 v[90:91], v[50:51], v[82:83] op_sel_hi:[1,0]
	v_mul_f32_e32 v66, v88, v88
	v_mul_f32_e32 v70, v90, v90
	v_mul_f32_e32 v72, v91, v91
	v_mul_f32_e32 v68, v89, v89
	v_pk_add_f32 v[70:71], v[70:71], v[72:73]
	v_pk_add_f32 v[66:67], v[66:67], v[68:69]
	v_ashrrev_i32_e32 v163, 31, v162
	v_pk_add_f32 v[66:67], v[70:71], v[66:67]
	v_lshl_add_u64 v[102:103], v[162:163], 2, s[58:59]
	v_add_f32_e32 v66, v66, v67
	ds_bpermute_b32 v67, v232, v66
	s_waitcnt lgkmcnt(0)
	v_add_f32_e32 v66, v66, v67
	ds_bpermute_b32 v67, v231, v66
	s_waitcnt lgkmcnt(0)
	v_add_f32_e32 v66, v66, v67
	v_fmamk_f32 v66, v66, 0x3c800000, v243
	s_nop 1
	v_readlane_b32 s0, v251, 47
	v_readlane_b32 s1, v251, 48
	v_rsq_f32_e32 v92, v66
	s_nop 0
	v_lshlrev_b64 v[66:67], 8, v[172:173]
	v_lshl_add_u64 v[66:67], s[0:1], 0, v[66:67]
	global_load_dwordx4 v[78:81], v[102:103], off
	global_load_dwordx4 v[70:73], v[102:103], off offset:128
	v_lshl_add_u64 v[104:105], v[162:163], 3, v[66:67]
	global_load_dwordx4 v[66:69], v[104:105], off
	global_load_dwordx4 v[74:77], v[104:105], off offset:16
	v_readlane_b32 s0, v251, 53
	v_readlane_b32 s1, v251, 54
	s_waitcnt vmcnt(3)
	v_pk_mul_f32 v[80:81], v[94:95], v[80:81]
	s_waitcnt vmcnt(2)
	v_pk_mul_f32 v[72:73], v[98:99], v[72:73]
	v_pk_mul_f32 v[70:71], v[100:101], v[70:71]
	v_pk_mul_f32 v[78:79], v[96:97], v[78:79]
	v_pk_mul_f32 v[72:73], v[72:73], v[92:93] op_sel_hi:[1,0]
	v_pk_mul_f32 v[70:71], v[70:71], v[92:93] op_sel_hi:[1,0]
	s_waitcnt vmcnt(1)
	v_mov_b32_e32 v96, v67
	v_mov_b32_e32 v97, v69
	s_waitcnt vmcnt(0)
	v_mov_b32_e32 v100, v75
	v_mov_b32_e32 v101, v77
	v_pk_mul_f32 v[78:79], v[78:79], v[92:93] op_sel_hi:[1,0]
	v_pk_mul_f32 v[80:81], v[80:81], v[92:93] op_sel_hi:[1,0]
	v_pk_mul_f32 v[98:99], v[96:97], v[70:71]
	v_pk_mul_f32 v[106:107], v[100:101], v[72:73]
	v_mov_b32_e32 v75, v76
	v_mov_b32_e32 v67, v68
	v_lshl_add_u64 v[94:95], v[174:175], 1, s[0:1]
	v_pk_fma_f32 v[76:77], v[74:75], v[80:81], v[106:107] neg_lo:[0,0,1] neg_hi:[0,0,1]
	v_pk_fma_f32 v[68:69], v[66:67], v[78:79], v[98:99] neg_lo:[0,0,1] neg_hi:[0,0,1]
	v_lshl_add_u64 v[94:95], v[162:163], 1, v[94:95]
	v_cvt_pk_bf16_f32 v68, v68, v69
	v_cvt_pk_bf16_f32 v69, v76, v77
	global_store_dwordx2 v[94:95], v[68:69], off
	v_pk_mul_f32 v[66:67], v[66:67], v[70:71]
	v_pk_mul_f32 v[68:69], v[74:75], v[72:73]
	v_pk_fma_f32 v[66:67], v[96:97], v[78:79], v[66:67]
	v_pk_fma_f32 v[68:69], v[100:101], v[80:81], v[68:69]
	v_cvt_pk_bf16_f32 v66, v66, v67
	v_cvt_pk_bf16_f32 v67, v68, v69
	global_store_dwordx2 v[94:95], v[66:67], off offset:64
	global_load_dwordx4 v[66:69], v[102:103], off offset:16
	s_nop 0
	global_load_dwordx4 v[70:73], v[102:103], off offset:144
	global_load_dwordx4 v[74:77], v[104:105], off offset:32
	global_load_dwordx4 v[78:81], v[104:105], off offset:48
	s_waitcnt vmcnt(3)
	v_pk_mul_f32 v[68:69], v[84:85], v[68:69]
	s_waitcnt vmcnt(2)
	v_pk_mul_f32 v[72:73], v[88:89], v[72:73]
	v_pk_mul_f32 v[70:71], v[90:91], v[70:71]
	v_pk_mul_f32 v[66:67], v[86:87], v[66:67]
	v_pk_mul_f32 v[72:73], v[92:93], v[72:73] op_sel_hi:[0,1]
	v_pk_mul_f32 v[70:71], v[92:93], v[70:71] op_sel_hi:[0,1]
	s_waitcnt vmcnt(1)
	v_mov_b32_e32 v84, v75
	v_mov_b32_e32 v85, v77
	s_waitcnt vmcnt(0)
	v_mov_b32_e32 v88, v79
	v_mov_b32_e32 v89, v81
	v_mov_b32_e32 v79, v80
	v_mov_b32_e32 v75, v76
	v_pk_mul_f32 v[66:67], v[92:93], v[66:67] op_sel_hi:[0,1]
	v_pk_mul_f32 v[68:69], v[92:93], v[68:69] op_sel_hi:[0,1]
	v_pk_mul_f32 v[86:87], v[70:71], v[84:85]
	v_pk_mul_f32 v[90:91], v[72:73], v[88:89]
	v_pk_mul_f32 v[70:71], v[70:71], v[74:75]
	v_pk_mul_f32 v[72:73], v[72:73], v[78:79]
	v_pk_fma_f32 v[80:81], v[68:69], v[78:79], v[90:91] neg_lo:[0,0,1] neg_hi:[0,0,1]
	v_pk_fma_f32 v[76:77], v[66:67], v[74:75], v[86:87] neg_lo:[0,0,1] neg_hi:[0,0,1]
	v_pk_fma_f32 v[68:69], v[68:69], v[88:89], v[72:73]
	v_pk_fma_f32 v[66:67], v[66:67], v[84:85], v[70:71]
	v_cvt_pk_bf16_f32 v76, v76, v77
	v_cvt_pk_bf16_f32 v77, v80, v81
	v_cvt_pk_bf16_f32 v66, v66, v67
	v_cvt_pk_bf16_f32 v67, v68, v69
	global_store_dwordx2 v[94:95], v[76:77], off offset:8
	global_store_dwordx2 v[94:95], v[66:67], off offset:72

.LBB0_132:
	v_add_f32_e32 v50, v237, v238
	v_fmamk_f32 v50, v50, 0x3a800000, v243
	s_waitcnt lgkmcnt(0)
	s_nop 1
	s_mov_b64 s[0:1], -1
	v_rsq_f32_e32 v66, v50
	s_nop 0
	s_and_b64 vcc, exec, s[48:49]
	s_cbranch_vccnz .LBB0_136
	s_and_b64 vcc, exec, s[46:47]
	s_cbranch_vccnz .LBB0_135
	v_pk_mul_f32 v[78:79], v[48:49], v[66:67] op_sel_hi:[1,0]
	v_pk_mul_f32 v[80:81], v[46:47], v[66:67] op_sel_hi:[1,0]
	v_pk_mul_f32 v[50:51], v[78:79], v[78:79]
	v_pk_mul_f32 v[52:53], v[80:81], v[80:81]
	v_pk_mul_f32 v[68:69], v[44:45], v[66:67] op_sel_hi:[1,0]
	v_pk_mov_b32 v[54:55], v[52:53], v[50:51] op_sel:[1,0]
	v_mov_b32_e32 v53, v51
	v_pk_add_f32 v[50:51], v[54:55], v[52:53]
	v_pk_mul_f32 v[70:71], v[42:43], v[66:67] op_sel_hi:[1,0]
	v_pk_add_f32 v[50:51], v[50:51], v[50:51] op_sel_hi:[0,1]
	v_pk_mul_f32 v[52:53], v[68:69], v[68:69]
	v_pk_mul_f32 v[54:55], v[70:71], v[70:71]
	v_pk_mul_f32 v[84:85], v[38:39], v[66:67] op_sel_hi:[1,0]
	v_pk_mov_b32 v[56:57], v[54:55], v[52:53] op_sel:[1,0]
	v_mov_b32_e32 v55, v53
	v_pk_mul_f32 v[82:83], v[40:41], v[66:67] op_sel_hi:[1,0]
	v_mul_f32_e32 v50, v84, v84
	v_pk_add_f32 v[52:53], v[56:57], v[54:55]
	v_pk_fma_f32 v[54:55], v[84:85], v[84:85], v[50:51] op_sel_hi:[1,1,0]
	v_mul_f32_e32 v50, v82, v82
	v_pk_add_f32 v[52:53], v[52:53], v[52:53] op_sel_hi:[0,1]
	v_pk_fma_f32 v[56:57], v[82:83], v[82:83], v[50:51] op_sel_hi:[1,1,0]
	v_pk_mul_f32 v[72:73], v[36:37], v[66:67] op_sel_hi:[1,0]
	v_pk_mul_f32 v[74:75], v[34:35], v[66:67] op_sel_hi:[1,0]
	v_mul_f32_e32 v50, v72, v72
	v_mul_f32_e32 v54, v74, v74
	v_mul_f32_e32 v56, v75, v75
	v_mul_f32_e32 v52, v73, v73
	v_pk_add_f32 v[54:55], v[54:55], v[56:57]
	v_pk_add_f32 v[50:51], v[50:51], v[52:53]
	v_ashrrev_i32_e32 v163, 31, v162
	v_pk_add_f32 v[50:51], v[54:55], v[50:51]
	v_lshl_add_u64 v[86:87], v[162:163], 2, s[58:59]
	v_add_f32_e32 v50, v50, v51
	ds_bpermute_b32 v51, v232, v50
	s_waitcnt lgkmcnt(0)
	v_add_f32_e32 v50, v50, v51
	ds_bpermute_b32 v51, v231, v50
	s_waitcnt lgkmcnt(0)
	v_add_f32_e32 v50, v50, v51
	v_fmamk_f32 v50, v50, 0x3c800000, v243
	s_nop 1
	v_readlane_b32 s0, v251, 47
	v_readlane_b32 s1, v251, 48
	v_rsq_f32_e32 v76, v50
	s_nop 0
	v_lshlrev_b64 v[50:51], 8, v[168:169]
	v_lshl_add_u64 v[50:51], s[0:1], 0, v[50:51]
	global_load_dwordx4 v[62:65], v[86:87], off
	global_load_dwordx4 v[54:57], v[86:87], off offset:128
	v_lshl_add_u64 v[88:89], v[162:163], 3, v[50:51]
	global_load_dwordx4 v[50:53], v[88:89], off
	global_load_dwordx4 v[58:61], v[88:89], off offset:16
	v_readlane_b32 s0, v251, 53
	v_readlane_b32 s1, v251, 54
	s_waitcnt vmcnt(3)
	v_pk_mul_f32 v[64:65], v[78:79], v[64:65]
	s_waitcnt vmcnt(2)
	v_pk_mul_f32 v[56:57], v[82:83], v[56:57]
	v_pk_mul_f32 v[54:55], v[84:85], v[54:55]
	v_pk_mul_f32 v[62:63], v[80:81], v[62:63]
	v_pk_mul_f32 v[56:57], v[56:57], v[76:77] op_sel_hi:[1,0]
	v_pk_mul_f32 v[54:55], v[54:55], v[76:77] op_sel_hi:[1,0]
	s_waitcnt vmcnt(1)
	v_mov_b32_e32 v80, v51
	v_mov_b32_e32 v81, v53
	s_waitcnt vmcnt(0)
	v_mov_b32_e32 v84, v59
	v_mov_b32_e32 v85, v61
	v_pk_mul_f32 v[62:63], v[62:63], v[76:77] op_sel_hi:[1,0]
	v_pk_mul_f32 v[64:65], v[64:65], v[76:77] op_sel_hi:[1,0]
	v_pk_mul_f32 v[82:83], v[80:81], v[54:55]
	v_pk_mul_f32 v[90:91], v[84:85], v[56:57]
	v_mov_b32_e32 v59, v60
	v_mov_b32_e32 v51, v52
	v_lshl_add_u64 v[78:79], v[170:171], 1, s[0:1]
	v_pk_fma_f32 v[60:61], v[58:59], v[64:65], v[90:91] neg_lo:[0,0,1] neg_hi:[0,0,1]
	v_pk_fma_f32 v[52:53], v[50:51], v[62:63], v[82:83] neg_lo:[0,0,1] neg_hi:[0,0,1]
	v_lshl_add_u64 v[78:79], v[162:163], 1, v[78:79]
	v_cvt_pk_bf16_f32 v52, v52, v53
	v_cvt_pk_bf16_f32 v53, v60, v61
	global_store_dwordx2 v[78:79], v[52:53], off
	v_pk_mul_f32 v[50:51], v[50:51], v[54:55]
	v_pk_mul_f32 v[52:53], v[58:59], v[56:57]
	v_pk_fma_f32 v[50:51], v[80:81], v[62:63], v[50:51]
	v_pk_fma_f32 v[52:53], v[84:85], v[64:65], v[52:53]
	v_cvt_pk_bf16_f32 v50, v50, v51
	v_cvt_pk_bf16_f32 v51, v52, v53
	global_store_dwordx2 v[78:79], v[50:51], off offset:64
	global_load_dwordx4 v[50:53], v[86:87], off offset:16
	s_nop 0
	global_load_dwordx4 v[54:57], v[86:87], off offset:144
	global_load_dwordx4 v[58:61], v[88:89], off offset:32
	global_load_dwordx4 v[62:65], v[88:89], off offset:48
	s_waitcnt vmcnt(3)
	v_pk_mul_f32 v[52:53], v[68:69], v[52:53]
	s_waitcnt vmcnt(2)
	v_pk_mul_f32 v[56:57], v[72:73], v[56:57]
	v_pk_mul_f32 v[54:55], v[74:75], v[54:55]
	v_pk_mul_f32 v[50:51], v[70:71], v[50:51]
	v_pk_mul_f32 v[56:57], v[76:77], v[56:57] op_sel_hi:[0,1]
	v_pk_mul_f32 v[54:55], v[76:77], v[54:55] op_sel_hi:[0,1]
	s_waitcnt vmcnt(1)
	v_mov_b32_e32 v68, v59
	v_mov_b32_e32 v69, v61
	s_waitcnt vmcnt(0)
	v_mov_b32_e32 v72, v63
	v_mov_b32_e32 v73, v65
	v_mov_b32_e32 v63, v64
	v_mov_b32_e32 v59, v60
	v_pk_mul_f32 v[50:51], v[76:77], v[50:51] op_sel_hi:[0,1]
	v_pk_mul_f32 v[52:53], v[76:77], v[52:53] op_sel_hi:[0,1]
	v_pk_mul_f32 v[70:71], v[54:55], v[68:69]
	v_pk_mul_f32 v[74:75], v[56:57], v[72:73]
	v_pk_mul_f32 v[54:55], v[54:55], v[58:59]
	v_pk_mul_f32 v[56:57], v[56:57], v[62:63]
	v_pk_fma_f32 v[64:65], v[52:53], v[62:63], v[74:75] neg_lo:[0,0,1] neg_hi:[0,0,1]
	v_pk_fma_f32 v[60:61], v[50:51], v[58:59], v[70:71] neg_lo:[0,0,1] neg_hi:[0,0,1]
	v_pk_fma_f32 v[52:53], v[52:53], v[72:73], v[56:57]
	v_pk_fma_f32 v[50:51], v[50:51], v[68:69], v[54:55]
	v_cvt_pk_bf16_f32 v60, v60, v61
	v_cvt_pk_bf16_f32 v61, v64, v65
	v_cvt_pk_bf16_f32 v50, v50, v51
	v_cvt_pk_bf16_f32 v51, v52, v53
	global_store_dwordx2 v[78:79], v[60:61], off offset:8
	global_store_dwordx2 v[78:79], v[50:51], off offset:72

.LBB0_143:
	v_add_f32_e32 v34, v235, v236
	v_fmamk_f32 v34, v34, 0x3a800000, v243
	s_waitcnt lgkmcnt(0)
	s_nop 1
	s_mov_b64 s[0:1], -1
	v_rsq_f32_e32 v50, v34
	s_nop 0
	s_and_b64 vcc, exec, s[48:49]
	s_cbranch_vccnz .LBB0_147
	s_and_b64 vcc, exec, s[46:47]
	s_cbranch_vccnz .LBB0_146
	v_pk_mul_f32 v[62:63], v[32:33], v[50:51] op_sel_hi:[1,0]
	v_pk_mul_f32 v[64:65], v[30:31], v[50:51] op_sel_hi:[1,0]
	v_pk_mul_f32 v[34:35], v[62:63], v[62:63]
	v_pk_mul_f32 v[36:37], v[64:65], v[64:65]
	v_pk_mul_f32 v[52:53], v[28:29], v[50:51] op_sel_hi:[1,0]
	v_pk_mov_b32 v[38:39], v[36:37], v[34:35] op_sel:[1,0]
	v_mov_b32_e32 v37, v35
	v_pk_add_f32 v[34:35], v[38:39], v[36:37]
	v_pk_mul_f32 v[54:55], v[26:27], v[50:51] op_sel_hi:[1,0]
	v_pk_add_f32 v[34:35], v[34:35], v[34:35] op_sel_hi:[0,1]
	v_pk_mul_f32 v[36:37], v[52:53], v[52:53]
	v_pk_mul_f32 v[38:39], v[54:55], v[54:55]
	v_pk_mul_f32 v[68:69], v[22:23], v[50:51] op_sel_hi:[1,0]
	v_pk_mov_b32 v[40:41], v[38:39], v[36:37] op_sel:[1,0]
	v_mov_b32_e32 v39, v37
	v_pk_mul_f32 v[66:67], v[24:25], v[50:51] op_sel_hi:[1,0]
	v_mul_f32_e32 v34, v68, v68
	v_pk_add_f32 v[36:37], v[40:41], v[38:39]
	v_pk_fma_f32 v[38:39], v[68:69], v[68:69], v[34:35] op_sel_hi:[1,1,0]
	v_mul_f32_e32 v34, v66, v66
	v_pk_add_f32 v[36:37], v[36:37], v[36:37] op_sel_hi:[0,1]
	v_pk_fma_f32 v[40:41], v[66:67], v[66:67], v[34:35] op_sel_hi:[1,1,0]
	v_pk_mul_f32 v[56:57], v[20:21], v[50:51] op_sel_hi:[1,0]
	v_pk_mul_f32 v[58:59], v[18:19], v[50:51] op_sel_hi:[1,0]
	v_mul_f32_e32 v34, v56, v56
	v_mul_f32_e32 v38, v58, v58
	v_mul_f32_e32 v40, v59, v59
	v_mul_f32_e32 v36, v57, v57
	v_pk_add_f32 v[38:39], v[38:39], v[40:41]
	v_pk_add_f32 v[34:35], v[34:35], v[36:37]
	v_ashrrev_i32_e32 v163, 31, v162
	v_pk_add_f32 v[34:35], v[38:39], v[34:35]
	v_lshl_add_u64 v[70:71], v[162:163], 2, s[58:59]
	v_add_f32_e32 v34, v34, v35
	ds_bpermute_b32 v35, v232, v34
	s_waitcnt lgkmcnt(0)
	v_add_f32_e32 v34, v34, v35
	ds_bpermute_b32 v35, v231, v34
	s_waitcnt lgkmcnt(0)
	v_add_f32_e32 v34, v34, v35
	v_fmamk_f32 v34, v34, 0x3c800000, v243
	s_nop 1
	v_readlane_b32 s0, v251, 47
	v_readlane_b32 s1, v251, 48
	v_rsq_f32_e32 v60, v34
	s_nop 0
	v_lshlrev_b64 v[34:35], 8, v[164:165]
	v_lshl_add_u64 v[34:35], s[0:1], 0, v[34:35]
	global_load_dwordx4 v[46:49], v[70:71], off
	global_load_dwordx4 v[38:41], v[70:71], off offset:128
	v_lshl_add_u64 v[72:73], v[162:163], 3, v[34:35]
	global_load_dwordx4 v[34:37], v[72:73], off
	global_load_dwordx4 v[42:45], v[72:73], off offset:16
	v_readlane_b32 s0, v251, 53
	v_readlane_b32 s1, v251, 54
	s_waitcnt vmcnt(3)
	v_pk_mul_f32 v[48:49], v[62:63], v[48:49]
	s_waitcnt vmcnt(2)
	v_pk_mul_f32 v[40:41], v[66:67], v[40:41]
	v_pk_mul_f32 v[38:39], v[68:69], v[38:39]
	v_pk_mul_f32 v[46:47], v[64:65], v[46:47]
	v_pk_mul_f32 v[40:41], v[40:41], v[60:61] op_sel_hi:[1,0]
	v_pk_mul_f32 v[38:39], v[38:39], v[60:61] op_sel_hi:[1,0]
	s_waitcnt vmcnt(1)
	v_mov_b32_e32 v64, v35
	v_mov_b32_e32 v65, v37
	s_waitcnt vmcnt(0)
	v_mov_b32_e32 v68, v43
	v_mov_b32_e32 v69, v45
	v_pk_mul_f32 v[46:47], v[46:47], v[60:61] op_sel_hi:[1,0]
	v_pk_mul_f32 v[48:49], v[48:49], v[60:61] op_sel_hi:[1,0]
	v_pk_mul_f32 v[66:67], v[64:65], v[38:39]
	v_pk_mul_f32 v[74:75], v[68:69], v[40:41]
	v_mov_b32_e32 v43, v44
	v_mov_b32_e32 v35, v36
	v_lshl_add_u64 v[62:63], v[166:167], 1, s[0:1]
	v_pk_fma_f32 v[44:45], v[42:43], v[48:49], v[74:75] neg_lo:[0,0,1] neg_hi:[0,0,1]
	v_pk_fma_f32 v[36:37], v[34:35], v[46:47], v[66:67] neg_lo:[0,0,1] neg_hi:[0,0,1]
	v_lshl_add_u64 v[62:63], v[162:163], 1, v[62:63]
	v_cvt_pk_bf16_f32 v36, v36, v37
	v_cvt_pk_bf16_f32 v37, v44, v45
	global_store_dwordx2 v[62:63], v[36:37], off
	v_pk_mul_f32 v[34:35], v[34:35], v[38:39]
	v_pk_mul_f32 v[36:37], v[42:43], v[40:41]
	v_pk_fma_f32 v[34:35], v[64:65], v[46:47], v[34:35]
	v_pk_fma_f32 v[36:37], v[68:69], v[48:49], v[36:37]
	v_cvt_pk_bf16_f32 v34, v34, v35
	v_cvt_pk_bf16_f32 v35, v36, v37
	global_store_dwordx2 v[62:63], v[34:35], off offset:64
	global_load_dwordx4 v[34:37], v[70:71], off offset:16
	s_nop 0
	global_load_dwordx4 v[38:41], v[70:71], off offset:144
	global_load_dwordx4 v[42:45], v[72:73], off offset:32
	global_load_dwordx4 v[46:49], v[72:73], off offset:48
	s_waitcnt vmcnt(3)
	v_pk_mul_f32 v[36:37], v[52:53], v[36:37]
	s_waitcnt vmcnt(2)
	v_pk_mul_f32 v[40:41], v[56:57], v[40:41]
	v_pk_mul_f32 v[38:39], v[58:59], v[38:39]
	v_pk_mul_f32 v[34:35], v[54:55], v[34:35]
	v_pk_mul_f32 v[40:41], v[60:61], v[40:41] op_sel_hi:[0,1]
	v_pk_mul_f32 v[38:39], v[60:61], v[38:39] op_sel_hi:[0,1]
	s_waitcnt vmcnt(1)
	v_mov_b32_e32 v52, v43
	v_mov_b32_e32 v53, v45
	s_waitcnt vmcnt(0)
	v_mov_b32_e32 v56, v47
	v_mov_b32_e32 v57, v49
	v_mov_b32_e32 v47, v48
	v_mov_b32_e32 v43, v44
	v_pk_mul_f32 v[34:35], v[60:61], v[34:35] op_sel_hi:[0,1]
	v_pk_mul_f32 v[36:37], v[60:61], v[36:37] op_sel_hi:[0,1]
	v_pk_mul_f32 v[54:55], v[38:39], v[52:53]
	v_pk_mul_f32 v[58:59], v[40:41], v[56:57]
	v_pk_mul_f32 v[38:39], v[38:39], v[42:43]
	v_pk_mul_f32 v[40:41], v[40:41], v[46:47]
	v_pk_fma_f32 v[48:49], v[36:37], v[46:47], v[58:59] neg_lo:[0,0,1] neg_hi:[0,0,1]
	v_pk_fma_f32 v[44:45], v[34:35], v[42:43], v[54:55] neg_lo:[0,0,1] neg_hi:[0,0,1]
	v_pk_fma_f32 v[36:37], v[36:37], v[56:57], v[40:41]
	v_pk_fma_f32 v[34:35], v[34:35], v[52:53], v[38:39]
	v_cvt_pk_bf16_f32 v44, v44, v45
	v_cvt_pk_bf16_f32 v45, v48, v49
	v_cvt_pk_bf16_f32 v34, v34, v35
	v_cvt_pk_bf16_f32 v35, v36, v37
	global_store_dwordx2 v[62:63], v[44:45], off offset:8
	global_store_dwordx2 v[62:63], v[34:35], off offset:72

.LBB0_154:
	v_add_f32_e32 v18, v233, v234
	v_fmamk_f32 v18, v18, 0x3a800000, v243
	s_waitcnt lgkmcnt(0)
	v_mov_b64_e32 v[234:235], v[244:245]
	s_nop 0
	s_nop 1
	s_mov_b64 s[0:1], -1
	v_rsq_f32_e32 v34, v18
	s_nop 0
	s_and_b64 vcc, exec, s[48:49]
	s_cbranch_vccnz .LBB0_158
	s_and_b64 vcc, exec, s[46:47]
	s_cbranch_vccnz .LBB0_157
	v_pk_mul_f32 v[46:47], v[16:17], v[34:35] op_sel_hi:[1,0]
	v_pk_mul_f32 v[48:49], v[14:15], v[34:35] op_sel_hi:[1,0]
	v_pk_mul_f32 v[18:19], v[46:47], v[46:47]
	v_pk_mul_f32 v[20:21], v[48:49], v[48:49]
	v_pk_mul_f32 v[36:37], v[12:13], v[34:35] op_sel_hi:[1,0]
	v_pk_mov_b32 v[22:23], v[20:21], v[18:19] op_sel:[1,0]
	v_mov_b32_e32 v21, v19
	v_pk_add_f32 v[18:19], v[22:23], v[20:21]
	v_pk_mul_f32 v[38:39], v[10:11], v[34:35] op_sel_hi:[1,0]
	v_pk_add_f32 v[18:19], v[18:19], v[18:19] op_sel_hi:[0,1]
	v_pk_mul_f32 v[20:21], v[36:37], v[36:37]
	v_pk_mul_f32 v[22:23], v[38:39], v[38:39]
	v_pk_mul_f32 v[52:53], v[6:7], v[34:35] op_sel_hi:[1,0]
	v_pk_mov_b32 v[24:25], v[22:23], v[20:21] op_sel:[1,0]
	v_mov_b32_e32 v23, v21
	v_pk_mul_f32 v[50:51], v[8:9], v[34:35] op_sel_hi:[1,0]
	v_mul_f32_e32 v18, v52, v52
	v_pk_add_f32 v[20:21], v[24:25], v[22:23]
	v_pk_fma_f32 v[22:23], v[52:53], v[52:53], v[18:19] op_sel_hi:[1,1,0]
	v_mul_f32_e32 v18, v50, v50
	v_pk_add_f32 v[20:21], v[20:21], v[20:21] op_sel_hi:[0,1]
	v_pk_fma_f32 v[24:25], v[50:51], v[50:51], v[18:19] op_sel_hi:[1,1,0]
	v_pk_mul_f32 v[40:41], v[4:5], v[34:35] op_sel_hi:[1,0]
	v_pk_mul_f32 v[42:43], v[2:3], v[34:35] op_sel_hi:[1,0]
	v_mul_f32_e32 v18, v40, v40
	v_mul_f32_e32 v22, v42, v42
	v_mul_f32_e32 v24, v43, v43
	v_mul_f32_e32 v20, v41, v41
	v_pk_add_f32 v[22:23], v[22:23], v[24:25]
	v_pk_add_f32 v[18:19], v[18:19], v[20:21]
	v_ashrrev_i32_e32 v163, 31, v162
	v_pk_add_f32 v[18:19], v[22:23], v[18:19]
	v_lshl_add_u64 v[54:55], v[162:163], 2, s[58:59]
	v_add_f32_e32 v18, v18, v19
	ds_bpermute_b32 v19, v232, v18
	s_waitcnt lgkmcnt(0)
	v_add_f32_e32 v18, v18, v19
	ds_bpermute_b32 v19, v231, v18
	s_waitcnt lgkmcnt(0)
	v_add_f32_e32 v18, v18, v19
	v_fmamk_f32 v18, v18, 0x3c800000, v243
	s_nop 1
	v_readlane_b32 s0, v251, 47
	v_readlane_b32 s1, v251, 48
	v_rsq_f32_e32 v44, v18
	s_nop 0
	v_lshlrev_b64 v[18:19], 8, v[158:159]
	v_lshl_add_u64 v[18:19], s[0:1], 0, v[18:19]
	global_load_dwordx4 v[30:33], v[54:55], off
	global_load_dwordx4 v[22:25], v[54:55], off offset:128
	v_lshl_add_u64 v[56:57], v[162:163], 3, v[18:19]
	global_load_dwordx4 v[18:21], v[56:57], off
	global_load_dwordx4 v[26:29], v[56:57], off offset:16
	v_readlane_b32 s0, v251, 53
	v_readlane_b32 s1, v251, 54
	s_waitcnt vmcnt(3)
	v_pk_mul_f32 v[32:33], v[46:47], v[32:33]
	s_waitcnt vmcnt(2)
	v_pk_mul_f32 v[24:25], v[50:51], v[24:25]
	v_pk_mul_f32 v[22:23], v[52:53], v[22:23]
	v_pk_mul_f32 v[30:31], v[48:49], v[30:31]
	v_pk_mul_f32 v[24:25], v[24:25], v[44:45] op_sel_hi:[1,0]
	v_pk_mul_f32 v[22:23], v[22:23], v[44:45] op_sel_hi:[1,0]
	s_waitcnt vmcnt(1)
	v_mov_b32_e32 v48, v19
	v_mov_b32_e32 v49, v21
	s_waitcnt vmcnt(0)
	v_mov_b32_e32 v52, v27
	v_mov_b32_e32 v53, v29
	v_pk_mul_f32 v[30:31], v[30:31], v[44:45] op_sel_hi:[1,0]
	v_pk_mul_f32 v[32:33], v[32:33], v[44:45] op_sel_hi:[1,0]
	v_pk_mul_f32 v[50:51], v[48:49], v[22:23]
	v_pk_mul_f32 v[58:59], v[52:53], v[24:25]
	v_mov_b32_e32 v27, v28
	v_mov_b32_e32 v19, v20
	v_lshl_add_u64 v[46:47], v[160:161], 1, s[0:1]
	v_pk_fma_f32 v[28:29], v[26:27], v[32:33], v[58:59] neg_lo:[0,0,1] neg_hi:[0,0,1]
	v_pk_fma_f32 v[20:21], v[18:19], v[30:31], v[50:51] neg_lo:[0,0,1] neg_hi:[0,0,1]
	v_lshl_add_u64 v[46:47], v[162:163], 1, v[46:47]
	v_cvt_pk_bf16_f32 v20, v20, v21
	v_cvt_pk_bf16_f32 v21, v28, v29
	global_store_dwordx2 v[46:47], v[20:21], off
	v_pk_mul_f32 v[18:19], v[18:19], v[22:23]
	v_pk_mul_f32 v[20:21], v[26:27], v[24:25]
	v_pk_fma_f32 v[18:19], v[48:49], v[30:31], v[18:19]
	v_pk_fma_f32 v[20:21], v[52:53], v[32:33], v[20:21]
	v_cvt_pk_bf16_f32 v18, v18, v19
	v_cvt_pk_bf16_f32 v19, v20, v21
	global_store_dwordx2 v[46:47], v[18:19], off offset:64
	global_load_dwordx4 v[18:21], v[54:55], off offset:16
	s_nop 0
	global_load_dwordx4 v[22:25], v[54:55], off offset:144
	global_load_dwordx4 v[26:29], v[56:57], off offset:32
	global_load_dwordx4 v[30:33], v[56:57], off offset:48
	s_waitcnt vmcnt(3)
	v_pk_mul_f32 v[20:21], v[36:37], v[20:21]
	s_waitcnt vmcnt(2)
	v_pk_mul_f32 v[24:25], v[40:41], v[24:25]
	v_pk_mul_f32 v[22:23], v[42:43], v[22:23]
	v_pk_mul_f32 v[18:19], v[38:39], v[18:19]
	v_pk_mul_f32 v[24:25], v[44:45], v[24:25] op_sel_hi:[0,1]
	v_pk_mul_f32 v[22:23], v[44:45], v[22:23] op_sel_hi:[0,1]
	s_waitcnt vmcnt(1)
	v_mov_b32_e32 v36, v27
	v_mov_b32_e32 v37, v29
	s_waitcnt vmcnt(0)
	v_mov_b32_e32 v40, v31
	v_mov_b32_e32 v41, v33
	v_mov_b32_e32 v31, v32
	v_mov_b32_e32 v27, v28
	v_pk_mul_f32 v[18:19], v[44:45], v[18:19] op_sel_hi:[0,1]
	v_pk_mul_f32 v[20:21], v[44:45], v[20:21] op_sel_hi:[0,1]
	v_pk_mul_f32 v[38:39], v[22:23], v[36:37]
	v_pk_mul_f32 v[42:43], v[24:25], v[40:41]
	v_pk_mul_f32 v[22:23], v[22:23], v[26:27]
	v_pk_mul_f32 v[24:25], v[24:25], v[30:31]
	v_pk_fma_f32 v[32:33], v[20:21], v[30:31], v[42:43] neg_lo:[0,0,1] neg_hi:[0,0,1]
	v_pk_fma_f32 v[28:29], v[18:19], v[26:27], v[38:39] neg_lo:[0,0,1] neg_hi:[0,0,1]
	v_pk_fma_f32 v[20:21], v[20:21], v[40:41], v[24:25]
	v_pk_fma_f32 v[18:19], v[18:19], v[36:37], v[22:23]
	v_cvt_pk_bf16_f32 v28, v28, v29
	v_cvt_pk_bf16_f32 v29, v32, v33
	v_cvt_pk_bf16_f32 v18, v18, v19
	v_cvt_pk_bf16_f32 v19, v20, v21
	global_store_dwordx2 v[46:47], v[28:29], off offset:8
	global_store_dwordx2 v[46:47], v[18:19], off offset:72

.LBB0_243:
	s_ashr_i32 s69, s68, 31
	s_lshl_b64 s[0:1], s[68:69], 8
	s_add_u32 s0, s0, s27
	s_addc_u32 s1, s1, s75
	v_ashrrev_i32_e32 v151, 31, v150
	v_lshl_add_u64 v[158:159], s[0:1], 0, v[150:151]
	v_readlane_b32 s8, v251, 57
	v_lshlrev_b64 v[130:131], 5, v[158:159]
	v_readlane_b32 s9, v251, 58
	s_lshl_b32 s0, s83, 8
	s_add_i32 s76, s78, s0
	v_lshl_add_u64 v[134:135], s[8:9], 0, v[130:131]
	global_load_dwordx4 v[130:133], v[134:135], off
	s_nop 0
	global_load_dwordx4 v[134:137], v[134:135], off offset:16
	v_lshlrev_b32_e32 v154, 3, v185
	v_readlane_b32 s4, v251, 47
	v_ashrrev_i32_e32 v155, 31, v154
	v_readlane_b32 s5, v251, 48
	v_lshlrev_b64 v[156:157], 3, v[154:155]
	v_readlane_b32 s6, v251, 55
	v_lshlrev_b64 v[180:181], 11, v[158:159]
	v_readlane_b32 s7, v251, 56
	s_lshl_b64 s[44:45], s[76:77], 1
	s_waitcnt vmcnt(0)
	v_mov_b32_e32 v152, v130
	v_mov_b32_e32 v153, v134
	v_mov_b32_e32 v134, v131
	v_pk_add_f32 v[130:131], v[152:153], v[134:135]
	v_mov_b32_e32 v134, v132
	v_mov_b32_e32 v135, v136
	v_mov_b32_e32 v136, v133
	v_pk_add_f32 v[132:133], v[134:135], v[136:137]
	v_lshl_add_u64 v[180:181], s[6:7], 0, v[180:181]
	v_pk_add_f32 v[130:131], v[130:131], v[132:133]
	v_lshl_add_u64 v[180:181], v[180:181], 0, s[44:45]
	v_add_f32_e32 v130, v130, v131
	v_fmamk_f32 v130, v130, 0x3b000000, v243
	v_rsq_f32_e32 v130, v130
	s_nop 0
	v_pk_mul_f32 v[172:173], v[126:127], v[130:131] op_sel_hi:[1,0]
	v_pk_mul_f32 v[174:175], v[128:129], v[130:131] op_sel_hi:[1,0]
	v_pk_mul_f32 v[134:135], v[172:173], v[172:173]
	v_pk_mul_f32 v[132:133], v[174:175], v[174:175]
	v_pk_mul_f32 v[160:161], v[122:123], v[130:131] op_sel_hi:[1,0]
	v_pk_mov_b32 v[136:137], v[134:135], v[132:133] op_sel:[1,0]
	v_mov_b32_e32 v135, v133
	v_pk_add_f32 v[132:133], v[136:137], v[134:135]
	v_pk_mul_f32 v[162:163], v[124:125], v[130:131] op_sel_hi:[1,0]
	v_pk_add_f32 v[132:133], v[132:133], v[132:133] op_sel_hi:[0,1]
	v_pk_mul_f32 v[134:135], v[162:163], v[162:163]
	v_pk_mul_f32 v[136:137], v[160:161], v[160:161]
	v_pk_mul_f32 v[178:179], v[118:119], v[130:131] op_sel_hi:[1,0]
	v_pk_mov_b32 v[152:153], v[136:137], v[134:135] op_sel:[1,0]
	v_mov_b32_e32 v137, v135
	v_pk_mul_f32 v[176:177], v[120:121], v[130:131] op_sel_hi:[1,0]
	v_mul_f32_e32 v132, v178, v178
	v_pk_add_f32 v[134:135], v[152:153], v[136:137]
	v_pk_fma_f32 v[136:137], v[178:179], v[178:179], v[132:133] op_sel_hi:[1,1,0]
	v_mul_f32_e32 v132, v176, v176
	v_pk_add_f32 v[134:135], v[134:135], v[134:135] op_sel_hi:[0,1]
	v_pk_fma_f32 v[152:153], v[176:177], v[176:177], v[132:133] op_sel_hi:[1,1,0]
	v_pk_mul_f32 v[164:165], v[116:117], v[130:131] op_sel_hi:[1,0]
	v_pk_mul_f32 v[166:167], v[114:115], v[130:131] op_sel_hi:[1,0]
	v_mul_f32_e32 v132, v164, v164
	v_mul_f32_e32 v136, v166, v166
	v_mul_f32_e32 v152, v167, v167
	v_mul_f32_e32 v134, v165, v165
	v_pk_add_f32 v[130:131], v[136:137], v[152:153]
	v_pk_add_f32 v[132:133], v[132:133], v[134:135]
	v_lshl_add_u64 v[152:153], v[154:155], 2, s[58:59]
	v_pk_add_f32 v[130:131], v[130:131], v[132:133]
	global_load_dwordx4 v[188:191], v[152:153], off
	global_load_dwordx4 v[192:195], v[152:153], off offset:128
	v_add_f32_e32 v130, v130, v131
	ds_bpermute_b32 v131, v187, v130
	v_lshlrev_b64 v[154:155], 1, v[154:155]
	v_lshl_add_u64 v[180:181], v[180:181], 0, v[154:155]
	s_waitcnt lgkmcnt(0)
	v_add_f32_e32 v130, v130, v131
	ds_bpermute_b32 v131, v186, v130
	s_waitcnt lgkmcnt(0)
	v_add_f32_e32 v130, v130, v131
	v_fmamk_f32 v130, v130, 0x3c800000, v243
	s_waitcnt vmcnt(1)
	v_pk_mul_f32 v[174:175], v[190:191], v[174:175]
	s_nop 1
	s_waitcnt vmcnt(0)
	v_pk_mul_f32 v[178:179], v[192:193], v[178:179]
	v_pk_mul_f32 v[176:177], v[194:195], v[176:177]
	v_pk_mul_f32 v[172:173], v[188:189], v[172:173]
	v_rsq_f32_e32 v130, v130
	s_nop 0
	v_mul_f32_e32 v168, 0x3dd53b94, v130
	v_lshlrev_b64 v[130:131], 8, v[158:159]
	v_lshl_add_u64 v[130:131], s[4:5], 0, v[130:131]
	v_lshl_add_u64 v[170:171], v[130:131], 0, v[156:157]
	global_load_dwordx4 v[130:133], v[170:171], off
	global_load_dwordx4 v[134:137], v[170:171], off offset:16
	v_pk_mul_f32 v[176:177], v[176:177], v[168:169] op_sel_hi:[1,0]
	v_pk_mul_f32 v[178:179], v[178:179], v[168:169] op_sel_hi:[1,0]
	v_pk_mul_f32 v[172:173], v[172:173], v[168:169] op_sel_hi:[1,0]
	v_pk_mul_f32 v[174:175], v[174:175], v[168:169] op_sel_hi:[1,0]
	s_waitcnt vmcnt(1)
	v_mov_b32_e32 v188, v131
	v_mov_b32_e32 v189, v133
	s_waitcnt vmcnt(0)
	v_mov_b32_e32 v192, v135
	v_mov_b32_e32 v193, v137
	v_pk_mul_f32 v[190:191], v[188:189], v[178:179]
	v_pk_mul_f32 v[194:195], v[192:193], v[176:177]
	v_mov_b32_e32 v135, v136
	v_mov_b32_e32 v131, v132
	v_pk_fma_f32 v[136:137], v[134:135], v[174:175], v[194:195] neg_lo:[0,0,1] neg_hi:[0,0,1]
	v_pk_fma_f32 v[132:133], v[130:131], v[172:173], v[190:191] neg_lo:[0,0,1] neg_hi:[0,0,1]
	v_pk_mul_f32 v[130:131], v[130:131], v[178:179]
	v_cvt_pk_bf16_f32 v132, v132, v133
	v_cvt_pk_bf16_f32 v133, v136, v137
	global_store_dwordx2 v[180:181], v[132:133], off
	v_pk_mul_f32 v[132:133], v[134:135], v[176:177]
	v_pk_fma_f32 v[130:131], v[188:189], v[172:173], v[130:131]
	v_pk_fma_f32 v[132:133], v[192:193], v[174:175], v[132:133]
	v_cvt_pk_bf16_f32 v130, v130, v131
	v_cvt_pk_bf16_f32 v131, v132, v133
	global_store_dwordx2 v[180:181], v[130:131], off offset:64
	global_load_dwordx4 v[130:133], v[152:153], off offset:16
	s_nop 0
	global_load_dwordx4 v[134:137], v[152:153], off offset:144
	global_load_dwordx4 v[172:175], v[170:171], off offset:32
	global_load_dwordx4 v[176:179], v[170:171], off offset:48
	v_lshl_add_u64 v[170:171], v[158:159], 0, 16
	s_waitcnt vmcnt(3)
	v_pk_mul_f32 v[132:133], v[132:133], v[162:163]
	s_waitcnt vmcnt(2)
	v_pk_mul_f32 v[134:135], v[134:135], v[166:167]
	v_pk_mul_f32 v[136:137], v[136:137], v[164:165]
	v_pk_mul_f32 v[130:131], v[130:131], v[160:161]
	v_pk_mul_f32 v[136:137], v[136:137], v[168:169] op_sel_hi:[1,0]
	v_pk_mul_f32 v[134:135], v[134:135], v[168:169] op_sel_hi:[1,0]
	s_waitcnt vmcnt(1)
	v_mov_b32_e32 v160, v173
	v_mov_b32_e32 v161, v175
	s_waitcnt vmcnt(0)
	v_mov_b32_e32 v164, v177
	v_mov_b32_e32 v165, v179
	v_mov_b32_e32 v177, v178
	v_mov_b32_e32 v173, v174
	v_pk_mul_f32 v[130:131], v[130:131], v[168:169] op_sel_hi:[1,0]
	v_pk_mul_f32 v[132:133], v[132:133], v[168:169] op_sel_hi:[1,0]
	v_pk_mul_f32 v[162:163], v[160:161], v[134:135]
	v_pk_mul_f32 v[166:167], v[164:165], v[136:137]
	v_pk_mul_f32 v[134:135], v[172:173], v[134:135]
	v_pk_mul_f32 v[136:137], v[176:177], v[136:137]
	v_pk_fma_f32 v[166:167], v[176:177], v[132:133], v[166:167] neg_lo:[0,0,1] neg_hi:[0,0,1]
	v_pk_fma_f32 v[162:163], v[172:173], v[130:131], v[162:163] neg_lo:[0,0,1] neg_hi:[0,0,1]
	v_pk_fma_f32 v[132:133], v[164:165], v[132:133], v[136:137]
	v_pk_fma_f32 v[130:131], v[160:161], v[130:131], v[134:135]
	v_cvt_pk_bf16_f32 v162, v162, v163
	v_cvt_pk_bf16_f32 v130, v130, v131
	v_cvt_pk_bf16_f32 v131, v132, v133
	v_cvt_pk_bf16_f32 v163, v166, v167
	global_store_dwordx2 v[180:181], v[130:131], off offset:72
	v_lshlrev_b64 v[130:131], 5, v[170:171]
	global_store_dwordx2 v[180:181], v[162:163], off offset:8
	v_lshl_add_u64 v[134:135], s[8:9], 0, v[130:131]
	global_load_dwordx4 v[130:133], v[134:135], off
	s_nop 0
	global_load_dwordx4 v[134:137], v[134:135], off offset:16
	s_nop 0
	global_load_dwordx4 v[188:191], v[152:153], off
	global_load_dwordx4 v[192:195], v[152:153], off offset:128
	s_waitcnt vmcnt(3)
	v_mov_b32_e32 v160, v130
	s_waitcnt vmcnt(2)
	v_mov_b32_e32 v161, v134
	v_mov_b32_e32 v134, v131
	v_pk_add_f32 v[130:131], v[160:161], v[134:135]
	v_mov_b32_e32 v134, v132
	v_mov_b32_e32 v135, v136
	v_mov_b32_e32 v136, v133
	v_pk_add_f32 v[132:133], v[134:135], v[136:137]
	s_nop 0
	v_pk_add_f32 v[130:131], v[130:131], v[132:133]
	s_nop 0
	v_add_f32_e32 v130, v130, v131
	v_fmamk_f32 v130, v130, 0x3b000000, v243
	v_rsq_f32_e32 v130, v130
	s_nop 0
	v_pk_mul_f32 v[174:175], v[110:111], v[130:131] op_sel_hi:[1,0]
	v_pk_mul_f32 v[176:177], v[112:113], v[130:131] op_sel_hi:[1,0]
	v_pk_mul_f32 v[134:135], v[174:175], v[174:175]
	v_pk_mul_f32 v[132:133], v[176:177], v[176:177]
	v_pk_mul_f32 v[160:161], v[106:107], v[130:131] op_sel_hi:[1,0]
	v_pk_mov_b32 v[136:137], v[134:135], v[132:133] op_sel:[1,0]
	v_mov_b32_e32 v135, v133
	v_pk_add_f32 v[132:133], v[136:137], v[134:135]
	v_pk_mul_f32 v[162:163], v[108:109], v[130:131] op_sel_hi:[1,0]
	v_pk_add_f32 v[132:133], v[132:133], v[132:133] op_sel_hi:[0,1]
	v_pk_mul_f32 v[134:135], v[162:163], v[162:163]
	v_pk_mul_f32 v[136:137], v[160:161], v[160:161]
	v_pk_mul_f32 v[180:181], v[102:103], v[130:131] op_sel_hi:[1,0]
	v_pk_mov_b32 v[164:165], v[136:137], v[134:135] op_sel:[1,0]
	v_mov_b32_e32 v137, v135
	v_pk_mul_f32 v[178:179], v[104:105], v[130:131] op_sel_hi:[1,0]
	v_mul_f32_e32 v132, v180, v180
	v_pk_add_f32 v[134:135], v[164:165], v[136:137]
	v_pk_fma_f32 v[136:137], v[180:181], v[180:181], v[132:133] op_sel_hi:[1,1,0]
	v_mul_f32_e32 v132, v178, v178
	v_pk_add_f32 v[134:135], v[134:135], v[134:135] op_sel_hi:[0,1]
	v_pk_fma_f32 v[168:169], v[178:179], v[178:179], v[132:133] op_sel_hi:[1,1,0]
	v_pk_mul_f32 v[164:165], v[100:101], v[130:131] op_sel_hi:[1,0]
	v_pk_mul_f32 v[166:167], v[98:99], v[130:131] op_sel_hi:[1,0]
	v_mul_f32_e32 v132, v164, v164
	v_mul_f32_e32 v136, v166, v166
	v_mul_f32_e32 v168, v167, v167
	v_mul_f32_e32 v134, v165, v165
	v_pk_add_f32 v[130:131], v[136:137], v[168:169]
	v_pk_add_f32 v[132:133], v[132:133], v[134:135]
	s_waitcnt vmcnt(0)
	v_pk_mul_f32 v[180:181], v[192:193], v[180:181]
	v_pk_add_f32 v[130:131], v[130:131], v[132:133]
	v_pk_mul_f32 v[178:179], v[194:195], v[178:179]
	v_add_f32_e32 v130, v130, v131
	ds_bpermute_b32 v131, v187, v130
	v_pk_mul_f32 v[176:177], v[190:191], v[176:177]
	v_pk_mul_f32 v[174:175], v[188:189], v[174:175]
	s_waitcnt lgkmcnt(0)
	v_add_f32_e32 v130, v130, v131
	ds_bpermute_b32 v131, v186, v130
	s_waitcnt lgkmcnt(0)
	v_add_f32_e32 v130, v130, v131
	v_fmamk_f32 v130, v130, 0x3c800000, v243
	v_rsq_f32_e32 v130, v130
	s_nop 0
	v_mul_f32_e32 v168, 0x3dd53b94, v130
	v_lshlrev_b64 v[130:131], 8, v[170:171]
	v_lshl_add_u64 v[130:131], s[4:5], 0, v[130:131]
	v_lshl_add_u64 v[172:173], v[130:131], 0, v[156:157]
	global_load_dwordx4 v[130:133], v[172:173], off
	global_load_dwordx4 v[134:137], v[172:173], off offset:16
	v_pk_mul_f32 v[178:179], v[178:179], v[168:169] op_sel_hi:[1,0]
	v_pk_mul_f32 v[180:181], v[180:181], v[168:169] op_sel_hi:[1,0]
	v_lshlrev_b64 v[170:171], 11, v[170:171]
	v_pk_mul_f32 v[174:175], v[174:175], v[168:169] op_sel_hi:[1,0]
	v_pk_mul_f32 v[176:177], v[176:177], v[168:169] op_sel_hi:[1,0]
	v_lshl_add_u64 v[170:171], s[6:7], 0, v[170:171]
	v_lshl_add_u64 v[170:171], v[170:171], 0, s[44:45]
	v_lshl_add_u64 v[170:171], v[170:171], 0, v[154:155]
	s_waitcnt vmcnt(1)
	v_mov_b32_e32 v188, v131
	v_mov_b32_e32 v189, v133
	s_waitcnt vmcnt(0)
	v_mov_b32_e32 v192, v135
	v_mov_b32_e32 v193, v137
	v_pk_mul_f32 v[190:191], v[188:189], v[180:181]
	v_pk_mul_f32 v[194:195], v[192:193], v[178:179]
	v_mov_b32_e32 v135, v136
	v_mov_b32_e32 v131, v132
	v_pk_fma_f32 v[136:137], v[134:135], v[176:177], v[194:195] neg_lo:[0,0,1] neg_hi:[0,0,1]
	v_pk_fma_f32 v[132:133], v[130:131], v[174:175], v[190:191] neg_lo:[0,0,1] neg_hi:[0,0,1]
	v_pk_mul_f32 v[130:131], v[130:131], v[180:181]
	v_cvt_pk_bf16_f32 v132, v132, v133
	v_cvt_pk_bf16_f32 v133, v136, v137
	global_store_dwordx2 v[170:171], v[132:133], off
	v_pk_mul_f32 v[132:133], v[134:135], v[178:179]
	v_pk_fma_f32 v[130:131], v[188:189], v[174:175], v[130:131]
	v_pk_fma_f32 v[132:133], v[192:193], v[176:177], v[132:133]
	v_cvt_pk_bf16_f32 v130, v130, v131
	v_cvt_pk_bf16_f32 v131, v132, v133
	global_store_dwordx2 v[170:171], v[130:131], off offset:64
	global_load_dwordx4 v[130:133], v[152:153], off offset:16
	s_nop 0
	global_load_dwordx4 v[134:137], v[152:153], off offset:144
	global_load_dwordx4 v[174:177], v[172:173], off offset:32
	global_load_dwordx4 v[178:181], v[172:173], off offset:48
	s_waitcnt vmcnt(3)
	v_pk_mul_f32 v[132:133], v[132:133], v[162:163]
	s_waitcnt vmcnt(2)
	v_pk_mul_f32 v[134:135], v[134:135], v[166:167]
	v_pk_mul_f32 v[136:137], v[136:137], v[164:165]
	v_pk_mul_f32 v[130:131], v[130:131], v[160:161]
	v_pk_mul_f32 v[136:137], v[136:137], v[168:169] op_sel_hi:[1,0]
	v_pk_mul_f32 v[134:135], v[134:135], v[168:169] op_sel_hi:[1,0]
	s_waitcnt vmcnt(1)
	v_mov_b32_e32 v160, v175
	v_mov_b32_e32 v161, v177
	s_waitcnt vmcnt(0)
	v_mov_b32_e32 v164, v179
	v_mov_b32_e32 v165, v181
	v_mov_b32_e32 v179, v180
	v_mov_b32_e32 v175, v176
	v_pk_mul_f32 v[130:131], v[130:131], v[168:169] op_sel_hi:[1,0]
	v_pk_mul_f32 v[132:133], v[132:133], v[168:169] op_sel_hi:[1,0]
	v_pk_mul_f32 v[162:163], v[160:161], v[134:135]
	v_pk_mul_f32 v[166:167], v[164:165], v[136:137]
	v_pk_mul_f32 v[134:135], v[174:175], v[134:135]
	v_pk_mul_f32 v[136:137], v[178:179], v[136:137]
	v_pk_fma_f32 v[166:167], v[178:179], v[132:133], v[166:167] neg_lo:[0,0,1] neg_hi:[0,0,1]
	v_pk_fma_f32 v[162:163], v[174:175], v[130:131], v[162:163] neg_lo:[0,0,1] neg_hi:[0,0,1]
	v_pk_fma_f32 v[132:133], v[164:165], v[132:133], v[136:137]
	v_pk_fma_f32 v[130:131], v[160:161], v[130:131], v[134:135]
	v_cvt_pk_bf16_f32 v162, v162, v163
	v_cvt_pk_bf16_f32 v163, v166, v167
	v_cvt_pk_bf16_f32 v130, v130, v131
	v_cvt_pk_bf16_f32 v131, v132, v133
	global_store_dwordx2 v[170:171], v[162:163], off offset:8
	global_store_dwordx2 v[170:171], v[130:131], off offset:72
	v_lshl_add_u64 v[170:171], v[158:159], 0, 32
	v_lshlrev_b64 v[130:131], 5, v[170:171]
	v_lshl_add_u64 v[134:135], s[8:9], 0, v[130:131]
	global_load_dwordx4 v[130:133], v[134:135], off
	s_nop 0
	global_load_dwordx4 v[134:137], v[134:135], off offset:16
	s_nop 0
	global_load_dwordx4 v[188:191], v[152:153], off
	global_load_dwordx4 v[192:195], v[152:153], off offset:128
	s_waitcnt vmcnt(3)
	v_mov_b32_e32 v160, v130
	s_waitcnt vmcnt(2)
	v_mov_b32_e32 v161, v134
	v_mov_b32_e32 v134, v131
	v_pk_add_f32 v[130:131], v[160:161], v[134:135]
	v_mov_b32_e32 v134, v132
	v_mov_b32_e32 v135, v136
	v_mov_b32_e32 v136, v133
	v_pk_add_f32 v[132:133], v[134:135], v[136:137]
	s_nop 0
	v_pk_add_f32 v[130:131], v[130:131], v[132:133]
	s_nop 0
	v_add_f32_e32 v130, v130, v131
	v_fmamk_f32 v130, v130, 0x3b000000, v243
	v_rsq_f32_e32 v130, v130
	s_nop 0
	v_pk_mul_f32 v[174:175], v[94:95], v[130:131] op_sel_hi:[1,0]
	v_pk_mul_f32 v[176:177], v[96:97], v[130:131] op_sel_hi:[1,0]
	v_pk_mul_f32 v[134:135], v[174:175], v[174:175]
	v_pk_mul_f32 v[132:133], v[176:177], v[176:177]
	v_pk_mul_f32 v[160:161], v[90:91], v[130:131] op_sel_hi:[1,0]
	v_pk_mov_b32 v[136:137], v[134:135], v[132:133] op_sel:[1,0]
	v_mov_b32_e32 v135, v133
	v_pk_add_f32 v[132:133], v[136:137], v[134:135]
	v_pk_mul_f32 v[162:163], v[92:93], v[130:131] op_sel_hi:[1,0]
	v_pk_add_f32 v[132:133], v[132:133], v[132:133] op_sel_hi:[0,1]
	v_pk_mul_f32 v[134:135], v[162:163], v[162:163]
	v_pk_mul_f32 v[136:137], v[160:161], v[160:161]
	v_pk_mul_f32 v[180:181], v[86:87], v[130:131] op_sel_hi:[1,0]
	v_pk_mov_b32 v[164:165], v[136:137], v[134:135] op_sel:[1,0]
	v_mov_b32_e32 v137, v135
	v_pk_mul_f32 v[178:179], v[88:89], v[130:131] op_sel_hi:[1,0]
	v_mul_f32_e32 v132, v180, v180
	v_pk_add_f32 v[134:135], v[164:165], v[136:137]
	v_pk_fma_f32 v[136:137], v[180:181], v[180:181], v[132:133] op_sel_hi:[1,1,0]
	v_mul_f32_e32 v132, v178, v178
	v_pk_add_f32 v[134:135], v[134:135], v[134:135] op_sel_hi:[0,1]
	v_pk_fma_f32 v[168:169], v[178:179], v[178:179], v[132:133] op_sel_hi:[1,1,0]
	v_pk_mul_f32 v[164:165], v[84:85], v[130:131] op_sel_hi:[1,0]
	v_pk_mul_f32 v[166:167], v[82:83], v[130:131] op_sel_hi:[1,0]
	v_mul_f32_e32 v132, v164, v164
	v_mul_f32_e32 v136, v166, v166
	v_mul_f32_e32 v168, v167, v167
	v_mul_f32_e32 v134, v165, v165
	v_pk_add_f32 v[130:131], v[136:137], v[168:169]
	v_pk_add_f32 v[132:133], v[132:133], v[134:135]
	s_waitcnt vmcnt(0)
	v_pk_mul_f32 v[180:181], v[192:193], v[180:181]
	v_pk_add_f32 v[130:131], v[130:131], v[132:133]
	v_pk_mul_f32 v[178:179], v[194:195], v[178:179]
	v_add_f32_e32 v130, v130, v131
	ds_bpermute_b32 v131, v187, v130
	v_pk_mul_f32 v[176:177], v[190:191], v[176:177]
	v_pk_mul_f32 v[174:175], v[188:189], v[174:175]
	s_waitcnt lgkmcnt(0)
	v_add_f32_e32 v130, v130, v131
	ds_bpermute_b32 v131, v186, v130
	s_waitcnt lgkmcnt(0)
	v_add_f32_e32 v130, v130, v131
	v_fmamk_f32 v130, v130, 0x3c800000, v243
	v_rsq_f32_e32 v130, v130
	s_nop 0
	v_mul_f32_e32 v168, 0x3dd53b94, v130
	v_lshlrev_b64 v[130:131], 8, v[170:171]
	v_lshl_add_u64 v[130:131], s[4:5], 0, v[130:131]
	v_lshl_add_u64 v[172:173], v[130:131], 0, v[156:157]
	global_load_dwordx4 v[130:133], v[172:173], off
	global_load_dwordx4 v[134:137], v[172:173], off offset:16
	v_pk_mul_f32 v[178:179], v[178:179], v[168:169] op_sel_hi:[1,0]
	v_pk_mul_f32 v[180:181], v[180:181], v[168:169] op_sel_hi:[1,0]
	v_lshlrev_b64 v[170:171], 11, v[170:171]
	v_pk_mul_f32 v[174:175], v[174:175], v[168:169] op_sel_hi:[1,0]
	v_pk_mul_f32 v[176:177], v[176:177], v[168:169] op_sel_hi:[1,0]
	v_lshl_add_u64 v[170:171], s[6:7], 0, v[170:171]
	v_lshl_add_u64 v[170:171], v[170:171], 0, s[44:45]
	v_lshl_add_u64 v[170:171], v[170:171], 0, v[154:155]
	s_waitcnt vmcnt(1)
	v_mov_b32_e32 v188, v131
	v_mov_b32_e32 v189, v133
	s_waitcnt vmcnt(0)
	v_mov_b32_e32 v192, v135
	v_mov_b32_e32 v193, v137
	v_pk_mul_f32 v[190:191], v[188:189], v[180:181]
	v_pk_mul_f32 v[194:195], v[192:193], v[178:179]
	v_mov_b32_e32 v135, v136
	v_mov_b32_e32 v131, v132
	v_pk_fma_f32 v[136:137], v[134:135], v[176:177], v[194:195] neg_lo:[0,0,1] neg_hi:[0,0,1]
	v_pk_fma_f32 v[132:133], v[130:131], v[174:175], v[190:191] neg_lo:[0,0,1] neg_hi:[0,0,1]
	v_pk_mul_f32 v[130:131], v[130:131], v[180:181]
	v_cvt_pk_bf16_f32 v132, v132, v133
	v_cvt_pk_bf16_f32 v133, v136, v137
	global_store_dwordx2 v[170:171], v[132:133], off
	v_pk_mul_f32 v[132:133], v[134:135], v[178:179]
	v_pk_fma_f32 v[130:131], v[188:189], v[174:175], v[130:131]
	v_pk_fma_f32 v[132:133], v[192:193], v[176:177], v[132:133]
	v_cvt_pk_bf16_f32 v130, v130, v131
	v_cvt_pk_bf16_f32 v131, v132, v133
	global_store_dwordx2 v[170:171], v[130:131], off offset:64
	global_load_dwordx4 v[130:133], v[152:153], off offset:16
	s_nop 0
	global_load_dwordx4 v[134:137], v[152:153], off offset:144
	global_load_dwordx4 v[174:177], v[172:173], off offset:32
	global_load_dwordx4 v[178:181], v[172:173], off offset:48
	s_waitcnt vmcnt(3)
	v_pk_mul_f32 v[132:133], v[132:133], v[162:163]
	s_waitcnt vmcnt(2)
	v_pk_mul_f32 v[134:135], v[134:135], v[166:167]
	v_pk_mul_f32 v[136:137], v[136:137], v[164:165]
	v_pk_mul_f32 v[130:131], v[130:131], v[160:161]
	v_pk_mul_f32 v[136:137], v[136:137], v[168:169] op_sel_hi:[1,0]
	v_pk_mul_f32 v[134:135], v[134:135], v[168:169] op_sel_hi:[1,0]
	s_waitcnt vmcnt(1)
	v_mov_b32_e32 v160, v175
	v_mov_b32_e32 v161, v177
	s_waitcnt vmcnt(0)
	v_mov_b32_e32 v164, v179
	v_mov_b32_e32 v165, v181
	v_mov_b32_e32 v179, v180
	v_mov_b32_e32 v175, v176
	v_pk_mul_f32 v[130:131], v[130:131], v[168:169] op_sel_hi:[1,0]
	v_pk_mul_f32 v[132:133], v[132:133], v[168:169] op_sel_hi:[1,0]
	v_pk_mul_f32 v[162:163], v[160:161], v[134:135]
	v_pk_mul_f32 v[166:167], v[164:165], v[136:137]
	v_pk_mul_f32 v[134:135], v[174:175], v[134:135]
	v_pk_mul_f32 v[136:137], v[178:179], v[136:137]
	v_pk_fma_f32 v[166:167], v[178:179], v[132:133], v[166:167] neg_lo:[0,0,1] neg_hi:[0,0,1]
	v_pk_fma_f32 v[162:163], v[174:175], v[130:131], v[162:163] neg_lo:[0,0,1] neg_hi:[0,0,1]
	v_pk_fma_f32 v[132:133], v[164:165], v[132:133], v[136:137]
	v_pk_fma_f32 v[130:131], v[160:161], v[130:131], v[134:135]
	v_cvt_pk_bf16_f32 v162, v162, v163
	v_cvt_pk_bf16_f32 v163, v166, v167
	v_cvt_pk_bf16_f32 v130, v130, v131
	v_cvt_pk_bf16_f32 v131, v132, v133
	global_store_dwordx2 v[170:171], v[162:163], off offset:8
	global_store_dwordx2 v[170:171], v[130:131], off offset:72
	v_lshl_add_u64 v[170:171], v[158:159], 0, 48
	v_lshlrev_b64 v[130:131], 5, v[170:171]
	v_lshl_add_u64 v[134:135], s[8:9], 0, v[130:131]
	global_load_dwordx4 v[130:133], v[134:135], off
	s_nop 0
	global_load_dwordx4 v[134:137], v[134:135], off offset:16
	s_nop 0
	global_load_dwordx4 v[188:191], v[152:153], off
	global_load_dwordx4 v[192:195], v[152:153], off offset:128
	s_waitcnt vmcnt(3)
	v_mov_b32_e32 v160, v130
	s_waitcnt vmcnt(2)
	v_mov_b32_e32 v161, v134
	v_mov_b32_e32 v134, v131
	v_pk_add_f32 v[130:131], v[160:161], v[134:135]
	v_mov_b32_e32 v134, v132
	v_mov_b32_e32 v135, v136
	v_mov_b32_e32 v136, v133
	v_pk_add_f32 v[132:133], v[134:135], v[136:137]
	s_nop 0
	v_pk_add_f32 v[130:131], v[130:131], v[132:133]
	s_nop 0
	v_add_f32_e32 v130, v130, v131
	v_fmamk_f32 v130, v130, 0x3b000000, v243
	v_rsq_f32_e32 v130, v130
	s_nop 0
	v_pk_mul_f32 v[174:175], v[78:79], v[130:131] op_sel_hi:[1,0]
	v_pk_mul_f32 v[176:177], v[80:81], v[130:131] op_sel_hi:[1,0]
	v_pk_mul_f32 v[134:135], v[174:175], v[174:175]
	v_pk_mul_f32 v[132:133], v[176:177], v[176:177]
	v_pk_mul_f32 v[160:161], v[74:75], v[130:131] op_sel_hi:[1,0]
	v_pk_mov_b32 v[136:137], v[134:135], v[132:133] op_sel:[1,0]
	v_mov_b32_e32 v135, v133
	v_pk_add_f32 v[132:133], v[136:137], v[134:135]
	v_pk_mul_f32 v[162:163], v[76:77], v[130:131] op_sel_hi:[1,0]
	v_pk_add_f32 v[132:133], v[132:133], v[132:133] op_sel_hi:[0,1]
	v_pk_mul_f32 v[134:135], v[162:163], v[162:163]
	v_pk_mul_f32 v[136:137], v[160:161], v[160:161]
	v_pk_mul_f32 v[180:181], v[70:71], v[130:131] op_sel_hi:[1,0]
	v_pk_mov_b32 v[164:165], v[136:137], v[134:135] op_sel:[1,0]
	v_mov_b32_e32 v137, v135
	v_pk_mul_f32 v[178:179], v[72:73], v[130:131] op_sel_hi:[1,0]
	v_mul_f32_e32 v132, v180, v180
	v_pk_add_f32 v[134:135], v[164:165], v[136:137]
	v_pk_fma_f32 v[136:137], v[180:181], v[180:181], v[132:133] op_sel_hi:[1,1,0]
	v_mul_f32_e32 v132, v178, v178
	v_pk_add_f32 v[134:135], v[134:135], v[134:135] op_sel_hi:[0,1]
	v_pk_fma_f32 v[168:169], v[178:179], v[178:179], v[132:133] op_sel_hi:[1,1,0]
	v_pk_mul_f32 v[164:165], v[68:69], v[130:131] op_sel_hi:[1,0]
	v_pk_mul_f32 v[166:167], v[66:67], v[130:131] op_sel_hi:[1,0]
	v_mul_f32_e32 v132, v164, v164
	v_mul_f32_e32 v136, v166, v166
	v_mul_f32_e32 v168, v167, v167
	v_mul_f32_e32 v134, v165, v165
	v_pk_add_f32 v[130:131], v[136:137], v[168:169]
	v_pk_add_f32 v[132:133], v[132:133], v[134:135]
	s_waitcnt vmcnt(0)
	v_pk_mul_f32 v[180:181], v[192:193], v[180:181]
	v_pk_add_f32 v[130:131], v[130:131], v[132:133]
	v_pk_mul_f32 v[178:179], v[194:195], v[178:179]
	v_add_f32_e32 v130, v130, v131
	ds_bpermute_b32 v131, v187, v130
	v_pk_mul_f32 v[176:177], v[190:191], v[176:177]
	v_pk_mul_f32 v[174:175], v[188:189], v[174:175]
	s_waitcnt lgkmcnt(0)
	v_add_f32_e32 v130, v130, v131
	ds_bpermute_b32 v131, v186, v130
	s_waitcnt lgkmcnt(0)
	v_add_f32_e32 v130, v130, v131
	v_fmamk_f32 v130, v130, 0x3c800000, v243
	v_rsq_f32_e32 v130, v130
	s_nop 0
	v_mul_f32_e32 v168, 0x3dd53b94, v130
	v_lshlrev_b64 v[130:131], 8, v[170:171]
	v_lshl_add_u64 v[130:131], s[4:5], 0, v[130:131]
	v_lshl_add_u64 v[172:173], v[130:131], 0, v[156:157]
	global_load_dwordx4 v[130:133], v[172:173], off
	global_load_dwordx4 v[134:137], v[172:173], off offset:16
	v_pk_mul_f32 v[178:179], v[178:179], v[168:169] op_sel_hi:[1,0]
	v_pk_mul_f32 v[180:181], v[180:181], v[168:169] op_sel_hi:[1,0]
	v_lshlrev_b64 v[170:171], 11, v[170:171]
	v_pk_mul_f32 v[174:175], v[174:175], v[168:169] op_sel_hi:[1,0]
	v_pk_mul_f32 v[176:177], v[176:177], v[168:169] op_sel_hi:[1,0]
	v_lshl_add_u64 v[170:171], s[6:7], 0, v[170:171]
	v_lshl_add_u64 v[170:171], v[170:171], 0, s[44:45]
	v_lshl_add_u64 v[170:171], v[170:171], 0, v[154:155]
	s_waitcnt vmcnt(1)
	v_mov_b32_e32 v188, v131
	v_mov_b32_e32 v189, v133
	s_waitcnt vmcnt(0)
	v_mov_b32_e32 v192, v135
	v_mov_b32_e32 v193, v137
	v_pk_mul_f32 v[190:191], v[188:189], v[180:181]
	v_pk_mul_f32 v[194:195], v[192:193], v[178:179]
	v_mov_b32_e32 v135, v136
	v_mov_b32_e32 v131, v132
	v_pk_fma_f32 v[136:137], v[134:135], v[176:177], v[194:195] neg_lo:[0,0,1] neg_hi:[0,0,1]
	v_pk_fma_f32 v[132:133], v[130:131], v[174:175], v[190:191] neg_lo:[0,0,1] neg_hi:[0,0,1]
	v_pk_mul_f32 v[130:131], v[130:131], v[180:181]
	v_cvt_pk_bf16_f32 v132, v132, v133
	v_cvt_pk_bf16_f32 v133, v136, v137
	global_store_dwordx2 v[170:171], v[132:133], off
	v_pk_mul_f32 v[132:133], v[134:135], v[178:179]
	v_pk_fma_f32 v[130:131], v[188:189], v[174:175], v[130:131]
	v_pk_fma_f32 v[132:133], v[192:193], v[176:177], v[132:133]
	v_cvt_pk_bf16_f32 v130, v130, v131
	v_cvt_pk_bf16_f32 v131, v132, v133
	global_store_dwordx2 v[170:171], v[130:131], off offset:64
	global_load_dwordx4 v[130:133], v[152:153], off offset:16
	s_nop 0
	global_load_dwordx4 v[134:137], v[152:153], off offset:144
	global_load_dwordx4 v[174:177], v[172:173], off offset:32
	global_load_dwordx4 v[178:181], v[172:173], off offset:48
	s_waitcnt vmcnt(3)
	v_pk_mul_f32 v[132:133], v[132:133], v[162:163]
	s_waitcnt vmcnt(2)
	v_pk_mul_f32 v[134:135], v[134:135], v[166:167]
	v_pk_mul_f32 v[136:137], v[136:137], v[164:165]
	v_pk_mul_f32 v[130:131], v[130:131], v[160:161]
	v_pk_mul_f32 v[136:137], v[136:137], v[168:169] op_sel_hi:[1,0]
	v_pk_mul_f32 v[134:135], v[134:135], v[168:169] op_sel_hi:[1,0]
	s_waitcnt vmcnt(1)
	v_mov_b32_e32 v160, v175
	v_mov_b32_e32 v161, v177
	s_waitcnt vmcnt(0)
	v_mov_b32_e32 v164, v179
	v_mov_b32_e32 v165, v181
	v_mov_b32_e32 v179, v180
	v_mov_b32_e32 v175, v176
	v_pk_mul_f32 v[130:131], v[130:131], v[168:169] op_sel_hi:[1,0]
	v_pk_mul_f32 v[132:133], v[132:133], v[168:169] op_sel_hi:[1,0]
	v_pk_mul_f32 v[162:163], v[160:161], v[134:135]
	v_pk_mul_f32 v[166:167], v[164:165], v[136:137]
	v_pk_mul_f32 v[134:135], v[174:175], v[134:135]
	v_pk_mul_f32 v[136:137], v[178:179], v[136:137]
	v_pk_fma_f32 v[166:167], v[178:179], v[132:133], v[166:167] neg_lo:[0,0,1] neg_hi:[0,0,1]
	v_pk_fma_f32 v[162:163], v[174:175], v[130:131], v[162:163] neg_lo:[0,0,1] neg_hi:[0,0,1]
	v_pk_fma_f32 v[132:133], v[164:165], v[132:133], v[136:137]
	v_pk_fma_f32 v[130:131], v[160:161], v[130:131], v[134:135]
	v_cvt_pk_bf16_f32 v162, v162, v163
	v_cvt_pk_bf16_f32 v163, v166, v167
	v_cvt_pk_bf16_f32 v130, v130, v131
	v_cvt_pk_bf16_f32 v131, v132, v133
	global_store_dwordx2 v[170:171], v[162:163], off offset:8
	global_store_dwordx2 v[170:171], v[130:131], off offset:72
	v_lshl_add_u64 v[170:171], v[158:159], 0, s[28:29]
	v_lshlrev_b64 v[130:131], 5, v[170:171]
	v_lshl_add_u64 v[134:135], s[8:9], 0, v[130:131]
	global_load_dwordx4 v[130:133], v[134:135], off
	s_nop 0
	global_load_dwordx4 v[134:137], v[134:135], off offset:16
	s_nop 0
	global_load_dwordx4 v[188:191], v[152:153], off
	global_load_dwordx4 v[192:195], v[152:153], off offset:128
	s_waitcnt vmcnt(3)
	v_mov_b32_e32 v160, v130
	s_waitcnt vmcnt(2)
	v_mov_b32_e32 v161, v134
	v_mov_b32_e32 v134, v131
	v_pk_add_f32 v[130:131], v[160:161], v[134:135]
	v_mov_b32_e32 v134, v132
	v_mov_b32_e32 v135, v136
	v_mov_b32_e32 v136, v133
	v_pk_add_f32 v[132:133], v[134:135], v[136:137]
	s_nop 0
	v_pk_add_f32 v[130:131], v[130:131], v[132:133]
	s_nop 0
	v_add_f32_e32 v130, v130, v131
	v_fmamk_f32 v130, v130, 0x3b000000, v243
	v_rsq_f32_e32 v130, v130
	s_nop 0
	v_pk_mul_f32 v[174:175], v[62:63], v[130:131] op_sel_hi:[1,0]
	v_pk_mul_f32 v[176:177], v[64:65], v[130:131] op_sel_hi:[1,0]
	v_pk_mul_f32 v[134:135], v[174:175], v[174:175]
	v_pk_mul_f32 v[132:133], v[176:177], v[176:177]
	v_pk_mul_f32 v[160:161], v[58:59], v[130:131] op_sel_hi:[1,0]
	v_pk_mov_b32 v[136:137], v[134:135], v[132:133] op_sel:[1,0]
	v_mov_b32_e32 v135, v133
	v_pk_add_f32 v[132:133], v[136:137], v[134:135]
	v_pk_mul_f32 v[162:163], v[60:61], v[130:131] op_sel_hi:[1,0]
	v_pk_add_f32 v[132:133], v[132:133], v[132:133] op_sel_hi:[0,1]
	v_pk_mul_f32 v[134:135], v[162:163], v[162:163]
	v_pk_mul_f32 v[136:137], v[160:161], v[160:161]
	v_pk_mul_f32 v[180:181], v[54:55], v[130:131] op_sel_hi:[1,0]
	v_pk_mov_b32 v[164:165], v[136:137], v[134:135] op_sel:[1,0]
	v_mov_b32_e32 v137, v135
	v_pk_mul_f32 v[178:179], v[56:57], v[130:131] op_sel_hi:[1,0]
	v_mul_f32_e32 v132, v180, v180
	v_pk_add_f32 v[134:135], v[164:165], v[136:137]
	v_pk_fma_f32 v[136:137], v[180:181], v[180:181], v[132:133] op_sel_hi:[1,1,0]
	v_mul_f32_e32 v132, v178, v178
	v_pk_add_f32 v[134:135], v[134:135], v[134:135] op_sel_hi:[0,1]
	v_pk_fma_f32 v[168:169], v[178:179], v[178:179], v[132:133] op_sel_hi:[1,1,0]
	v_pk_mul_f32 v[164:165], v[52:53], v[130:131] op_sel_hi:[1,0]
	v_pk_mul_f32 v[166:167], v[50:51], v[130:131] op_sel_hi:[1,0]
	v_mul_f32_e32 v132, v164, v164
	v_mul_f32_e32 v136, v166, v166
	v_mul_f32_e32 v168, v167, v167
	v_mul_f32_e32 v134, v165, v165
	v_pk_add_f32 v[130:131], v[136:137], v[168:169]
	v_pk_add_f32 v[132:133], v[132:133], v[134:135]
	s_waitcnt vmcnt(0)
	v_pk_mul_f32 v[180:181], v[192:193], v[180:181]
	v_pk_add_f32 v[130:131], v[130:131], v[132:133]
	v_pk_mul_f32 v[178:179], v[194:195], v[178:179]
	v_add_f32_e32 v130, v130, v131
	ds_bpermute_b32 v131, v187, v130
	v_pk_mul_f32 v[176:177], v[190:191], v[176:177]
	v_pk_mul_f32 v[174:175], v[188:189], v[174:175]
	s_waitcnt lgkmcnt(0)
	v_add_f32_e32 v130, v130, v131
	ds_bpermute_b32 v131, v186, v130
	s_waitcnt lgkmcnt(0)
	v_add_f32_e32 v130, v130, v131
	v_fmamk_f32 v130, v130, 0x3c800000, v243
	s_nop 1
	s_mov_b64 s[0:1], 0x90
	v_rsq_f32_e32 v130, v130
	s_nop 0
	v_mul_f32_e32 v168, 0x3dd53b94, v130
	v_lshlrev_b64 v[130:131], 8, v[170:171]
	v_lshl_add_u64 v[130:131], s[4:5], 0, v[130:131]
	v_lshl_add_u64 v[172:173], v[130:131], 0, v[156:157]
	global_load_dwordx4 v[130:133], v[172:173], off
	global_load_dwordx4 v[134:137], v[172:173], off offset:16
	v_pk_mul_f32 v[178:179], v[178:179], v[168:169] op_sel_hi:[1,0]
	v_pk_mul_f32 v[180:181], v[180:181], v[168:169] op_sel_hi:[1,0]
	v_lshlrev_b64 v[170:171], 11, v[170:171]
	v_pk_mul_f32 v[174:175], v[174:175], v[168:169] op_sel_hi:[1,0]
	v_pk_mul_f32 v[176:177], v[176:177], v[168:169] op_sel_hi:[1,0]
	v_lshl_add_u64 v[170:171], s[6:7], 0, v[170:171]
	v_lshl_add_u64 v[170:171], v[170:171], 0, s[44:45]
	v_lshl_add_u64 v[170:171], v[170:171], 0, v[154:155]
	s_waitcnt vmcnt(1)
	v_mov_b32_e32 v188, v131
	v_mov_b32_e32 v189, v133
	s_waitcnt vmcnt(0)
	v_mov_b32_e32 v192, v135
	v_mov_b32_e32 v193, v137
	v_pk_mul_f32 v[190:191], v[188:189], v[180:181]
	v_pk_mul_f32 v[194:195], v[192:193], v[178:179]
	v_mov_b32_e32 v135, v136
	v_mov_b32_e32 v131, v132
	v_pk_fma_f32 v[136:137], v[134:135], v[176:177], v[194:195] neg_lo:[0,0,1] neg_hi:[0,0,1]
	v_pk_fma_f32 v[132:133], v[130:131], v[174:175], v[190:191] neg_lo:[0,0,1] neg_hi:[0,0,1]
	v_pk_mul_f32 v[130:131], v[130:131], v[180:181]
	v_cvt_pk_bf16_f32 v132, v132, v133
	v_cvt_pk_bf16_f32 v133, v136, v137
	global_store_dwordx2 v[170:171], v[132:133], off
	v_pk_mul_f32 v[132:133], v[134:135], v[178:179]
	v_pk_fma_f32 v[130:131], v[188:189], v[174:175], v[130:131]
	v_pk_fma_f32 v[132:133], v[192:193], v[176:177], v[132:133]
	v_cvt_pk_bf16_f32 v130, v130, v131
	v_cvt_pk_bf16_f32 v131, v132, v133
	global_store_dwordx2 v[170:171], v[130:131], off offset:64
	global_load_dwordx4 v[130:133], v[152:153], off offset:16
	s_nop 0
	global_load_dwordx4 v[134:137], v[152:153], off offset:144
	global_load_dwordx4 v[174:177], v[172:173], off offset:32
	global_load_dwordx4 v[178:181], v[172:173], off offset:48
	s_waitcnt vmcnt(3)
	v_pk_mul_f32 v[132:133], v[132:133], v[162:163]
	s_waitcnt vmcnt(2)
	v_pk_mul_f32 v[134:135], v[134:135], v[166:167]
	v_pk_mul_f32 v[136:137], v[136:137], v[164:165]
	v_pk_mul_f32 v[130:131], v[130:131], v[160:161]
	v_pk_mul_f32 v[136:137], v[136:137], v[168:169] op_sel_hi:[1,0]
	v_pk_mul_f32 v[134:135], v[134:135], v[168:169] op_sel_hi:[1,0]
	s_waitcnt vmcnt(1)
	v_mov_b32_e32 v160, v175
	v_mov_b32_e32 v161, v177
	s_waitcnt vmcnt(0)
	v_mov_b32_e32 v164, v179
	v_mov_b32_e32 v165, v181
	v_mov_b32_e32 v179, v180
	v_mov_b32_e32 v175, v176
	v_pk_mul_f32 v[130:131], v[130:131], v[168:169] op_sel_hi:[1,0]
	v_pk_mul_f32 v[132:133], v[132:133], v[168:169] op_sel_hi:[1,0]
	v_pk_mul_f32 v[162:163], v[160:161], v[134:135]
	v_pk_mul_f32 v[166:167], v[164:165], v[136:137]
	v_pk_mul_f32 v[134:135], v[174:175], v[134:135]
	v_pk_mul_f32 v[136:137], v[178:179], v[136:137]
	v_pk_fma_f32 v[166:167], v[178:179], v[132:133], v[166:167] neg_lo:[0,0,1] neg_hi:[0,0,1]
	v_pk_fma_f32 v[162:163], v[174:175], v[130:131], v[162:163] neg_lo:[0,0,1] neg_hi:[0,0,1]
	v_pk_fma_f32 v[132:133], v[164:165], v[132:133], v[136:137]
	v_pk_fma_f32 v[130:131], v[160:161], v[130:131], v[134:135]
	v_cvt_pk_bf16_f32 v162, v162, v163
	v_cvt_pk_bf16_f32 v163, v166, v167
	v_cvt_pk_bf16_f32 v130, v130, v131
	v_cvt_pk_bf16_f32 v131, v132, v133
	global_store_dwordx2 v[170:171], v[162:163], off offset:8
	global_store_dwordx2 v[170:171], v[130:131], off offset:72
	v_lshl_add_u64 v[170:171], v[158:159], 0, s[0:1]
	v_lshlrev_b64 v[130:131], 5, v[170:171]
	v_lshl_add_u64 v[134:135], s[8:9], 0, v[130:131]
	global_load_dwordx4 v[130:133], v[134:135], off
	s_nop 0
	global_load_dwordx4 v[134:137], v[134:135], off offset:16
	s_nop 0
	global_load_dwordx4 v[188:191], v[152:153], off
	global_load_dwordx4 v[192:195], v[152:153], off offset:128
	s_waitcnt vmcnt(3)
	v_mov_b32_e32 v160, v130
	s_waitcnt vmcnt(2)
	v_mov_b32_e32 v161, v134
	v_mov_b32_e32 v134, v131
	v_pk_add_f32 v[130:131], v[160:161], v[134:135]
	v_mov_b32_e32 v134, v132
	v_mov_b32_e32 v135, v136
	v_mov_b32_e32 v136, v133
	v_pk_add_f32 v[132:133], v[134:135], v[136:137]
	s_nop 0
	v_pk_add_f32 v[130:131], v[130:131], v[132:133]
	s_nop 0
	v_add_f32_e32 v130, v130, v131
	v_fmamk_f32 v130, v130, 0x3b000000, v243
	v_rsq_f32_e32 v130, v130
	s_nop 0
	v_pk_mul_f32 v[174:175], v[46:47], v[130:131] op_sel_hi:[1,0]
	v_pk_mul_f32 v[176:177], v[48:49], v[130:131] op_sel_hi:[1,0]
	v_pk_mul_f32 v[134:135], v[174:175], v[174:175]
	v_pk_mul_f32 v[132:133], v[176:177], v[176:177]
	v_pk_mul_f32 v[160:161], v[42:43], v[130:131] op_sel_hi:[1,0]
	v_pk_mov_b32 v[136:137], v[134:135], v[132:133] op_sel:[1,0]
	v_mov_b32_e32 v135, v133
	v_pk_add_f32 v[132:133], v[136:137], v[134:135]
	v_pk_mul_f32 v[162:163], v[44:45], v[130:131] op_sel_hi:[1,0]
	v_pk_add_f32 v[132:133], v[132:133], v[132:133] op_sel_hi:[0,1]
	v_pk_mul_f32 v[134:135], v[162:163], v[162:163]
	v_pk_mul_f32 v[136:137], v[160:161], v[160:161]
	v_pk_mul_f32 v[180:181], v[38:39], v[130:131] op_sel_hi:[1,0]
	v_pk_mov_b32 v[164:165], v[136:137], v[134:135] op_sel:[1,0]
	v_mov_b32_e32 v137, v135
	v_pk_mul_f32 v[178:179], v[40:41], v[130:131] op_sel_hi:[1,0]
	v_mul_f32_e32 v132, v180, v180
	v_pk_add_f32 v[134:135], v[164:165], v[136:137]
	v_pk_fma_f32 v[136:137], v[180:181], v[180:181], v[132:133] op_sel_hi:[1,1,0]
	v_mul_f32_e32 v132, v178, v178
	v_pk_add_f32 v[134:135], v[134:135], v[134:135] op_sel_hi:[0,1]
	v_pk_fma_f32 v[168:169], v[178:179], v[178:179], v[132:133] op_sel_hi:[1,1,0]
	v_pk_mul_f32 v[164:165], v[36:37], v[130:131] op_sel_hi:[1,0]
	v_pk_mul_f32 v[166:167], v[34:35], v[130:131] op_sel_hi:[1,0]
	v_mul_f32_e32 v132, v164, v164
	v_mul_f32_e32 v136, v166, v166
	v_mul_f32_e32 v168, v167, v167
	v_mul_f32_e32 v134, v165, v165
	v_pk_add_f32 v[130:131], v[136:137], v[168:169]
	v_pk_add_f32 v[132:133], v[132:133], v[134:135]
	s_waitcnt vmcnt(0)
	v_pk_mul_f32 v[180:181], v[192:193], v[180:181]
	v_pk_add_f32 v[130:131], v[130:131], v[132:133]
	v_pk_mul_f32 v[178:179], v[194:195], v[178:179]
	v_add_f32_e32 v130, v130, v131
	ds_bpermute_b32 v131, v187, v130
	v_pk_mul_f32 v[176:177], v[190:191], v[176:177]
	v_pk_mul_f32 v[174:175], v[188:189], v[174:175]
	s_waitcnt lgkmcnt(0)
	v_add_f32_e32 v130, v130, v131
	ds_bpermute_b32 v131, v186, v130
	s_waitcnt lgkmcnt(0)
	v_add_f32_e32 v130, v130, v131
	v_fmamk_f32 v130, v130, 0x3c800000, v243
	s_nop 1
	s_mov_b64 s[0:1], 0xa0
	v_rsq_f32_e32 v130, v130
	s_nop 0
	v_mul_f32_e32 v168, 0x3dd53b94, v130
	v_lshlrev_b64 v[130:131], 8, v[170:171]
	v_lshl_add_u64 v[130:131], s[4:5], 0, v[130:131]
	v_lshl_add_u64 v[172:173], v[130:131], 0, v[156:157]
	global_load_dwordx4 v[130:133], v[172:173], off
	global_load_dwordx4 v[134:137], v[172:173], off offset:16
	v_pk_mul_f32 v[178:179], v[178:179], v[168:169] op_sel_hi:[1,0]
	v_pk_mul_f32 v[180:181], v[180:181], v[168:169] op_sel_hi:[1,0]
	v_lshlrev_b64 v[170:171], 11, v[170:171]
	v_pk_mul_f32 v[174:175], v[174:175], v[168:169] op_sel_hi:[1,0]
	v_pk_mul_f32 v[176:177], v[176:177], v[168:169] op_sel_hi:[1,0]
	v_lshl_add_u64 v[170:171], s[6:7], 0, v[170:171]
	v_lshl_add_u64 v[170:171], v[170:171], 0, s[44:45]
	v_lshl_add_u64 v[170:171], v[170:171], 0, v[154:155]
	s_waitcnt vmcnt(1)
	v_mov_b32_e32 v188, v131
	v_mov_b32_e32 v189, v133
	s_waitcnt vmcnt(0)
	v_mov_b32_e32 v192, v135
	v_mov_b32_e32 v193, v137
	v_pk_mul_f32 v[190:191], v[188:189], v[180:181]
	v_pk_mul_f32 v[194:195], v[192:193], v[178:179]
	v_mov_b32_e32 v135, v136
	v_mov_b32_e32 v131, v132
	v_pk_fma_f32 v[136:137], v[134:135], v[176:177], v[194:195] neg_lo:[0,0,1] neg_hi:[0,0,1]
	v_pk_fma_f32 v[132:133], v[130:131], v[174:175], v[190:191] neg_lo:[0,0,1] neg_hi:[0,0,1]
	v_pk_mul_f32 v[130:131], v[130:131], v[180:181]
	v_cvt_pk_bf16_f32 v132, v132, v133
	v_cvt_pk_bf16_f32 v133, v136, v137
	global_store_dwordx2 v[170:171], v[132:133], off
	v_pk_mul_f32 v[132:133], v[134:135], v[178:179]
	v_pk_fma_f32 v[130:131], v[188:189], v[174:175], v[130:131]
	v_pk_fma_f32 v[132:133], v[192:193], v[176:177], v[132:133]
	v_cvt_pk_bf16_f32 v130, v130, v131
	v_cvt_pk_bf16_f32 v131, v132, v133
	global_store_dwordx2 v[170:171], v[130:131], off offset:64
	global_load_dwordx4 v[130:133], v[152:153], off offset:16
	s_nop 0
	global_load_dwordx4 v[134:137], v[152:153], off offset:144
	global_load_dwordx4 v[174:177], v[172:173], off offset:32
	global_load_dwordx4 v[178:181], v[172:173], off offset:48
	s_waitcnt vmcnt(3)
	v_pk_mul_f32 v[132:133], v[132:133], v[162:163]
	s_waitcnt vmcnt(2)
	v_pk_mul_f32 v[134:135], v[134:135], v[166:167]
	v_pk_mul_f32 v[136:137], v[136:137], v[164:165]
	v_pk_mul_f32 v[130:131], v[130:131], v[160:161]
	v_pk_mul_f32 v[136:137], v[136:137], v[168:169] op_sel_hi:[1,0]
	v_pk_mul_f32 v[134:135], v[134:135], v[168:169] op_sel_hi:[1,0]
	s_waitcnt vmcnt(1)
	v_mov_b32_e32 v160, v175
	v_mov_b32_e32 v161, v177
	s_waitcnt vmcnt(0)
	v_mov_b32_e32 v164, v179
	v_mov_b32_e32 v165, v181
	v_mov_b32_e32 v179, v180
	v_mov_b32_e32 v175, v176
	v_pk_mul_f32 v[130:131], v[130:131], v[168:169] op_sel_hi:[1,0]
	v_pk_mul_f32 v[132:133], v[132:133], v[168:169] op_sel_hi:[1,0]
	v_pk_mul_f32 v[162:163], v[160:161], v[134:135]
	v_pk_mul_f32 v[166:167], v[164:165], v[136:137]
	v_pk_mul_f32 v[134:135], v[174:175], v[134:135]
	v_pk_mul_f32 v[136:137], v[178:179], v[136:137]
	v_pk_fma_f32 v[166:167], v[178:179], v[132:133], v[166:167] neg_lo:[0,0,1] neg_hi:[0,0,1]
	v_pk_fma_f32 v[162:163], v[174:175], v[130:131], v[162:163] neg_lo:[0,0,1] neg_hi:[0,0,1]
	v_pk_fma_f32 v[132:133], v[164:165], v[132:133], v[136:137]
	v_pk_fma_f32 v[130:131], v[160:161], v[130:131], v[134:135]
	v_cvt_pk_bf16_f32 v162, v162, v163
	v_cvt_pk_bf16_f32 v163, v166, v167
	v_cvt_pk_bf16_f32 v130, v130, v131
	v_cvt_pk_bf16_f32 v131, v132, v133
	global_store_dwordx2 v[170:171], v[162:163], off offset:8
	global_store_dwordx2 v[170:171], v[130:131], off offset:72
	v_lshl_add_u64 v[170:171], v[158:159], 0, s[0:1]
	v_lshlrev_b64 v[130:131], 5, v[170:171]
	v_lshl_add_u64 v[134:135], s[8:9], 0, v[130:131]
	global_load_dwordx4 v[130:133], v[134:135], off
	s_nop 0
	global_load_dwordx4 v[134:137], v[134:135], off offset:16
	s_nop 0
	global_load_dwordx4 v[188:191], v[152:153], off
	global_load_dwordx4 v[192:195], v[152:153], off offset:128
	s_waitcnt vmcnt(3)
	v_mov_b32_e32 v160, v130
	s_waitcnt vmcnt(2)
	v_mov_b32_e32 v161, v134
	v_mov_b32_e32 v134, v131
	v_pk_add_f32 v[130:131], v[160:161], v[134:135]
	v_mov_b32_e32 v134, v132
	v_mov_b32_e32 v135, v136
	v_mov_b32_e32 v136, v133
	v_pk_add_f32 v[132:133], v[134:135], v[136:137]
	s_nop 0
	v_pk_add_f32 v[130:131], v[130:131], v[132:133]
	s_nop 0
	v_add_f32_e32 v130, v130, v131
	v_fmamk_f32 v130, v130, 0x3b000000, v243
	v_rsq_f32_e32 v130, v130
	s_nop 0
	v_pk_mul_f32 v[174:175], v[30:31], v[130:131] op_sel_hi:[1,0]
	v_pk_mul_f32 v[176:177], v[32:33], v[130:131] op_sel_hi:[1,0]
	v_pk_mul_f32 v[134:135], v[174:175], v[174:175]
	v_pk_mul_f32 v[132:133], v[176:177], v[176:177]
	v_pk_mul_f32 v[160:161], v[26:27], v[130:131] op_sel_hi:[1,0]
	v_pk_mov_b32 v[136:137], v[134:135], v[132:133] op_sel:[1,0]
	v_mov_b32_e32 v135, v133
	v_pk_add_f32 v[132:133], v[136:137], v[134:135]
	v_pk_mul_f32 v[162:163], v[28:29], v[130:131] op_sel_hi:[1,0]
	v_pk_add_f32 v[132:133], v[132:133], v[132:133] op_sel_hi:[0,1]
	v_pk_mul_f32 v[134:135], v[162:163], v[162:163]
	v_pk_mul_f32 v[136:137], v[160:161], v[160:161]
	v_pk_mul_f32 v[180:181], v[22:23], v[130:131] op_sel_hi:[1,0]
	v_pk_mov_b32 v[164:165], v[136:137], v[134:135] op_sel:[1,0]
	v_mov_b32_e32 v137, v135
	v_pk_mul_f32 v[178:179], v[24:25], v[130:131] op_sel_hi:[1,0]
	v_mul_f32_e32 v132, v180, v180
	v_pk_add_f32 v[134:135], v[164:165], v[136:137]
	v_pk_fma_f32 v[136:137], v[180:181], v[180:181], v[132:133] op_sel_hi:[1,1,0]
	v_mul_f32_e32 v132, v178, v178
	v_pk_add_f32 v[134:135], v[134:135], v[134:135] op_sel_hi:[0,1]
	v_pk_fma_f32 v[168:169], v[178:179], v[178:179], v[132:133] op_sel_hi:[1,1,0]
	v_pk_mul_f32 v[164:165], v[20:21], v[130:131] op_sel_hi:[1,0]
	v_pk_mul_f32 v[166:167], v[18:19], v[130:131] op_sel_hi:[1,0]
	v_mul_f32_e32 v132, v164, v164
	v_mul_f32_e32 v136, v166, v166
	v_mul_f32_e32 v168, v167, v167
	v_mul_f32_e32 v134, v165, v165
	v_pk_add_f32 v[130:131], v[136:137], v[168:169]
	v_pk_add_f32 v[132:133], v[132:133], v[134:135]
	s_waitcnt vmcnt(0)
	v_pk_mul_f32 v[180:181], v[192:193], v[180:181]
	v_pk_add_f32 v[130:131], v[130:131], v[132:133]
	v_pk_mul_f32 v[178:179], v[194:195], v[178:179]
	v_add_f32_e32 v130, v130, v131
	ds_bpermute_b32 v131, v187, v130
	v_pk_mul_f32 v[176:177], v[190:191], v[176:177]
	v_pk_mul_f32 v[174:175], v[188:189], v[174:175]
	s_waitcnt lgkmcnt(0)
	v_add_f32_e32 v130, v130, v131
	ds_bpermute_b32 v131, v186, v130
	s_waitcnt lgkmcnt(0)
	v_add_f32_e32 v130, v130, v131
	v_fmamk_f32 v130, v130, 0x3c800000, v243
	s_nop 1
	s_mov_b64 s[0:1], 0xb0
	v_rsq_f32_e32 v130, v130
	s_nop 0
	v_mul_f32_e32 v168, 0x3dd53b94, v130
	v_lshlrev_b64 v[130:131], 8, v[170:171]
	v_lshl_add_u64 v[130:131], s[4:5], 0, v[130:131]
	v_lshl_add_u64 v[172:173], v[130:131], 0, v[156:157]
	global_load_dwordx4 v[130:133], v[172:173], off
	global_load_dwordx4 v[134:137], v[172:173], off offset:16
	v_pk_mul_f32 v[178:179], v[178:179], v[168:169] op_sel_hi:[1,0]
	v_pk_mul_f32 v[180:181], v[180:181], v[168:169] op_sel_hi:[1,0]
	v_lshlrev_b64 v[170:171], 11, v[170:171]
	v_pk_mul_f32 v[174:175], v[174:175], v[168:169] op_sel_hi:[1,0]
	v_pk_mul_f32 v[176:177], v[176:177], v[168:169] op_sel_hi:[1,0]
	v_lshl_add_u64 v[170:171], s[6:7], 0, v[170:171]
	v_lshl_add_u64 v[170:171], v[170:171], 0, s[44:45]
	v_lshl_add_u64 v[170:171], v[170:171], 0, v[154:155]
	s_waitcnt vmcnt(1)
	v_mov_b32_e32 v188, v131
	v_mov_b32_e32 v189, v133
	s_waitcnt vmcnt(0)
	v_mov_b32_e32 v192, v135
	v_mov_b32_e32 v193, v137
	v_pk_mul_f32 v[190:191], v[188:189], v[180:181]
	v_pk_mul_f32 v[194:195], v[192:193], v[178:179]
	v_mov_b32_e32 v135, v136
	v_mov_b32_e32 v131, v132
	v_pk_fma_f32 v[136:137], v[134:135], v[176:177], v[194:195] neg_lo:[0,0,1] neg_hi:[0,0,1]
	v_pk_fma_f32 v[132:133], v[130:131], v[174:175], v[190:191] neg_lo:[0,0,1] neg_hi:[0,0,1]
	v_pk_mul_f32 v[130:131], v[130:131], v[180:181]
	v_cvt_pk_bf16_f32 v132, v132, v133
	v_cvt_pk_bf16_f32 v133, v136, v137
	global_store_dwordx2 v[170:171], v[132:133], off
	v_pk_mul_f32 v[132:133], v[134:135], v[178:179]
	v_pk_fma_f32 v[130:131], v[188:189], v[174:175], v[130:131]
	v_pk_fma_f32 v[132:133], v[192:193], v[176:177], v[132:133]
	v_cvt_pk_bf16_f32 v130, v130, v131
	v_cvt_pk_bf16_f32 v131, v132, v133
	global_store_dwordx2 v[170:171], v[130:131], off offset:64
	global_load_dwordx4 v[130:133], v[152:153], off offset:16
	s_nop 0
	global_load_dwordx4 v[134:137], v[152:153], off offset:144
	global_load_dwordx4 v[174:177], v[172:173], off offset:32
	global_load_dwordx4 v[178:181], v[172:173], off offset:48
	s_waitcnt vmcnt(3)
	v_pk_mul_f32 v[132:133], v[132:133], v[162:163]
	s_waitcnt vmcnt(2)
	v_pk_mul_f32 v[134:135], v[134:135], v[166:167]
	v_pk_mul_f32 v[136:137], v[136:137], v[164:165]
	v_pk_mul_f32 v[130:131], v[130:131], v[160:161]
	v_pk_mul_f32 v[136:137], v[136:137], v[168:169] op_sel_hi:[1,0]
	v_pk_mul_f32 v[134:135], v[134:135], v[168:169] op_sel_hi:[1,0]
	s_waitcnt vmcnt(1)
	v_mov_b32_e32 v160, v175
	v_mov_b32_e32 v161, v177
	s_waitcnt vmcnt(0)
	v_mov_b32_e32 v164, v179
	v_mov_b32_e32 v165, v181
	v_mov_b32_e32 v179, v180
	v_mov_b32_e32 v175, v176
	v_pk_mul_f32 v[130:131], v[130:131], v[168:169] op_sel_hi:[1,0]
	v_pk_mul_f32 v[132:133], v[132:133], v[168:169] op_sel_hi:[1,0]
	v_pk_mul_f32 v[162:163], v[160:161], v[134:135]
	v_pk_mul_f32 v[166:167], v[164:165], v[136:137]
	v_pk_mul_f32 v[134:135], v[174:175], v[134:135]
	v_pk_mul_f32 v[136:137], v[178:179], v[136:137]
	v_pk_fma_f32 v[166:167], v[178:179], v[132:133], v[166:167] neg_lo:[0,0,1] neg_hi:[0,0,1]
	v_pk_fma_f32 v[162:163], v[174:175], v[130:131], v[162:163] neg_lo:[0,0,1] neg_hi:[0,0,1]
	v_pk_fma_f32 v[132:133], v[164:165], v[132:133], v[136:137]
	v_pk_fma_f32 v[130:131], v[160:161], v[130:131], v[134:135]
	v_lshl_add_u64 v[168:169], v[158:159], 0, s[0:1]
	v_cvt_pk_bf16_f32 v130, v130, v131
	v_cvt_pk_bf16_f32 v131, v132, v133
	v_cvt_pk_bf16_f32 v162, v162, v163
	v_cvt_pk_bf16_f32 v163, v166, v167
	global_store_dwordx2 v[170:171], v[130:131], off offset:72
	v_lshlrev_b64 v[130:131], 5, v[168:169]
	global_store_dwordx2 v[170:171], v[162:163], off offset:8
	v_lshl_add_u64 v[134:135], s[8:9], 0, v[130:131]
	global_load_dwordx4 v[130:133], v[134:135], off
	s_nop 0
	global_load_dwordx4 v[134:137], v[134:135], off offset:16
	s_nop 0
	global_load_dwordx4 v[178:181], v[152:153], off
	global_load_dwordx4 v[188:191], v[152:153], off offset:128
	s_waitcnt vmcnt(3)
	v_mov_b32_e32 v158, v130
	s_waitcnt vmcnt(2)
	v_mov_b32_e32 v159, v134
	v_mov_b32_e32 v134, v131
	v_pk_add_f32 v[130:131], v[158:159], v[134:135]
	v_mov_b32_e32 v134, v132
	v_mov_b32_e32 v135, v136
	v_mov_b32_e32 v136, v133
	v_pk_add_f32 v[132:133], v[134:135], v[136:137]
	s_nop 0
	v_pk_add_f32 v[130:131], v[130:131], v[132:133]
	s_nop 0
	v_add_f32_e32 v130, v130, v131
	v_fmamk_f32 v130, v130, 0x3b000000, v243
	v_rsq_f32_e32 v130, v130
	s_nop 0
	v_pk_mul_f32 v[170:171], v[14:15], v[130:131] op_sel_hi:[1,0]
	v_pk_mul_f32 v[172:173], v[16:17], v[130:131] op_sel_hi:[1,0]
	v_pk_mul_f32 v[134:135], v[170:171], v[170:171]
	v_pk_mul_f32 v[132:133], v[172:173], v[172:173]
	v_pk_mul_f32 v[158:159], v[10:11], v[130:131] op_sel_hi:[1,0]
	v_pk_mov_b32 v[136:137], v[134:135], v[132:133] op_sel:[1,0]
	v_mov_b32_e32 v135, v133
	v_pk_add_f32 v[132:133], v[136:137], v[134:135]
	v_pk_mul_f32 v[162:163], v[12:13], v[130:131] op_sel_hi:[1,0]
	v_pk_add_f32 v[132:133], v[132:133], v[132:133] op_sel_hi:[0,1]
	v_pk_mul_f32 v[134:135], v[162:163], v[162:163]
	v_pk_mul_f32 v[136:137], v[158:159], v[158:159]
	v_pk_mul_f32 v[176:177], v[6:7], v[130:131] op_sel_hi:[1,0]
	v_pk_mov_b32 v[160:161], v[136:137], v[134:135] op_sel:[1,0]
	v_mov_b32_e32 v137, v135
	v_pk_mul_f32 v[174:175], v[8:9], v[130:131] op_sel_hi:[1,0]
	v_mul_f32_e32 v132, v176, v176
	v_pk_add_f32 v[134:135], v[160:161], v[136:137]
	v_pk_fma_f32 v[136:137], v[176:177], v[176:177], v[132:133] op_sel_hi:[1,1,0]
	v_mul_f32_e32 v132, v174, v174
	v_pk_add_f32 v[134:135], v[134:135], v[134:135] op_sel_hi:[0,1]
	v_pk_fma_f32 v[166:167], v[174:175], v[174:175], v[132:133] op_sel_hi:[1,1,0]
	v_pk_mul_f32 v[160:161], v[4:5], v[130:131] op_sel_hi:[1,0]
	v_pk_mul_f32 v[164:165], v[2:3], v[130:131] op_sel_hi:[1,0]
	v_mul_f32_e32 v132, v160, v160
	v_mul_f32_e32 v136, v164, v164
	v_mul_f32_e32 v166, v165, v165
	v_mul_f32_e32 v134, v161, v161
	v_pk_add_f32 v[130:131], v[136:137], v[166:167]
	v_pk_add_f32 v[132:133], v[132:133], v[134:135]
	s_waitcnt vmcnt(0)
	v_pk_mul_f32 v[176:177], v[188:189], v[176:177]
	v_pk_add_f32 v[130:131], v[130:131], v[132:133]
	v_pk_mul_f32 v[174:175], v[190:191], v[174:175]
	v_add_f32_e32 v130, v130, v131
	ds_bpermute_b32 v131, v187, v130
	v_pk_mul_f32 v[172:173], v[180:181], v[172:173]
	v_pk_mul_f32 v[170:171], v[178:179], v[170:171]
	s_waitcnt lgkmcnt(0)
	v_add_f32_e32 v130, v130, v131
	ds_bpermute_b32 v131, v186, v130
	s_waitcnt lgkmcnt(0)
	v_add_f32_e32 v130, v130, v131
	v_fmamk_f32 v130, v130, 0x3c800000, v243
	v_rsq_f32_e32 v130, v130
	s_nop 0
	v_mul_f32_e32 v166, 0x3dd53b94, v130
	v_lshlrev_b64 v[130:131], 8, v[168:169]
	v_lshl_add_u64 v[130:131], s[4:5], 0, v[130:131]
	v_lshl_add_u64 v[156:157], v[130:131], 0, v[156:157]
	global_load_dwordx4 v[130:133], v[156:157], off
	global_load_dwordx4 v[134:137], v[156:157], off offset:16
	v_lshlrev_b64 v[168:169], 11, v[168:169]
	v_lshl_add_u64 v[168:169], s[6:7], 0, v[168:169]
	v_lshl_add_u64 v[168:169], v[168:169], 0, s[44:45]
	v_pk_mul_f32 v[174:175], v[174:175], v[166:167] op_sel_hi:[1,0]
	v_pk_mul_f32 v[176:177], v[176:177], v[166:167] op_sel_hi:[1,0]
	v_lshl_add_u64 v[154:155], v[168:169], 0, v[154:155]
	v_pk_mul_f32 v[170:171], v[170:171], v[166:167] op_sel_hi:[1,0]
	v_pk_mul_f32 v[172:173], v[172:173], v[166:167] op_sel_hi:[1,0]
	s_waitcnt vmcnt(1)
	v_mov_b32_e32 v168, v131
	v_mov_b32_e32 v169, v133
	s_waitcnt vmcnt(0)
	v_mov_b32_e32 v180, v135
	v_mov_b32_e32 v181, v137
	v_pk_mul_f32 v[178:179], v[168:169], v[176:177]
	v_pk_mul_f32 v[188:189], v[180:181], v[174:175]
	v_mov_b32_e32 v135, v136
	v_mov_b32_e32 v131, v132
	v_pk_fma_f32 v[136:137], v[134:135], v[172:173], v[188:189] neg_lo:[0,0,1] neg_hi:[0,0,1]
	v_pk_fma_f32 v[132:133], v[130:131], v[170:171], v[178:179] neg_lo:[0,0,1] neg_hi:[0,0,1]
	v_pk_mul_f32 v[130:131], v[130:131], v[176:177]
	v_cvt_pk_bf16_f32 v132, v132, v133
	v_cvt_pk_bf16_f32 v133, v136, v137
	global_store_dwordx2 v[154:155], v[132:133], off
	v_pk_mul_f32 v[132:133], v[134:135], v[174:175]
	v_pk_fma_f32 v[130:131], v[168:169], v[170:171], v[130:131]
	v_pk_fma_f32 v[132:133], v[180:181], v[172:173], v[132:133]
	v_cvt_pk_bf16_f32 v130, v130, v131
	v_cvt_pk_bf16_f32 v131, v132, v133
	global_store_dwordx2 v[154:155], v[130:131], off offset:64
	global_load_dwordx4 v[130:133], v[152:153], off offset:16
	s_nop 0
	global_load_dwordx4 v[134:137], v[152:153], off offset:144
	global_load_dwordx4 v[168:171], v[156:157], off offset:32
	global_load_dwordx4 v[172:175], v[156:157], off offset:48
	s_waitcnt vmcnt(3)
	v_pk_mul_f32 v[132:133], v[132:133], v[162:163]
	s_waitcnt vmcnt(2)
	v_pk_mul_f32 v[134:135], v[134:135], v[164:165]
	v_pk_mul_f32 v[136:137], v[136:137], v[160:161]
	v_pk_mul_f32 v[130:131], v[130:131], v[158:159]
	v_pk_mul_f32 v[136:137], v[136:137], v[166:167] op_sel_hi:[1,0]
	v_pk_mul_f32 v[134:135], v[134:135], v[166:167] op_sel_hi:[1,0]
	s_waitcnt vmcnt(1)
	v_mov_b32_e32 v152, v169
	v_mov_b32_e32 v153, v171
	s_waitcnt vmcnt(0)
	v_mov_b32_e32 v158, v173
	v_mov_b32_e32 v159, v175
	v_mov_b32_e32 v173, v174
	v_mov_b32_e32 v169, v170
	v_pk_mul_f32 v[130:131], v[130:131], v[166:167] op_sel_hi:[1,0]
	v_pk_mul_f32 v[132:133], v[132:133], v[166:167] op_sel_hi:[1,0]
	v_pk_mul_f32 v[156:157], v[152:153], v[134:135]
	v_pk_mul_f32 v[160:161], v[158:159], v[136:137]
	v_pk_mul_f32 v[134:135], v[168:169], v[134:135]
	v_pk_mul_f32 v[136:137], v[172:173], v[136:137]
	v_pk_fma_f32 v[160:161], v[172:173], v[132:133], v[160:161] neg_lo:[0,0,1] neg_hi:[0,0,1]
	v_pk_fma_f32 v[156:157], v[168:169], v[130:131], v[156:157] neg_lo:[0,0,1] neg_hi:[0,0,1]
	v_pk_fma_f32 v[132:133], v[158:159], v[132:133], v[136:137]
	v_pk_fma_f32 v[130:131], v[152:153], v[130:131], v[134:135]
	v_cvt_pk_bf16_f32 v156, v156, v157
	v_cvt_pk_bf16_f32 v157, v160, v161
	v_cvt_pk_bf16_f32 v130, v130, v131
	v_cvt_pk_bf16_f32 v131, v132, v133
	global_store_dwordx2 v[154:155], v[156:157], off offset:8
	global_store_dwordx2 v[154:155], v[130:131], off offset:72
	s_cbranch_execnz .LBB0_242
.LBB0_244:
	s_ashr_i32 s69, s68, 31
	v_add_u32_e32 v168, s27, v150
	s_lshl_b64 s[0:1], s[68:69], 13
	v_readlane_b32 s4, v251, 57
	v_ashrrev_i32_e32 v169, 31, v168
	v_readlane_b32 s5, v251, 58
	s_add_u32 s0, s4, s0
	s_addc_u32 s1, s5, s1
	v_lshlrev_b64 v[130:131], 5, v[168:169]
	v_lshl_add_u64 v[134:135], s[0:1], 0, v[130:131]
	global_load_dwordx4 v[130:133], v[134:135], off
	s_nop 0
	global_load_dwordx4 v[134:137], v[134:135], off offset:16
	v_lshlrev_b32_e32 v177, 5, v168
	s_waitcnt vmcnt(0)
	v_mov_b32_e32 v150, v130
	v_mov_b32_e32 v151, v134
	v_mov_b32_e32 v134, v131
	v_mov_b32_e32 v130, v132
	v_mov_b32_e32 v131, v136
	v_mov_b32_e32 v136, v133
	v_pk_add_f32 v[132:133], v[150:151], v[134:135]
	v_pk_add_f32 v[130:131], v[130:131], v[136:137]
	s_nop 0
	v_pk_add_f32 v[130:131], v[132:133], v[130:131]
	s_nop 0
	v_add_f32_e32 v130, v130, v131
	v_fmamk_f32 v130, v130, 0x3b000000, v243
	s_nop 1
	v_cmp_eq_u32_e64 s[42:43], 0, v185
	s_nop 0
	v_rsq_f32_e32 v130, v130
	s_nop 0
	v_pk_mul_f32 v[160:161], v[128:129], v[130:131] op_sel_hi:[1,0]
	v_pk_mul_f32 v[162:163], v[126:127], v[130:131] op_sel_hi:[1,0]
	v_pk_mul_f32 v[164:165], v[124:125], v[130:131] op_sel_hi:[1,0]
	v_pk_mul_f32 v[166:167], v[122:123], v[130:131] op_sel_hi:[1,0]
	v_mul_f32_e32 v122, v163, v163
	v_mul_f32_e32 v123, v161, v161
	v_mul_f32_e32 v124, v167, v167
	v_mul_f32_e32 v125, v165, v165
	v_fmac_f32_e32 v122, v162, v162
	v_fmac_f32_e32 v123, v160, v160
	v_fmac_f32_e32 v124, v166, v166
	v_fmac_f32_e32 v125, v164, v164
	v_add_f32_e32 v122, v122, v123
	v_add_f32_e32 v123, v124, v125
	v_add_f32_e32 v122, v122, v123
	ds_bpermute_b32 v123, v187, v122
	s_waitcnt lgkmcnt(0)
	v_add_f32_e32 v123, v122, v123
	ds_bpermute_b32 v124, v186, v123
	v_add_u32_e32 v122, s79, v177
	s_and_saveexec_b64 s[10:11], s[42:43]
	s_cbranch_execz .LBB0_246
	s_waitcnt lgkmcnt(0)
	v_add_f32_e32 v123, v123, v124
	ds_write_b32 v122, v123

.LBB0_248:
	s_or_b64 exec, exec, s[10:11]
	v_add_u32_e32 v154, 16, v168
	v_ashrrev_i32_e32 v155, 31, v154
	s_waitcnt lgkmcnt(0)
	v_lshlrev_b64 v[114:115], 5, v[154:155]
	v_lshl_add_u64 v[118:119], s[0:1], 0, v[114:115]
	global_load_dwordx4 v[114:117], v[118:119], off
	s_nop 0
	global_load_dwordx4 v[118:121], v[118:119], off offset:16
	v_lshlrev_b32_e32 v176, 5, v154
	s_waitcnt vmcnt(1)
	v_mov_b32_e32 v122, v114
	s_waitcnt vmcnt(0)
	v_mov_b32_e32 v123, v118
	v_mov_b32_e32 v118, v115
	v_mov_b32_e32 v114, v116
	v_mov_b32_e32 v115, v120
	v_mov_b32_e32 v120, v117
	v_pk_add_f32 v[116:117], v[122:123], v[118:119]
	v_pk_add_f32 v[114:115], v[114:115], v[120:121]
	s_nop 0
	v_pk_add_f32 v[114:115], v[116:117], v[114:115]
	s_nop 0
	v_add_f32_e32 v114, v114, v115
	v_fmamk_f32 v114, v114, 0x3b000000, v243
	v_rsq_f32_e32 v114, v114
	s_nop 0
	v_pk_mul_f32 v[130:131], v[112:113], v[114:115] op_sel_hi:[1,0]
	v_pk_mul_f32 v[132:133], v[110:111], v[114:115] op_sel_hi:[1,0]
	v_pk_mul_f32 v[134:135], v[108:109], v[114:115] op_sel_hi:[1,0]
	v_pk_mul_f32 v[136:137], v[106:107], v[114:115] op_sel_hi:[1,0]
	v_mul_f32_e32 v106, v133, v133
	v_mul_f32_e32 v107, v131, v131
	v_mul_f32_e32 v108, v137, v137
	v_mul_f32_e32 v109, v135, v135
	v_fmac_f32_e32 v106, v132, v132
	v_fmac_f32_e32 v107, v130, v130
	v_fmac_f32_e32 v108, v136, v136
	v_fmac_f32_e32 v109, v134, v134
	v_add_f32_e32 v106, v106, v107
	v_add_f32_e32 v107, v108, v109
	v_add_f32_e32 v106, v106, v107
	ds_bpermute_b32 v107, v187, v106
	s_waitcnt lgkmcnt(0)
	v_add_f32_e32 v107, v106, v107
	ds_bpermute_b32 v108, v186, v107
	v_add_u32_e32 v106, s79, v176
	s_and_saveexec_b64 s[10:11], s[42:43]
	s_cbranch_execz .LBB0_250
	s_waitcnt lgkmcnt(0)
	v_add_f32_e32 v107, v107, v108
	ds_write_b32 v106, v107

.LBB0_252:
	s_or_b64 exec, exec, s[10:11]
	v_add_u32_e32 v124, 32, v168
	v_ashrrev_i32_e32 v125, 31, v124
	s_waitcnt lgkmcnt(0)
	v_lshlrev_b64 v[98:99], 5, v[124:125]
	v_lshl_add_u64 v[102:103], s[0:1], 0, v[98:99]
	global_load_dwordx4 v[98:101], v[102:103], off
	s_nop 0
	global_load_dwordx4 v[102:105], v[102:103], off offset:16
	v_lshlrev_b32_e32 v175, 5, v124
	s_waitcnt vmcnt(1)
	v_mov_b32_e32 v106, v98
	s_waitcnt vmcnt(0)
	v_mov_b32_e32 v107, v102
	v_mov_b32_e32 v102, v99
	v_mov_b32_e32 v98, v100
	v_mov_b32_e32 v99, v104
	v_mov_b32_e32 v104, v101
	v_pk_add_f32 v[100:101], v[106:107], v[102:103]
	v_pk_add_f32 v[98:99], v[98:99], v[104:105]
	s_nop 0
	v_pk_add_f32 v[98:99], v[100:101], v[98:99]
	s_nop 0
	v_add_f32_e32 v98, v98, v99
	v_fmamk_f32 v98, v98, 0x3b000000, v243
	v_rsq_f32_e32 v98, v98
	s_nop 0
	v_pk_mul_f32 v[112:113], v[96:97], v[98:99] op_sel_hi:[1,0]
	v_pk_mul_f32 v[114:115], v[94:95], v[98:99] op_sel_hi:[1,0]
	v_pk_mul_f32 v[116:117], v[92:93], v[98:99] op_sel_hi:[1,0]
	v_pk_mul_f32 v[118:119], v[90:91], v[98:99] op_sel_hi:[1,0]
	v_mul_f32_e32 v90, v115, v115
	v_mul_f32_e32 v91, v113, v113
	v_mul_f32_e32 v92, v119, v119
	v_mul_f32_e32 v93, v117, v117
	v_fmac_f32_e32 v90, v114, v114
	v_fmac_f32_e32 v91, v112, v112
	v_fmac_f32_e32 v92, v118, v118
	v_fmac_f32_e32 v93, v116, v116
	v_add_f32_e32 v90, v90, v91
	v_add_f32_e32 v91, v92, v93
	v_add_f32_e32 v90, v90, v91
	ds_bpermute_b32 v91, v187, v90
	s_waitcnt lgkmcnt(0)
	v_add_f32_e32 v91, v90, v91
	ds_bpermute_b32 v92, v186, v91
	v_add_u32_e32 v90, s79, v175
	s_and_saveexec_b64 s[10:11], s[42:43]
	s_cbranch_execz .LBB0_254
	s_waitcnt lgkmcnt(0)
	v_add_f32_e32 v91, v91, v92
	ds_write_b32 v90, v91

.LBB0_256:
	s_or_b64 exec, exec, s[10:11]
	v_add_u32_e32 v106, 48, v168
	v_ashrrev_i32_e32 v107, 31, v106
	s_waitcnt lgkmcnt(0)
	v_lshlrev_b64 v[82:83], 5, v[106:107]
	v_lshl_add_u64 v[86:87], s[0:1], 0, v[82:83]
	global_load_dwordx4 v[82:85], v[86:87], off
	s_nop 0
	global_load_dwordx4 v[86:89], v[86:87], off offset:16
	v_lshlrev_b32_e32 v174, 5, v106
	s_waitcnt vmcnt(1)
	v_mov_b32_e32 v90, v82
	s_waitcnt vmcnt(0)
	v_mov_b32_e32 v91, v86
	v_mov_b32_e32 v86, v83
	v_mov_b32_e32 v82, v84
	v_mov_b32_e32 v83, v88
	v_mov_b32_e32 v88, v85
	v_pk_add_f32 v[84:85], v[90:91], v[86:87]
	v_pk_add_f32 v[82:83], v[82:83], v[88:89]
	s_nop 0
	v_pk_add_f32 v[82:83], v[84:85], v[82:83]
	s_nop 0
	v_add_f32_e32 v82, v82, v83
	v_fmamk_f32 v82, v82, 0x3b000000, v243
	v_rsq_f32_e32 v82, v82
	s_nop 0
	v_pk_mul_f32 v[94:95], v[80:81], v[82:83] op_sel_hi:[1,0]
	v_pk_mul_f32 v[96:97], v[78:79], v[82:83] op_sel_hi:[1,0]
	v_pk_mul_f32 v[98:99], v[76:77], v[82:83] op_sel_hi:[1,0]
	v_pk_mul_f32 v[100:101], v[74:75], v[82:83] op_sel_hi:[1,0]
	v_mul_f32_e32 v74, v97, v97
	v_mul_f32_e32 v75, v95, v95
	v_mul_f32_e32 v76, v101, v101
	v_mul_f32_e32 v77, v99, v99
	v_fmac_f32_e32 v74, v96, v96
	v_fmac_f32_e32 v75, v94, v94
	v_fmac_f32_e32 v76, v100, v100
	v_fmac_f32_e32 v77, v98, v98
	v_add_f32_e32 v74, v74, v75
	v_add_f32_e32 v75, v76, v77
	v_add_f32_e32 v74, v74, v75
	ds_bpermute_b32 v75, v187, v74
	s_waitcnt lgkmcnt(0)
	v_add_f32_e32 v75, v74, v75
	ds_bpermute_b32 v76, v186, v75
	v_add_u32_e32 v74, s79, v174
	s_and_saveexec_b64 s[10:11], s[42:43]
	s_cbranch_execz .LBB0_258
	s_waitcnt lgkmcnt(0)
	v_add_f32_e32 v75, v75, v76
	ds_write_b32 v74, v75

.LBB0_260:
	s_or_b64 exec, exec, s[10:11]
	v_add_u32_e32 v88, 0x80, v168
	v_ashrrev_i32_e32 v89, 31, v88
	s_waitcnt lgkmcnt(0)
	v_lshlrev_b64 v[66:67], 5, v[88:89]
	v_lshl_add_u64 v[70:71], s[0:1], 0, v[66:67]
	global_load_dwordx4 v[66:69], v[70:71], off
	s_nop 0
	global_load_dwordx4 v[70:73], v[70:71], off offset:16
	v_lshlrev_b32_e32 v173, 5, v88
	s_waitcnt vmcnt(1)
	v_mov_b32_e32 v74, v66
	s_waitcnt vmcnt(0)
	v_mov_b32_e32 v75, v70
	v_mov_b32_e32 v70, v67
	v_mov_b32_e32 v66, v68
	v_mov_b32_e32 v67, v72
	v_mov_b32_e32 v72, v69
	v_pk_add_f32 v[68:69], v[74:75], v[70:71]
	v_pk_add_f32 v[66:67], v[66:67], v[72:73]
	s_nop 0
	v_pk_add_f32 v[66:67], v[68:69], v[66:67]
	s_nop 0
	v_add_f32_e32 v66, v66, v67
	v_fmamk_f32 v66, v66, 0x3b000000, v243
	v_rsq_f32_e32 v68, v66
	s_nop 0
	v_pk_mul_f32 v[76:77], v[64:65], v[68:69] op_sel_hi:[1,0]
	v_pk_mul_f32 v[78:79], v[62:63], v[68:69] op_sel_hi:[1,0]
	v_pk_mul_f32 v[80:81], v[60:61], v[68:69] op_sel_hi:[1,0]
	v_pk_mul_f32 v[82:83], v[58:59], v[68:69] op_sel_hi:[1,0]
	v_mul_f32_e32 v58, v79, v79
	v_mul_f32_e32 v59, v77, v77
	v_mul_f32_e32 v60, v83, v83
	v_mul_f32_e32 v61, v81, v81
	v_fmac_f32_e32 v58, v78, v78
	v_fmac_f32_e32 v59, v76, v76
	v_fmac_f32_e32 v60, v82, v82
	v_fmac_f32_e32 v61, v80, v80
	v_add_f32_e32 v58, v58, v59
	v_add_f32_e32 v59, v60, v61
	v_add_f32_e32 v58, v58, v59
	ds_bpermute_b32 v59, v187, v58
	s_waitcnt lgkmcnt(0)
	v_add_f32_e32 v59, v58, v59
	ds_bpermute_b32 v60, v186, v59
	v_add_u32_e32 v58, s79, v173
	s_and_saveexec_b64 s[10:11], s[42:43]
	s_cbranch_execz .LBB0_262
	s_waitcnt lgkmcnt(0)
	v_add_f32_e32 v59, v59, v60
	ds_write_b32 v58, v59

.LBB0_264:
	s_or_b64 exec, exec, s[10:11]
	v_add_u32_e32 v70, 0x90, v168
	v_ashrrev_i32_e32 v71, 31, v70
	s_waitcnt lgkmcnt(0)
	v_lshlrev_b64 v[50:51], 5, v[70:71]
	v_lshl_add_u64 v[54:55], s[0:1], 0, v[50:51]
	global_load_dwordx4 v[50:53], v[54:55], off
	s_nop 0
	global_load_dwordx4 v[54:57], v[54:55], off offset:16
	v_lshlrev_b32_e32 v172, 5, v70
	s_waitcnt vmcnt(1)
	v_mov_b32_e32 v58, v50
	s_waitcnt vmcnt(0)
	v_mov_b32_e32 v59, v54
	v_mov_b32_e32 v54, v51
	v_mov_b32_e32 v50, v52
	v_mov_b32_e32 v51, v56
	v_mov_b32_e32 v56, v53
	v_pk_add_f32 v[52:53], v[58:59], v[54:55]
	v_pk_add_f32 v[50:51], v[50:51], v[56:57]
	s_nop 0
	v_pk_add_f32 v[50:51], v[52:53], v[50:51]
	s_nop 0
	v_add_f32_e32 v50, v50, v51
	v_fmamk_f32 v50, v50, 0x3b000000, v243
	v_rsq_f32_e32 v50, v50
	s_nop 0
	v_pk_mul_f32 v[58:59], v[48:49], v[50:51] op_sel_hi:[1,0]
	v_pk_mul_f32 v[60:61], v[46:47], v[50:51] op_sel_hi:[1,0]
	v_pk_mul_f32 v[62:63], v[44:45], v[50:51] op_sel_hi:[1,0]
	v_pk_mul_f32 v[64:65], v[42:43], v[50:51] op_sel_hi:[1,0]
	v_mul_f32_e32 v42, v61, v61
	v_mul_f32_e32 v43, v59, v59
	v_mul_f32_e32 v44, v65, v65
	v_mul_f32_e32 v45, v63, v63
	v_fmac_f32_e32 v42, v60, v60
	v_fmac_f32_e32 v43, v58, v58
	v_fmac_f32_e32 v44, v64, v64
	v_fmac_f32_e32 v45, v62, v62
	v_add_f32_e32 v42, v42, v43
	v_add_f32_e32 v43, v44, v45
	v_add_f32_e32 v42, v42, v43
	ds_bpermute_b32 v43, v187, v42
	s_waitcnt lgkmcnt(0)
	v_add_f32_e32 v43, v42, v43
	ds_bpermute_b32 v44, v186, v43
	v_add_u32_e32 v42, s79, v172
	s_and_saveexec_b64 s[10:11], s[42:43]
	s_cbranch_execz .LBB0_266
	s_waitcnt lgkmcnt(0)
	v_add_f32_e32 v43, v43, v44
	ds_write_b32 v42, v43

.LBB0_268:
	s_or_b64 exec, exec, s[10:11]
	v_add_u32_e32 v52, 0xa0, v168
	v_ashrrev_i32_e32 v53, 31, v52
	s_waitcnt lgkmcnt(0)
	v_lshlrev_b64 v[34:35], 5, v[52:53]
	v_lshl_add_u64 v[38:39], s[0:1], 0, v[34:35]
	global_load_dwordx4 v[34:37], v[38:39], off
	s_nop 0
	global_load_dwordx4 v[38:41], v[38:39], off offset:16
	v_lshlrev_b32_e32 v171, 5, v52
	s_waitcnt vmcnt(1)
	v_mov_b32_e32 v42, v34
	s_waitcnt vmcnt(0)
	v_mov_b32_e32 v43, v38
	v_mov_b32_e32 v38, v35
	v_mov_b32_e32 v34, v36
	v_mov_b32_e32 v35, v40
	v_mov_b32_e32 v40, v37
	v_pk_add_f32 v[36:37], v[42:43], v[38:39]
	v_pk_add_f32 v[34:35], v[34:35], v[40:41]
	s_nop 0
	v_pk_add_f32 v[34:35], v[36:37], v[34:35]
	s_nop 0
	v_add_f32_e32 v34, v34, v35
	v_fmamk_f32 v34, v34, 0x3b000000, v243
	v_rsq_f32_e32 v38, v34
	s_nop 0
	v_pk_mul_f32 v[40:41], v[32:33], v[38:39] op_sel_hi:[1,0]
	v_pk_mul_f32 v[42:43], v[30:31], v[38:39] op_sel_hi:[1,0]
	v_pk_mul_f32 v[44:45], v[28:29], v[38:39] op_sel_hi:[1,0]
	v_pk_mul_f32 v[46:47], v[26:27], v[38:39] op_sel_hi:[1,0]
	v_mul_f32_e32 v26, v43, v43
	v_mul_f32_e32 v27, v41, v41
	v_mul_f32_e32 v28, v47, v47
	v_mul_f32_e32 v29, v45, v45
	v_fmac_f32_e32 v26, v42, v42
	v_fmac_f32_e32 v27, v40, v40
	v_fmac_f32_e32 v28, v46, v46
	v_fmac_f32_e32 v29, v44, v44
	v_add_f32_e32 v26, v26, v27
	v_add_f32_e32 v27, v28, v29
	v_add_f32_e32 v26, v26, v27
	ds_bpermute_b32 v27, v187, v26
	s_waitcnt lgkmcnt(0)
	v_add_f32_e32 v27, v26, v27
	ds_bpermute_b32 v28, v186, v27
	v_add_u32_e32 v26, s79, v171
	s_and_saveexec_b64 s[10:11], s[42:43]
	s_cbranch_execz .LBB0_270
	s_waitcnt lgkmcnt(0)
	v_add_f32_e32 v27, v27, v28
	ds_write_b32 v26, v27

.LBB0_272:
	s_or_b64 exec, exec, s[10:11]
	v_add_u32_e32 v32, 0xb0, v168
	v_ashrrev_i32_e32 v33, 31, v32
	s_waitcnt lgkmcnt(0)
	v_lshlrev_b64 v[18:19], 5, v[32:33]
	v_lshl_add_u64 v[22:23], s[0:1], 0, v[18:19]
	global_load_dwordx4 v[18:21], v[22:23], off
	s_nop 0
	global_load_dwordx4 v[22:25], v[22:23], off offset:16
	v_lshlrev_b32_e32 v170, 5, v32
	v_add_u32_e32 v38, s79, v170
	s_waitcnt vmcnt(1)
	v_mov_b32_e32 v26, v18
	s_waitcnt vmcnt(0)
	v_mov_b32_e32 v27, v22
	v_mov_b32_e32 v22, v19
	v_mov_b32_e32 v18, v20
	v_mov_b32_e32 v19, v24
	v_mov_b32_e32 v24, v21
	v_pk_add_f32 v[20:21], v[26:27], v[22:23]
	v_pk_add_f32 v[18:19], v[18:19], v[24:25]
	s_nop 0
	v_pk_add_f32 v[18:19], v[20:21], v[18:19]
	s_nop 0
	v_add_f32_e32 v18, v18, v19
	v_fmamk_f32 v18, v18, 0x3b000000, v243
	v_rsq_f32_e32 v18, v18
	s_nop 0
	v_pk_mul_f32 v[20:21], v[16:17], v[18:19] op_sel_hi:[1,0]
	v_pk_mul_f32 v[22:23], v[14:15], v[18:19] op_sel_hi:[1,0]
	v_pk_mul_f32 v[24:25], v[12:13], v[18:19] op_sel_hi:[1,0]
	v_pk_mul_f32 v[26:27], v[10:11], v[18:19] op_sel_hi:[1,0]
	v_mul_f32_e32 v10, v23, v23
	v_mul_f32_e32 v11, v21, v21
	v_mul_f32_e32 v12, v27, v27
	v_mul_f32_e32 v13, v25, v25
	v_fmac_f32_e32 v10, v22, v22
	v_fmac_f32_e32 v11, v20, v20
	v_fmac_f32_e32 v12, v26, v26
	v_fmac_f32_e32 v13, v24, v24
	v_add_f32_e32 v10, v10, v11
	v_add_f32_e32 v11, v12, v13
	v_add_f32_e32 v10, v10, v11
	ds_bpermute_b32 v11, v187, v10
	s_waitcnt lgkmcnt(0)
	v_add_f32_e32 v10, v10, v11
	ds_bpermute_b32 v11, v186, v10
	s_and_saveexec_b64 s[0:1], s[42:43]
	s_cbranch_execz .LBB0_274
	s_waitcnt lgkmcnt(0)
	v_add_f32_e32 v10, v10, v11
	ds_write_b32 v38, v10

.LBB0_276:
	s_or_b64 exec, exec, s[0:1]
	s_add_i32 s4, 0, 0x20000
	s_waitcnt lgkmcnt(0)
	s_barrier
	v_add_u32_e32 v2, s4, v177
	ds_read_b128 v[6:9], v2
	s_waitcnt lgkmcnt(1)
	ds_read_b128 v[2:5], v2 offset:16
	v_lshl_add_u32 v38, v185, 3, s73
	v_ashrrev_i32_e32 v39, 31, v38
	s_lshl_b64 s[10:11], s[68:69], 20
	s_waitcnt lgkmcnt(1)
	v_mov_b32_e32 v18, v7
	v_mov_b32_e32 v19, v8
	v_mov_b32_e32 v7, v9
	v_pk_add_f32 v[6:7], v[18:19], v[6:7]
	s_lshl_b32 s0, s83, 8
	v_add_f32_e32 v6, v6, v7
	v_fmamk_f32 v6, v6, 0x3c000000, v243
	v_lshlrev_b64 v[168:169], 12, v[168:169]
	s_nop 1
	v_readlane_b32 s6, v251, 45
	v_readlane_b32 s7, v251, 46
	s_add_u32 s44, s6, s10
	v_rsq_f32_e32 v6, v6
	s_nop 0
	v_lshl_add_u64 v[18:19], v[38:39], 2, s[56:57]
	v_mul_f32_e32 v186, 0x3dd53b94, v6
	global_load_dwordx4 v[6:9], v[18:19], off offset:16
	global_load_dwordx4 v[178:181], v[18:19], off
	s_addc_u32 s45, s7, s11
	s_ashr_i32 s1, s0, 31
	s_lshl_b64 s[68:69], s[0:1], 1
	v_lshlrev_b64 v[38:39], 1, v[38:39]
	s_waitcnt vmcnt(1)
	v_pk_mul_f32 v[8:9], v[164:165], v[8:9]
	s_waitcnt vmcnt(0)
	v_pk_mul_f32 v[160:161], v[160:161], v[180:181]
	v_pk_mul_f32 v[6:7], v[166:167], v[6:7]
	v_pk_mul_f32 v[160:161], v[160:161], v[186:187] op_sel_hi:[1,0]
	v_pk_mul_f32 v[162:163], v[162:163], v[178:179]
	v_pk_mul_f32 v[164:165], v[8:9], v[186:187] op_sel_hi:[1,0]
	v_pk_mul_f32 v[8:9], v[6:7], v[186:187] op_sel_hi:[1,0]
	v_cvt_pk_bf16_f32 v7, v160, v161
	v_lshl_add_u64 v[160:161], s[44:45], 0, v[168:169]
	v_pk_mul_f32 v[162:163], v[162:163], v[186:187] op_sel_hi:[1,0]
	v_lshl_add_u64 v[160:161], v[160:161], 0, s[68:69]
	v_cvt_pk_bf16_f32 v6, v162, v163
	v_cvt_pk_bf16_f32 v8, v8, v9
	v_cvt_pk_bf16_f32 v9, v164, v165
	v_lshl_add_u64 v[160:161], v[160:161], 0, v[38:39]
	global_store_dwordx4 v[160:161], v[6:9], off
	s_waitcnt lgkmcnt(0)
	s_nop 0
	v_mov_b32_e32 v6, v3
	v_mov_b32_e32 v7, v4
	v_mov_b32_e32 v3, v5
	v_pk_add_f32 v[2:3], v[6:7], v[2:3]
	s_nop 0
	v_add_f32_e32 v2, v2, v3
	v_fmamk_f32 v2, v2, 0x3c000000, v243
	v_rsq_f32_e32 v2, v2
	s_nop 0
	v_mul_f32_e32 v6, 0x3dd53b94, v2
	global_load_dwordx4 v[2:5], v[18:19], off offset:16
	global_load_dwordx4 v[162:165], v[18:19], off
	s_waitcnt vmcnt(1)
	v_pk_mul_f32 v[4:5], v[150:151], v[4:5]
	s_waitcnt vmcnt(0)
	v_pk_mul_f32 v[8:9], v[156:157], v[164:165]
	v_pk_mul_f32 v[156:157], v[158:159], v[162:163]
	v_pk_mul_f32 v[2:3], v[152:153], v[2:3]
	v_pk_mul_f32 v[8:9], v[8:9], v[6:7] op_sel_hi:[1,0]
	v_pk_mul_f32 v[156:157], v[156:157], v[6:7] op_sel_hi:[1,0]
	v_pk_mul_f32 v[150:151], v[4:5], v[6:7] op_sel_hi:[1,0]
	v_pk_mul_f32 v[4:5], v[2:3], v[6:7] op_sel_hi:[1,0]
	v_cvt_pk_bf16_f32 v2, v156, v157
	v_cvt_pk_bf16_f32 v3, v8, v9
	v_cvt_pk_bf16_f32 v4, v4, v5
	v_cvt_pk_bf16_f32 v5, v150, v151
	global_store_dwordx4 v[160:161], v[2:5], off offset:256
	v_lshlrev_b64 v[150:151], 12, v[154:155]
	s_nop 0
	v_add_u32_e32 v2, s4, v176
	ds_read_b128 v[6:9], v2
	ds_read_b128 v[2:5], v2 offset:16
	s_waitcnt lgkmcnt(1)
	v_mov_b32_e32 v152, v7
	v_mov_b32_e32 v153, v8
	v_mov_b32_e32 v7, v9
	v_pk_add_f32 v[6:7], v[152:153], v[6:7]
	s_nop 0
	v_add_f32_e32 v6, v6, v7
	v_fmamk_f32 v6, v6, 0x3c000000, v243
	v_rsq_f32_e32 v6, v6
	s_nop 0
	v_mul_f32_e32 v156, 0x3dd53b94, v6
	global_load_dwordx4 v[6:9], v[18:19], off offset:16
	global_load_dwordx4 v[152:155], v[18:19], off
	s_waitcnt vmcnt(1)
	v_pk_mul_f32 v[8:9], v[134:135], v[8:9]
	s_waitcnt vmcnt(0)
	v_pk_mul_f32 v[130:131], v[130:131], v[154:155]
	v_pk_mul_f32 v[6:7], v[136:137], v[6:7]
	v_pk_mul_f32 v[130:131], v[130:131], v[156:157] op_sel_hi:[1,0]
	v_pk_mul_f32 v[132:133], v[132:133], v[152:153]
	v_pk_mul_f32 v[134:135], v[8:9], v[156:157] op_sel_hi:[1,0]
	v_pk_mul_f32 v[8:9], v[6:7], v[156:157] op_sel_hi:[1,0]
	v_cvt_pk_bf16_f32 v7, v130, v131
	v_lshl_add_u64 v[130:131], s[44:45], 0, v[150:151]
	v_pk_mul_f32 v[132:133], v[132:133], v[156:157] op_sel_hi:[1,0]
	v_lshl_add_u64 v[130:131], v[130:131], 0, s[68:69]
	v_cvt_pk_bf16_f32 v6, v132, v133
	v_cvt_pk_bf16_f32 v8, v8, v9
	v_cvt_pk_bf16_f32 v9, v134, v135
	v_lshl_add_u64 v[130:131], v[130:131], 0, v[38:39]
	global_store_dwordx4 v[130:131], v[6:9], off
	s_waitcnt lgkmcnt(0)
	s_nop 0
	v_mov_b32_e32 v6, v3
	v_mov_b32_e32 v7, v4
	v_mov_b32_e32 v3, v5
	v_pk_add_f32 v[2:3], v[6:7], v[2:3]
	s_nop 0
	v_add_f32_e32 v2, v2, v3
	v_fmamk_f32 v2, v2, 0x3c000000, v243
	v_rsq_f32_e32 v2, v2
	s_nop 0
	v_mul_f32_e32 v6, 0x3dd53b94, v2
	global_load_dwordx4 v[2:5], v[18:19], off offset:16
	global_load_dwordx4 v[132:135], v[18:19], off
	s_waitcnt vmcnt(1)
	v_pk_mul_f32 v[4:5], v[120:121], v[4:5]
	s_waitcnt vmcnt(0)
	v_pk_mul_f32 v[8:9], v[126:127], v[134:135]
	v_pk_mul_f32 v[126:127], v[128:129], v[132:133]
	v_pk_mul_f32 v[2:3], v[122:123], v[2:3]
	v_pk_mul_f32 v[8:9], v[8:9], v[6:7] op_sel_hi:[1,0]
	v_pk_mul_f32 v[126:127], v[126:127], v[6:7] op_sel_hi:[1,0]
	v_pk_mul_f32 v[120:121], v[4:5], v[6:7] op_sel_hi:[1,0]
	v_pk_mul_f32 v[4:5], v[2:3], v[6:7] op_sel_hi:[1,0]
	v_cvt_pk_bf16_f32 v2, v126, v127
	v_cvt_pk_bf16_f32 v3, v8, v9
	v_cvt_pk_bf16_f32 v4, v4, v5
	v_cvt_pk_bf16_f32 v5, v120, v121
	v_add_u32_e32 v123, s4, v175
	global_store_dwordx4 v[130:131], v[2:5], off offset:256
	ds_read_b128 v[2:5], v123
	v_lshlrev_b64 v[120:121], 12, v[124:125]
	s_waitcnt lgkmcnt(0)
	v_mov_b32_e32 v6, v3
	v_mov_b32_e32 v7, v4
	v_mov_b32_e32 v3, v5
	v_pk_add_f32 v[2:3], v[6:7], v[2:3]
	s_nop 0
	v_add_f32_e32 v2, v2, v3
	v_fmamk_f32 v2, v2, 0x3c000000, v243
	v_rsq_f32_e32 v2, v2
	s_nop 0
	v_mul_f32_e32 v122, 0x3dd53b94, v2
	global_load_dwordx4 v[2:5], v[18:19], off offset:16
	global_load_dwordx4 v[6:9], v[18:19], off
	s_waitcnt vmcnt(1)
	v_pk_mul_f32 v[4:5], v[116:117], v[4:5]
	s_waitcnt vmcnt(0)
	v_pk_mul_f32 v[6:7], v[114:115], v[6:7]
	v_pk_mul_f32 v[2:3], v[118:119], v[2:3]
	v_pk_mul_f32 v[6:7], v[6:7], v[122:123] op_sel_hi:[1,0]
	v_pk_mul_f32 v[8:9], v[112:113], v[8:9]
	v_pk_mul_f32 v[112:113], v[4:5], v[122:123] op_sel_hi:[1,0]
	v_pk_mul_f32 v[4:5], v[2:3], v[122:123] op_sel_hi:[1,0]
	v_cvt_pk_bf16_f32 v2, v6, v7
	v_lshl_add_u64 v[6:7], s[44:45], 0, v[120:121]
	v_pk_mul_f32 v[8:9], v[8:9], v[122:123] op_sel_hi:[1,0]
	v_lshl_add_u64 v[6:7], v[6:7], 0, s[68:69]
	v_cvt_pk_bf16_f32 v3, v8, v9
	v_cvt_pk_bf16_f32 v4, v4, v5
	v_cvt_pk_bf16_f32 v5, v112, v113
	v_lshl_add_u64 v[6:7], v[6:7], 0, v[38:39]
	global_store_dwordx4 v[6:7], v[2:5], off
	ds_read_b128 v[2:5], v123 offset:16
	s_waitcnt lgkmcnt(0)
	v_mov_b32_e32 v8, v3
	v_mov_b32_e32 v9, v4
	v_mov_b32_e32 v3, v5
	v_pk_add_f32 v[2:3], v[8:9], v[2:3]
	s_nop 0
	v_add_f32_e32 v2, v2, v3
	v_fmamk_f32 v2, v2, 0x3c000000, v243
	v_rsq_f32_e32 v2, v2
	s_nop 0
	v_mul_f32_e32 v8, 0x3dd53b94, v2
	global_load_dwordx4 v[2:5], v[18:19], off offset:16
	global_load_dwordx4 v[112:115], v[18:19], off
	s_waitcnt vmcnt(1)
	v_pk_mul_f32 v[4:5], v[102:103], v[4:5]
	s_waitcnt vmcnt(0)
	v_pk_mul_f32 v[108:109], v[108:109], v[114:115]
	v_pk_mul_f32 v[110:111], v[110:111], v[112:113]
	v_pk_mul_f32 v[2:3], v[104:105], v[2:3]
	v_pk_mul_f32 v[108:109], v[108:109], v[8:9] op_sel_hi:[1,0]
	v_pk_mul_f32 v[110:111], v[110:111], v[8:9] op_sel_hi:[1,0]
	v_pk_mul_f32 v[102:103], v[4:5], v[8:9] op_sel_hi:[1,0]
	v_pk_mul_f32 v[4:5], v[2:3], v[8:9] op_sel_hi:[1,0]
	v_cvt_pk_bf16_f32 v2, v110, v111
	v_cvt_pk_bf16_f32 v3, v108, v109
	v_cvt_pk_bf16_f32 v4, v4, v5
	v_cvt_pk_bf16_f32 v5, v102, v103
	v_add_u32_e32 v105, s4, v174
	global_store_dwordx4 v[6:7], v[2:5], off offset:256
	ds_read_b128 v[2:5], v105
	v_lshlrev_b64 v[102:103], 12, v[106:107]
	s_waitcnt lgkmcnt(0)
	v_mov_b32_e32 v6, v3
	v_mov_b32_e32 v7, v4
	v_mov_b32_e32 v3, v5
	v_pk_add_f32 v[2:3], v[6:7], v[2:3]
	s_nop 0
	v_add_f32_e32 v2, v2, v3
	v_fmamk_f32 v2, v2, 0x3c000000, v243
	v_rsq_f32_e32 v2, v2
	s_nop 0
	v_mul_f32_e32 v104, 0x3dd53b94, v2
	global_load_dwordx4 v[2:5], v[18:19], off offset:16
	global_load_dwordx4 v[6:9], v[18:19], off
	s_waitcnt vmcnt(1)
	v_pk_mul_f32 v[4:5], v[98:99], v[4:5]
	s_waitcnt vmcnt(0)
	v_pk_mul_f32 v[6:7], v[96:97], v[6:7]
	v_pk_mul_f32 v[2:3], v[100:101], v[2:3]
	v_pk_mul_f32 v[6:7], v[6:7], v[104:105] op_sel_hi:[1,0]
	v_pk_mul_f32 v[8:9], v[94:95], v[8:9]
	v_pk_mul_f32 v[94:95], v[4:5], v[104:105] op_sel_hi:[1,0]
	v_pk_mul_f32 v[4:5], v[2:3], v[104:105] op_sel_hi:[1,0]
	v_cvt_pk_bf16_f32 v2, v6, v7
	v_lshl_add_u64 v[6:7], s[44:45], 0, v[102:103]
	v_pk_mul_f32 v[8:9], v[8:9], v[104:105] op_sel_hi:[1,0]
	v_lshl_add_u64 v[6:7], v[6:7], 0, s[68:69]
	v_cvt_pk_bf16_f32 v3, v8, v9
	v_cvt_pk_bf16_f32 v4, v4, v5
	v_cvt_pk_bf16_f32 v5, v94, v95
	v_lshl_add_u64 v[6:7], v[6:7], 0, v[38:39]
	global_store_dwordx4 v[6:7], v[2:5], off
	ds_read_b128 v[2:5], v105 offset:16
	s_waitcnt lgkmcnt(0)
	v_mov_b32_e32 v8, v3
	v_mov_b32_e32 v9, v4
	v_mov_b32_e32 v3, v5
	v_pk_add_f32 v[2:3], v[8:9], v[2:3]
	s_nop 0
	v_add_f32_e32 v2, v2, v3
	v_fmamk_f32 v2, v2, 0x3c000000, v243
	v_rsq_f32_e32 v2, v2
	s_nop 0
	v_mul_f32_e32 v8, 0x3dd53b94, v2
	global_load_dwordx4 v[2:5], v[18:19], off offset:16
	global_load_dwordx4 v[94:97], v[18:19], off
	s_waitcnt vmcnt(1)
	v_pk_mul_f32 v[4:5], v[84:85], v[4:5]
	s_waitcnt vmcnt(0)
	v_pk_mul_f32 v[90:91], v[90:91], v[96:97]
	v_pk_mul_f32 v[92:93], v[92:93], v[94:95]
	v_pk_mul_f32 v[2:3], v[86:87], v[2:3]
	v_pk_mul_f32 v[90:91], v[90:91], v[8:9] op_sel_hi:[1,0]
	v_pk_mul_f32 v[92:93], v[92:93], v[8:9] op_sel_hi:[1,0]
	v_pk_mul_f32 v[84:85], v[4:5], v[8:9] op_sel_hi:[1,0]
	v_pk_mul_f32 v[4:5], v[2:3], v[8:9] op_sel_hi:[1,0]
	v_cvt_pk_bf16_f32 v2, v92, v93
	v_cvt_pk_bf16_f32 v3, v90, v91
	v_cvt_pk_bf16_f32 v4, v4, v5
	v_cvt_pk_bf16_f32 v5, v84, v85
	v_add_u32_e32 v87, s4, v173
	global_store_dwordx4 v[6:7], v[2:5], off offset:256
	ds_read_b128 v[2:5], v87
	v_lshlrev_b64 v[84:85], 12, v[88:89]
	s_waitcnt lgkmcnt(0)
	v_mov_b32_e32 v6, v3
	v_mov_b32_e32 v7, v4
	v_mov_b32_e32 v3, v5
	v_pk_add_f32 v[2:3], v[6:7], v[2:3]
	s_nop 0
	v_add_f32_e32 v2, v2, v3
	v_fmamk_f32 v2, v2, 0x3c000000, v243
	v_rsq_f32_e32 v2, v2
	s_nop 0
	v_mul_f32_e32 v86, 0x3dd53b94, v2
	global_load_dwordx4 v[2:5], v[18:19], off offset:16
	global_load_dwordx4 v[6:9], v[18:19], off
	s_waitcnt vmcnt(1)
	v_pk_mul_f32 v[4:5], v[80:81], v[4:5]
	s_waitcnt vmcnt(0)
	v_pk_mul_f32 v[6:7], v[78:79], v[6:7]
	v_pk_mul_f32 v[2:3], v[82:83], v[2:3]
	v_pk_mul_f32 v[6:7], v[6:7], v[86:87] op_sel_hi:[1,0]
	v_pk_mul_f32 v[8:9], v[76:77], v[8:9]
	v_pk_mul_f32 v[76:77], v[4:5], v[86:87] op_sel_hi:[1,0]
	v_pk_mul_f32 v[4:5], v[2:3], v[86:87] op_sel_hi:[1,0]
	v_cvt_pk_bf16_f32 v2, v6, v7
	v_lshl_add_u64 v[6:7], s[44:45], 0, v[84:85]
	v_pk_mul_f32 v[8:9], v[8:9], v[86:87] op_sel_hi:[1,0]
	v_lshl_add_u64 v[6:7], v[6:7], 0, s[68:69]
	v_cvt_pk_bf16_f32 v3, v8, v9
	v_cvt_pk_bf16_f32 v4, v4, v5
	v_cvt_pk_bf16_f32 v5, v76, v77
	v_lshl_add_u64 v[6:7], v[6:7], 0, v[38:39]
	global_store_dwordx4 v[6:7], v[2:5], off
	ds_read_b128 v[2:5], v87 offset:16
	s_waitcnt lgkmcnt(0)
	v_mov_b32_e32 v8, v3
	v_mov_b32_e32 v9, v4
	v_mov_b32_e32 v3, v5
	v_pk_add_f32 v[2:3], v[8:9], v[2:3]
	s_nop 0
	v_add_f32_e32 v2, v2, v3
	v_fmamk_f32 v2, v2, 0x3c000000, v243
	v_rsq_f32_e32 v2, v2
	s_nop 0
	v_mul_f32_e32 v8, 0x3dd53b94, v2
	global_load_dwordx4 v[2:5], v[18:19], off offset:16
	global_load_dwordx4 v[76:79], v[18:19], off
	s_waitcnt vmcnt(1)
	v_pk_mul_f32 v[4:5], v[66:67], v[4:5]
	s_waitcnt vmcnt(0)
	v_pk_mul_f32 v[72:73], v[72:73], v[78:79]
	v_pk_mul_f32 v[74:75], v[74:75], v[76:77]
	v_pk_mul_f32 v[2:3], v[68:69], v[2:3]
	v_pk_mul_f32 v[72:73], v[72:73], v[8:9] op_sel_hi:[1,0]
	v_pk_mul_f32 v[74:75], v[74:75], v[8:9] op_sel_hi:[1,0]
	v_pk_mul_f32 v[66:67], v[4:5], v[8:9] op_sel_hi:[1,0]
	v_pk_mul_f32 v[4:5], v[2:3], v[8:9] op_sel_hi:[1,0]
	v_cvt_pk_bf16_f32 v2, v74, v75
	v_cvt_pk_bf16_f32 v3, v72, v73
	v_cvt_pk_bf16_f32 v4, v4, v5
	v_cvt_pk_bf16_f32 v5, v66, v67
	v_add_u32_e32 v69, s4, v172
	global_store_dwordx4 v[6:7], v[2:5], off offset:256
	ds_read_b128 v[2:5], v69
	v_lshlrev_b64 v[66:67], 12, v[70:71]
	s_waitcnt lgkmcnt(0)
	v_mov_b32_e32 v6, v3
	v_mov_b32_e32 v7, v4
	v_mov_b32_e32 v3, v5
	v_pk_add_f32 v[2:3], v[6:7], v[2:3]
	s_nop 0
	v_add_f32_e32 v2, v2, v3
	v_fmamk_f32 v2, v2, 0x3c000000, v243
	v_rsq_f32_e32 v2, v2
	s_nop 0
	v_mul_f32_e32 v68, 0x3dd53b94, v2
	global_load_dwordx4 v[2:5], v[18:19], off offset:16
	global_load_dwordx4 v[6:9], v[18:19], off
	s_waitcnt vmcnt(1)
	v_pk_mul_f32 v[4:5], v[62:63], v[4:5]
	s_waitcnt vmcnt(0)
	v_pk_mul_f32 v[6:7], v[60:61], v[6:7]
	v_pk_mul_f32 v[2:3], v[64:65], v[2:3]
	v_pk_mul_f32 v[6:7], v[6:7], v[68:69] op_sel_hi:[1,0]
	v_pk_mul_f32 v[8:9], v[58:59], v[8:9]
	v_pk_mul_f32 v[58:59], v[4:5], v[68:69] op_sel_hi:[1,0]
	v_pk_mul_f32 v[4:5], v[2:3], v[68:69] op_sel_hi:[1,0]
	v_cvt_pk_bf16_f32 v2, v6, v7
	v_lshl_add_u64 v[6:7], s[44:45], 0, v[66:67]
	v_pk_mul_f32 v[8:9], v[8:9], v[68:69] op_sel_hi:[1,0]
	v_lshl_add_u64 v[6:7], v[6:7], 0, s[68:69]
	v_cvt_pk_bf16_f32 v3, v8, v9
	v_cvt_pk_bf16_f32 v4, v4, v5
	v_cvt_pk_bf16_f32 v5, v58, v59
	v_lshl_add_u64 v[6:7], v[6:7], 0, v[38:39]
	global_store_dwordx4 v[6:7], v[2:5], off
	ds_read_b128 v[2:5], v69 offset:16
	s_waitcnt lgkmcnt(0)
	v_mov_b32_e32 v8, v3
	v_mov_b32_e32 v9, v4
	v_mov_b32_e32 v3, v5
	v_pk_add_f32 v[2:3], v[8:9], v[2:3]
	s_nop 0
	v_add_f32_e32 v2, v2, v3
	v_fmamk_f32 v2, v2, 0x3c000000, v243
	v_rsq_f32_e32 v2, v2
	s_nop 0
	v_mul_f32_e32 v8, 0x3dd53b94, v2
	global_load_dwordx4 v[2:5], v[18:19], off offset:16
	global_load_dwordx4 v[58:61], v[18:19], off
	s_waitcnt vmcnt(1)
	v_pk_mul_f32 v[4:5], v[48:49], v[4:5]
	s_waitcnt vmcnt(0)
	v_pk_mul_f32 v[54:55], v[54:55], v[60:61]
	v_pk_mul_f32 v[56:57], v[56:57], v[58:59]
	v_pk_mul_f32 v[2:3], v[50:51], v[2:3]
	v_pk_mul_f32 v[54:55], v[54:55], v[8:9] op_sel_hi:[1,0]
	v_pk_mul_f32 v[56:57], v[56:57], v[8:9] op_sel_hi:[1,0]
	v_pk_mul_f32 v[48:49], v[4:5], v[8:9] op_sel_hi:[1,0]
	v_pk_mul_f32 v[4:5], v[2:3], v[8:9] op_sel_hi:[1,0]
	v_cvt_pk_bf16_f32 v2, v56, v57
	v_cvt_pk_bf16_f32 v3, v54, v55
	v_cvt_pk_bf16_f32 v4, v4, v5
	v_cvt_pk_bf16_f32 v5, v48, v49
	v_add_u32_e32 v51, s4, v171
	global_store_dwordx4 v[6:7], v[2:5], off offset:256
	ds_read_b128 v[2:5], v51
	v_lshlrev_b64 v[48:49], 12, v[52:53]
	s_waitcnt lgkmcnt(0)
	v_mov_b32_e32 v6, v3
	v_mov_b32_e32 v7, v4
	v_mov_b32_e32 v3, v5
	v_pk_add_f32 v[2:3], v[6:7], v[2:3]
	s_nop 0
	v_add_f32_e32 v2, v2, v3
	v_fmamk_f32 v2, v2, 0x3c000000, v243
	v_rsq_f32_e32 v2, v2
	s_nop 0
	v_mul_f32_e32 v50, 0x3dd53b94, v2
	global_load_dwordx4 v[2:5], v[18:19], off offset:16
	global_load_dwordx4 v[6:9], v[18:19], off
	s_waitcnt vmcnt(1)
	v_pk_mul_f32 v[4:5], v[44:45], v[4:5]
	s_waitcnt vmcnt(0)
	v_pk_mul_f32 v[6:7], v[42:43], v[6:7]
	v_pk_mul_f32 v[2:3], v[46:47], v[2:3]
	v_pk_mul_f32 v[6:7], v[6:7], v[50:51] op_sel_hi:[1,0]
	v_pk_mul_f32 v[8:9], v[40:41], v[8:9]
	v_pk_mul_f32 v[40:41], v[4:5], v[50:51] op_sel_hi:[1,0]
	v_pk_mul_f32 v[4:5], v[2:3], v[50:51] op_sel_hi:[1,0]
	v_cvt_pk_bf16_f32 v2, v6, v7
	v_lshl_add_u64 v[6:7], s[44:45], 0, v[48:49]
	v_pk_mul_f32 v[8:9], v[8:9], v[50:51] op_sel_hi:[1,0]
	v_lshl_add_u64 v[6:7], v[6:7], 0, s[68:69]
	v_cvt_pk_bf16_f32 v3, v8, v9
	v_cvt_pk_bf16_f32 v4, v4, v5
	v_cvt_pk_bf16_f32 v5, v40, v41
	v_lshl_add_u64 v[6:7], v[6:7], 0, v[38:39]
	global_store_dwordx4 v[6:7], v[2:5], off
	ds_read_b128 v[2:5], v51 offset:16
	s_waitcnt lgkmcnt(0)
	v_mov_b32_e32 v8, v3
	v_mov_b32_e32 v9, v4
	v_mov_b32_e32 v3, v5
	v_pk_add_f32 v[2:3], v[8:9], v[2:3]
	s_nop 0
	v_add_f32_e32 v2, v2, v3
	v_fmamk_f32 v2, v2, 0x3c000000, v243
	v_rsq_f32_e32 v2, v2
	s_nop 0
	v_mul_f32_e32 v8, 0x3dd53b94, v2
	global_load_dwordx4 v[2:5], v[18:19], off offset:16
	global_load_dwordx4 v[40:43], v[18:19], off
	s_waitcnt vmcnt(1)
	v_pk_mul_f32 v[4:5], v[28:29], v[4:5]
	s_waitcnt vmcnt(0)
	v_pk_mul_f32 v[34:35], v[34:35], v[42:43]
	v_pk_mul_f32 v[36:37], v[36:37], v[40:41]
	v_pk_mul_f32 v[2:3], v[30:31], v[2:3]
	v_pk_mul_f32 v[34:35], v[34:35], v[8:9] op_sel_hi:[1,0]
	v_pk_mul_f32 v[36:37], v[36:37], v[8:9] op_sel_hi:[1,0]
	v_pk_mul_f32 v[28:29], v[4:5], v[8:9] op_sel_hi:[1,0]
	v_pk_mul_f32 v[4:5], v[2:3], v[8:9] op_sel_hi:[1,0]
	v_cvt_pk_bf16_f32 v2, v36, v37
	v_cvt_pk_bf16_f32 v3, v34, v35
	v_cvt_pk_bf16_f32 v4, v4, v5
	v_cvt_pk_bf16_f32 v5, v28, v29
	v_add_u32_e32 v31, s4, v170
	global_store_dwordx4 v[6:7], v[2:5], off offset:256
	ds_read_b128 v[2:5], v31
	v_lshlrev_b64 v[28:29], 12, v[32:33]
	s_waitcnt lgkmcnt(0)
	v_mov_b32_e32 v6, v3
	v_mov_b32_e32 v7, v4
	v_mov_b32_e32 v3, v5
	v_pk_add_f32 v[2:3], v[6:7], v[2:3]
	s_nop 0
	v_add_f32_e32 v2, v2, v3
	v_fmamk_f32 v2, v2, 0x3c000000, v243
	v_rsq_f32_e32 v2, v2
	s_nop 0
	v_mul_f32_e32 v30, 0x3dd53b94, v2
	global_load_dwordx4 v[2:5], v[18:19], off offset:16
	global_load_dwordx4 v[6:9], v[18:19], off
	s_waitcnt vmcnt(1)
	v_pk_mul_f32 v[4:5], v[24:25], v[4:5]
	s_waitcnt vmcnt(0)
	v_pk_mul_f32 v[6:7], v[22:23], v[6:7]
	v_pk_mul_f32 v[2:3], v[26:27], v[2:3]
	v_pk_mul_f32 v[6:7], v[6:7], v[30:31] op_sel_hi:[1,0]
	v_pk_mul_f32 v[8:9], v[20:21], v[8:9]
	v_pk_mul_f32 v[20:21], v[4:5], v[30:31] op_sel_hi:[1,0]
	v_pk_mul_f32 v[4:5], v[2:3], v[30:31] op_sel_hi:[1,0]
	v_cvt_pk_bf16_f32 v2, v6, v7
	v_lshl_add_u64 v[6:7], s[44:45], 0, v[28:29]
	v_pk_mul_f32 v[8:9], v[8:9], v[30:31] op_sel_hi:[1,0]
	v_lshl_add_u64 v[6:7], v[6:7], 0, s[68:69]
	v_cvt_pk_bf16_f32 v3, v8, v9
	v_cvt_pk_bf16_f32 v4, v4, v5
	v_cvt_pk_bf16_f32 v5, v20, v21
	v_lshl_add_u64 v[6:7], v[6:7], 0, v[38:39]
	global_store_dwordx4 v[6:7], v[2:5], off
	ds_read_b128 v[2:5], v31 offset:16
	s_waitcnt lgkmcnt(0)
	v_mov_b32_e32 v8, v3
	v_mov_b32_e32 v9, v4
	v_mov_b32_e32 v3, v5
	v_pk_add_f32 v[2:3], v[8:9], v[2:3]
	s_nop 0
	v_add_f32_e32 v2, v2, v3
	v_fmamk_f32 v2, v2, 0x3c000000, v243
	v_rsq_f32_e32 v2, v2
	s_nop 0
	v_mul_f32_e32 v8, 0x3dd53b94, v2
	global_load_dwordx4 v[2:5], v[18:19], off offset:16
	s_nop 0
	global_load_dwordx4 v[18:21], v[18:19], off
	s_waitcnt vmcnt(1)
	v_pk_mul_f32 v[4:5], v[10:11], v[4:5]
	s_waitcnt vmcnt(0)
	v_pk_mul_f32 v[14:15], v[14:15], v[20:21]
	v_pk_mul_f32 v[16:17], v[16:17], v[18:19]
	v_pk_mul_f32 v[2:3], v[12:13], v[2:3]
	v_pk_mul_f32 v[14:15], v[14:15], v[8:9] op_sel_hi:[1,0]
	v_pk_mul_f32 v[16:17], v[16:17], v[8:9] op_sel_hi:[1,0]
	v_pk_mul_f32 v[10:11], v[4:5], v[8:9] op_sel_hi:[1,0]
	v_pk_mul_f32 v[4:5], v[2:3], v[8:9] op_sel_hi:[1,0]
	v_cvt_pk_bf16_f32 v2, v16, v17
	v_cvt_pk_bf16_f32 v3, v14, v15
	v_cvt_pk_bf16_f32 v4, v4, v5
	v_cvt_pk_bf16_f32 v5, v10, v11
	global_store_dwordx4 v[6:7], v[2:5], off offset:256
	s_and_b64 vcc, exec, s[40:41]
	s_mov_b64 s[0:1], -1
	s_cbranch_vccnz .LBB0_228

.LBB0_304:
	s_or_b64 exec, exec, s[10:11]
	v_add_u32_e32 v150, 16, v160
	v_ashrrev_i32_e32 v151, 31, v150
	s_waitcnt lgkmcnt(0)
	v_lshl_add_u64 v[122:123], v[150:151], 4, s[0:1]
	global_load_dwordx4 v[122:125], v[122:123], off
	s_waitcnt vmcnt(0)
	v_mov_b32_e32 v126, v123
	v_mov_b32_e32 v127, v124
	v_mov_b32_e32 v123, v125
	v_pk_add_f32 v[122:123], v[126:127], v[122:123]
	s_nop 0
	v_add_f32_e32 v122, v122, v123
	v_fmamk_f32 v122, v122, 0x3b800000, v243
	v_rsq_f32_e32 v172, v122
	s_nop 0
	v_pk_mul_f32 v[152:153], v[120:121], v[172:173] op_sel_hi:[1,0]
	v_pk_mul_f32 v[154:155], v[118:119], v[172:173] op_sel_hi:[1,0]
	v_pk_mul_f32 v[156:157], v[116:117], v[172:173] op_sel_hi:[1,0]
	v_pk_mul_f32 v[158:159], v[114:115], v[172:173] op_sel_hi:[1,0]
	v_mul_f32_e32 v114, v155, v155
	v_mul_f32_e32 v115, v153, v153
	v_mul_f32_e32 v116, v159, v159
	v_mul_f32_e32 v117, v157, v157
	v_fmac_f32_e32 v114, v154, v154
	v_fmac_f32_e32 v115, v152, v152
	v_fmac_f32_e32 v116, v158, v158
	v_fmac_f32_e32 v117, v156, v156
	v_add_f32_e32 v114, v114, v115
	v_add_f32_e32 v115, v116, v117
	v_add_f32_e32 v114, v114, v115
	ds_bpermute_b32 v115, v143, v114
	s_waitcnt lgkmcnt(0)
	v_add_f32_e32 v114, v114, v115
	ds_bpermute_b32 v115, v171, v114
	s_and_saveexec_b64 s[10:11], s[42:43]
	s_cbranch_execz .LBB0_306
	v_lshl_add_u32 v116, v150, 4, s71
	s_waitcnt lgkmcnt(0)
	v_add_f32_e32 v114, v114, v115
	ds_write_b32 v116, v114
.LBB0_306:
	s_or_b64 exec, exec, s[10:11]
	v_add_u32_e32 v126, 32, v160
	v_ashrrev_i32_e32 v127, 31, v126
	s_waitcnt lgkmcnt(0)
	v_lshl_add_u64 v[114:115], v[126:127], 4, s[0:1]
	global_load_dwordx4 v[114:117], v[114:115], off
	s_waitcnt vmcnt(0)
	v_mov_b32_e32 v118, v115
	v_mov_b32_e32 v119, v116
	v_mov_b32_e32 v115, v117
	v_pk_add_f32 v[114:115], v[118:119], v[114:115]
	s_nop 0
	v_add_f32_e32 v114, v114, v115
	v_fmamk_f32 v114, v114, 0x3b800000, v243
	v_rsq_f32_e32 v114, v114
	s_nop 0
	v_pk_mul_f32 v[128:129], v[112:113], v[114:115] op_sel_hi:[1,0]
	v_pk_mul_f32 v[144:145], v[110:111], v[114:115] op_sel_hi:[1,0]
	v_pk_mul_f32 v[146:147], v[108:109], v[114:115] op_sel_hi:[1,0]
	v_pk_mul_f32 v[148:149], v[106:107], v[114:115] op_sel_hi:[1,0]
	v_mul_f32_e32 v106, v145, v145
	v_mul_f32_e32 v107, v129, v129
	v_mul_f32_e32 v108, v149, v149
	v_mul_f32_e32 v109, v147, v147
	v_fmac_f32_e32 v106, v144, v144
	v_fmac_f32_e32 v107, v128, v128
	v_fmac_f32_e32 v108, v148, v148
	v_fmac_f32_e32 v109, v146, v146
	v_add_f32_e32 v106, v106, v107
	v_add_f32_e32 v107, v108, v109
	v_add_f32_e32 v106, v106, v107
	ds_bpermute_b32 v107, v143, v106
	s_waitcnt lgkmcnt(0)
	v_add_f32_e32 v106, v106, v107
	ds_bpermute_b32 v107, v171, v106
	s_and_saveexec_b64 s[10:11], s[42:43]
	s_cbranch_execz .LBB0_308
	v_lshl_add_u32 v108, v126, 4, s71
	s_waitcnt lgkmcnt(0)
	v_add_f32_e32 v106, v106, v107
	ds_write_b32 v108, v106
.LBB0_308:
	s_or_b64 exec, exec, s[10:11]
	v_add_u32_e32 v116, 48, v160
	v_ashrrev_i32_e32 v117, 31, v116
	s_waitcnt lgkmcnt(0)
	v_lshl_add_u64 v[106:107], v[116:117], 4, s[0:1]
	global_load_dwordx4 v[106:109], v[106:107], off
	s_waitcnt vmcnt(0)
	v_mov_b32_e32 v110, v107
	v_mov_b32_e32 v111, v108
	v_mov_b32_e32 v107, v109
	v_pk_add_f32 v[106:107], v[110:111], v[106:107]
	s_nop 0
	v_add_f32_e32 v106, v106, v107
	v_fmamk_f32 v106, v106, 0x3b800000, v243
	v_rsq_f32_e32 v112, v106
	s_nop 0
	v_pk_mul_f32 v[118:119], v[104:105], v[112:113] op_sel_hi:[1,0]
	v_pk_mul_f32 v[120:121], v[102:103], v[112:113] op_sel_hi:[1,0]
	v_pk_mul_f32 v[122:123], v[100:101], v[112:113] op_sel_hi:[1,0]
	v_pk_mul_f32 v[124:125], v[98:99], v[112:113] op_sel_hi:[1,0]
	v_mul_f32_e32 v98, v121, v121
	v_mul_f32_e32 v99, v119, v119
	v_mul_f32_e32 v100, v125, v125
	v_mul_f32_e32 v101, v123, v123
	v_fmac_f32_e32 v98, v120, v120
	v_fmac_f32_e32 v99, v118, v118
	v_fmac_f32_e32 v100, v124, v124
	v_fmac_f32_e32 v101, v122, v122
	v_add_f32_e32 v98, v98, v99
	v_add_f32_e32 v99, v100, v101
	v_add_f32_e32 v98, v98, v99
	ds_bpermute_b32 v99, v143, v98
	s_waitcnt lgkmcnt(0)
	v_add_f32_e32 v98, v98, v99
	ds_bpermute_b32 v99, v171, v98
	s_and_saveexec_b64 s[10:11], s[42:43]
	s_cbranch_execz .LBB0_310
	v_lshl_add_u32 v100, v116, 4, s71
	s_waitcnt lgkmcnt(0)
	v_add_f32_e32 v98, v98, v99
	ds_write_b32 v100, v98
.LBB0_310:
	s_or_b64 exec, exec, s[10:11]
	v_add_u32_e32 v98, 0x80, v160
	s_waitcnt lgkmcnt(0)
	v_ashrrev_i32_e32 v99, 31, v98
	v_lshl_add_u64 v[100:101], v[98:99], 4, s[0:1]
	global_load_dwordx4 v[100:103], v[100:101], off
	s_waitcnt vmcnt(0)
	v_mov_b32_e32 v104, v101
	v_mov_b32_e32 v105, v102
	v_mov_b32_e32 v101, v103
	v_pk_add_f32 v[100:101], v[104:105], v[100:101]
	s_nop 0
	v_add_f32_e32 v100, v100, v101
	v_fmamk_f32 v100, v100, 0x3b800000, v243
	v_rsq_f32_e32 v174, v100
	s_nop 0
	v_pk_mul_f32 v[104:105], v[96:97], v[174:175] op_sel_hi:[1,0]
	v_pk_mul_f32 v[106:107], v[94:95], v[174:175] op_sel_hi:[1,0]
	v_pk_mul_f32 v[108:109], v[92:93], v[174:175] op_sel_hi:[1,0]
	v_pk_mul_f32 v[110:111], v[90:91], v[174:175] op_sel_hi:[1,0]
	v_mul_f32_e32 v90, v107, v107
	v_mul_f32_e32 v91, v105, v105
	v_mul_f32_e32 v92, v111, v111
	v_mul_f32_e32 v93, v109, v109
	v_fmac_f32_e32 v90, v106, v106
	v_fmac_f32_e32 v91, v104, v104
	v_fmac_f32_e32 v92, v110, v110
	v_fmac_f32_e32 v93, v108, v108
	v_add_f32_e32 v90, v90, v91
	v_add_f32_e32 v91, v92, v93
	v_add_f32_e32 v90, v90, v91
	ds_bpermute_b32 v91, v143, v90
	s_waitcnt lgkmcnt(0)
	v_add_f32_e32 v90, v90, v91
	ds_bpermute_b32 v91, v171, v90
	s_and_saveexec_b64 s[10:11], s[42:43]
	s_cbranch_execz .LBB0_312
	v_lshl_add_u32 v92, v98, 4, s71
	s_waitcnt lgkmcnt(0)
	v_add_f32_e32 v90, v90, v91
	ds_write_b32 v92, v90
.LBB0_312:
	s_or_b64 exec, exec, s[10:11]
	v_add_u32_e32 v90, 0x90, v160
	s_waitcnt lgkmcnt(0)
	v_ashrrev_i32_e32 v91, 31, v90
	v_lshl_add_u64 v[92:93], v[90:91], 4, s[0:1]
	global_load_dwordx4 v[92:95], v[92:93], off
	s_waitcnt vmcnt(0)
	v_mov_b32_e32 v96, v93
	v_mov_b32_e32 v97, v94
	v_mov_b32_e32 v93, v95
	v_pk_add_f32 v[92:93], v[96:97], v[92:93]
	s_nop 0
	v_add_f32_e32 v92, v92, v93
	v_fmamk_f32 v92, v92, 0x3b800000, v243
	v_rsq_f32_e32 v176, v92
	s_nop 0
	v_pk_mul_f32 v[94:95], v[88:89], v[176:177] op_sel_hi:[1,0]
	v_pk_mul_f32 v[96:97], v[86:87], v[176:177] op_sel_hi:[1,0]
	v_pk_mul_f32 v[100:101], v[84:85], v[176:177] op_sel_hi:[1,0]
	v_pk_mul_f32 v[102:103], v[82:83], v[176:177] op_sel_hi:[1,0]
	v_mul_f32_e32 v82, v97, v97
	v_mul_f32_e32 v83, v95, v95
	v_mul_f32_e32 v84, v103, v103
	v_mul_f32_e32 v85, v101, v101
	v_fmac_f32_e32 v82, v96, v96
	v_fmac_f32_e32 v83, v94, v94
	v_fmac_f32_e32 v84, v102, v102
	v_fmac_f32_e32 v85, v100, v100
	v_add_f32_e32 v82, v82, v83
	v_add_f32_e32 v83, v84, v85
	v_add_f32_e32 v82, v82, v83
	ds_bpermute_b32 v83, v143, v82
	s_waitcnt lgkmcnt(0)
	v_add_f32_e32 v82, v82, v83
	ds_bpermute_b32 v83, v171, v82
	s_and_saveexec_b64 s[10:11], s[42:43]
	s_cbranch_execz .LBB0_314
	v_lshl_add_u32 v84, v90, 4, s71
	s_waitcnt lgkmcnt(0)
	v_add_f32_e32 v82, v82, v83
	ds_write_b32 v84, v82
.LBB0_314:
	s_or_b64 exec, exec, s[10:11]
	v_add_u32_e32 v82, 0xa0, v160
	s_waitcnt lgkmcnt(0)
	v_ashrrev_i32_e32 v83, 31, v82
	v_lshl_add_u64 v[84:85], v[82:83], 4, s[0:1]
	global_load_dwordx4 v[84:87], v[84:85], off
	s_waitcnt vmcnt(0)
	v_mov_b32_e32 v88, v85
	v_mov_b32_e32 v89, v86
	v_mov_b32_e32 v85, v87
	v_pk_add_f32 v[84:85], v[88:89], v[84:85]
	s_nop 0
	v_add_f32_e32 v84, v84, v85
	v_fmamk_f32 v84, v84, 0x3b800000, v243
	v_rsq_f32_e32 v178, v84
	s_nop 0
	v_pk_mul_f32 v[84:85], v[80:81], v[178:179] op_sel_hi:[1,0]
	v_pk_mul_f32 v[86:87], v[78:79], v[178:179] op_sel_hi:[1,0]
	v_pk_mul_f32 v[88:89], v[76:77], v[178:179] op_sel_hi:[1,0]
	v_pk_mul_f32 v[92:93], v[74:75], v[178:179] op_sel_hi:[1,0]
	v_mul_f32_e32 v74, v87, v87
	v_mul_f32_e32 v75, v85, v85
	v_mul_f32_e32 v76, v93, v93
	v_mul_f32_e32 v77, v89, v89
	v_fmac_f32_e32 v74, v86, v86
	v_fmac_f32_e32 v75, v84, v84
	v_fmac_f32_e32 v76, v92, v92
	v_fmac_f32_e32 v77, v88, v88
	v_add_f32_e32 v74, v74, v75
	v_add_f32_e32 v75, v76, v77
	v_add_f32_e32 v74, v74, v75
	ds_bpermute_b32 v75, v143, v74
	s_waitcnt lgkmcnt(0)
	v_add_f32_e32 v74, v74, v75
	ds_bpermute_b32 v75, v171, v74
	s_and_saveexec_b64 s[10:11], s[42:43]
	s_cbranch_execz .LBB0_316
	v_lshl_add_u32 v76, v82, 4, s71
	s_waitcnt lgkmcnt(0)
	v_add_f32_e32 v74, v74, v75
	ds_write_b32 v76, v74
.LBB0_316:
	s_or_b64 exec, exec, s[10:11]
	v_add_u32_e32 v74, 0xb0, v160
	s_waitcnt lgkmcnt(0)
	v_ashrrev_i32_e32 v75, 31, v74
	v_lshl_add_u64 v[76:77], v[74:75], 4, s[0:1]
	global_load_dwordx4 v[76:79], v[76:77], off
	s_waitcnt vmcnt(0)
	v_mov_b32_e32 v80, v77
	v_mov_b32_e32 v81, v78
	v_mov_b32_e32 v77, v79
	v_pk_add_f32 v[76:77], v[80:81], v[76:77]
	s_nop 0
	v_add_f32_e32 v76, v76, v77
	v_fmamk_f32 v76, v76, 0x3b800000, v243
	v_rsq_f32_e32 v80, v76
	s_nop 0
	v_pk_mul_f32 v[72:73], v[72:73], v[80:81] op_sel_hi:[1,0]
	v_pk_mul_f32 v[70:71], v[70:71], v[80:81] op_sel_hi:[1,0]
	v_pk_mul_f32 v[76:77], v[68:69], v[80:81] op_sel_hi:[1,0]
	v_pk_mul_f32 v[78:79], v[66:67], v[80:81] op_sel_hi:[1,0]
	v_mul_f32_e32 v66, v71, v71
	v_mul_f32_e32 v67, v73, v73
	v_mul_f32_e32 v68, v79, v79
	v_mul_f32_e32 v69, v77, v77
	v_fmac_f32_e32 v66, v70, v70
	v_fmac_f32_e32 v67, v72, v72
	v_fmac_f32_e32 v68, v78, v78
	v_fmac_f32_e32 v69, v76, v76
	v_add_f32_e32 v66, v66, v67
	v_add_f32_e32 v67, v68, v69
	v_add_f32_e32 v66, v66, v67
	ds_bpermute_b32 v67, v143, v66
	v_lshlrev_b32_e32 v143, 4, v74
	s_waitcnt lgkmcnt(0)
	v_add_f32_e32 v66, v66, v67
	ds_bpermute_b32 v67, v171, v66
	s_and_saveexec_b64 s[0:1], s[42:43]
	s_cbranch_execz .LBB0_318
	v_add_u32_e32 v68, s71, v143
	s_waitcnt lgkmcnt(0)
	v_add_f32_e32 v66, v66, v67
	ds_write_b32 v68, v66
.LBB0_318:
	s_or_b64 exec, exec, s[0:1]
	v_mov_b32_e32 v66, v80
	s_waitcnt lgkmcnt(0)
	v_mov_b32_e32 v67, v80
	v_pk_mul_f32 v[64:65], v[64:65], v[66:67]
	v_pk_mul_f32 v[56:57], v[56:57], v[66:67]
	v_mov_b32_e32 v66, v178
	v_mov_b32_e32 v67, v178
	v_pk_mul_f32 v[60:61], v[60:61], v[66:67]
	v_pk_mul_f32 v[52:53], v[52:53], v[66:67]
	v_mov_b32_e32 v66, v176
	v_mov_b32_e32 v67, v176
	v_pk_mul_f32 v[48:49], v[48:49], v[66:67]
	v_pk_mul_f32 v[44:45], v[44:45], v[66:67]
	v_mov_b32_e32 v66, v174
	v_mov_b32_e32 v67, v174
	v_pk_mul_f32 v[40:41], v[40:41], v[66:67]
	v_pk_mul_f32 v[32:33], v[32:33], v[66:67]
	v_mov_b32_e32 v66, v112
	v_mov_b32_e32 v67, v112
	v_mov_b32_e32 v81, v80
	v_pk_mul_f32 v[36:37], v[36:37], v[66:67]
	v_pk_mul_f32 v[28:29], v[28:29], v[66:67]
	v_mov_b32_e32 v66, v114
	v_mov_b32_e32 v67, v114
	v_mov_b32_e32 v171, v170
	v_pk_mul_f32 v[62:63], v[62:63], v[80:81]
	v_pk_mul_f32 v[54:55], v[54:55], v[80:81]
	v_pk_mul_f32 v[24:25], v[24:25], v[66:67]
	v_pk_mul_f32 v[20:21], v[20:21], v[66:67]
	v_mov_b32_e32 v66, v172
	v_mov_b32_e32 v67, v172
	v_mov_b32_e32 v80, v170
	v_mov_b32_e32 v81, v170
	s_add_i32 s5, 0, 0x20000
	v_pk_mul_f32 v[16:17], v[16:17], v[66:67]
	v_pk_mul_f32 v[12:13], v[12:13], v[66:67]
	v_pk_mul_f32 v[66:67], v[8:9], v[80:81]
	v_pk_mul_f32 v[8:9], v[2:3], v[170:171]
	s_waitcnt lgkmcnt(0)
	s_barrier
	v_lshl_add_u32 v2, v160, 4, s5
	v_pk_mul_f32 v[68:69], v[6:7], v[170:171]
	v_pk_mul_f32 v[6:7], v[4:5], v[80:81]
	ds_read_b128 v[2:5], v2
	v_mov_b32_e32 v115, v114
	v_pk_mul_f32 v[22:23], v[22:23], v[114:115]
	v_pk_mul_f32 v[18:19], v[18:19], v[114:115]
	v_mov_b32_e32 v113, v112
	s_waitcnt lgkmcnt(0)
	v_mov_b32_e32 v114, v3
	v_mov_b32_e32 v115, v4
	v_mov_b32_e32 v3, v5
	v_pk_add_f32 v[2:3], v[114:115], v[2:3]
	v_lshlrev_b32_e32 v80, 3, v183
	v_add_f32_e32 v2, v2, v3
	v_fmamk_f32 v2, v2, 0x3c000000, v243
	v_cmp_gt_f32_e32 vcc, s37, v2
	v_mul_f32_e32 v3, 0x4f800000, v2
	v_pk_mul_f32 v[34:35], v[34:35], v[112:113]
	v_cndmask_b32_e32 v2, v2, v3, vcc
	v_sqrt_f32_e32 v3, v2
	v_pk_mul_f32 v[26:27], v[26:27], v[112:113]
	v_add_u32_e32 v112, s76, v80
	v_ashrrev_i32_e32 v113, 31, v112
	v_add_u32_e32 v4, -1, v3
	v_fma_f32 v5, -v4, v3, v2
	v_cmp_ge_f32_e64 s[42:43], 0, v5
	v_add_u32_e32 v5, 1, v3
	v_mov_b32_e32 v173, v172
	v_cndmask_b32_e64 v4, v3, v4, s[42:43]
	v_fma_f32 v3, -v5, v3, v2
	v_cmp_lt_f32_e64 s[42:43], 0, v3
	v_mov_b32_e32 v175, v174
	v_pk_mul_f32 v[38:39], v[38:39], v[174:175]
	v_cndmask_b32_e64 v3, v4, v5, s[42:43]
	v_mul_f32_e32 v4, 0x37800000, v3
	v_cndmask_b32_e32 v3, v3, v4, vcc
	v_cmp_class_f32_e32 vcc, v2, v241
	v_pk_mul_f32 v[30:31], v[30:31], v[174:175]
	v_pk_mul_f32 v[14:15], v[14:15], v[172:173]
	v_cndmask_b32_e32 v2, v3, v2, vcc
	v_div_scale_f32 v3, s[6:7], v2, v2, 1.0
	v_rcp_f32_e32 v4, v3
	v_pk_mul_f32 v[10:11], v[10:11], v[172:173]
	s_lshl_b32 s10, s4, 7
	s_lshl_b64 s[0:1], s[64:65], 20
	v_fma_f32 v5, -v3, v4, 1.0
	v_fmac_f32_e32 v4, v5, v4
	v_div_scale_f32 v5, vcc, 1.0, v2, 1.0
	v_mul_f32_e32 v81, v5, v4
	v_fma_f32 v114, -v3, v81, v5
	v_fmac_f32_e32 v81, v114, v4
	v_fma_f32 v3, -v3, v81, v5
	v_div_fmas_f32 v3, v3, v4, v81
	v_lshl_add_u64 v[114:115], v[112:113], 2, s[46:47]
	v_div_fixup_f32 v174, v3, v2, 1.0
	global_load_dwordx4 v[2:5], v[114:115], off offset:16
	global_load_dwordx4 v[170:173], v[114:115], off
	s_ashr_i32 s11, s10, 31
	v_readlane_b32 s6, v251, 43
	v_readlane_b32 s7, v251, 44
	s_add_u32 s0, s6, s0
	s_addc_u32 s1, s7, s1
	v_lshlrev_b64 v[160:161], 12, v[160:161]
	v_lshl_add_u64 v[160:161], s[0:1], 0, v[160:161]
	s_lshl_b64 s[10:11], s[10:11], 1
	v_lshl_add_u64 v[160:161], v[160:161], 0, s[10:11]
	v_lshlrev_b64 v[112:113], 1, v[112:113]
	v_lshl_add_u64 v[160:161], v[160:161], 0, v[112:113]
	v_cvt_pk_bf16_f32 v8, v8, v9
	v_cvt_pk_bf16_f32 v14, v14, v15
	v_cvt_pk_bf16_f32 v10, v10, v11
	v_cvt_pk_bf16_f32 v15, v16, v17
	v_cvt_pk_bf16_f32 v11, v12, v13
	v_mov_b32_e32 v177, v176
	v_pk_mul_f32 v[46:47], v[46:47], v[176:177]
	v_mov_b32_e32 v179, v178
	v_pk_mul_f32 v[42:43], v[42:43], v[176:177]
	v_pk_mul_f32 v[58:59], v[58:59], v[178:179]
	v_pk_mul_f32 v[50:51], v[50:51], v[178:179]
	s_waitcnt vmcnt(1)
	v_pk_mul_f32 v[4:5], v[166:167], v[4:5]
	s_waitcnt vmcnt(0)
	v_pk_mul_f32 v[162:163], v[162:163], v[172:173]
	v_pk_mul_f32 v[164:165], v[164:165], v[170:171]
	v_pk_mul_f32 v[2:3], v[168:169], v[2:3]
	v_pk_mul_f32 v[162:163], v[162:163], v[174:175] op_sel_hi:[1,0]
	v_pk_mul_f32 v[164:165], v[164:165], v[174:175] op_sel_hi:[1,0]
	v_pk_mul_f32 v[166:167], v[4:5], v[174:175] op_sel_hi:[1,0]
	v_pk_mul_f32 v[4:5], v[2:3], v[174:175] op_sel_hi:[1,0]
	v_cvt_pk_bf16_f32 v2, v164, v165
	v_cvt_pk_bf16_f32 v3, v162, v163
	v_cvt_pk_bf16_f32 v4, v4, v5
	v_cvt_pk_bf16_f32 v5, v166, v167
	global_store_dwordx4 v[160:161], v[2:5], off
	s_nop 1
	v_lshl_add_u32 v2, v150, 4, s5
	ds_read_b128 v[2:5], v2
	v_lshlrev_b64 v[150:151], 12, v[150:151]
	v_lshl_add_u64 v[150:151], s[0:1], 0, v[150:151]
	v_lshl_add_u64 v[150:151], v[150:151], 0, s[10:11]
	v_lshl_add_u64 v[150:151], v[150:151], 0, v[112:113]
	s_waitcnt lgkmcnt(0)
	v_mov_b32_e32 v160, v3
	v_mov_b32_e32 v161, v4
	v_mov_b32_e32 v3, v5
	v_pk_add_f32 v[2:3], v[160:161], v[2:3]
	s_nop 0
	v_add_f32_e32 v2, v2, v3
	v_fmamk_f32 v2, v2, 0x3c000000, v243
	v_rsq_f32_e32 v164, v2
	s_nop 0
	global_load_dwordx4 v[2:5], v[114:115], off offset:16
	global_load_dwordx4 v[160:163], v[114:115], off
	s_waitcnt vmcnt(1)
	v_pk_mul_f32 v[4:5], v[156:157], v[4:5]
	s_waitcnt vmcnt(0)
	v_pk_mul_f32 v[152:153], v[152:153], v[162:163]
	v_pk_mul_f32 v[154:155], v[154:155], v[160:161]
	v_pk_mul_f32 v[2:3], v[158:159], v[2:3]
	v_pk_mul_f32 v[152:153], v[152:153], v[164:165] op_sel_hi:[1,0]
	v_pk_mul_f32 v[154:155], v[154:155], v[164:165] op_sel_hi:[1,0]
	v_pk_mul_f32 v[156:157], v[4:5], v[164:165] op_sel_hi:[1,0]
	v_pk_mul_f32 v[4:5], v[2:3], v[164:165] op_sel_hi:[1,0]
	v_cvt_pk_bf16_f32 v2, v154, v155
	v_cvt_pk_bf16_f32 v3, v152, v153
	v_cvt_pk_bf16_f32 v4, v4, v5
	v_cvt_pk_bf16_f32 v5, v156, v157
	global_store_dwordx4 v[150:151], v[2:5], off
	s_nop 1
	v_lshl_add_u32 v2, v126, 4, s5
	ds_read_b128 v[2:5], v2
	v_lshlrev_b64 v[126:127], 12, v[126:127]
	v_lshl_add_u64 v[126:127], s[0:1], 0, v[126:127]
	v_lshl_add_u64 v[126:127], v[126:127], 0, s[10:11]
	v_lshl_add_u64 v[126:127], v[126:127], 0, v[112:113]
	s_waitcnt lgkmcnt(0)
	v_mov_b32_e32 v150, v3
	v_mov_b32_e32 v151, v4
	v_mov_b32_e32 v3, v5
	v_pk_add_f32 v[2:3], v[150:151], v[2:3]
	s_nop 0
	v_add_f32_e32 v2, v2, v3
	v_fmamk_f32 v2, v2, 0x3c000000, v243
	v_rsq_f32_e32 v150, v2
	s_nop 0
	global_load_dwordx4 v[2:5], v[114:115], off offset:16
	global_load_dwordx4 v[152:155], v[114:115], off
	s_waitcnt vmcnt(1)
	v_pk_mul_f32 v[4:5], v[146:147], v[4:5]
	s_waitcnt vmcnt(0)
	v_pk_mul_f32 v[128:129], v[128:129], v[154:155]
	v_pk_mul_f32 v[144:145], v[144:145], v[152:153]
	v_pk_mul_f32 v[2:3], v[148:149], v[2:3]
	v_pk_mul_f32 v[128:129], v[128:129], v[150:151] op_sel_hi:[1,0]
	v_pk_mul_f32 v[144:145], v[144:145], v[150:151] op_sel_hi:[1,0]
	v_pk_mul_f32 v[146:147], v[4:5], v[150:151] op_sel_hi:[1,0]
	v_pk_mul_f32 v[4:5], v[2:3], v[150:151] op_sel_hi:[1,0]
	v_cvt_pk_bf16_f32 v2, v144, v145
	v_cvt_pk_bf16_f32 v3, v128, v129
	v_cvt_pk_bf16_f32 v4, v4, v5
	v_cvt_pk_bf16_f32 v5, v146, v147
	global_store_dwordx4 v[126:127], v[2:5], off
	s_nop 1
	v_lshl_add_u32 v2, v116, 4, s5
	ds_read_b128 v[2:5], v2
	v_lshlrev_b64 v[116:117], 12, v[116:117]
	v_lshl_add_u64 v[116:117], s[0:1], 0, v[116:117]
	v_lshl_add_u64 v[116:117], v[116:117], 0, s[10:11]
	v_lshl_add_u64 v[116:117], v[116:117], 0, v[112:113]
	s_waitcnt lgkmcnt(0)
	v_mov_b32_e32 v126, v3
	v_mov_b32_e32 v127, v4
	v_mov_b32_e32 v3, v5
	v_pk_add_f32 v[2:3], v[126:127], v[2:3]
	s_nop 0
	v_add_f32_e32 v2, v2, v3
	v_fmamk_f32 v2, v2, 0x3c000000, v243
	v_rsq_f32_e32 v144, v2
	s_nop 0
	global_load_dwordx4 v[2:5], v[114:115], off offset:16
	global_load_dwordx4 v[126:129], v[114:115], off
	s_waitcnt vmcnt(1)
	v_pk_mul_f32 v[4:5], v[122:123], v[4:5]
	s_waitcnt vmcnt(0)
	v_pk_mul_f32 v[118:119], v[118:119], v[128:129]
	v_pk_mul_f32 v[120:121], v[120:121], v[126:127]
	v_pk_mul_f32 v[2:3], v[124:125], v[2:3]
	v_pk_mul_f32 v[118:119], v[118:119], v[144:145] op_sel_hi:[1,0]
	v_pk_mul_f32 v[120:121], v[120:121], v[144:145] op_sel_hi:[1,0]
	v_pk_mul_f32 v[122:123], v[4:5], v[144:145] op_sel_hi:[1,0]
	v_pk_mul_f32 v[4:5], v[2:3], v[144:145] op_sel_hi:[1,0]
	v_cvt_pk_bf16_f32 v2, v120, v121
	v_cvt_pk_bf16_f32 v3, v118, v119
	v_cvt_pk_bf16_f32 v4, v4, v5
	v_cvt_pk_bf16_f32 v5, v122, v123
	global_store_dwordx4 v[116:117], v[2:5], off
	s_nop 1
	v_lshl_add_u32 v2, v98, 4, s5
	ds_read_b128 v[2:5], v2
	v_lshlrev_b64 v[98:99], 12, v[98:99]
	v_lshl_add_u64 v[98:99], s[0:1], 0, v[98:99]
	v_lshl_add_u64 v[98:99], v[98:99], 0, s[10:11]
	v_lshl_add_u64 v[98:99], v[98:99], 0, v[112:113]
	s_waitcnt lgkmcnt(0)
	v_mov_b32_e32 v116, v3
	v_mov_b32_e32 v117, v4
	v_mov_b32_e32 v3, v5
	v_pk_add_f32 v[2:3], v[116:117], v[2:3]
	s_nop 0
	v_add_f32_e32 v2, v2, v3
	v_fmamk_f32 v2, v2, 0x3c000000, v243
	v_rsq_f32_e32 v116, v2
	s_nop 0
	global_load_dwordx4 v[2:5], v[114:115], off offset:16
	global_load_dwordx4 v[118:121], v[114:115], off
	s_waitcnt vmcnt(1)
	v_pk_mul_f32 v[4:5], v[108:109], v[4:5]
	s_waitcnt vmcnt(0)
	v_pk_mul_f32 v[104:105], v[104:105], v[120:121]
	v_pk_mul_f32 v[106:107], v[106:107], v[118:119]
	v_pk_mul_f32 v[2:3], v[110:111], v[2:3]
	v_pk_mul_f32 v[104:105], v[104:105], v[116:117] op_sel_hi:[1,0]
	v_pk_mul_f32 v[106:107], v[106:107], v[116:117] op_sel_hi:[1,0]
	v_pk_mul_f32 v[108:109], v[4:5], v[116:117] op_sel_hi:[1,0]
	v_pk_mul_f32 v[4:5], v[2:3], v[116:117] op_sel_hi:[1,0]
	v_cvt_pk_bf16_f32 v2, v106, v107
	v_cvt_pk_bf16_f32 v3, v104, v105
	v_cvt_pk_bf16_f32 v4, v4, v5
	v_cvt_pk_bf16_f32 v5, v108, v109
	global_store_dwordx4 v[98:99], v[2:5], off
	s_nop 1
	v_lshl_add_u32 v2, v90, 4, s5
	ds_read_b128 v[2:5], v2
	v_lshlrev_b64 v[90:91], 12, v[90:91]
	v_lshl_add_u64 v[90:91], s[0:1], 0, v[90:91]
	v_lshl_add_u64 v[90:91], v[90:91], 0, s[10:11]
	v_lshl_add_u64 v[90:91], v[90:91], 0, v[112:113]
	s_waitcnt lgkmcnt(0)
	v_mov_b32_e32 v98, v3
	v_mov_b32_e32 v99, v4
	v_mov_b32_e32 v3, v5
	v_pk_add_f32 v[2:3], v[98:99], v[2:3]
	s_nop 0
	v_add_f32_e32 v2, v2, v3
	v_fmamk_f32 v2, v2, 0x3c000000, v243
	v_rsq_f32_e32 v98, v2
	s_nop 0
	global_load_dwordx4 v[2:5], v[114:115], off offset:16
	global_load_dwordx4 v[104:107], v[114:115], off
	s_waitcnt vmcnt(1)
	v_pk_mul_f32 v[4:5], v[100:101], v[4:5]
	s_waitcnt vmcnt(0)
	v_pk_mul_f32 v[94:95], v[94:95], v[106:107]
	v_pk_mul_f32 v[96:97], v[96:97], v[104:105]
	v_pk_mul_f32 v[2:3], v[102:103], v[2:3]
	v_pk_mul_f32 v[94:95], v[94:95], v[98:99] op_sel_hi:[1,0]
	v_pk_mul_f32 v[96:97], v[96:97], v[98:99] op_sel_hi:[1,0]
	v_pk_mul_f32 v[100:101], v[4:5], v[98:99] op_sel_hi:[1,0]
	v_pk_mul_f32 v[4:5], v[2:3], v[98:99] op_sel_hi:[1,0]
	v_cvt_pk_bf16_f32 v2, v96, v97
	v_cvt_pk_bf16_f32 v3, v94, v95
	v_cvt_pk_bf16_f32 v4, v4, v5
	v_cvt_pk_bf16_f32 v5, v100, v101
	global_store_dwordx4 v[90:91], v[2:5], off
	s_nop 1
	v_lshl_add_u32 v2, v82, 4, s5
	ds_read_b128 v[2:5], v2
	v_lshlrev_b64 v[82:83], 12, v[82:83]
	v_lshl_add_u64 v[82:83], s[0:1], 0, v[82:83]
	v_lshl_add_u64 v[82:83], v[82:83], 0, s[10:11]
	v_lshl_add_u64 v[82:83], v[82:83], 0, v[112:113]
	s_waitcnt lgkmcnt(0)
	v_mov_b32_e32 v90, v3
	v_mov_b32_e32 v91, v4
	v_mov_b32_e32 v3, v5
	v_pk_add_f32 v[2:3], v[90:91], v[2:3]
	s_nop 0
	v_add_f32_e32 v2, v2, v3
	v_fmamk_f32 v2, v2, 0x3c000000, v243
	v_rsq_f32_e32 v90, v2
	s_nop 0
	global_load_dwordx4 v[2:5], v[114:115], off offset:16
	global_load_dwordx4 v[94:97], v[114:115], off
	s_waitcnt vmcnt(1)
	v_pk_mul_f32 v[4:5], v[88:89], v[4:5]
	s_waitcnt vmcnt(0)
	v_pk_mul_f32 v[84:85], v[84:85], v[96:97]
	v_pk_mul_f32 v[86:87], v[86:87], v[94:95]
	v_pk_mul_f32 v[2:3], v[92:93], v[2:3]
	v_pk_mul_f32 v[84:85], v[84:85], v[90:91] op_sel_hi:[1,0]
	v_pk_mul_f32 v[86:87], v[86:87], v[90:91] op_sel_hi:[1,0]
	v_pk_mul_f32 v[88:89], v[4:5], v[90:91] op_sel_hi:[1,0]
	v_pk_mul_f32 v[4:5], v[2:3], v[90:91] op_sel_hi:[1,0]
	v_cvt_pk_bf16_f32 v2, v86, v87
	v_cvt_pk_bf16_f32 v3, v84, v85
	v_cvt_pk_bf16_f32 v4, v4, v5
	v_cvt_pk_bf16_f32 v5, v88, v89
	global_store_dwordx4 v[82:83], v[2:5], off
	s_nop 1
	v_add_u32_e32 v2, s5, v143
	ds_read_b128 v[2:5], v2
	v_ashrrev_i32_e32 v143, 31, v142
	s_waitcnt lgkmcnt(0)
	v_mov_b32_e32 v82, v3
	v_mov_b32_e32 v83, v4
	v_mov_b32_e32 v3, v5
	v_pk_add_f32 v[2:3], v[82:83], v[2:3]
	s_nop 0
	v_add_f32_e32 v2, v2, v3
	v_fmamk_f32 v2, v2, 0x3c000000, v243
	v_rsq_f32_e32 v86, v2
	s_nop 0
	global_load_dwordx4 v[2:5], v[114:115], off offset:16
	global_load_dwordx4 v[82:85], v[114:115], off
	v_ashrrev_i32_e32 v81, 31, v80
	s_waitcnt vmcnt(1)
	v_pk_mul_f32 v[4:5], v[76:77], v[4:5]
	s_waitcnt vmcnt(0)
	v_pk_mul_f32 v[70:71], v[70:71], v[82:83]
	v_pk_mul_f32 v[2:3], v[78:79], v[2:3]
	v_pk_mul_f32 v[70:71], v[70:71], v[86:87] op_sel_hi:[1,0]
	v_pk_mul_f32 v[76:77], v[4:5], v[86:87] op_sel_hi:[1,0]
	v_pk_mul_f32 v[4:5], v[2:3], v[86:87] op_sel_hi:[1,0]
	v_cvt_pk_bf16_f32 v2, v70, v71
	v_lshlrev_b64 v[70:71], 12, v[74:75]
	v_pk_mul_f32 v[72:73], v[72:73], v[84:85]
	v_lshl_add_u64 v[70:71], s[0:1], 0, v[70:71]
	s_lshl_b64 s[0:1], s[64:65], 8
	v_pk_mul_f32 v[72:73], v[72:73], v[86:87] op_sel_hi:[1,0]
	v_lshl_add_u64 v[70:71], v[70:71], 0, s[10:11]
	s_add_u32 s0, s0, s68
	v_cvt_pk_bf16_f32 v3, v72, v73
	v_cvt_pk_bf16_f32 v4, v4, v5
	v_cvt_pk_bf16_f32 v5, v76, v77
	v_lshl_add_u64 v[70:71], v[70:71], 0, v[112:113]
	s_addc_u32 s1, s1, s70
	global_store_dwordx4 v[70:71], v[2:5], off
	v_lshl_add_u64 v[70:71], v[80:81], 0, s[76:77]
	v_lshlrev_b64 v[70:71], 13, v[70:71]
	v_lshl_add_u64 v[2:3], s[0:1], 0, v[142:143]
	v_alignbit_b32 v3, v3, v2, 8
	v_and_b32_e32 v3, -16, v3
	v_add_u32_e32 v4, s4, v3
	v_ashrrev_i32_e32 v5, 31, v4
	v_readlane_b32 s0, v251, 51
	v_lshlrev_b64 v[4:5], 20, v[4:5]
	v_readlane_b32 s1, v251, 52
	v_and_b32_e32 v72, 0xff0, v2
	v_and_b32_e32 v73, 3, v142
	v_lshl_add_u64 v[4:5], s[0:1], 0, v[4:5]
	v_lshl_add_u64 v[4:5], v[4:5], 0, v[70:71]
	v_lshlrev_b32_e32 v70, 1, v72
	v_mov_b32_e32 v71, v0
	v_lshl_add_u64 v[4:5], v[4:5], 0, v[70:71]
	v_and_b32_e32 v70, 8, v142
	v_lshl_add_u64 v[4:5], v[4:5], 0, v[70:71]
	v_lshlrev_b32_e32 v70, 1, v73
	v_lshlrev_b32_e32 v2, 2, v2
	v_lshl_add_u64 v[4:5], v[4:5], 0, v[70:71]
	v_and_b32_e32 v2, 16, v2
	v_mov_b32_e32 v3, v0
	v_lshl_add_u64 v[70:71], v[4:5], 0, v[2:3]
	s_movk_i32 s0, 0x2000
	v_cvt_pk_bf16_f32 v3, v66, v67
	v_add_co_u32_e32 v66, vcc, s0, v70
	s_movk_i32 s0, 0x4000
	s_nop 0
	v_addc_co_u32_e32 v67, vcc, 0, v71, vcc
	v_cvt_pk_bf16_f32 v2, v68, v69
	v_add_co_u32_e32 v68, vcc, s0, v70
	s_movk_i32 s0, 0x6000
	s_nop 0
	v_addc_co_u32_e32 v69, vcc, 0, v71, vcc
	v_add_co_u32_e32 v72, vcc, s0, v70
	s_mov_b32 s0, 0x8000
	s_nop 0
	v_addc_co_u32_e32 v73, vcc, 0, v71, vcc
	global_store_short v[70:71], v2, off
	global_store_short_d16_hi v[66:67], v2, off
	v_add_co_u32_e32 v2, vcc, s0, v70
	global_store_short v[68:69], v3, off
	global_store_short_d16_hi v[72:73], v3, off
	v_addc_co_u32_e32 v3, vcc, 0, v71, vcc
	s_mov_b32 s0, 0xa000
	v_add_co_u32_e32 v4, vcc, s0, v70
	s_mov_b32 s0, 0xc000
	s_nop 0
	v_addc_co_u32_e32 v5, vcc, 0, v71, vcc
	v_cvt_pk_bf16_f32 v74, v6, v7
	v_add_co_u32_e32 v6, vcc, s0, v70
	s_mov_b32 s0, 0xe000
	s_nop 0
	v_addc_co_u32_e32 v7, vcc, 0, v71, vcc
	global_store_short v[2:3], v8, off
	global_store_short_d16_hi v[4:5], v8, off
	v_add_co_u32_e32 v8, vcc, s0, v70
	global_store_short v[6:7], v74, off
	s_nop 0
	v_addc_co_u32_e32 v9, vcc, 0, v71, vcc
	global_store_short_d16_hi v[8:9], v74, off
	global_store_short v[70:71], v14, off offset:32
	global_store_short_d16_hi v[66:67], v14, off offset:32
	global_store_short v[68:69], v15, off offset:32
	global_store_short_d16_hi v[72:73], v15, off offset:32
	global_store_short v[2:3], v10, off offset:32
	global_store_short_d16_hi v[4:5], v10, off offset:32
	global_store_short v[6:7], v11, off offset:32
	global_store_short_d16_hi v[8:9], v11, off offset:32
	v_cvt_pk_bf16_f32 v10, v22, v23
	v_cvt_pk_bf16_f32 v11, v24, v25
	global_store_short v[70:71], v10, off offset:64
	global_store_short_d16_hi v[66:67], v10, off offset:64
	global_store_short v[68:69], v11, off offset:64
	global_store_short_d16_hi v[72:73], v11, off offset:64
	v_cvt_pk_bf16_f32 v10, v18, v19
	v_cvt_pk_bf16_f32 v11, v20, v21
	global_store_short v[2:3], v10, off offset:64
	global_store_short_d16_hi v[4:5], v10, off offset:64
	global_store_short v[6:7], v11, off offset:64
	global_store_short_d16_hi v[8:9], v11, off offset:64
	v_cvt_pk_bf16_f32 v10, v34, v35
	v_cvt_pk_bf16_f32 v11, v36, v37
	global_store_short v[70:71], v10, off offset:96
	global_store_short_d16_hi v[66:67], v10, off offset:96
	global_store_short v[68:69], v11, off offset:96
	global_store_short_d16_hi v[72:73], v11, off offset:96
	v_cvt_pk_bf16_f32 v10, v26, v27
	v_cvt_pk_bf16_f32 v11, v28, v29
	global_store_short v[2:3], v10, off offset:96
	global_store_short_d16_hi v[4:5], v10, off offset:96
	global_store_short v[6:7], v11, off offset:96
	global_store_short_d16_hi v[8:9], v11, off offset:96
	v_cvt_pk_bf16_f32 v10, v38, v39
	v_cvt_pk_bf16_f32 v11, v40, v41
	global_store_short v[70:71], v10, off offset:256
	global_store_short_d16_hi v[66:67], v10, off offset:256
	global_store_short v[68:69], v11, off offset:256
	global_store_short_d16_hi v[72:73], v11, off offset:256
	v_cvt_pk_bf16_f32 v10, v30, v31
	v_cvt_pk_bf16_f32 v11, v32, v33
	global_store_short v[2:3], v10, off offset:256
	global_store_short_d16_hi v[4:5], v10, off offset:256
	global_store_short v[6:7], v11, off offset:256
	global_store_short_d16_hi v[8:9], v11, off offset:256
	v_cvt_pk_bf16_f32 v10, v46, v47
	v_cvt_pk_bf16_f32 v11, v48, v49
	global_store_short v[70:71], v10, off offset:288
	global_store_short_d16_hi v[66:67], v10, off offset:288
	global_store_short v[68:69], v11, off offset:288
	global_store_short_d16_hi v[72:73], v11, off offset:288
	v_cvt_pk_bf16_f32 v10, v42, v43
	v_cvt_pk_bf16_f32 v11, v44, v45
	global_store_short v[2:3], v10, off offset:288
	global_store_short_d16_hi v[4:5], v10, off offset:288
	global_store_short v[6:7], v11, off offset:288
	global_store_short_d16_hi v[8:9], v11, off offset:288
	v_cvt_pk_bf16_f32 v10, v58, v59
	v_cvt_pk_bf16_f32 v11, v60, v61
	global_store_short v[70:71], v10, off offset:320
	global_store_short_d16_hi v[66:67], v10, off offset:320
	global_store_short v[68:69], v11, off offset:320
	global_store_short_d16_hi v[72:73], v11, off offset:320
	v_cvt_pk_bf16_f32 v10, v50, v51
	v_cvt_pk_bf16_f32 v11, v52, v53
	global_store_short v[2:3], v10, off offset:320
	global_store_short_d16_hi v[4:5], v10, off offset:320
	global_store_short v[6:7], v11, off offset:320
	global_store_short_d16_hi v[8:9], v11, off offset:320
	v_cvt_pk_bf16_f32 v10, v62, v63
	v_cvt_pk_bf16_f32 v11, v64, v65
	global_store_short v[70:71], v10, off offset:352
	global_store_short_d16_hi v[66:67], v10, off offset:352
	global_store_short v[68:69], v11, off offset:352
	global_store_short_d16_hi v[72:73], v11, off offset:352
	v_cvt_pk_bf16_f32 v10, v54, v55
	s_mov_b64 s[0:1], -1
	s_and_b64 vcc, exec, s[40:41]
	v_cvt_pk_bf16_f32 v11, v56, v57
	global_store_short v[2:3], v10, off offset:352
	global_store_short_d16_hi v[4:5], v10, off offset:352
	global_store_short v[6:7], v11, off offset:352
	global_store_short_d16_hi v[8:9], v11, off offset:352
	s_cbranch_vccnz .LBB0_286
	s_andn2_b64 vcc, exec, s[54:55]
	s_cbranch_vccnz .LBB0_285
	s_barrier
	s_branch .LBB0_285

.LBB0_526:
	s_waitcnt vmcnt(0)
	v_mov_b32_e32 v154, v1
	v_mov_b32_e32 v146, v171
	s_ashr_i32 s1, s0, 31
	s_lshl_b64 s[0:1], s[0:1], 8
	v_lshlrev_b32_e32 v142, 2, v146
	v_readlane_b32 s8, v251, 0
	s_add_u32 s0, s0, s74
	v_ashrrev_i32_e32 v143, 31, v142
	v_readlane_b32 s10, v251, 2
	v_readlane_b32 s11, v251, 3
	s_addc_u32 s1, s1, s79
	v_ashrrev_i32_e32 v155, 31, v154
	v_lshl_add_u64 v[144:145], v[142:143], 2, s[10:11]
	v_lshlrev_b32_e32 v142, 2, v154
	v_lshl_add_u64 v[168:169], s[0:1], 0, v[154:155]
	v_lshl_add_u32 v142, v146, 6, v142
	v_xor_b32_e32 v185, 64, v142
	v_xor_b32_e32 v184, 0x80, v142
	v_lshlrev_b64 v[142:143], 6, v[168:169]
	v_lshl_add_u64 v[142:143], v[144:145], 0, v[142:143]
	global_load_dwordx4 v[148:151], v[142:143], off
	v_lshl_add_u64 v[166:167], v[168:169], 0, 16
	v_lshl_add_u64 v[164:165], v[168:169], 0, 32
	v_lshl_add_u64 v[162:163], v[168:169], 0, 48
	v_lshl_add_u64 v[160:161], v[168:169], 0, s[28:29]
	s_mov_b64 s[10:11], -1
	v_and_b32_e32 v188, 3, v154
	v_and_b32_e32 v154, 8, v154
	v_readlane_b32 s9, v251, 1
	s_waitcnt vmcnt(0)
	v_add_f32_e32 v142, v148, v149
	v_add_f32_e32 v143, v150, v151
	v_add_f32_e32 v142, v142, v143
	ds_bpermute_b32 v143, v185, v142
	s_waitcnt lgkmcnt(0)
	v_add_f32_e32 v142, v142, v143
	ds_bpermute_b32 v143, v184, v142
	s_waitcnt lgkmcnt(0)
	v_add_f32_e32 v142, v142, v143
	v_fmamk_f32 v142, v142, 0x3a800000, v243
	s_nop 1
	s_mov_b64 s[0:1], 0x90
	v_lshl_add_u64 v[158:159], v[168:169], 0, s[0:1]
	s_mov_b64 s[0:1], 0xa0
	v_rsq_f32_e32 v170, v142
	s_nop 0
	v_lshlrev_b64 v[142:143], 6, v[166:167]
	v_lshl_add_u64 v[142:143], v[144:145], 0, v[142:143]
	global_load_dwordx4 v[148:151], v[142:143], off
	v_lshl_add_u64 v[156:157], v[168:169], 0, s[0:1]
	s_mov_b64 s[0:1], 0xb0
	s_waitcnt vmcnt(0)
	v_add_f32_e32 v142, v148, v149
	v_add_f32_e32 v143, v150, v151
	v_add_f32_e32 v142, v142, v143
	ds_bpermute_b32 v143, v185, v142
	s_waitcnt lgkmcnt(0)
	v_add_f32_e32 v199, v142, v143
	v_lshlrev_b64 v[142:143], 6, v[164:165]
	v_lshl_add_u64 v[142:143], v[144:145], 0, v[142:143]
	global_load_dwordx4 v[148:151], v[142:143], off
	ds_bpermute_b32 v200, v184, v199
	s_waitcnt vmcnt(0)
	v_add_f32_e32 v142, v148, v149
	v_add_f32_e32 v143, v150, v151
	v_add_f32_e32 v142, v142, v143
	ds_bpermute_b32 v143, v185, v142
	s_waitcnt lgkmcnt(0)
	v_add_f32_e32 v197, v142, v143
	v_lshlrev_b64 v[142:143], 6, v[162:163]
	v_lshl_add_u64 v[142:143], v[144:145], 0, v[142:143]
	global_load_dwordx4 v[148:151], v[142:143], off
	ds_bpermute_b32 v198, v184, v197
	s_waitcnt vmcnt(0)
	v_add_f32_e32 v142, v148, v149
	v_add_f32_e32 v143, v150, v151
	v_add_f32_e32 v142, v142, v143
	ds_bpermute_b32 v143, v185, v142
	s_waitcnt lgkmcnt(0)
	v_add_f32_e32 v195, v142, v143
	v_lshlrev_b64 v[142:143], 6, v[160:161]
	v_lshl_add_u64 v[142:143], v[144:145], 0, v[142:143]
	global_load_dwordx4 v[148:151], v[142:143], off
	ds_bpermute_b32 v196, v184, v195
	s_waitcnt vmcnt(0)
	v_add_f32_e32 v142, v148, v149
	v_add_f32_e32 v143, v150, v151
	v_add_f32_e32 v142, v142, v143
	ds_bpermute_b32 v143, v185, v142
	s_waitcnt lgkmcnt(0)
	v_add_f32_e32 v193, v142, v143
	v_lshlrev_b64 v[142:143], 6, v[158:159]
	v_lshl_add_u64 v[142:143], v[144:145], 0, v[142:143]
	global_load_dwordx4 v[148:151], v[142:143], off
	ds_bpermute_b32 v194, v184, v193
	s_waitcnt vmcnt(0)
	v_add_f32_e32 v142, v148, v149
	v_add_f32_e32 v143, v150, v151
	v_add_f32_e32 v142, v142, v143
	ds_bpermute_b32 v143, v185, v142
	s_waitcnt lgkmcnt(0)
	v_add_f32_e32 v191, v142, v143
	v_lshlrev_b64 v[142:143], 6, v[156:157]
	v_lshl_add_u64 v[142:143], v[144:145], 0, v[142:143]
	global_load_dwordx4 v[148:151], v[142:143], off
	ds_bpermute_b32 v192, v184, v191
	s_waitcnt vmcnt(0)
	v_add_f32_e32 v142, v148, v149
	v_add_f32_e32 v143, v150, v151
	v_add_f32_e32 v142, v142, v143
	ds_bpermute_b32 v143, v185, v142
	s_waitcnt lgkmcnt(0)
	v_add_f32_e32 v189, v142, v143
	v_lshl_add_u64 v[142:143], v[168:169], 0, s[0:1]
	v_lshlrev_b64 v[148:149], 6, v[142:143]
	v_lshl_add_u64 v[144:145], v[144:145], 0, v[148:149]
	global_load_dwordx4 v[148:151], v[144:145], off
	s_lshl_b32 s0, s4, 8
	s_or_b32 s76, s0, s78
	ds_bpermute_b32 v190, v184, v189
	s_cmp_gt_i32 s4, 7
	s_cselect_b64 s[0:1], -1, 0
	s_add_i32 s5, s76, 0xfffff800
	s_cmp_lt_i32 s4, 4
	s_cselect_b64 s[42:43], -1, 0
	s_and_b64 vcc, exec, s[0:1]
	s_waitcnt vmcnt(0)
	v_add_f32_e32 v144, v148, v149
	v_add_f32_e32 v145, v150, v151
	v_add_f32_e32 v144, v144, v145
	ds_bpermute_b32 v145, v185, v144
	s_waitcnt lgkmcnt(0)
	v_add_f32_e32 v186, v144, v145
	ds_bpermute_b32 v187, v184, v186
	v_lshlrev_b32_e32 v144, 3, v146
	v_add_u32_e32 v152, s5, v144
	v_or_b32_e32 v150, 4, v152
	v_add_u32_e32 v148, 32, v152
	v_add_u32_e32 v146, 36, v152
	v_ashrrev_i32_e32 v153, 31, v152
	v_ashrrev_i32_e32 v151, 31, v150
	v_ashrrev_i32_e32 v149, 31, v148
	v_ashrrev_i32_e32 v147, 31, v146
	s_cbranch_vccz .LBB0_528
	v_and_b32_e32 v145, 0xff0, v168
	v_readlane_b32 s4, v251, 51
	v_lshlrev_b32_e32 v174, 1, v145
	v_mov_b32_e32 v175, v0
	v_readlane_b32 s5, v251, 52
	v_mov_b32_e32 v155, v0
	v_ashrrev_i64 v[172:173], 2, v[168:169]
	v_lshl_add_u64 v[174:175], s[4:5], 0, v[174:175]
	v_lshl_add_u64 v[174:175], v[174:175], 0, v[154:155]
	v_lshlrev_b32_e32 v176, 1, v188
	v_mov_b32_e32 v177, v0
	v_lshlrev_b32_e32 v145, 2, v168
	v_and_b32_e32 v172, 0xfffffc00, v172
	v_lshl_add_u64 v[174:175], v[174:175], 0, v[176:177]
	v_and_b32_e32 v176, 16, v145
	v_lshl_add_u64 v[174:175], v[174:175], 0, v[176:177]
	v_lshl_add_u64 v[176:177], v[172:173], 0, v[152:153]
	v_lshlrev_b64 v[176:177], 13, v[176:177]
	v_lshl_add_u64 v[176:177], v[174:175], 0, v[176:177]
	v_pk_mul_f32 v[178:179], v[128:129], v[170:171] op_sel_hi:[1,0]
	v_pk_mul_f32 v[180:181], v[126:127], v[170:171] op_sel_hi:[1,0]
	v_cvt_pk_bf16_f32 v155, v178, v179
	v_add_co_u32_e32 v178, vcc, s19, v176
	v_cvt_pk_bf16_f32 v145, v180, v181
	s_nop 0
	v_addc_co_u32_e32 v179, vcc, 0, v177, vcc
	global_store_short_d16_hi v[178:179], v145, off
	v_add_co_u32_e32 v178, vcc, s20, v176
	global_store_short v[176:177], v145, off
	s_nop 0
	v_addc_co_u32_e32 v179, vcc, 0, v177, vcc
	v_add_co_u32_e32 v176, vcc, s21, v176
	global_store_short v[178:179], v155, off
	s_nop 0
	v_addc_co_u32_e32 v177, vcc, 0, v177, vcc
	global_store_short_d16_hi v[176:177], v155, off
	v_lshl_add_u64 v[176:177], v[172:173], 0, v[150:151]
	v_lshlrev_b64 v[176:177], 13, v[176:177]
	v_lshl_add_u64 v[176:177], v[174:175], 0, v[176:177]
	v_pk_mul_f32 v[178:179], v[124:125], v[170:171] op_sel_hi:[1,0]
	v_pk_mul_f32 v[180:181], v[122:123], v[170:171] op_sel_hi:[1,0]
	v_cvt_pk_bf16_f32 v155, v178, v179
	v_add_co_u32_e32 v178, vcc, s19, v176
	v_cvt_pk_bf16_f32 v145, v180, v181
	s_nop 0
	v_addc_co_u32_e32 v179, vcc, 0, v177, vcc
	global_store_short_d16_hi v[178:179], v145, off
	v_add_co_u32_e32 v178, vcc, s20, v176
	global_store_short v[176:177], v145, off
	s_nop 0
	v_addc_co_u32_e32 v179, vcc, 0, v177, vcc
	v_add_co_u32_e32 v176, vcc, s21, v176
	global_store_short v[178:179], v155, off
	s_nop 0
	v_addc_co_u32_e32 v177, vcc, 0, v177, vcc
	global_store_short_d16_hi v[176:177], v155, off
	v_lshl_add_u64 v[176:177], v[172:173], 0, v[148:149]
	v_lshlrev_b64 v[176:177], 13, v[176:177]
	v_lshl_add_u64 v[176:177], v[174:175], 0, v[176:177]
	v_pk_mul_f32 v[178:179], v[120:121], v[170:171] op_sel_hi:[1,0]
	v_pk_mul_f32 v[180:181], v[118:119], v[170:171] op_sel_hi:[1,0]
	v_cvt_pk_bf16_f32 v155, v178, v179
	v_add_co_u32_e32 v178, vcc, s19, v176
	v_cvt_pk_bf16_f32 v145, v180, v181
	s_nop 0
	v_addc_co_u32_e32 v179, vcc, 0, v177, vcc
	global_store_short_d16_hi v[178:179], v145, off
	v_add_co_u32_e32 v178, vcc, s20, v176
	v_lshl_add_u64 v[172:173], v[172:173], 0, v[146:147]
	s_nop 0
	v_addc_co_u32_e32 v179, vcc, 0, v177, vcc
	global_store_short v[176:177], v145, off
	v_add_co_u32_e32 v176, vcc, s21, v176
	v_lshlrev_b64 v[172:173], 13, v[172:173]
	s_nop 0
	v_addc_co_u32_e32 v177, vcc, 0, v177, vcc
	v_lshl_add_u64 v[172:173], v[174:175], 0, v[172:173]
	v_pk_mul_f32 v[174:175], v[116:117], v[170:171] op_sel_hi:[1,0]
	global_store_short v[178:179], v155, off
	global_store_short_d16_hi v[176:177], v155, off
	v_pk_mul_f32 v[176:177], v[114:115], v[170:171] op_sel_hi:[1,0]
	v_cvt_pk_bf16_f32 v155, v174, v175
	v_add_co_u32_e32 v174, vcc, 0x2000, v172
	v_cvt_pk_bf16_f32 v145, v176, v177
	s_nop 0
	v_addc_co_u32_e32 v175, vcc, 0, v173, vcc
	global_store_short_d16_hi v[174:175], v145, off
	v_add_co_u32_e32 v174, vcc, 0x4000, v172
	global_store_short v[172:173], v145, off
	s_nop 0
	v_addc_co_u32_e32 v175, vcc, 0, v173, vcc
	v_add_co_u32_e32 v172, vcc, 0x6000, v172
	global_store_short v[174:175], v155, off
	s_nop 0
	v_addc_co_u32_e32 v173, vcc, 0, v173, vcc
	global_store_short_d16_hi v[172:173], v155, off
	s_mov_b64 s[10:11], 0
.LBB0_528:
	s_ashr_i32 s65, s76, 31
	s_mov_b32 s64, s76
	s_andn2_b64 vcc, exec, s[10:11]
	v_ashrrev_i32_e32 v145, 31, v144
	s_cbranch_vccnz .LBB0_530
	v_pk_mul_f32 v[172:173], v[128:129], v[170:171] op_sel_hi:[1,0]
	v_pk_mul_f32 v[174:175], v[126:127], v[170:171] op_sel_hi:[1,0]
	v_pk_mul_f32 v[126:127], v[172:173], v[172:173]
	v_pk_mul_f32 v[128:129], v[174:175], v[174:175]
	v_pk_mul_f32 v[178:179], v[122:123], v[170:171] op_sel_hi:[1,0]
	v_pk_mov_b32 v[176:177], v[128:129], v[126:127] op_sel:[1,0]
	v_mov_b32_e32 v129, v127
	v_pk_add_f32 v[126:127], v[176:177], v[128:129]
	v_pk_mul_f32 v[176:177], v[124:125], v[170:171] op_sel_hi:[1,0]
	v_pk_mul_f32 v[124:125], v[178:179], v[178:179]
	v_pk_mul_f32 v[122:123], v[176:177], v[176:177]
	v_pk_mul_f32 v[128:129], v[118:119], v[170:171] op_sel_hi:[1,0]
	v_pk_add_f32 v[180:181], v[126:127], v[126:127] op_sel_hi:[0,1]
	v_pk_mov_b32 v[126:127], v[124:125], v[122:123] op_sel:[1,0]
	v_mov_b32_e32 v125, v123
	v_mul_f32_e32 v118, v128, v128
	v_pk_add_f32 v[122:123], v[126:127], v[124:125]
	v_pk_mul_f32 v[126:127], v[120:121], v[170:171] op_sel_hi:[1,0]
	v_pk_fma_f32 v[118:119], v[128:129], v[128:129], v[118:119] op_sel_hi:[1,1,0]
	v_pk_add_f32 v[202:203], v[122:123], v[122:123] op_sel_hi:[0,1]
	v_mul_f32_e32 v118, v126, v126
	v_pk_fma_f32 v[120:121], v[126:127], v[126:127], v[118:119] op_sel_hi:[1,1,0]
	v_pk_mul_f32 v[122:123], v[116:117], v[170:171] op_sel_hi:[1,0]
	v_pk_mul_f32 v[124:125], v[114:115], v[170:171] op_sel_hi:[1,0]
	v_mul_f32_e32 v180, v122, v122
	v_mul_f32_e32 v118, v124, v124
	v_mul_f32_e32 v120, v125, v125
	v_mul_f32_e32 v202, v123, v123
	v_pk_add_f32 v[114:115], v[118:119], v[120:121]
	v_pk_add_f32 v[116:117], v[180:181], v[202:203]
	s_and_b64 s[4:5], s[42:43], exec
	v_pk_add_f32 v[114:115], v[114:115], v[116:117]
	s_nop 0
	v_add_f32_e32 v114, v114, v115
	ds_bpermute_b32 v115, v185, v114
	s_waitcnt lgkmcnt(0)
	v_add_f32_e32 v114, v114, v115
	ds_bpermute_b32 v115, v184, v114
	s_waitcnt lgkmcnt(0)
	v_add_f32_e32 v114, v114, v115
	v_fmamk_f32 v114, v114, 0x3c800000, v243
	s_nop 1
	s_cselect_b32 s4, s27, s39
	s_cselect_b32 s5, s26, s38
	v_rsq_f32_e32 v116, v114
	s_nop 0
	v_mov_b32_e32 v114, s5
	v_mov_b32_e32 v115, s4
	v_mul_f32_e32 v117, 0x3e38aa3b, v116
	v_readlane_b32 s4, v251, 43
	v_cndmask_b32_e64 v170, v116, v117, s[42:43]
	v_lshlrev_b64 v[116:117], 11, v[168:169]
	v_readlane_b32 s5, v251, 44
	v_lshl_add_u64 v[180:181], v[144:145], 2, v[114:115]
	s_nop 0
	v_lshl_add_u64 v[118:119], s[4:5], 0, v[116:117]
	v_readlane_b32 s4, v253, 16
	v_readlane_b32 s5, v253, 17
	v_lshl_add_u64 v[118:119], s[64:65], 1, v[118:119]
	s_nop 0
	v_lshl_add_u64 v[116:117], s[4:5], 0, v[116:117]
	s_movk_i32 s4, 0xf800
	v_lshl_add_u64 v[116:117], s[76:77], 1, v[116:117]
	s_mov_b32 s5, -1
	v_lshl_add_u64 v[116:117], v[116:117], 0, s[4:5]
	v_cndmask_b32_e64 v169, v117, v119, s[42:43]
	v_cndmask_b32_e64 v168, v116, v118, s[42:43]
	global_load_dwordx4 v[114:117], v[180:181], off offset:16
	global_load_dwordx4 v[118:121], v[180:181], off
	v_lshl_add_u64 v[168:169], v[144:145], 1, v[168:169]
	s_waitcnt vmcnt(1)
	v_pk_mul_f32 v[116:117], v[176:177], v[116:117]
	s_waitcnt vmcnt(0)
	v_pk_mul_f32 v[120:121], v[172:173], v[120:121]
	v_pk_mul_f32 v[118:119], v[174:175], v[118:119]
	v_pk_mul_f32 v[114:115], v[178:179], v[114:115]
	v_pk_mul_f32 v[120:121], v[170:171], v[120:121] op_sel_hi:[0,1]
	v_pk_mul_f32 v[118:119], v[170:171], v[118:119] op_sel_hi:[0,1]
	v_pk_mul_f32 v[172:173], v[170:171], v[116:117] op_sel_hi:[0,1]
	v_pk_mul_f32 v[116:117], v[170:171], v[114:115] op_sel_hi:[0,1]
	v_cvt_pk_bf16_f32 v114, v118, v119
	v_cvt_pk_bf16_f32 v115, v120, v121
	v_cvt_pk_bf16_f32 v116, v116, v117
	v_cvt_pk_bf16_f32 v117, v172, v173
	global_store_dwordx4 v[168:169], v[114:117], off
	global_load_dwordx4 v[114:117], v[180:181], off offset:144
	s_nop 0
	global_load_dwordx4 v[118:121], v[180:181], off offset:128
	s_waitcnt vmcnt(1)
	v_pk_mul_f32 v[116:117], v[122:123], v[116:117]
	s_waitcnt vmcnt(0)
	v_pk_mul_f32 v[120:121], v[126:127], v[120:121]
	v_pk_mul_f32 v[118:119], v[128:129], v[118:119]
	v_pk_mul_f32 v[114:115], v[124:125], v[114:115]
	v_pk_mul_f32 v[120:121], v[170:171], v[120:121] op_sel_hi:[0,1]
	v_pk_mul_f32 v[118:119], v[170:171], v[118:119] op_sel_hi:[0,1]
	v_pk_mul_f32 v[122:123], v[170:171], v[116:117] op_sel_hi:[0,1]
	v_pk_mul_f32 v[116:117], v[170:171], v[114:115] op_sel_hi:[0,1]
	v_cvt_pk_bf16_f32 v114, v118, v119
	v_cvt_pk_bf16_f32 v115, v120, v121
	v_cvt_pk_bf16_f32 v116, v116, v117
	v_cvt_pk_bf16_f32 v117, v122, v123
	global_store_dwordx4 v[168:169], v[114:117], off offset:64
.LBB0_530:
	s_nop 1
	v_add_f32_e32 v114, v199, v200
	v_fmamk_f32 v114, v114, 0x3a800000, v243
	v_rsq_f32_e32 v122, v114
	s_nop 0
	v_cndmask_b32_e64 v114, 0, 1, s[0:1]
	v_cmp_ne_u32_e64 s[44:45], 1, v114
	s_andn2_b64 vcc, exec, s[0:1]
	s_mov_b64 s[0:1], -1
	s_cbranch_vccnz .LBB0_532
	v_and_b32_e32 v116, 0xff0, v166
	v_readlane_b32 s0, v251, 51
	v_lshlrev_b32_e32 v116, 1, v116
	v_mov_b32_e32 v117, v0
	v_readlane_b32 s1, v251, 52
	v_mov_b32_e32 v155, v0
	v_lshlrev_b32_e32 v118, 1, v188
	v_lshl_add_u64 v[116:117], s[0:1], 0, v[116:117]
	v_lshl_add_u64 v[116:117], v[116:117], 0, v[154:155]
	v_mov_b32_e32 v119, v0
	v_ashrrev_i64 v[114:115], 2, v[166:167]
	v_lshl_add_u64 v[116:117], v[116:117], 0, v[118:119]
	v_lshlrev_b32_e32 v118, 2, v166
	v_and_b32_e32 v114, 0xfffffc00, v114
	v_and_b32_e32 v118, 16, v118
	v_lshl_add_u64 v[116:117], v[116:117], 0, v[118:119]
	v_lshl_add_u64 v[118:119], v[114:115], 0, v[152:153]
	v_lshlrev_b64 v[118:119], 13, v[118:119]
	v_lshl_add_u64 v[118:119], v[116:117], 0, v[118:119]
	v_pk_mul_f32 v[120:121], v[112:113], v[122:123] op_sel_hi:[1,0]
	v_pk_mul_f32 v[124:125], v[110:111], v[122:123] op_sel_hi:[1,0]
	s_mov_b64 s[0:1], 0
	v_cvt_pk_bf16_f32 v123, v124, v125
	v_cvt_pk_bf16_f32 v124, v120, v121
	v_add_co_u32_e32 v120, vcc, s19, v118
	global_store_short v[118:119], v123, off
	s_nop 0
	v_addc_co_u32_e32 v121, vcc, 0, v119, vcc
	global_store_short_d16_hi v[120:121], v123, off
	v_add_co_u32_e32 v120, vcc, s20, v118
	s_nop 1
	v_addc_co_u32_e32 v121, vcc, 0, v119, vcc
	v_add_co_u32_e32 v118, vcc, s21, v118
	global_store_short v[120:121], v124, off
	s_nop 0
	v_addc_co_u32_e32 v119, vcc, 0, v119, vcc
	global_store_short_d16_hi v[118:119], v124, off
	v_lshl_add_u64 v[118:119], v[114:115], 0, v[150:151]
	v_lshlrev_b64 v[118:119], 13, v[118:119]
	v_lshl_add_u64 v[118:119], v[116:117], 0, v[118:119]
	v_pk_mul_f32 v[120:121], v[108:109], v[122:123] op_sel_hi:[1,0]
	v_pk_mul_f32 v[124:125], v[106:107], v[122:123] op_sel_hi:[1,0]
	s_nop 0
	v_cvt_pk_bf16_f32 v123, v124, v125
	v_cvt_pk_bf16_f32 v124, v120, v121
	v_add_co_u32_e32 v120, vcc, s19, v118
	global_store_short v[118:119], v123, off
	s_nop 0
	v_addc_co_u32_e32 v121, vcc, 0, v119, vcc
	global_store_short_d16_hi v[120:121], v123, off
	v_add_co_u32_e32 v120, vcc, s20, v118
	s_nop 1
	v_addc_co_u32_e32 v121, vcc, 0, v119, vcc
	v_add_co_u32_e32 v118, vcc, s21, v118
	global_store_short v[120:121], v124, off
	s_nop 0
	v_addc_co_u32_e32 v119, vcc, 0, v119, vcc
	global_store_short_d16_hi v[118:119], v124, off
	v_lshl_add_u64 v[118:119], v[114:115], 0, v[148:149]
	v_lshlrev_b64 v[118:119], 13, v[118:119]
	v_lshl_add_u64 v[118:119], v[116:117], 0, v[118:119]
	v_pk_mul_f32 v[120:121], v[104:105], v[122:123] op_sel_hi:[1,0]
	v_pk_mul_f32 v[124:125], v[102:103], v[122:123] op_sel_hi:[1,0]
	v_lshl_add_u64 v[114:115], v[114:115], 0, v[146:147]
	v_cvt_pk_bf16_f32 v123, v124, v125
	v_cvt_pk_bf16_f32 v124, v120, v121
	v_add_co_u32_e32 v120, vcc, s19, v118
	global_store_short v[118:119], v123, off
	s_nop 0
	v_addc_co_u32_e32 v121, vcc, 0, v119, vcc
	global_store_short_d16_hi v[120:121], v123, off
	v_add_co_u32_e32 v120, vcc, s20, v118
	v_lshlrev_b64 v[114:115], 13, v[114:115]
	s_nop 0
	v_addc_co_u32_e32 v121, vcc, 0, v119, vcc
	v_add_co_u32_e32 v118, vcc, s21, v118
	v_lshl_add_u64 v[114:115], v[116:117], 0, v[114:115]
	s_nop 0
	v_addc_co_u32_e32 v119, vcc, 0, v119, vcc
	global_store_short_d16_hi v[118:119], v124, off
	v_pk_mul_f32 v[116:117], v[100:101], v[122:123] op_sel_hi:[1,0]
	v_pk_mul_f32 v[118:119], v[98:99], v[122:123] op_sel_hi:[1,0]
	global_store_short v[120:121], v124, off
	v_cvt_pk_bf16_f32 v118, v118, v119
	v_cvt_pk_bf16_f32 v119, v116, v117
	v_add_co_u32_e32 v116, vcc, 0x2000, v114
	global_store_short v[114:115], v118, off
	s_nop 0
	v_addc_co_u32_e32 v117, vcc, 0, v115, vcc
	global_store_short_d16_hi v[116:117], v118, off
	v_add_co_u32_e32 v116, vcc, 0x4000, v114
	s_nop 1
	v_addc_co_u32_e32 v117, vcc, 0, v115, vcc
	v_add_co_u32_e32 v114, vcc, 0x6000, v114
	global_store_short v[116:117], v119, off
	s_nop 0
	v_addc_co_u32_e32 v115, vcc, 0, v115, vcc
	global_store_short_d16_hi v[114:115], v119, off
.LBB0_532:
	v_readlane_b32 s4, v253, 16
	s_andn2_b64 vcc, exec, s[0:1]
	v_readlane_b32 s5, v253, 17
	s_cbranch_vccnz .LBB0_534
	v_pk_mul_f32 v[114:115], v[112:113], v[122:123] op_sel_hi:[1,0]
	v_pk_mul_f32 v[116:117], v[110:111], v[122:123] op_sel_hi:[1,0]
	v_pk_mul_f32 v[110:111], v[114:115], v[114:115]
	v_pk_mul_f32 v[112:113], v[116:117], v[116:117]
	v_pk_mul_f32 v[120:121], v[106:107], v[122:123] op_sel_hi:[1,0]
	v_pk_mov_b32 v[118:119], v[112:113], v[110:111] op_sel:[1,0]
	v_mov_b32_e32 v113, v111
	v_pk_add_f32 v[110:111], v[118:119], v[112:113]
	v_pk_mul_f32 v[118:119], v[108:109], v[122:123] op_sel_hi:[1,0]
	v_pk_mul_f32 v[108:109], v[120:121], v[120:121]
	v_pk_mul_f32 v[106:107], v[118:119], v[118:119]
	v_pk_mul_f32 v[112:113], v[102:103], v[122:123] op_sel_hi:[1,0]
	v_pk_add_f32 v[124:125], v[110:111], v[110:111] op_sel_hi:[0,1]
	v_pk_mov_b32 v[110:111], v[108:109], v[106:107] op_sel:[1,0]
	v_mov_b32_e32 v109, v107
	v_mul_f32_e32 v102, v112, v112
	v_pk_add_f32 v[106:107], v[110:111], v[108:109]
	v_pk_mul_f32 v[110:111], v[104:105], v[122:123] op_sel_hi:[1,0]
	v_pk_fma_f32 v[102:103], v[112:113], v[112:113], v[102:103] op_sel_hi:[1,1,0]
	v_pk_add_f32 v[126:127], v[106:107], v[106:107] op_sel_hi:[0,1]
	v_mul_f32_e32 v102, v110, v110
	v_pk_fma_f32 v[104:105], v[110:111], v[110:111], v[102:103] op_sel_hi:[1,1,0]
	v_pk_mul_f32 v[106:107], v[100:101], v[122:123] op_sel_hi:[1,0]
	v_pk_mul_f32 v[108:109], v[98:99], v[122:123] op_sel_hi:[1,0]
	v_mul_f32_e32 v124, v106, v106
	v_mul_f32_e32 v102, v108, v108
	v_mul_f32_e32 v104, v109, v109
	v_mul_f32_e32 v126, v107, v107
	v_pk_add_f32 v[98:99], v[102:103], v[104:105]
	v_pk_add_f32 v[100:101], v[124:125], v[126:127]
	s_and_b64 s[0:1], s[42:43], exec
	v_pk_add_f32 v[98:99], v[98:99], v[100:101]
	s_nop 0
	v_add_f32_e32 v98, v98, v99
	ds_bpermute_b32 v99, v185, v98
	s_waitcnt lgkmcnt(0)
	v_add_f32_e32 v98, v98, v99
	ds_bpermute_b32 v99, v184, v98
	s_waitcnt lgkmcnt(0)
	v_add_f32_e32 v98, v98, v99
	v_fmamk_f32 v98, v98, 0x3c800000, v243
	s_nop 1
	s_cselect_b32 s0, s27, s39
	s_cselect_b32 s1, s26, s38
	v_rsq_f32_e32 v100, v98
	s_nop 0
	v_mov_b32_e32 v98, s1
	v_mov_b32_e32 v99, s0
	v_mul_f32_e32 v101, 0x3e38aa3b, v100
	v_readlane_b32 s0, v251, 43
	v_cndmask_b32_e64 v122, v100, v101, s[42:43]
	v_lshlrev_b64 v[100:101], 11, v[166:167]
	v_readlane_b32 s1, v251, 44
	v_lshl_add_u64 v[126:127], v[144:145], 2, v[98:99]
	s_nop 0
	v_lshl_add_u64 v[102:103], s[0:1], 0, v[100:101]
	v_lshl_add_u64 v[100:101], s[4:5], 0, v[100:101]
	s_movk_i32 s0, 0xf800
	v_lshl_add_u64 v[100:101], s[76:77], 1, v[100:101]
	s_mov_b32 s1, -1
	v_lshl_add_u64 v[102:103], s[64:65], 1, v[102:103]
	v_lshl_add_u64 v[100:101], v[100:101], 0, s[0:1]
	v_cndmask_b32_e64 v125, v101, v103, s[42:43]
	v_cndmask_b32_e64 v124, v100, v102, s[42:43]
	global_load_dwordx4 v[98:101], v[126:127], off offset:16
	global_load_dwordx4 v[102:105], v[126:127], off
	s_waitcnt vmcnt(1)
	v_pk_mul_f32 v[100:101], v[118:119], v[100:101]
	s_waitcnt vmcnt(0)
	v_pk_mul_f32 v[104:105], v[114:115], v[104:105]
	v_pk_mul_f32 v[102:103], v[116:117], v[102:103]
	v_pk_mul_f32 v[98:99], v[120:121], v[98:99]
	v_pk_mul_f32 v[104:105], v[122:123], v[104:105] op_sel_hi:[0,1]
	v_pk_mul_f32 v[102:103], v[122:123], v[102:103] op_sel_hi:[0,1]
	v_pk_mul_f32 v[114:115], v[122:123], v[100:101] op_sel_hi:[0,1]
	v_pk_mul_f32 v[100:101], v[122:123], v[98:99] op_sel_hi:[0,1]
	v_cvt_pk_bf16_f32 v98, v102, v103
	v_cvt_pk_bf16_f32 v99, v104, v105
	v_cvt_pk_bf16_f32 v100, v100, v101
	v_cvt_pk_bf16_f32 v101, v114, v115
	v_lshl_add_u64 v[114:115], v[144:145], 1, v[124:125]
	global_store_dwordx4 v[114:115], v[98:101], off
	global_load_dwordx4 v[98:101], v[126:127], off offset:144
	s_nop 0
	global_load_dwordx4 v[102:105], v[126:127], off offset:128
	s_waitcnt vmcnt(1)
	v_pk_mul_f32 v[100:101], v[106:107], v[100:101]
	s_waitcnt vmcnt(0)
	v_pk_mul_f32 v[104:105], v[110:111], v[104:105]
	v_pk_mul_f32 v[102:103], v[112:113], v[102:103]
	v_pk_mul_f32 v[98:99], v[108:109], v[98:99]
	v_pk_mul_f32 v[104:105], v[122:123], v[104:105] op_sel_hi:[0,1]
	v_pk_mul_f32 v[102:103], v[122:123], v[102:103] op_sel_hi:[0,1]
	v_pk_mul_f32 v[106:107], v[122:123], v[100:101] op_sel_hi:[0,1]
	v_pk_mul_f32 v[100:101], v[122:123], v[98:99] op_sel_hi:[0,1]
	v_cvt_pk_bf16_f32 v98, v102, v103
	v_cvt_pk_bf16_f32 v99, v104, v105
	v_cvt_pk_bf16_f32 v100, v100, v101
	v_cvt_pk_bf16_f32 v101, v106, v107
	global_store_dwordx4 v[114:115], v[98:101], off offset:64
.LBB0_534:
	s_nop 1
	v_add_f32_e32 v98, v197, v198
	v_fmamk_f32 v98, v98, 0x3a800000, v243
	v_rsq_f32_e32 v106, v98
	s_nop 0
	s_and_b64 vcc, exec, s[44:45]
	s_mov_b64 s[0:1], -1
	s_cbranch_vccnz .LBB0_536
	v_and_b32_e32 v100, 0xff0, v164
	v_readlane_b32 s0, v251, 51
	v_lshlrev_b32_e32 v100, 1, v100
	v_mov_b32_e32 v101, v0
	v_readlane_b32 s1, v251, 52
	v_mov_b32_e32 v155, v0
	v_lshlrev_b32_e32 v102, 1, v188
	v_lshl_add_u64 v[100:101], s[0:1], 0, v[100:101]
	v_lshl_add_u64 v[100:101], v[100:101], 0, v[154:155]
	v_mov_b32_e32 v103, v0
	v_ashrrev_i64 v[98:99], 2, v[164:165]
	v_lshl_add_u64 v[100:101], v[100:101], 0, v[102:103]
	v_lshlrev_b32_e32 v102, 2, v164
	v_and_b32_e32 v98, 0xfffffc00, v98
	v_and_b32_e32 v102, 16, v102
	v_lshl_add_u64 v[100:101], v[100:101], 0, v[102:103]
	v_lshl_add_u64 v[102:103], v[98:99], 0, v[152:153]
	v_lshlrev_b64 v[102:103], 13, v[102:103]
	v_lshl_add_u64 v[102:103], v[100:101], 0, v[102:103]
	v_pk_mul_f32 v[104:105], v[96:97], v[106:107] op_sel_hi:[1,0]
	v_pk_mul_f32 v[108:109], v[94:95], v[106:107] op_sel_hi:[1,0]
	s_mov_b64 s[0:1], 0
	v_cvt_pk_bf16_f32 v107, v108, v109
	v_cvt_pk_bf16_f32 v108, v104, v105
	v_add_co_u32_e32 v104, vcc, s19, v102
	global_store_short v[102:103], v107, off
	s_nop 0
	v_addc_co_u32_e32 v105, vcc, 0, v103, vcc
	global_store_short_d16_hi v[104:105], v107, off
	v_add_co_u32_e32 v104, vcc, s20, v102
	s_nop 1
	v_addc_co_u32_e32 v105, vcc, 0, v103, vcc
	v_add_co_u32_e32 v102, vcc, s21, v102
	global_store_short v[104:105], v108, off
	s_nop 0
	v_addc_co_u32_e32 v103, vcc, 0, v103, vcc
	global_store_short_d16_hi v[102:103], v108, off
	v_lshl_add_u64 v[102:103], v[98:99], 0, v[150:151]
	v_lshlrev_b64 v[102:103], 13, v[102:103]
	v_lshl_add_u64 v[102:103], v[100:101], 0, v[102:103]
	v_pk_mul_f32 v[104:105], v[92:93], v[106:107] op_sel_hi:[1,0]
	v_pk_mul_f32 v[108:109], v[90:91], v[106:107] op_sel_hi:[1,0]
	s_nop 0
	v_cvt_pk_bf16_f32 v107, v108, v109
	v_cvt_pk_bf16_f32 v108, v104, v105
	v_add_co_u32_e32 v104, vcc, s19, v102
	global_store_short v[102:103], v107, off
	s_nop 0
	v_addc_co_u32_e32 v105, vcc, 0, v103, vcc
	global_store_short_d16_hi v[104:105], v107, off
	v_add_co_u32_e32 v104, vcc, s20, v102
	s_nop 1
	v_addc_co_u32_e32 v105, vcc, 0, v103, vcc
	v_add_co_u32_e32 v102, vcc, s21, v102
	global_store_short v[104:105], v108, off
	s_nop 0
	v_addc_co_u32_e32 v103, vcc, 0, v103, vcc
	global_store_short_d16_hi v[102:103], v108, off
	v_lshl_add_u64 v[102:103], v[98:99], 0, v[148:149]
	v_lshlrev_b64 v[102:103], 13, v[102:103]
	v_lshl_add_u64 v[102:103], v[100:101], 0, v[102:103]
	v_pk_mul_f32 v[104:105], v[88:89], v[106:107] op_sel_hi:[1,0]
	v_pk_mul_f32 v[108:109], v[86:87], v[106:107] op_sel_hi:[1,0]
	v_lshl_add_u64 v[98:99], v[98:99], 0, v[146:147]
	v_cvt_pk_bf16_f32 v107, v108, v109
	v_cvt_pk_bf16_f32 v108, v104, v105
	v_add_co_u32_e32 v104, vcc, s19, v102
	global_store_short v[102:103], v107, off
	s_nop 0
	v_addc_co_u32_e32 v105, vcc, 0, v103, vcc
	global_store_short_d16_hi v[104:105], v107, off
	v_add_co_u32_e32 v104, vcc, s20, v102
	v_lshlrev_b64 v[98:99], 13, v[98:99]
	s_nop 0
	v_addc_co_u32_e32 v105, vcc, 0, v103, vcc
	v_add_co_u32_e32 v102, vcc, s21, v102
	v_lshl_add_u64 v[98:99], v[100:101], 0, v[98:99]
	s_nop 0
	v_addc_co_u32_e32 v103, vcc, 0, v103, vcc
	global_store_short_d16_hi v[102:103], v108, off
	v_pk_mul_f32 v[100:101], v[84:85], v[106:107] op_sel_hi:[1,0]
	v_pk_mul_f32 v[102:103], v[82:83], v[106:107] op_sel_hi:[1,0]
	global_store_short v[104:105], v108, off
	v_cvt_pk_bf16_f32 v102, v102, v103
	v_cvt_pk_bf16_f32 v103, v100, v101
	v_add_co_u32_e32 v100, vcc, 0x2000, v98
	global_store_short v[98:99], v102, off
	s_nop 0
	v_addc_co_u32_e32 v101, vcc, 0, v99, vcc
	global_store_short_d16_hi v[100:101], v102, off
	v_add_co_u32_e32 v100, vcc, 0x4000, v98
	s_nop 1
	v_addc_co_u32_e32 v101, vcc, 0, v99, vcc
	v_add_co_u32_e32 v98, vcc, 0x6000, v98
	global_store_short v[100:101], v103, off
	s_nop 0
	v_addc_co_u32_e32 v99, vcc, 0, v99, vcc
	global_store_short_d16_hi v[98:99], v103, off
.LBB0_536:
	s_andn2_b64 vcc, exec, s[0:1]
	s_cbranch_vccnz .LBB0_538
	v_pk_mul_f32 v[98:99], v[96:97], v[106:107] op_sel_hi:[1,0]
	v_pk_mul_f32 v[100:101], v[94:95], v[106:107] op_sel_hi:[1,0]
	v_pk_mul_f32 v[94:95], v[98:99], v[98:99]
	v_pk_mul_f32 v[96:97], v[100:101], v[100:101]
	v_pk_mul_f32 v[104:105], v[90:91], v[106:107] op_sel_hi:[1,0]
	v_pk_mov_b32 v[102:103], v[96:97], v[94:95] op_sel:[1,0]
	v_mov_b32_e32 v97, v95
	v_pk_add_f32 v[94:95], v[102:103], v[96:97]
	v_pk_mul_f32 v[102:103], v[92:93], v[106:107] op_sel_hi:[1,0]
	v_pk_mul_f32 v[92:93], v[104:105], v[104:105]
	v_pk_mul_f32 v[90:91], v[102:103], v[102:103]
	v_pk_mul_f32 v[96:97], v[86:87], v[106:107] op_sel_hi:[1,0]
	v_pk_add_f32 v[108:109], v[94:95], v[94:95] op_sel_hi:[0,1]
	v_pk_mov_b32 v[94:95], v[92:93], v[90:91] op_sel:[1,0]
	v_mov_b32_e32 v93, v91
	v_mul_f32_e32 v86, v96, v96
	v_pk_add_f32 v[90:91], v[94:95], v[92:93]
	v_pk_mul_f32 v[94:95], v[88:89], v[106:107] op_sel_hi:[1,0]
	v_pk_fma_f32 v[86:87], v[96:97], v[96:97], v[86:87] op_sel_hi:[1,1,0]
	v_pk_add_f32 v[110:111], v[90:91], v[90:91] op_sel_hi:[0,1]
	v_mul_f32_e32 v86, v94, v94
	v_pk_fma_f32 v[88:89], v[94:95], v[94:95], v[86:87] op_sel_hi:[1,1,0]
	v_pk_mul_f32 v[90:91], v[84:85], v[106:107] op_sel_hi:[1,0]
	v_pk_mul_f32 v[92:93], v[82:83], v[106:107] op_sel_hi:[1,0]
	v_mul_f32_e32 v108, v90, v90
	v_mul_f32_e32 v86, v92, v92
	v_mul_f32_e32 v88, v93, v93
	v_mul_f32_e32 v110, v91, v91
	v_pk_add_f32 v[82:83], v[86:87], v[88:89]
	v_pk_add_f32 v[84:85], v[108:109], v[110:111]
	s_and_b64 s[0:1], s[42:43], exec
	v_pk_add_f32 v[82:83], v[82:83], v[84:85]
	s_nop 0
	v_add_f32_e32 v82, v82, v83
	ds_bpermute_b32 v83, v185, v82
	s_waitcnt lgkmcnt(0)
	v_add_f32_e32 v82, v82, v83
	ds_bpermute_b32 v83, v184, v82
	s_waitcnt lgkmcnt(0)
	v_add_f32_e32 v82, v82, v83
	v_fmamk_f32 v82, v82, 0x3c800000, v243
	s_nop 1
	s_cselect_b32 s0, s27, s39
	s_cselect_b32 s1, s26, s38
	v_rsq_f32_e32 v84, v82
	s_nop 0
	v_mov_b32_e32 v82, s1
	v_mov_b32_e32 v83, s0
	v_mul_f32_e32 v85, 0x3e38aa3b, v84
	v_readlane_b32 s0, v251, 43
	v_cndmask_b32_e64 v106, v84, v85, s[42:43]
	v_lshlrev_b64 v[84:85], 11, v[164:165]
	v_readlane_b32 s1, v251, 44
	v_lshl_add_u64 v[110:111], v[144:145], 2, v[82:83]
	s_nop 0
	v_lshl_add_u64 v[86:87], s[0:1], 0, v[84:85]
	v_lshl_add_u64 v[84:85], s[4:5], 0, v[84:85]
	s_movk_i32 s0, 0xf800
	v_lshl_add_u64 v[84:85], s[76:77], 1, v[84:85]
	s_mov_b32 s1, -1
	v_lshl_add_u64 v[86:87], s[64:65], 1, v[86:87]
	v_lshl_add_u64 v[84:85], v[84:85], 0, s[0:1]
	v_cndmask_b32_e64 v109, v85, v87, s[42:43]
	v_cndmask_b32_e64 v108, v84, v86, s[42:43]
	global_load_dwordx4 v[82:85], v[110:111], off offset:16
	global_load_dwordx4 v[86:89], v[110:111], off
	s_waitcnt vmcnt(1)
	v_pk_mul_f32 v[84:85], v[102:103], v[84:85]
	s_waitcnt vmcnt(0)
	v_pk_mul_f32 v[88:89], v[98:99], v[88:89]
	v_pk_mul_f32 v[86:87], v[100:101], v[86:87]
	v_pk_mul_f32 v[82:83], v[104:105], v[82:83]
	v_pk_mul_f32 v[88:89], v[106:107], v[88:89] op_sel_hi:[0,1]
	v_pk_mul_f32 v[86:87], v[106:107], v[86:87] op_sel_hi:[0,1]
	v_pk_mul_f32 v[98:99], v[106:107], v[84:85] op_sel_hi:[0,1]
	v_pk_mul_f32 v[84:85], v[106:107], v[82:83] op_sel_hi:[0,1]
	v_cvt_pk_bf16_f32 v82, v86, v87
	v_cvt_pk_bf16_f32 v83, v88, v89
	v_cvt_pk_bf16_f32 v84, v84, v85
	v_cvt_pk_bf16_f32 v85, v98, v99
	v_lshl_add_u64 v[98:99], v[144:145], 1, v[108:109]
	global_store_dwordx4 v[98:99], v[82:85], off
	global_load_dwordx4 v[82:85], v[110:111], off offset:144
	s_nop 0
	global_load_dwordx4 v[86:89], v[110:111], off offset:128
	s_waitcnt vmcnt(1)
	v_pk_mul_f32 v[84:85], v[90:91], v[84:85]
	s_waitcnt vmcnt(0)
	v_pk_mul_f32 v[88:89], v[94:95], v[88:89]
	v_pk_mul_f32 v[86:87], v[96:97], v[86:87]
	v_pk_mul_f32 v[82:83], v[92:93], v[82:83]
	v_pk_mul_f32 v[88:89], v[106:107], v[88:89] op_sel_hi:[0,1]
	v_pk_mul_f32 v[86:87], v[106:107], v[86:87] op_sel_hi:[0,1]
	v_pk_mul_f32 v[90:91], v[106:107], v[84:85] op_sel_hi:[0,1]
	v_pk_mul_f32 v[84:85], v[106:107], v[82:83] op_sel_hi:[0,1]
	v_cvt_pk_bf16_f32 v82, v86, v87
	v_cvt_pk_bf16_f32 v83, v88, v89
	v_cvt_pk_bf16_f32 v84, v84, v85
	v_cvt_pk_bf16_f32 v85, v90, v91
	global_store_dwordx4 v[98:99], v[82:85], off offset:64
.LBB0_538:
	s_nop 1
	v_add_f32_e32 v82, v195, v196
	v_fmamk_f32 v82, v82, 0x3a800000, v243
	v_rsq_f32_e32 v90, v82
	s_nop 0
	s_and_b64 vcc, exec, s[44:45]
	s_mov_b64 s[0:1], -1
	s_cbranch_vccnz .LBB0_540
	v_and_b32_e32 v84, 0xff0, v162
	v_readlane_b32 s0, v251, 51
	v_lshlrev_b32_e32 v84, 1, v84
	v_mov_b32_e32 v85, v0
	v_readlane_b32 s1, v251, 52
	v_mov_b32_e32 v155, v0
	v_lshlrev_b32_e32 v86, 1, v188
	v_lshl_add_u64 v[84:85], s[0:1], 0, v[84:85]
	v_lshl_add_u64 v[84:85], v[84:85], 0, v[154:155]
	v_mov_b32_e32 v87, v0
	v_ashrrev_i64 v[82:83], 2, v[162:163]
	v_lshl_add_u64 v[84:85], v[84:85], 0, v[86:87]
	v_lshlrev_b32_e32 v86, 2, v162
	v_and_b32_e32 v82, 0xfffffc00, v82
	v_and_b32_e32 v86, 16, v86
	v_lshl_add_u64 v[84:85], v[84:85], 0, v[86:87]
	v_lshl_add_u64 v[86:87], v[82:83], 0, v[152:153]
	v_lshlrev_b64 v[86:87], 13, v[86:87]
	v_lshl_add_u64 v[86:87], v[84:85], 0, v[86:87]
	v_pk_mul_f32 v[88:89], v[80:81], v[90:91] op_sel_hi:[1,0]
	v_pk_mul_f32 v[92:93], v[78:79], v[90:91] op_sel_hi:[1,0]
	s_mov_b64 s[0:1], 0
	v_cvt_pk_bf16_f32 v91, v92, v93
	v_cvt_pk_bf16_f32 v92, v88, v89
	v_add_co_u32_e32 v88, vcc, s19, v86
	global_store_short v[86:87], v91, off
	s_nop 0
	v_addc_co_u32_e32 v89, vcc, 0, v87, vcc
	global_store_short_d16_hi v[88:89], v91, off
	v_add_co_u32_e32 v88, vcc, s20, v86
	s_nop 1
	v_addc_co_u32_e32 v89, vcc, 0, v87, vcc
	v_add_co_u32_e32 v86, vcc, s21, v86
	global_store_short v[88:89], v92, off
	s_nop 0
	v_addc_co_u32_e32 v87, vcc, 0, v87, vcc
	global_store_short_d16_hi v[86:87], v92, off
	v_lshl_add_u64 v[86:87], v[82:83], 0, v[150:151]
	v_lshlrev_b64 v[86:87], 13, v[86:87]
	v_lshl_add_u64 v[86:87], v[84:85], 0, v[86:87]
	v_pk_mul_f32 v[88:89], v[76:77], v[90:91] op_sel_hi:[1,0]
	v_pk_mul_f32 v[92:93], v[74:75], v[90:91] op_sel_hi:[1,0]
	s_nop 0
	v_cvt_pk_bf16_f32 v91, v92, v93
	v_cvt_pk_bf16_f32 v92, v88, v89
	v_add_co_u32_e32 v88, vcc, s19, v86
	global_store_short v[86:87], v91, off
	s_nop 0
	v_addc_co_u32_e32 v89, vcc, 0, v87, vcc
	global_store_short_d16_hi v[88:89], v91, off
	v_add_co_u32_e32 v88, vcc, s20, v86
	s_nop 1
	v_addc_co_u32_e32 v89, vcc, 0, v87, vcc
	v_add_co_u32_e32 v86, vcc, s21, v86
	global_store_short v[88:89], v92, off
	s_nop 0
	v_addc_co_u32_e32 v87, vcc, 0, v87, vcc
	global_store_short_d16_hi v[86:87], v92, off
	v_lshl_add_u64 v[86:87], v[82:83], 0, v[148:149]
	v_lshlrev_b64 v[86:87], 13, v[86:87]
	v_lshl_add_u64 v[86:87], v[84:85], 0, v[86:87]
	v_pk_mul_f32 v[88:89], v[72:73], v[90:91] op_sel_hi:[1,0]
	v_pk_mul_f32 v[92:93], v[70:71], v[90:91] op_sel_hi:[1,0]
	v_lshl_add_u64 v[82:83], v[82:83], 0, v[146:147]
	v_cvt_pk_bf16_f32 v91, v92, v93
	v_cvt_pk_bf16_f32 v92, v88, v89
	v_add_co_u32_e32 v88, vcc, s19, v86
	global_store_short v[86:87], v91, off
	s_nop 0
	v_addc_co_u32_e32 v89, vcc, 0, v87, vcc
	global_store_short_d16_hi v[88:89], v91, off
	v_add_co_u32_e32 v88, vcc, s20, v86
	v_lshlrev_b64 v[82:83], 13, v[82:83]
	s_nop 0
	v_addc_co_u32_e32 v89, vcc, 0, v87, vcc
	v_add_co_u32_e32 v86, vcc, s21, v86
	v_lshl_add_u64 v[82:83], v[84:85], 0, v[82:83]
	s_nop 0
	v_addc_co_u32_e32 v87, vcc, 0, v87, vcc
	global_store_short_d16_hi v[86:87], v92, off
	v_pk_mul_f32 v[84:85], v[68:69], v[90:91] op_sel_hi:[1,0]
	v_pk_mul_f32 v[86:87], v[66:67], v[90:91] op_sel_hi:[1,0]
	global_store_short v[88:89], v92, off
	v_cvt_pk_bf16_f32 v86, v86, v87
	v_cvt_pk_bf16_f32 v87, v84, v85
	v_add_co_u32_e32 v84, vcc, 0x2000, v82
	global_store_short v[82:83], v86, off
	s_nop 0
	v_addc_co_u32_e32 v85, vcc, 0, v83, vcc
	global_store_short_d16_hi v[84:85], v86, off
	v_add_co_u32_e32 v84, vcc, 0x4000, v82
	s_nop 1
	v_addc_co_u32_e32 v85, vcc, 0, v83, vcc
	v_add_co_u32_e32 v82, vcc, 0x6000, v82
	global_store_short v[84:85], v87, off
	s_nop 0
	v_addc_co_u32_e32 v83, vcc, 0, v83, vcc
	global_store_short_d16_hi v[82:83], v87, off
.LBB0_540:
	s_andn2_b64 vcc, exec, s[0:1]
	s_cbranch_vccnz .LBB0_542
	v_pk_mul_f32 v[82:83], v[80:81], v[90:91] op_sel_hi:[1,0]
	v_pk_mul_f32 v[84:85], v[78:79], v[90:91] op_sel_hi:[1,0]
	v_pk_mul_f32 v[78:79], v[82:83], v[82:83]
	v_pk_mul_f32 v[80:81], v[84:85], v[84:85]
	v_pk_mul_f32 v[88:89], v[74:75], v[90:91] op_sel_hi:[1,0]
	v_pk_mov_b32 v[86:87], v[80:81], v[78:79] op_sel:[1,0]
	v_mov_b32_e32 v81, v79
	v_pk_add_f32 v[78:79], v[86:87], v[80:81]
	v_pk_mul_f32 v[86:87], v[76:77], v[90:91] op_sel_hi:[1,0]
	v_pk_mul_f32 v[76:77], v[88:89], v[88:89]
	v_pk_mul_f32 v[74:75], v[86:87], v[86:87]
	v_pk_mul_f32 v[80:81], v[70:71], v[90:91] op_sel_hi:[1,0]
	v_pk_add_f32 v[92:93], v[78:79], v[78:79] op_sel_hi:[0,1]
	v_pk_mov_b32 v[78:79], v[76:77], v[74:75] op_sel:[1,0]
	v_mov_b32_e32 v77, v75
	v_mul_f32_e32 v70, v80, v80
	v_pk_add_f32 v[74:75], v[78:79], v[76:77]
	v_pk_mul_f32 v[78:79], v[72:73], v[90:91] op_sel_hi:[1,0]
	v_pk_fma_f32 v[70:71], v[80:81], v[80:81], v[70:71] op_sel_hi:[1,1,0]
	v_pk_add_f32 v[94:95], v[74:75], v[74:75] op_sel_hi:[0,1]
	v_mul_f32_e32 v70, v78, v78
	v_pk_fma_f32 v[72:73], v[78:79], v[78:79], v[70:71] op_sel_hi:[1,1,0]
	v_pk_mul_f32 v[74:75], v[68:69], v[90:91] op_sel_hi:[1,0]
	v_pk_mul_f32 v[76:77], v[66:67], v[90:91] op_sel_hi:[1,0]
	v_mul_f32_e32 v92, v74, v74
	v_mul_f32_e32 v70, v76, v76
	v_mul_f32_e32 v72, v77, v77
	v_mul_f32_e32 v94, v75, v75
	v_pk_add_f32 v[66:67], v[70:71], v[72:73]
	v_pk_add_f32 v[68:69], v[92:93], v[94:95]
	s_and_b64 s[0:1], s[42:43], exec
	v_pk_add_f32 v[66:67], v[66:67], v[68:69]
	s_nop 0
	v_add_f32_e32 v66, v66, v67
	ds_bpermute_b32 v67, v185, v66
	s_waitcnt lgkmcnt(0)
	v_add_f32_e32 v66, v66, v67
	ds_bpermute_b32 v67, v184, v66
	s_waitcnt lgkmcnt(0)
	v_add_f32_e32 v66, v66, v67
	v_fmamk_f32 v66, v66, 0x3c800000, v243
	s_nop 1
	s_cselect_b32 s0, s27, s39
	s_cselect_b32 s1, s26, s38
	v_rsq_f32_e32 v68, v66
	s_nop 0
	v_mov_b32_e32 v66, s1
	v_mov_b32_e32 v67, s0
	v_mul_f32_e32 v69, 0x3e38aa3b, v68
	v_readlane_b32 s0, v251, 43
	v_cndmask_b32_e64 v90, v68, v69, s[42:43]
	v_lshlrev_b64 v[68:69], 11, v[162:163]
	v_readlane_b32 s1, v251, 44
	v_lshl_add_u64 v[94:95], v[144:145], 2, v[66:67]
	s_nop 0
	v_lshl_add_u64 v[70:71], s[0:1], 0, v[68:69]
	v_lshl_add_u64 v[68:69], s[4:5], 0, v[68:69]
	s_movk_i32 s0, 0xf800
	v_lshl_add_u64 v[68:69], s[76:77], 1, v[68:69]
	s_mov_b32 s1, -1
	v_lshl_add_u64 v[70:71], s[64:65], 1, v[70:71]
	v_lshl_add_u64 v[68:69], v[68:69], 0, s[0:1]
	v_cndmask_b32_e64 v93, v69, v71, s[42:43]
	v_cndmask_b32_e64 v92, v68, v70, s[42:43]
	global_load_dwordx4 v[66:69], v[94:95], off offset:16
	global_load_dwordx4 v[70:73], v[94:95], off
	s_waitcnt vmcnt(1)
	v_pk_mul_f32 v[68:69], v[86:87], v[68:69]
	s_waitcnt vmcnt(0)
	v_pk_mul_f32 v[72:73], v[82:83], v[72:73]
	v_pk_mul_f32 v[70:71], v[84:85], v[70:71]
	v_pk_mul_f32 v[66:67], v[88:89], v[66:67]
	v_pk_mul_f32 v[72:73], v[90:91], v[72:73] op_sel_hi:[0,1]
	v_pk_mul_f32 v[70:71], v[90:91], v[70:71] op_sel_hi:[0,1]
	v_pk_mul_f32 v[82:83], v[90:91], v[68:69] op_sel_hi:[0,1]
	v_pk_mul_f32 v[68:69], v[90:91], v[66:67] op_sel_hi:[0,1]
	v_cvt_pk_bf16_f32 v66, v70, v71
	v_cvt_pk_bf16_f32 v67, v72, v73
	v_cvt_pk_bf16_f32 v68, v68, v69
	v_cvt_pk_bf16_f32 v69, v82, v83
	v_lshl_add_u64 v[82:83], v[144:145], 1, v[92:93]
	global_store_dwordx4 v[82:83], v[66:69], off
	global_load_dwordx4 v[66:69], v[94:95], off offset:144
	s_nop 0
	global_load_dwordx4 v[70:73], v[94:95], off offset:128
	s_waitcnt vmcnt(1)
	v_pk_mul_f32 v[68:69], v[74:75], v[68:69]
	s_waitcnt vmcnt(0)
	v_pk_mul_f32 v[72:73], v[78:79], v[72:73]
	v_pk_mul_f32 v[70:71], v[80:81], v[70:71]
	v_pk_mul_f32 v[66:67], v[76:77], v[66:67]
	v_pk_mul_f32 v[72:73], v[90:91], v[72:73] op_sel_hi:[0,1]
	v_pk_mul_f32 v[70:71], v[90:91], v[70:71] op_sel_hi:[0,1]
	v_pk_mul_f32 v[74:75], v[90:91], v[68:69] op_sel_hi:[0,1]
	v_pk_mul_f32 v[68:69], v[90:91], v[66:67] op_sel_hi:[0,1]
	v_cvt_pk_bf16_f32 v66, v70, v71
	v_cvt_pk_bf16_f32 v67, v72, v73
	v_cvt_pk_bf16_f32 v68, v68, v69
	v_cvt_pk_bf16_f32 v69, v74, v75
	global_store_dwordx4 v[82:83], v[66:69], off offset:64
.LBB0_542:
	s_nop 1
	v_add_f32_e32 v66, v193, v194
	v_fmamk_f32 v66, v66, 0x3a800000, v243
	v_rsq_f32_e32 v74, v66
	s_nop 0
	s_and_b64 vcc, exec, s[44:45]
	s_mov_b64 s[0:1], -1
	s_cbranch_vccnz .LBB0_544
	v_and_b32_e32 v68, 0xff0, v160
	v_readlane_b32 s0, v251, 51
	v_lshlrev_b32_e32 v68, 1, v68
	v_mov_b32_e32 v69, v0
	v_readlane_b32 s1, v251, 52
	v_mov_b32_e32 v155, v0
	v_lshlrev_b32_e32 v70, 1, v188
	v_lshl_add_u64 v[68:69], s[0:1], 0, v[68:69]
	v_lshl_add_u64 v[68:69], v[68:69], 0, v[154:155]
	v_mov_b32_e32 v71, v0
	v_ashrrev_i64 v[66:67], 2, v[160:161]
	v_lshl_add_u64 v[68:69], v[68:69], 0, v[70:71]
	v_lshlrev_b32_e32 v70, 2, v160
	v_and_b32_e32 v66, 0xfffffc00, v66
	v_and_b32_e32 v70, 16, v70
	v_lshl_add_u64 v[68:69], v[68:69], 0, v[70:71]
	v_lshl_add_u64 v[70:71], v[66:67], 0, v[152:153]
	v_lshlrev_b64 v[70:71], 13, v[70:71]
	v_lshl_add_u64 v[70:71], v[68:69], 0, v[70:71]
	v_pk_mul_f32 v[72:73], v[64:65], v[74:75] op_sel_hi:[1,0]
	v_pk_mul_f32 v[76:77], v[62:63], v[74:75] op_sel_hi:[1,0]
	s_mov_b64 s[0:1], 0
	v_cvt_pk_bf16_f32 v75, v76, v77
	v_cvt_pk_bf16_f32 v76, v72, v73
	v_add_co_u32_e32 v72, vcc, s19, v70
	global_store_short v[70:71], v75, off
	s_nop 0
	v_addc_co_u32_e32 v73, vcc, 0, v71, vcc
	global_store_short_d16_hi v[72:73], v75, off
	v_add_co_u32_e32 v72, vcc, s20, v70
	s_nop 1
	v_addc_co_u32_e32 v73, vcc, 0, v71, vcc
	v_add_co_u32_e32 v70, vcc, s21, v70
	global_store_short v[72:73], v76, off
	s_nop 0
	v_addc_co_u32_e32 v71, vcc, 0, v71, vcc
	global_store_short_d16_hi v[70:71], v76, off
	v_lshl_add_u64 v[70:71], v[66:67], 0, v[150:151]
	v_lshlrev_b64 v[70:71], 13, v[70:71]
	v_lshl_add_u64 v[70:71], v[68:69], 0, v[70:71]
	v_pk_mul_f32 v[72:73], v[60:61], v[74:75] op_sel_hi:[1,0]
	v_pk_mul_f32 v[76:77], v[58:59], v[74:75] op_sel_hi:[1,0]
	s_nop 0
	v_cvt_pk_bf16_f32 v75, v76, v77
	v_cvt_pk_bf16_f32 v76, v72, v73
	v_add_co_u32_e32 v72, vcc, s19, v70
	global_store_short v[70:71], v75, off
	s_nop 0
	v_addc_co_u32_e32 v73, vcc, 0, v71, vcc
	global_store_short_d16_hi v[72:73], v75, off
	v_add_co_u32_e32 v72, vcc, s20, v70
	s_nop 1
	v_addc_co_u32_e32 v73, vcc, 0, v71, vcc
	v_add_co_u32_e32 v70, vcc, s21, v70
	global_store_short v[72:73], v76, off
	s_nop 0
	v_addc_co_u32_e32 v71, vcc, 0, v71, vcc
	global_store_short_d16_hi v[70:71], v76, off
	v_lshl_add_u64 v[70:71], v[66:67], 0, v[148:149]
	v_lshlrev_b64 v[70:71], 13, v[70:71]
	v_lshl_add_u64 v[70:71], v[68:69], 0, v[70:71]
	v_pk_mul_f32 v[72:73], v[56:57], v[74:75] op_sel_hi:[1,0]
	v_pk_mul_f32 v[76:77], v[54:55], v[74:75] op_sel_hi:[1,0]
	v_lshl_add_u64 v[66:67], v[66:67], 0, v[146:147]
	v_cvt_pk_bf16_f32 v75, v76, v77
	v_cvt_pk_bf16_f32 v76, v72, v73
	v_add_co_u32_e32 v72, vcc, s19, v70
	global_store_short v[70:71], v75, off
	s_nop 0
	v_addc_co_u32_e32 v73, vcc, 0, v71, vcc
	global_store_short_d16_hi v[72:73], v75, off
	v_add_co_u32_e32 v72, vcc, s20, v70
	v_lshlrev_b64 v[66:67], 13, v[66:67]
	s_nop 0
	v_addc_co_u32_e32 v73, vcc, 0, v71, vcc
	v_add_co_u32_e32 v70, vcc, s21, v70
	v_lshl_add_u64 v[66:67], v[68:69], 0, v[66:67]
	s_nop 0
	v_addc_co_u32_e32 v71, vcc, 0, v71, vcc
	global_store_short_d16_hi v[70:71], v76, off
	v_pk_mul_f32 v[68:69], v[52:53], v[74:75] op_sel_hi:[1,0]
	v_pk_mul_f32 v[70:71], v[50:51], v[74:75] op_sel_hi:[1,0]
	global_store_short v[72:73], v76, off
	v_cvt_pk_bf16_f32 v70, v70, v71
	v_cvt_pk_bf16_f32 v71, v68, v69
	v_add_co_u32_e32 v68, vcc, 0x2000, v66
	global_store_short v[66:67], v70, off
	s_nop 0
	v_addc_co_u32_e32 v69, vcc, 0, v67, vcc
	global_store_short_d16_hi v[68:69], v70, off
	v_add_co_u32_e32 v68, vcc, 0x4000, v66
	s_nop 1
	v_addc_co_u32_e32 v69, vcc, 0, v67, vcc
	v_add_co_u32_e32 v66, vcc, 0x6000, v66
	global_store_short v[68:69], v71, off
	s_nop 0
	v_addc_co_u32_e32 v67, vcc, 0, v67, vcc
	global_store_short_d16_hi v[66:67], v71, off
.LBB0_544:
	s_andn2_b64 vcc, exec, s[0:1]
	s_cbranch_vccnz .LBB0_546
	v_pk_mul_f32 v[66:67], v[64:65], v[74:75] op_sel_hi:[1,0]
	v_pk_mul_f32 v[68:69], v[62:63], v[74:75] op_sel_hi:[1,0]
	v_pk_mul_f32 v[62:63], v[66:67], v[66:67]
	v_pk_mul_f32 v[64:65], v[68:69], v[68:69]
	v_pk_mul_f32 v[72:73], v[58:59], v[74:75] op_sel_hi:[1,0]
	v_pk_mov_b32 v[70:71], v[64:65], v[62:63] op_sel:[1,0]
	v_mov_b32_e32 v65, v63
	v_pk_add_f32 v[62:63], v[70:71], v[64:65]
	v_pk_mul_f32 v[70:71], v[60:61], v[74:75] op_sel_hi:[1,0]
	v_pk_mul_f32 v[60:61], v[72:73], v[72:73]
	v_pk_mul_f32 v[58:59], v[70:71], v[70:71]
	v_pk_mul_f32 v[64:65], v[54:55], v[74:75] op_sel_hi:[1,0]
	v_pk_add_f32 v[76:77], v[62:63], v[62:63] op_sel_hi:[0,1]
	v_pk_mov_b32 v[62:63], v[60:61], v[58:59] op_sel:[1,0]
	v_mov_b32_e32 v61, v59
	v_mul_f32_e32 v54, v64, v64
	v_pk_add_f32 v[58:59], v[62:63], v[60:61]
	v_pk_mul_f32 v[62:63], v[56:57], v[74:75] op_sel_hi:[1,0]
	v_pk_fma_f32 v[54:55], v[64:65], v[64:65], v[54:55] op_sel_hi:[1,1,0]
	v_pk_add_f32 v[78:79], v[58:59], v[58:59] op_sel_hi:[0,1]
	v_mul_f32_e32 v54, v62, v62
	v_pk_fma_f32 v[56:57], v[62:63], v[62:63], v[54:55] op_sel_hi:[1,1,0]
	v_pk_mul_f32 v[58:59], v[52:53], v[74:75] op_sel_hi:[1,0]
	v_pk_mul_f32 v[60:61], v[50:51], v[74:75] op_sel_hi:[1,0]
	v_mul_f32_e32 v76, v58, v58
	v_mul_f32_e32 v54, v60, v60
	v_mul_f32_e32 v56, v61, v61
	v_mul_f32_e32 v78, v59, v59
	v_pk_add_f32 v[50:51], v[54:55], v[56:57]
	v_pk_add_f32 v[52:53], v[76:77], v[78:79]
	s_and_b64 s[0:1], s[42:43], exec
	v_pk_add_f32 v[50:51], v[50:51], v[52:53]
	s_nop 0
	v_add_f32_e32 v50, v50, v51
	ds_bpermute_b32 v51, v185, v50
	s_waitcnt lgkmcnt(0)
	v_add_f32_e32 v50, v50, v51
	ds_bpermute_b32 v51, v184, v50
	s_waitcnt lgkmcnt(0)
	v_add_f32_e32 v50, v50, v51
	v_fmamk_f32 v50, v50, 0x3c800000, v243
	s_nop 1
	s_cselect_b32 s0, s27, s39
	s_cselect_b32 s1, s26, s38
	v_rsq_f32_e32 v52, v50
	s_nop 0
	v_mov_b32_e32 v50, s1
	v_mov_b32_e32 v51, s0
	v_mul_f32_e32 v53, 0x3e38aa3b, v52
	v_readlane_b32 s0, v251, 43
	v_cndmask_b32_e64 v74, v52, v53, s[42:43]
	v_lshlrev_b64 v[52:53], 11, v[160:161]
	v_readlane_b32 s1, v251, 44
	v_lshl_add_u64 v[78:79], v[144:145], 2, v[50:51]
	s_nop 0
	v_lshl_add_u64 v[54:55], s[0:1], 0, v[52:53]
	v_lshl_add_u64 v[52:53], s[4:5], 0, v[52:53]
	s_movk_i32 s0, 0xf800
	v_lshl_add_u64 v[52:53], s[76:77], 1, v[52:53]
	s_mov_b32 s1, -1
	v_lshl_add_u64 v[54:55], s[64:65], 1, v[54:55]
	v_lshl_add_u64 v[52:53], v[52:53], 0, s[0:1]
	v_cndmask_b32_e64 v77, v53, v55, s[42:43]
	v_cndmask_b32_e64 v76, v52, v54, s[42:43]
	global_load_dwordx4 v[50:53], v[78:79], off offset:16
	global_load_dwordx4 v[54:57], v[78:79], off
	s_waitcnt vmcnt(1)
	v_pk_mul_f32 v[52:53], v[70:71], v[52:53]
	s_waitcnt vmcnt(0)
	v_pk_mul_f32 v[56:57], v[66:67], v[56:57]
	v_pk_mul_f32 v[54:55], v[68:69], v[54:55]
	v_pk_mul_f32 v[50:51], v[72:73], v[50:51]
	v_pk_mul_f32 v[56:57], v[74:75], v[56:57] op_sel_hi:[0,1]
	v_pk_mul_f32 v[54:55], v[74:75], v[54:55] op_sel_hi:[0,1]
	v_pk_mul_f32 v[66:67], v[74:75], v[52:53] op_sel_hi:[0,1]
	v_pk_mul_f32 v[52:53], v[74:75], v[50:51] op_sel_hi:[0,1]
	v_cvt_pk_bf16_f32 v50, v54, v55
	v_cvt_pk_bf16_f32 v51, v56, v57
	v_cvt_pk_bf16_f32 v52, v52, v53
	v_cvt_pk_bf16_f32 v53, v66, v67
	v_lshl_add_u64 v[66:67], v[144:145], 1, v[76:77]
	global_store_dwordx4 v[66:67], v[50:53], off
	global_load_dwordx4 v[50:53], v[78:79], off offset:144
	s_nop 0
	global_load_dwordx4 v[54:57], v[78:79], off offset:128
	s_waitcnt vmcnt(1)
	v_pk_mul_f32 v[52:53], v[58:59], v[52:53]
	s_waitcnt vmcnt(0)
	v_pk_mul_f32 v[56:57], v[62:63], v[56:57]
	v_pk_mul_f32 v[54:55], v[64:65], v[54:55]
	v_pk_mul_f32 v[50:51], v[60:61], v[50:51]
	v_pk_mul_f32 v[56:57], v[74:75], v[56:57] op_sel_hi:[0,1]
	v_pk_mul_f32 v[54:55], v[74:75], v[54:55] op_sel_hi:[0,1]
	v_pk_mul_f32 v[58:59], v[74:75], v[52:53] op_sel_hi:[0,1]
	v_pk_mul_f32 v[52:53], v[74:75], v[50:51] op_sel_hi:[0,1]
	v_cvt_pk_bf16_f32 v50, v54, v55
	v_cvt_pk_bf16_f32 v51, v56, v57
	v_cvt_pk_bf16_f32 v52, v52, v53
	v_cvt_pk_bf16_f32 v53, v58, v59
	global_store_dwordx4 v[66:67], v[50:53], off offset:64
.LBB0_546:
	s_nop 1
	v_add_f32_e32 v50, v191, v192
	v_fmamk_f32 v50, v50, 0x3a800000, v243
	v_rsq_f32_e32 v58, v50
	s_nop 0
	s_and_b64 vcc, exec, s[44:45]
	s_mov_b64 s[0:1], -1
	s_cbranch_vccnz .LBB0_548
	v_and_b32_e32 v52, 0xff0, v158
	v_readlane_b32 s0, v251, 51
	v_lshlrev_b32_e32 v52, 1, v52
	v_mov_b32_e32 v53, v0
	v_readlane_b32 s1, v251, 52
	v_mov_b32_e32 v155, v0
	v_lshlrev_b32_e32 v54, 1, v188
	v_lshl_add_u64 v[52:53], s[0:1], 0, v[52:53]
	v_lshl_add_u64 v[52:53], v[52:53], 0, v[154:155]
	v_mov_b32_e32 v55, v0
	v_ashrrev_i64 v[50:51], 2, v[158:159]
	v_lshl_add_u64 v[52:53], v[52:53], 0, v[54:55]
	v_lshlrev_b32_e32 v54, 2, v158
	v_and_b32_e32 v50, 0xfffffc00, v50
	v_and_b32_e32 v54, 16, v54
	v_lshl_add_u64 v[52:53], v[52:53], 0, v[54:55]
	v_lshl_add_u64 v[54:55], v[50:51], 0, v[152:153]
	v_lshlrev_b64 v[54:55], 13, v[54:55]
	v_lshl_add_u64 v[54:55], v[52:53], 0, v[54:55]
	v_pk_mul_f32 v[56:57], v[48:49], v[58:59] op_sel_hi:[1,0]
	v_pk_mul_f32 v[60:61], v[46:47], v[58:59] op_sel_hi:[1,0]
	s_mov_b64 s[0:1], 0
	v_cvt_pk_bf16_f32 v59, v60, v61
	v_cvt_pk_bf16_f32 v60, v56, v57
	v_add_co_u32_e32 v56, vcc, s19, v54
	global_store_short v[54:55], v59, off
	s_nop 0
	v_addc_co_u32_e32 v57, vcc, 0, v55, vcc
	global_store_short_d16_hi v[56:57], v59, off
	v_add_co_u32_e32 v56, vcc, s20, v54
	s_nop 1
	v_addc_co_u32_e32 v57, vcc, 0, v55, vcc
	v_add_co_u32_e32 v54, vcc, s21, v54
	global_store_short v[56:57], v60, off
	s_nop 0
	v_addc_co_u32_e32 v55, vcc, 0, v55, vcc
	global_store_short_d16_hi v[54:55], v60, off
	v_lshl_add_u64 v[54:55], v[50:51], 0, v[150:151]
	v_lshlrev_b64 v[54:55], 13, v[54:55]
	v_lshl_add_u64 v[54:55], v[52:53], 0, v[54:55]
	v_pk_mul_f32 v[56:57], v[44:45], v[58:59] op_sel_hi:[1,0]
	v_pk_mul_f32 v[60:61], v[42:43], v[58:59] op_sel_hi:[1,0]
	s_nop 0
	v_cvt_pk_bf16_f32 v59, v60, v61
	v_cvt_pk_bf16_f32 v60, v56, v57
	v_add_co_u32_e32 v56, vcc, s19, v54
	global_store_short v[54:55], v59, off
	s_nop 0
	v_addc_co_u32_e32 v57, vcc, 0, v55, vcc
	global_store_short_d16_hi v[56:57], v59, off
	v_add_co_u32_e32 v56, vcc, s20, v54
	s_nop 1
	v_addc_co_u32_e32 v57, vcc, 0, v55, vcc
	v_add_co_u32_e32 v54, vcc, s21, v54
	global_store_short v[56:57], v60, off
	s_nop 0
	v_addc_co_u32_e32 v55, vcc, 0, v55, vcc
	global_store_short_d16_hi v[54:55], v60, off
	v_lshl_add_u64 v[54:55], v[50:51], 0, v[148:149]
	v_lshlrev_b64 v[54:55], 13, v[54:55]
	v_lshl_add_u64 v[54:55], v[52:53], 0, v[54:55]
	v_pk_mul_f32 v[56:57], v[40:41], v[58:59] op_sel_hi:[1,0]
	v_pk_mul_f32 v[60:61], v[38:39], v[58:59] op_sel_hi:[1,0]
	v_lshl_add_u64 v[50:51], v[50:51], 0, v[146:147]
	v_cvt_pk_bf16_f32 v59, v60, v61
	v_cvt_pk_bf16_f32 v60, v56, v57
	v_add_co_u32_e32 v56, vcc, s19, v54
	global_store_short v[54:55], v59, off
	s_nop 0
	v_addc_co_u32_e32 v57, vcc, 0, v55, vcc
	global_store_short_d16_hi v[56:57], v59, off
	v_add_co_u32_e32 v56, vcc, s20, v54
	v_lshlrev_b64 v[50:51], 13, v[50:51]
	s_nop 0
	v_addc_co_u32_e32 v57, vcc, 0, v55, vcc
	v_add_co_u32_e32 v54, vcc, s21, v54
	v_lshl_add_u64 v[50:51], v[52:53], 0, v[50:51]
	s_nop 0
	v_addc_co_u32_e32 v55, vcc, 0, v55, vcc
	global_store_short_d16_hi v[54:55], v60, off
	v_pk_mul_f32 v[52:53], v[36:37], v[58:59] op_sel_hi:[1,0]
	v_pk_mul_f32 v[54:55], v[34:35], v[58:59] op_sel_hi:[1,0]
	global_store_short v[56:57], v60, off
	v_cvt_pk_bf16_f32 v54, v54, v55
	v_cvt_pk_bf16_f32 v55, v52, v53
	v_add_co_u32_e32 v52, vcc, 0x2000, v50
	global_store_short v[50:51], v54, off
	s_nop 0
	v_addc_co_u32_e32 v53, vcc, 0, v51, vcc
	global_store_short_d16_hi v[52:53], v54, off
	v_add_co_u32_e32 v52, vcc, 0x4000, v50
	s_nop 1
	v_addc_co_u32_e32 v53, vcc, 0, v51, vcc
	v_add_co_u32_e32 v50, vcc, 0x6000, v50
	global_store_short v[52:53], v55, off
	s_nop 0
	v_addc_co_u32_e32 v51, vcc, 0, v51, vcc
	global_store_short_d16_hi v[50:51], v55, off
.LBB0_548:
	s_andn2_b64 vcc, exec, s[0:1]
	s_cbranch_vccnz .LBB0_550
	v_pk_mul_f32 v[50:51], v[48:49], v[58:59] op_sel_hi:[1,0]
	v_pk_mul_f32 v[52:53], v[46:47], v[58:59] op_sel_hi:[1,0]
	v_pk_mul_f32 v[46:47], v[50:51], v[50:51]
	v_pk_mul_f32 v[48:49], v[52:53], v[52:53]
	v_pk_mul_f32 v[56:57], v[42:43], v[58:59] op_sel_hi:[1,0]
	v_pk_mov_b32 v[54:55], v[48:49], v[46:47] op_sel:[1,0]
	v_mov_b32_e32 v49, v47
	v_pk_add_f32 v[46:47], v[54:55], v[48:49]
	v_pk_mul_f32 v[54:55], v[44:45], v[58:59] op_sel_hi:[1,0]
	v_pk_mul_f32 v[44:45], v[56:57], v[56:57]
	v_pk_mul_f32 v[42:43], v[54:55], v[54:55]
	v_pk_mul_f32 v[48:49], v[38:39], v[58:59] op_sel_hi:[1,0]
	v_pk_add_f32 v[60:61], v[46:47], v[46:47] op_sel_hi:[0,1]
	v_pk_mov_b32 v[46:47], v[44:45], v[42:43] op_sel:[1,0]
	v_mov_b32_e32 v45, v43
	v_mul_f32_e32 v38, v48, v48
	v_pk_add_f32 v[42:43], v[46:47], v[44:45]
	v_pk_mul_f32 v[46:47], v[40:41], v[58:59] op_sel_hi:[1,0]
	v_pk_fma_f32 v[38:39], v[48:49], v[48:49], v[38:39] op_sel_hi:[1,1,0]
	v_pk_add_f32 v[62:63], v[42:43], v[42:43] op_sel_hi:[0,1]
	v_mul_f32_e32 v38, v46, v46
	v_pk_fma_f32 v[40:41], v[46:47], v[46:47], v[38:39] op_sel_hi:[1,1,0]
	v_pk_mul_f32 v[42:43], v[36:37], v[58:59] op_sel_hi:[1,0]
	v_pk_mul_f32 v[44:45], v[34:35], v[58:59] op_sel_hi:[1,0]
	v_mul_f32_e32 v60, v42, v42
	v_mul_f32_e32 v38, v44, v44
	v_mul_f32_e32 v40, v45, v45
	v_mul_f32_e32 v62, v43, v43
	v_pk_add_f32 v[34:35], v[38:39], v[40:41]
	v_pk_add_f32 v[36:37], v[60:61], v[62:63]
	s_and_b64 s[0:1], s[42:43], exec
	v_pk_add_f32 v[34:35], v[34:35], v[36:37]
	s_nop 0
	v_add_f32_e32 v34, v34, v35
	ds_bpermute_b32 v35, v185, v34
	s_waitcnt lgkmcnt(0)
	v_add_f32_e32 v34, v34, v35
	ds_bpermute_b32 v35, v184, v34
	s_waitcnt lgkmcnt(0)
	v_add_f32_e32 v34, v34, v35
	v_fmamk_f32 v34, v34, 0x3c800000, v243
	s_nop 1
	s_cselect_b32 s0, s27, s39
	s_cselect_b32 s1, s26, s38
	v_rsq_f32_e32 v36, v34
	s_nop 0
	v_mov_b32_e32 v34, s1
	v_mov_b32_e32 v35, s0
	v_mul_f32_e32 v37, 0x3e38aa3b, v36
	v_readlane_b32 s0, v251, 43
	v_cndmask_b32_e64 v58, v36, v37, s[42:43]
	v_lshlrev_b64 v[36:37], 11, v[158:159]
	v_readlane_b32 s1, v251, 44
	v_lshl_add_u64 v[62:63], v[144:145], 2, v[34:35]
	s_nop 0
	v_lshl_add_u64 v[38:39], s[0:1], 0, v[36:37]
	v_lshl_add_u64 v[36:37], s[4:5], 0, v[36:37]
	s_movk_i32 s0, 0xf800
	v_lshl_add_u64 v[36:37], s[76:77], 1, v[36:37]
	s_mov_b32 s1, -1
	v_lshl_add_u64 v[38:39], s[64:65], 1, v[38:39]
	v_lshl_add_u64 v[36:37], v[36:37], 0, s[0:1]
	v_cndmask_b32_e64 v61, v37, v39, s[42:43]
	v_cndmask_b32_e64 v60, v36, v38, s[42:43]
	global_load_dwordx4 v[34:37], v[62:63], off offset:16
	global_load_dwordx4 v[38:41], v[62:63], off
	s_waitcnt vmcnt(1)
	v_pk_mul_f32 v[36:37], v[54:55], v[36:37]
	s_waitcnt vmcnt(0)
	v_pk_mul_f32 v[40:41], v[50:51], v[40:41]
	v_pk_mul_f32 v[38:39], v[52:53], v[38:39]
	v_pk_mul_f32 v[34:35], v[56:57], v[34:35]
	v_pk_mul_f32 v[40:41], v[58:59], v[40:41] op_sel_hi:[0,1]
	v_pk_mul_f32 v[38:39], v[58:59], v[38:39] op_sel_hi:[0,1]
	v_pk_mul_f32 v[50:51], v[58:59], v[36:37] op_sel_hi:[0,1]
	v_pk_mul_f32 v[36:37], v[58:59], v[34:35] op_sel_hi:[0,1]
	v_cvt_pk_bf16_f32 v34, v38, v39
	v_cvt_pk_bf16_f32 v35, v40, v41
	v_cvt_pk_bf16_f32 v36, v36, v37
	v_cvt_pk_bf16_f32 v37, v50, v51
	v_lshl_add_u64 v[50:51], v[144:145], 1, v[60:61]
	global_store_dwordx4 v[50:51], v[34:37], off
	global_load_dwordx4 v[34:37], v[62:63], off offset:144
	s_nop 0
	global_load_dwordx4 v[38:41], v[62:63], off offset:128
	s_waitcnt vmcnt(1)
	v_pk_mul_f32 v[36:37], v[42:43], v[36:37]
	s_waitcnt vmcnt(0)
	v_pk_mul_f32 v[40:41], v[46:47], v[40:41]
	v_pk_mul_f32 v[38:39], v[48:49], v[38:39]
	v_pk_mul_f32 v[34:35], v[44:45], v[34:35]
	v_pk_mul_f32 v[40:41], v[58:59], v[40:41] op_sel_hi:[0,1]
	v_pk_mul_f32 v[38:39], v[58:59], v[38:39] op_sel_hi:[0,1]
	v_pk_mul_f32 v[42:43], v[58:59], v[36:37] op_sel_hi:[0,1]
	v_pk_mul_f32 v[36:37], v[58:59], v[34:35] op_sel_hi:[0,1]
	v_cvt_pk_bf16_f32 v34, v38, v39
	v_cvt_pk_bf16_f32 v35, v40, v41
	v_cvt_pk_bf16_f32 v36, v36, v37
	v_cvt_pk_bf16_f32 v37, v42, v43
	global_store_dwordx4 v[50:51], v[34:37], off offset:64
.LBB0_550:
	s_nop 1
	v_add_f32_e32 v34, v189, v190
	v_fmamk_f32 v34, v34, 0x3a800000, v243
	v_rsq_f32_e32 v42, v34
	s_nop 0
	s_and_b64 vcc, exec, s[44:45]
	s_mov_b64 s[0:1], -1
	s_cbranch_vccnz .LBB0_552
	v_and_b32_e32 v36, 0xff0, v156
	v_readlane_b32 s0, v251, 51
	v_lshlrev_b32_e32 v36, 1, v36
	v_mov_b32_e32 v37, v0
	v_readlane_b32 s1, v251, 52
	v_mov_b32_e32 v155, v0
	v_lshlrev_b32_e32 v38, 1, v188
	v_lshl_add_u64 v[36:37], s[0:1], 0, v[36:37]
	v_lshl_add_u64 v[36:37], v[36:37], 0, v[154:155]
	v_mov_b32_e32 v39, v0
	v_ashrrev_i64 v[34:35], 2, v[156:157]
	v_lshl_add_u64 v[36:37], v[36:37], 0, v[38:39]
	v_lshlrev_b32_e32 v38, 2, v156
	v_and_b32_e32 v34, 0xfffffc00, v34
	v_and_b32_e32 v38, 16, v38
	v_lshl_add_u64 v[36:37], v[36:37], 0, v[38:39]
	v_lshl_add_u64 v[38:39], v[34:35], 0, v[152:153]
	v_lshlrev_b64 v[38:39], 13, v[38:39]
	v_lshl_add_u64 v[38:39], v[36:37], 0, v[38:39]
	v_pk_mul_f32 v[40:41], v[32:33], v[42:43] op_sel_hi:[1,0]
	v_pk_mul_f32 v[44:45], v[30:31], v[42:43] op_sel_hi:[1,0]
	s_mov_b64 s[0:1], 0
	v_cvt_pk_bf16_f32 v43, v44, v45
	v_cvt_pk_bf16_f32 v44, v40, v41
	v_add_co_u32_e32 v40, vcc, s19, v38
	global_store_short v[38:39], v43, off
	s_nop 0
	v_addc_co_u32_e32 v41, vcc, 0, v39, vcc
	global_store_short_d16_hi v[40:41], v43, off
	v_add_co_u32_e32 v40, vcc, s20, v38
	s_nop 1
	v_addc_co_u32_e32 v41, vcc, 0, v39, vcc
	v_add_co_u32_e32 v38, vcc, s21, v38
	global_store_short v[40:41], v44, off
	s_nop 0
	v_addc_co_u32_e32 v39, vcc, 0, v39, vcc
	global_store_short_d16_hi v[38:39], v44, off
	v_lshl_add_u64 v[38:39], v[34:35], 0, v[150:151]
	v_lshlrev_b64 v[38:39], 13, v[38:39]
	v_lshl_add_u64 v[38:39], v[36:37], 0, v[38:39]
	v_pk_mul_f32 v[40:41], v[28:29], v[42:43] op_sel_hi:[1,0]
	v_pk_mul_f32 v[44:45], v[26:27], v[42:43] op_sel_hi:[1,0]
	s_nop 0
	v_cvt_pk_bf16_f32 v43, v44, v45
	v_cvt_pk_bf16_f32 v44, v40, v41
	v_add_co_u32_e32 v40, vcc, s19, v38
	global_store_short v[38:39], v43, off
	s_nop 0
	v_addc_co_u32_e32 v41, vcc, 0, v39, vcc
	global_store_short_d16_hi v[40:41], v43, off
	v_add_co_u32_e32 v40, vcc, s20, v38
	s_nop 1
	v_addc_co_u32_e32 v41, vcc, 0, v39, vcc
	v_add_co_u32_e32 v38, vcc, s21, v38
	global_store_short v[40:41], v44, off
	s_nop 0
	v_addc_co_u32_e32 v39, vcc, 0, v39, vcc
	global_store_short_d16_hi v[38:39], v44, off
	v_lshl_add_u64 v[38:39], v[34:35], 0, v[148:149]
	v_lshlrev_b64 v[38:39], 13, v[38:39]
	v_lshl_add_u64 v[38:39], v[36:37], 0, v[38:39]
	v_pk_mul_f32 v[40:41], v[24:25], v[42:43] op_sel_hi:[1,0]
	v_pk_mul_f32 v[44:45], v[22:23], v[42:43] op_sel_hi:[1,0]
	v_lshl_add_u64 v[34:35], v[34:35], 0, v[146:147]
	v_cvt_pk_bf16_f32 v43, v44, v45
	v_cvt_pk_bf16_f32 v44, v40, v41
	v_add_co_u32_e32 v40, vcc, s19, v38
	global_store_short v[38:39], v43, off
	s_nop 0
	v_addc_co_u32_e32 v41, vcc, 0, v39, vcc
	global_store_short_d16_hi v[40:41], v43, off
	v_add_co_u32_e32 v40, vcc, s20, v38
	v_lshlrev_b64 v[34:35], 13, v[34:35]
	s_nop 0
	v_addc_co_u32_e32 v41, vcc, 0, v39, vcc
	v_add_co_u32_e32 v38, vcc, s21, v38
	v_lshl_add_u64 v[34:35], v[36:37], 0, v[34:35]
	s_nop 0
	v_addc_co_u32_e32 v39, vcc, 0, v39, vcc
	global_store_short_d16_hi v[38:39], v44, off
	v_pk_mul_f32 v[36:37], v[20:21], v[42:43] op_sel_hi:[1,0]
	v_pk_mul_f32 v[38:39], v[18:19], v[42:43] op_sel_hi:[1,0]
	global_store_short v[40:41], v44, off
	v_cvt_pk_bf16_f32 v38, v38, v39
	v_cvt_pk_bf16_f32 v39, v36, v37
	v_add_co_u32_e32 v36, vcc, 0x2000, v34
	global_store_short v[34:35], v38, off
	s_nop 0
	v_addc_co_u32_e32 v37, vcc, 0, v35, vcc
	global_store_short_d16_hi v[36:37], v38, off
	v_add_co_u32_e32 v36, vcc, 0x4000, v34
	s_nop 1
	v_addc_co_u32_e32 v37, vcc, 0, v35, vcc
	v_add_co_u32_e32 v34, vcc, 0x6000, v34
	global_store_short v[36:37], v39, off
	s_nop 0
	v_addc_co_u32_e32 v35, vcc, 0, v35, vcc
	global_store_short_d16_hi v[34:35], v39, off
.LBB0_552:
	s_andn2_b64 vcc, exec, s[0:1]
	s_cbranch_vccnz .LBB0_554
	v_pk_mul_f32 v[34:35], v[32:33], v[42:43] op_sel_hi:[1,0]
	v_pk_mul_f32 v[36:37], v[30:31], v[42:43] op_sel_hi:[1,0]
	v_pk_mul_f32 v[30:31], v[34:35], v[34:35]
	v_pk_mul_f32 v[32:33], v[36:37], v[36:37]
	v_pk_mul_f32 v[40:41], v[26:27], v[42:43] op_sel_hi:[1,0]
	v_pk_mov_b32 v[38:39], v[32:33], v[30:31] op_sel:[1,0]
	v_mov_b32_e32 v33, v31
	v_pk_add_f32 v[30:31], v[38:39], v[32:33]
	v_pk_mul_f32 v[38:39], v[28:29], v[42:43] op_sel_hi:[1,0]
	v_pk_mul_f32 v[28:29], v[40:41], v[40:41]
	v_pk_mul_f32 v[26:27], v[38:39], v[38:39]
	v_pk_mul_f32 v[32:33], v[22:23], v[42:43] op_sel_hi:[1,0]
	v_pk_add_f32 v[44:45], v[30:31], v[30:31] op_sel_hi:[0,1]
	v_pk_mov_b32 v[30:31], v[28:29], v[26:27] op_sel:[1,0]
	v_mov_b32_e32 v29, v27
	v_mul_f32_e32 v22, v32, v32
	v_pk_add_f32 v[26:27], v[30:31], v[28:29]
	v_pk_mul_f32 v[30:31], v[24:25], v[42:43] op_sel_hi:[1,0]
	v_pk_fma_f32 v[22:23], v[32:33], v[32:33], v[22:23] op_sel_hi:[1,1,0]
	v_pk_add_f32 v[46:47], v[26:27], v[26:27] op_sel_hi:[0,1]
	v_mul_f32_e32 v22, v30, v30
	v_pk_fma_f32 v[24:25], v[30:31], v[30:31], v[22:23] op_sel_hi:[1,1,0]
	v_pk_mul_f32 v[26:27], v[20:21], v[42:43] op_sel_hi:[1,0]
	v_pk_mul_f32 v[28:29], v[18:19], v[42:43] op_sel_hi:[1,0]
	v_mul_f32_e32 v44, v26, v26
	v_mul_f32_e32 v22, v28, v28
	v_mul_f32_e32 v24, v29, v29
	v_mul_f32_e32 v46, v27, v27
	v_pk_add_f32 v[18:19], v[22:23], v[24:25]
	v_pk_add_f32 v[20:21], v[44:45], v[46:47]
	s_and_b64 s[0:1], s[42:43], exec
	v_pk_add_f32 v[18:19], v[18:19], v[20:21]
	s_nop 0
	v_add_f32_e32 v18, v18, v19
	ds_bpermute_b32 v19, v185, v18
	s_waitcnt lgkmcnt(0)
	v_add_f32_e32 v18, v18, v19
	ds_bpermute_b32 v19, v184, v18
	s_waitcnt lgkmcnt(0)
	v_add_f32_e32 v18, v18, v19
	v_fmamk_f32 v18, v18, 0x3c800000, v243
	s_nop 1
	s_cselect_b32 s0, s27, s39
	s_cselect_b32 s1, s26, s38
	v_rsq_f32_e32 v20, v18
	s_nop 0
	v_mov_b32_e32 v18, s1
	v_mov_b32_e32 v19, s0
	v_mul_f32_e32 v21, 0x3e38aa3b, v20
	v_readlane_b32 s0, v251, 43
	v_cndmask_b32_e64 v42, v20, v21, s[42:43]
	v_lshlrev_b64 v[20:21], 11, v[156:157]
	v_readlane_b32 s1, v251, 44
	v_lshl_add_u64 v[46:47], v[144:145], 2, v[18:19]
	s_nop 0
	v_lshl_add_u64 v[22:23], s[0:1], 0, v[20:21]
	v_lshl_add_u64 v[20:21], s[4:5], 0, v[20:21]
	s_movk_i32 s0, 0xf800
	v_lshl_add_u64 v[20:21], s[76:77], 1, v[20:21]
	s_mov_b32 s1, -1
	v_lshl_add_u64 v[22:23], s[64:65], 1, v[22:23]
	v_lshl_add_u64 v[20:21], v[20:21], 0, s[0:1]
	v_cndmask_b32_e64 v45, v21, v23, s[42:43]
	v_cndmask_b32_e64 v44, v20, v22, s[42:43]
	global_load_dwordx4 v[18:21], v[46:47], off offset:16
	global_load_dwordx4 v[22:25], v[46:47], off
	s_waitcnt vmcnt(1)
	v_pk_mul_f32 v[20:21], v[38:39], v[20:21]
	s_waitcnt vmcnt(0)
	v_pk_mul_f32 v[24:25], v[34:35], v[24:25]
	v_pk_mul_f32 v[22:23], v[36:37], v[22:23]
	v_pk_mul_f32 v[18:19], v[40:41], v[18:19]
	v_pk_mul_f32 v[24:25], v[42:43], v[24:25] op_sel_hi:[0,1]
	v_pk_mul_f32 v[22:23], v[42:43], v[22:23] op_sel_hi:[0,1]
	v_pk_mul_f32 v[34:35], v[42:43], v[20:21] op_sel_hi:[0,1]
	v_pk_mul_f32 v[20:21], v[42:43], v[18:19] op_sel_hi:[0,1]
	v_cvt_pk_bf16_f32 v18, v22, v23
	v_cvt_pk_bf16_f32 v19, v24, v25
	v_cvt_pk_bf16_f32 v20, v20, v21
	v_cvt_pk_bf16_f32 v21, v34, v35
	v_lshl_add_u64 v[34:35], v[144:145], 1, v[44:45]
	global_store_dwordx4 v[34:35], v[18:21], off
	global_load_dwordx4 v[18:21], v[46:47], off offset:144
	s_nop 0
	global_load_dwordx4 v[22:25], v[46:47], off offset:128
	s_waitcnt vmcnt(1)
	v_pk_mul_f32 v[20:21], v[26:27], v[20:21]
	s_waitcnt vmcnt(0)
	v_pk_mul_f32 v[24:25], v[30:31], v[24:25]
	v_pk_mul_f32 v[22:23], v[32:33], v[22:23]
	v_pk_mul_f32 v[18:19], v[28:29], v[18:19]
	v_pk_mul_f32 v[24:25], v[42:43], v[24:25] op_sel_hi:[0,1]
	v_pk_mul_f32 v[22:23], v[42:43], v[22:23] op_sel_hi:[0,1]
	v_pk_mul_f32 v[26:27], v[42:43], v[20:21] op_sel_hi:[0,1]
	v_pk_mul_f32 v[20:21], v[42:43], v[18:19] op_sel_hi:[0,1]
	v_cvt_pk_bf16_f32 v18, v22, v23
	v_cvt_pk_bf16_f32 v19, v24, v25
	v_cvt_pk_bf16_f32 v20, v20, v21
	v_cvt_pk_bf16_f32 v21, v26, v27
	global_store_dwordx4 v[34:35], v[18:21], off offset:64
.LBB0_554:
	s_waitcnt lgkmcnt(0)
	s_nop 0
	v_add_f32_e32 v18, v186, v187
	v_fmamk_f32 v18, v18, 0x3a800000, v243
	v_rsq_f32_e32 v26, v18
	s_nop 0
	s_and_b64 vcc, exec, s[44:45]
	s_mov_b64 s[0:1], -1
	s_cbranch_vccnz .LBB0_556
	v_and_b32_e32 v20, 0xff0, v142
	v_readlane_b32 s0, v251, 51
	v_lshlrev_b32_e32 v20, 1, v20
	v_mov_b32_e32 v21, v0
	v_readlane_b32 s1, v251, 52
	v_mov_b32_e32 v155, v0
	v_lshlrev_b32_e32 v22, 1, v188
	v_lshl_add_u64 v[20:21], s[0:1], 0, v[20:21]
	v_lshl_add_u64 v[20:21], v[20:21], 0, v[154:155]
	v_mov_b32_e32 v23, v0
	v_ashrrev_i64 v[18:19], 2, v[142:143]
	v_lshl_add_u64 v[20:21], v[20:21], 0, v[22:23]
	v_lshlrev_b32_e32 v22, 2, v142
	v_and_b32_e32 v18, 0xfffffc00, v18
	v_and_b32_e32 v22, 16, v22
	v_lshl_add_u64 v[20:21], v[20:21], 0, v[22:23]
	v_lshl_add_u64 v[22:23], v[18:19], 0, v[152:153]
	v_lshlrev_b64 v[22:23], 13, v[22:23]
	v_lshl_add_u64 v[22:23], v[20:21], 0, v[22:23]
	v_pk_mul_f32 v[24:25], v[16:17], v[26:27] op_sel_hi:[1,0]
	v_pk_mul_f32 v[28:29], v[14:15], v[26:27] op_sel_hi:[1,0]
	s_mov_b64 s[0:1], 0
	v_cvt_pk_bf16_f32 v27, v28, v29
	v_cvt_pk_bf16_f32 v28, v24, v25
	v_add_co_u32_e32 v24, vcc, s19, v22
	global_store_short v[22:23], v27, off
	s_nop 0
	v_addc_co_u32_e32 v25, vcc, 0, v23, vcc
	global_store_short_d16_hi v[24:25], v27, off
	v_add_co_u32_e32 v24, vcc, s20, v22
	s_nop 1
	v_addc_co_u32_e32 v25, vcc, 0, v23, vcc
	v_add_co_u32_e32 v22, vcc, s21, v22
	global_store_short v[24:25], v28, off
	s_nop 0
	v_addc_co_u32_e32 v23, vcc, 0, v23, vcc
	global_store_short_d16_hi v[22:23], v28, off
	v_lshl_add_u64 v[22:23], v[18:19], 0, v[150:151]
	v_lshlrev_b64 v[22:23], 13, v[22:23]
	v_lshl_add_u64 v[22:23], v[20:21], 0, v[22:23]
	v_pk_mul_f32 v[24:25], v[12:13], v[26:27] op_sel_hi:[1,0]
	v_pk_mul_f32 v[28:29], v[10:11], v[26:27] op_sel_hi:[1,0]
	s_nop 0
	v_cvt_pk_bf16_f32 v27, v28, v29
	v_cvt_pk_bf16_f32 v28, v24, v25
	v_add_co_u32_e32 v24, vcc, s19, v22
	global_store_short v[22:23], v27, off
	s_nop 0
	v_addc_co_u32_e32 v25, vcc, 0, v23, vcc
	global_store_short_d16_hi v[24:25], v27, off
	v_add_co_u32_e32 v24, vcc, s20, v22
	s_nop 1
	v_addc_co_u32_e32 v25, vcc, 0, v23, vcc
	v_add_co_u32_e32 v22, vcc, s21, v22
	global_store_short v[24:25], v28, off
	s_nop 0
	v_addc_co_u32_e32 v23, vcc, 0, v23, vcc
	global_store_short_d16_hi v[22:23], v28, off
	v_lshl_add_u64 v[22:23], v[18:19], 0, v[148:149]
	v_lshlrev_b64 v[22:23], 13, v[22:23]
	v_lshl_add_u64 v[22:23], v[20:21], 0, v[22:23]
	v_pk_mul_f32 v[24:25], v[8:9], v[26:27] op_sel_hi:[1,0]
	v_pk_mul_f32 v[28:29], v[6:7], v[26:27] op_sel_hi:[1,0]
	v_lshl_add_u64 v[18:19], v[18:19], 0, v[146:147]
	v_cvt_pk_bf16_f32 v27, v28, v29
	v_cvt_pk_bf16_f32 v28, v24, v25
	v_add_co_u32_e32 v24, vcc, s19, v22
	global_store_short v[22:23], v27, off
	s_nop 0
	v_addc_co_u32_e32 v25, vcc, 0, v23, vcc
	global_store_short_d16_hi v[24:25], v27, off
	v_add_co_u32_e32 v24, vcc, s20, v22
	v_lshlrev_b64 v[18:19], 13, v[18:19]
	s_nop 0
	v_addc_co_u32_e32 v25, vcc, 0, v23, vcc
	v_add_co_u32_e32 v22, vcc, s21, v22
	v_lshl_add_u64 v[18:19], v[20:21], 0, v[18:19]
	s_nop 0
	v_addc_co_u32_e32 v23, vcc, 0, v23, vcc
	global_store_short_d16_hi v[22:23], v28, off
	v_pk_mul_f32 v[20:21], v[4:5], v[26:27] op_sel_hi:[1,0]
	v_pk_mul_f32 v[22:23], v[2:3], v[26:27] op_sel_hi:[1,0]
	global_store_short v[24:25], v28, off
	v_cvt_pk_bf16_f32 v22, v22, v23
	v_cvt_pk_bf16_f32 v23, v20, v21
	v_add_co_u32_e32 v20, vcc, 0x2000, v18
	global_store_short v[18:19], v22, off
	s_nop 0
	v_addc_co_u32_e32 v21, vcc, 0, v19, vcc
	global_store_short_d16_hi v[20:21], v22, off
	v_add_co_u32_e32 v20, vcc, 0x4000, v18
	s_nop 1
	v_addc_co_u32_e32 v21, vcc, 0, v19, vcc
	v_add_co_u32_e32 v18, vcc, 0x6000, v18
	global_store_short v[20:21], v23, off
	s_nop 0
	v_addc_co_u32_e32 v19, vcc, 0, v19, vcc
	global_store_short_d16_hi v[18:19], v23, off
.LBB0_556:
	s_andn2_b64 vcc, exec, s[0:1]
	s_cbranch_vccnz .LBB0_558
	v_pk_mul_f32 v[18:19], v[16:17], v[26:27] op_sel_hi:[1,0]
	v_pk_mul_f32 v[20:21], v[14:15], v[26:27] op_sel_hi:[1,0]
	v_pk_mul_f32 v[14:15], v[18:19], v[18:19]
	v_pk_mul_f32 v[16:17], v[20:21], v[20:21]
	v_pk_mul_f32 v[24:25], v[10:11], v[26:27] op_sel_hi:[1,0]
	v_pk_mov_b32 v[22:23], v[16:17], v[14:15] op_sel:[1,0]
	v_mov_b32_e32 v17, v15
	v_pk_add_f32 v[14:15], v[22:23], v[16:17]
	v_pk_mul_f32 v[22:23], v[12:13], v[26:27] op_sel_hi:[1,0]
	v_pk_mul_f32 v[12:13], v[24:25], v[24:25]
	v_pk_mul_f32 v[10:11], v[22:23], v[22:23]
	v_pk_mul_f32 v[16:17], v[6:7], v[26:27] op_sel_hi:[1,0]
	v_pk_add_f32 v[28:29], v[14:15], v[14:15] op_sel_hi:[0,1]
	v_pk_mov_b32 v[14:15], v[12:13], v[10:11] op_sel:[1,0]
	v_mov_b32_e32 v13, v11
	v_mul_f32_e32 v6, v16, v16
	v_pk_add_f32 v[10:11], v[14:15], v[12:13]
	v_pk_mul_f32 v[14:15], v[8:9], v[26:27] op_sel_hi:[1,0]
	v_pk_fma_f32 v[6:7], v[16:17], v[16:17], v[6:7] op_sel_hi:[1,1,0]
	v_pk_add_f32 v[30:31], v[10:11], v[10:11] op_sel_hi:[0,1]
	v_mul_f32_e32 v6, v14, v14
	v_pk_fma_f32 v[8:9], v[14:15], v[14:15], v[6:7] op_sel_hi:[1,1,0]
	v_pk_mul_f32 v[10:11], v[4:5], v[26:27] op_sel_hi:[1,0]
	v_pk_mul_f32 v[12:13], v[2:3], v[26:27] op_sel_hi:[1,0]
	v_mul_f32_e32 v28, v10, v10
	v_mul_f32_e32 v6, v12, v12
	v_mul_f32_e32 v8, v13, v13
	v_mul_f32_e32 v30, v11, v11
	v_pk_add_f32 v[2:3], v[6:7], v[8:9]
	v_pk_add_f32 v[4:5], v[28:29], v[30:31]
	s_and_b64 s[0:1], s[42:43], exec
	v_pk_add_f32 v[2:3], v[2:3], v[4:5]
	s_nop 0
	v_add_f32_e32 v2, v2, v3
	ds_bpermute_b32 v3, v185, v2
	s_waitcnt lgkmcnt(0)
	v_add_f32_e32 v2, v2, v3
	ds_bpermute_b32 v3, v184, v2
	s_waitcnt lgkmcnt(0)
	v_add_f32_e32 v2, v2, v3
	v_fmamk_f32 v2, v2, 0x3c800000, v243
	s_nop 1
	s_cselect_b32 s0, s27, s39
	s_cselect_b32 s1, s26, s38
	v_rsq_f32_e32 v4, v2
	s_nop 0
	v_mov_b32_e32 v2, s1
	v_mov_b32_e32 v3, s0
	v_mul_f32_e32 v5, 0x3e38aa3b, v4
	v_readlane_b32 s0, v251, 43
	v_cndmask_b32_e64 v26, v4, v5, s[42:43]
	v_lshlrev_b64 v[4:5], 11, v[142:143]
	v_readlane_b32 s1, v251, 44
	v_lshl_add_u64 v[30:31], v[144:145], 2, v[2:3]
	s_nop 0
	v_lshl_add_u64 v[6:7], s[0:1], 0, v[4:5]
	v_lshl_add_u64 v[4:5], s[4:5], 0, v[4:5]
	s_movk_i32 s0, 0xf800
	v_lshl_add_u64 v[4:5], s[76:77], 1, v[4:5]
	s_mov_b32 s1, -1
	v_lshl_add_u64 v[6:7], s[64:65], 1, v[6:7]
	v_lshl_add_u64 v[4:5], v[4:5], 0, s[0:1]
	v_cndmask_b32_e64 v29, v5, v7, s[42:43]
	v_cndmask_b32_e64 v28, v4, v6, s[42:43]
	global_load_dwordx4 v[2:5], v[30:31], off offset:16
	global_load_dwordx4 v[6:9], v[30:31], off
	s_waitcnt vmcnt(1)
	v_pk_mul_f32 v[4:5], v[22:23], v[4:5]
	s_waitcnt vmcnt(0)
	v_pk_mul_f32 v[8:9], v[18:19], v[8:9]
	v_pk_mul_f32 v[6:7], v[20:21], v[6:7]
	v_pk_mul_f32 v[2:3], v[24:25], v[2:3]
	v_pk_mul_f32 v[8:9], v[26:27], v[8:9] op_sel_hi:[0,1]
	v_pk_mul_f32 v[6:7], v[26:27], v[6:7] op_sel_hi:[0,1]
	v_pk_mul_f32 v[18:19], v[26:27], v[4:5] op_sel_hi:[0,1]
	v_pk_mul_f32 v[4:5], v[26:27], v[2:3] op_sel_hi:[0,1]
	v_cvt_pk_bf16_f32 v2, v6, v7
	v_cvt_pk_bf16_f32 v3, v8, v9
	v_cvt_pk_bf16_f32 v4, v4, v5
	v_cvt_pk_bf16_f32 v5, v18, v19
	v_lshl_add_u64 v[18:19], v[144:145], 1, v[28:29]
	global_store_dwordx4 v[18:19], v[2:5], off
	global_load_dwordx4 v[2:5], v[30:31], off offset:144
	s_nop 0
	global_load_dwordx4 v[6:9], v[30:31], off offset:128
	s_waitcnt vmcnt(1)
	v_pk_mul_f32 v[4:5], v[10:11], v[4:5]
	s_waitcnt vmcnt(0)
	v_pk_mul_f32 v[8:9], v[14:15], v[8:9]
	v_pk_mul_f32 v[6:7], v[16:17], v[6:7]
	v_pk_mul_f32 v[2:3], v[12:13], v[2:3]
	v_pk_mul_f32 v[8:9], v[26:27], v[8:9] op_sel_hi:[0,1]
	v_pk_mul_f32 v[6:7], v[26:27], v[6:7] op_sel_hi:[0,1]
	v_pk_mul_f32 v[10:11], v[26:27], v[4:5] op_sel_hi:[0,1]
	v_pk_mul_f32 v[4:5], v[26:27], v[2:3] op_sel_hi:[0,1]
	v_cvt_pk_bf16_f32 v2, v6, v7
	v_cvt_pk_bf16_f32 v3, v8, v9
	v_cvt_pk_bf16_f32 v4, v4, v5
	v_cvt_pk_bf16_f32 v5, v10, v11
	global_store_dwordx4 v[18:19], v[2:5], off offset:64

.LBB0_934:
	s_mul_hi_i32 s0, s31, 0x78787879
	s_lshr_b32 s1, s0, 31
	s_ashr_i32 s0, s0, 3
	s_add_i32 s0, s0, s1
	s_mul_i32 s1, s0, 17
	v_mov_b32_e32 v136, v200
	v_mov_b32_e32 v203, v1
	s_sub_i32 s12, s31, s1
	s_mul_i32 s31, s12, 0xfe
	v_lshlrev_b32_e32 v130, 2, v203
	v_readlane_b32 s1, v254, 58
	s_add_i32 s31, s31, -2
	v_mov_b32_e32 v144, 0xfff
	v_add_u32_e32 v199, s1, v130
	v_add_u32_e32 v190, s31, v199
	v_lshl_add_u32 v130, v136, 6, v130
	s_lshl_b32 s1, s0, 12
	v_xor_b32_e32 v138, 64, v130
	v_xor_b32_e32 v137, 0x80, v130
	v_med3_i32 v130, v190, 0, v144
	v_or_b32_e32 v130, s1, v130
	v_lshlrev_b32_e32 v134, 2, v136
	v_ashrrev_i32_e32 v131, 31, v130
	v_readlane_b32 s24, v254, 45
	v_ashrrev_i32_e32 v135, 31, v134
	v_lshlrev_b64 v[130:131], 6, v[130:131]
	v_readlane_b32 s25, v254, 46
	s_nop 1
	v_lshl_add_u64 v[132:133], s[24:25], 0, v[130:131]
	v_lshlrev_b64 v[130:131], 2, v[134:135]
	v_lshl_add_u64 v[132:133], v[132:133], 0, v[130:131]
	global_load_dwordx4 v[146:149], v[132:133], off
	v_or_b32_e32 v192, 1, v190
	v_med3_i32 v192, v192, 0, v144
	v_or_b32_e32 v192, s1, v192
	v_ashrrev_i32_e32 v193, 31, v192
	v_lshlrev_b64 v[192:193], 6, v[192:193]
	v_lshl_add_u64 v[192:193], s[24:25], 0, v[192:193]
	v_lshl_add_u64 v[192:193], v[192:193], 0, v[130:131]
	global_load_dwordx4 v[150:153], v[192:193], off
	v_max_i32_e32 v192, -2, v190
	v_add_u32_e32 v192, 2, v192
	v_min_u32_e32 v192, 0xfff, v192
	v_or_b32_e32 v192, s1, v192
	v_ashrrev_i32_e32 v193, 31, v192
	v_lshlrev_b64 v[192:193], 6, v[192:193]
	v_lshl_add_u64 v[192:193], s[24:25], 0, v[192:193]
	v_lshl_add_u64 v[192:193], v[192:193], 0, v[130:131]
	global_load_dwordx4 v[154:157], v[192:193], off
	v_max_i32_e32 v192, -3, v190
	v_add_u32_e32 v192, 3, v192
	v_min_u32_e32 v192, 0xfff, v192
	v_or_b32_e32 v192, s1, v192
	v_ashrrev_i32_e32 v193, 31, v192
	v_lshlrev_b64 v[192:193], 6, v[192:193]
	v_lshl_add_u64 v[192:193], s[24:25], 0, v[192:193]
	v_lshl_add_u64 v[192:193], v[192:193], 0, v[130:131]
	global_load_dwordx4 v[158:161], v[192:193], off
	v_add_u32_e32 v192, 0x80, v190
	v_med3_i32 v192, v192, 0, v144
	v_or_b32_e32 v192, s1, v192
	v_ashrrev_i32_e32 v193, 31, v192
	v_lshlrev_b64 v[192:193], 6, v[192:193]
	v_lshl_add_u64 v[192:193], s[24:25], 0, v[192:193]
	v_lshl_add_u64 v[192:193], v[192:193], 0, v[130:131]
	global_load_dwordx4 v[162:165], v[192:193], off
	v_add_u32_e32 v192, 0x81, v190
	v_med3_i32 v192, v192, 0, v144
	v_or_b32_e32 v192, s1, v192
	v_ashrrev_i32_e32 v193, 31, v192
	v_lshlrev_b64 v[192:193], 6, v[192:193]
	v_lshl_add_u64 v[192:193], s[24:25], 0, v[192:193]
	v_lshl_add_u64 v[192:193], v[192:193], 0, v[130:131]
	global_load_dwordx4 v[166:169], v[192:193], off
	v_add_u32_e32 v192, 0x82, v190
	v_med3_i32 v192, v192, 0, v144
	v_or_b32_e32 v192, s1, v192
	v_ashrrev_i32_e32 v193, 31, v192
	v_lshlrev_b64 v[192:193], 6, v[192:193]
	v_lshl_add_u64 v[192:193], s[24:25], 0, v[192:193]
	v_lshl_add_u64 v[192:193], v[192:193], 0, v[130:131]
	global_load_dwordx4 v[170:173], v[192:193], off
	v_add_u32_e32 v192, 0x83, v190
	v_med3_i32 v192, v192, 0, v144
	v_or_b32_e32 v192, s1, v192
	v_ashrrev_i32_e32 v193, 31, v192
	v_lshlrev_b64 v[192:193], 6, v[192:193]
	v_lshl_add_u64 v[192:193], s[24:25], 0, v[192:193]
	v_lshl_add_u64 v[192:193], v[192:193], 0, v[130:131]
	global_load_dwordx4 v[174:177], v[192:193], off
	s_waitcnt vmcnt(7)
	v_mov_b64_e32 v[140:141], v[146:147]
	v_mov_b64_e32 v[142:143], v[148:149]
	v_mov_b32_e32 v132, v141
	v_mov_b32_e32 v133, v142
	v_mov_b32_e32 v141, v143
	v_pk_add_f32 v[132:133], v[132:133], v[140:141]
	s_nop 0
	v_add_f32_e32 v132, v132, v133
	ds_bpermute_b32 v133, v138, v132
	s_waitcnt lgkmcnt(0)
	v_add_f32_e32 v191, v132, v133
	v_or_b32_e32 v132, 1, v190
	v_med3_i32 v132, v132, 0, v144
	v_or_b32_e32 v132, s1, v132
	v_ashrrev_i32_e32 v133, 31, v132
	v_lshlrev_b64 v[132:133], 6, v[132:133]
	v_lshl_add_u64 v[132:133], s[24:25], 0, v[132:133]
	v_lshl_add_u64 v[132:133], v[132:133], 0, v[130:131]
	ds_bpermute_b32 v198, v137, v191
	s_waitcnt vmcnt(6)
	v_mov_b64_e32 v[140:141], v[150:151]
	v_mov_b64_e32 v[142:143], v[152:153]
	v_mov_b32_e32 v132, v141
	v_mov_b32_e32 v133, v142
	v_mov_b32_e32 v141, v143
	v_pk_add_f32 v[132:133], v[132:133], v[140:141]
	s_nop 0
	v_add_f32_e32 v132, v132, v133
	ds_bpermute_b32 v133, v138, v132
	s_waitcnt lgkmcnt(0)
	v_add_f32_e32 v208, v132, v133
	v_max_i32_e32 v132, -2, v190
	v_add_u32_e32 v132, 2, v132
	v_min_u32_e32 v132, 0xfff, v132
	v_or_b32_e32 v132, s1, v132
	v_ashrrev_i32_e32 v133, 31, v132
	v_lshlrev_b64 v[132:133], 6, v[132:133]
	v_lshl_add_u64 v[132:133], s[24:25], 0, v[132:133]
	v_lshl_add_u64 v[132:133], v[132:133], 0, v[130:131]
	ds_bpermute_b32 v209, v137, v208
	s_waitcnt vmcnt(5)
	v_mov_b64_e32 v[140:141], v[154:155]
	v_mov_b64_e32 v[142:143], v[156:157]
	v_mov_b32_e32 v132, v141
	v_mov_b32_e32 v133, v142
	v_mov_b32_e32 v141, v143
	v_pk_add_f32 v[132:133], v[132:133], v[140:141]
	s_nop 0
	v_add_f32_e32 v132, v132, v133
	ds_bpermute_b32 v133, v138, v132
	s_waitcnt lgkmcnt(0)
	v_add_f32_e32 v132, v132, v133
	ds_bpermute_b32 v133, v137, v132
	s_waitcnt lgkmcnt(0)
	v_add_f32_e32 v132, v132, v133
	v_fmamk_f32 v132, v132, 0x3a800000, v243
	v_rsq_f32_e32 v132, v132
	s_nop 0
	v_pk_mul_f32 v[116:117], v[116:117], v[132:133] op_sel_hi:[1,0]
	v_pk_mul_f32 v[114:115], v[114:115], v[132:133] op_sel_hi:[1,0]
	v_pk_mul_f32 v[44:45], v[44:45], v[132:133] op_sel_hi:[1,0]
	v_pk_mul_f32 v[42:43], v[42:43], v[132:133] op_sel_hi:[1,0]
	v_pk_mul_f32 v[120:121], v[120:121], v[132:133] op_sel_hi:[1,0]
	v_pk_mul_f32 v[118:119], v[118:119], v[132:133] op_sel_hi:[1,0]
	v_pk_mul_f32 v[56:57], v[56:57], v[132:133] op_sel_hi:[1,0]
	v_pk_mul_f32 v[54:55], v[54:55], v[132:133] op_sel_hi:[1,0]
	v_max_i32_e32 v132, -3, v190
	v_add_u32_e32 v132, 3, v132
	v_min_u32_e32 v132, 0xfff, v132
	v_or_b32_e32 v132, s1, v132
	v_ashrrev_i32_e32 v133, 31, v132
	v_lshlrev_b64 v[132:133], 6, v[132:133]
	v_lshl_add_u64 v[132:133], s[24:25], 0, v[132:133]
	v_lshl_add_u64 v[132:133], v[132:133], 0, v[130:131]
	s_waitcnt vmcnt(4)
	v_mov_b64_e32 v[140:141], v[158:159]
	v_mov_b64_e32 v[142:143], v[160:161]
	v_mov_b32_e32 v132, v141
	v_mov_b32_e32 v133, v142
	v_mov_b32_e32 v141, v143
	v_pk_add_f32 v[132:133], v[132:133], v[140:141]
	s_nop 0
	v_add_f32_e32 v132, v132, v133
	ds_bpermute_b32 v133, v138, v132
	s_waitcnt lgkmcnt(0)
	v_add_f32_e32 v132, v132, v133
	ds_bpermute_b32 v133, v137, v132
	s_waitcnt lgkmcnt(0)
	v_add_f32_e32 v132, v132, v133
	v_fmamk_f32 v132, v132, 0x3a800000, v243
	v_rsq_f32_e32 v132, v132
	s_nop 0
	v_pk_mul_f32 v[124:125], v[124:125], v[132:133] op_sel_hi:[1,0]
	v_pk_mul_f32 v[122:123], v[122:123], v[132:133] op_sel_hi:[1,0]
	v_pk_mul_f32 v[60:61], v[60:61], v[132:133] op_sel_hi:[1,0]
	v_pk_mul_f32 v[58:59], v[58:59], v[132:133] op_sel_hi:[1,0]
	v_pk_mul_f32 v[128:129], v[128:129], v[132:133] op_sel_hi:[1,0]
	v_pk_mul_f32 v[126:127], v[126:127], v[132:133] op_sel_hi:[1,0]
	v_pk_mul_f32 v[64:65], v[64:65], v[132:133] op_sel_hi:[1,0]
	v_pk_mul_f32 v[62:63], v[62:63], v[132:133] op_sel_hi:[1,0]
	v_add_u32_e32 v132, 0x80, v190
	v_med3_i32 v132, v132, 0, v144
	v_or_b32_e32 v132, s1, v132
	v_ashrrev_i32_e32 v133, 31, v132
	v_lshlrev_b64 v[132:133], 6, v[132:133]
	v_lshl_add_u64 v[132:133], s[24:25], 0, v[132:133]
	v_lshl_add_u64 v[132:133], v[132:133], 0, v[130:131]
	s_waitcnt vmcnt(3)
	v_mov_b64_e32 v[140:141], v[162:163]
	v_mov_b64_e32 v[142:143], v[164:165]
	v_mov_b32_e32 v132, v141
	v_mov_b32_e32 v133, v142
	v_mov_b32_e32 v141, v143
	v_pk_add_f32 v[132:133], v[132:133], v[140:141]
	s_nop 0
	v_add_f32_e32 v132, v132, v133
	ds_bpermute_b32 v133, v138, v132
	s_waitcnt lgkmcnt(0)
	v_add_f32_e32 v206, v132, v133
	v_add_u32_e32 v132, 0x81, v190
	v_med3_i32 v132, v132, 0, v144
	v_or_b32_e32 v132, s1, v132
	v_ashrrev_i32_e32 v133, 31, v132
	v_lshlrev_b64 v[132:133], 6, v[132:133]
	v_lshl_add_u64 v[132:133], s[24:25], 0, v[132:133]
	v_lshl_add_u64 v[132:133], v[132:133], 0, v[130:131]
	ds_bpermute_b32 v207, v137, v206
	s_waitcnt vmcnt(2)
	v_mov_b64_e32 v[140:141], v[166:167]
	v_mov_b64_e32 v[142:143], v[168:169]
	v_mov_b32_e32 v132, v141
	v_mov_b32_e32 v133, v142
	v_mov_b32_e32 v141, v143
	v_pk_add_f32 v[132:133], v[132:133], v[140:141]
	s_nop 0
	v_add_f32_e32 v132, v132, v133
	ds_bpermute_b32 v133, v138, v132
	s_waitcnt lgkmcnt(0)
	v_add_f32_e32 v204, v132, v133
	v_add_u32_e32 v132, 0x82, v190
	v_med3_i32 v132, v132, 0, v144
	v_or_b32_e32 v132, s1, v132
	v_ashrrev_i32_e32 v133, 31, v132
	v_lshlrev_b64 v[132:133], 6, v[132:133]
	v_lshl_add_u64 v[132:133], s[24:25], 0, v[132:133]
	v_lshl_add_u64 v[132:133], v[132:133], 0, v[130:131]
	ds_bpermute_b32 v205, v137, v204
	s_waitcnt vmcnt(1)
	v_mov_b64_e32 v[140:141], v[170:171]
	v_mov_b64_e32 v[142:143], v[172:173]
	v_mov_b32_e32 v132, v141
	v_mov_b32_e32 v133, v142
	v_mov_b32_e32 v141, v143
	v_pk_add_f32 v[132:133], v[132:133], v[140:141]
	s_nop 0
	v_add_f32_e32 v132, v132, v133
	ds_bpermute_b32 v133, v138, v132
	s_waitcnt lgkmcnt(0)
	v_add_f32_e32 v132, v132, v133
	ds_bpermute_b32 v133, v137, v132
	s_waitcnt lgkmcnt(0)
	v_add_f32_e32 v132, v132, v133
	v_fmamk_f32 v132, v132, 0x3a800000, v243
	v_rsq_f32_e32 v132, v132
	s_nop 0
	v_pk_mul_f32 v[108:109], v[108:109], v[132:133] op_sel_hi:[1,0]
	v_pk_mul_f32 v[106:107], v[106:107], v[132:133] op_sel_hi:[1,0]
	v_pk_mul_f32 v[36:37], v[36:37], v[132:133] op_sel_hi:[1,0]
	v_pk_mul_f32 v[34:35], v[34:35], v[132:133] op_sel_hi:[1,0]
	v_pk_mul_f32 v[112:113], v[112:113], v[132:133] op_sel_hi:[1,0]
	v_pk_mul_f32 v[110:111], v[110:111], v[132:133] op_sel_hi:[1,0]
	v_pk_mul_f32 v[40:41], v[40:41], v[132:133] op_sel_hi:[1,0]
	v_pk_mul_f32 v[38:39], v[38:39], v[132:133] op_sel_hi:[1,0]
	v_add_u32_e32 v132, 0x83, v190
	v_med3_i32 v132, v132, 0, v144
	v_or_b32_e32 v132, s1, v132
	v_ashrrev_i32_e32 v133, 31, v132
	v_lshlrev_b64 v[132:133], 6, v[132:133]
	v_lshl_add_u64 v[132:133], s[24:25], 0, v[132:133]
	v_lshl_add_u64 v[130:131], v[132:133], 0, v[130:131]
	s_waitcnt vmcnt(0)
	v_mov_b64_e32 v[130:131], v[174:175]
	v_mov_b64_e32 v[132:133], v[176:177]
	v_mov_b32_e32 v140, v131
	v_mov_b32_e32 v141, v132
	v_mov_b32_e32 v131, v133
	v_pk_add_f32 v[130:131], v[140:141], v[130:131]
	s_nop 0
	v_add_f32_e32 v130, v130, v131
	ds_bpermute_b32 v131, v138, v130
	s_waitcnt lgkmcnt(0)
	v_add_f32_e32 v130, v130, v131
	ds_bpermute_b32 v131, v137, v130
	s_waitcnt lgkmcnt(0)
	v_add_f32_e32 v130, v130, v131
	v_fmamk_f32 v130, v130, 0x3a800000, v243
	v_rsq_f32_e32 v130, v130
	s_nop 0
	v_pk_mul_f32 v[104:105], v[104:105], v[130:131] op_sel_hi:[1,0]
	v_pk_mul_f32 v[102:103], v[102:103], v[130:131] op_sel_hi:[1,0]
	v_pk_mul_f32 v[76:77], v[76:77], v[130:131] op_sel_hi:[1,0]
	v_pk_mul_f32 v[74:75], v[74:75], v[130:131] op_sel_hi:[1,0]
	v_pk_mul_f32 v[100:101], v[100:101], v[130:131] op_sel_hi:[1,0]
	v_pk_mul_f32 v[98:99], v[98:99], v[130:131] op_sel_hi:[1,0]
	v_pk_mul_f32 v[88:89], v[88:89], v[130:131] op_sel_hi:[1,0]
	v_pk_mul_f32 v[86:87], v[86:87], v[130:131] op_sel_hi:[1,0]
	v_cmp_eq_u32_e32 vcc, 15, v203
	s_and_saveexec_b64 s[10:11], vcc
	s_cbranch_execz .LBB0_936
	v_lshlrev_b32_e32 v130, 4, v136
	v_readlane_b32 s1, v255, 5
	s_nop 1
	v_add_u32_e32 v131, s1, v130
	v_readlane_b32 s1, v255, 6
	ds_write_b128 v131, v[114:117]
	ds_write_b128 v131, v[122:125] offset:1024
	ds_write_b128 v131, v[42:45] offset:64
	ds_write_b128 v131, v[58:61] offset:1088
	ds_write_b128 v131, v[118:121] offset:512
	ds_write_b128 v131, v[126:129] offset:1536
	ds_write_b128 v131, v[54:57] offset:576
	ds_write_b128 v131, v[62:65] offset:1600
	v_add_u32_e32 v130, s1, v130
	ds_write_b128 v130, v[106:109]
	ds_write_b128 v130, v[102:105] offset:1024
	ds_write_b128 v131, v[34:37] offset:4160
	ds_write_b128 v131, v[74:77] offset:5184
	ds_write_b128 v131, v[110:113] offset:4608
	ds_write_b128 v131, v[98:101] offset:5632
	ds_write_b128 v131, v[38:41] offset:4672
	ds_write_b128 v131, v[86:89] offset:5696

.LBB0_939:
	v_add_f32_e32 v191, v191, v198
	v_fmamk_f32 v191, v191, 0x3a800000, v243
	s_ashr_i32 s1, s0, 31
	s_lshl_b64 s[0:1], s[0:1], 12
	s_nop 1
	s_waitcnt lgkmcnt(3)
	v_mov_b32_dpp v170, v114 row_shr:1 row_mask:0xf bank_mask:0xf
	s_waitcnt lgkmcnt(2)
	v_mov_b32_dpp v162, v122 row_shr:1 row_mask:0xf bank_mask:0xf
	s_waitcnt lgkmcnt(1)
	v_mov_b32_dpp v174, v118 row_shr:1 row_mask:0xf bank_mask:0xf
	s_nop 1
	s_waitcnt lgkmcnt(0)
	v_mov_b32_dpp v166, v126 row_shr:1 row_mask:0xf bank_mask:0xf
	v_mov_b32_dpp v171, v115 row_shr:1 row_mask:0xf bank_mask:0xf
	s_nop 1
	v_mov_b32_dpp v163, v123 row_shr:1 row_mask:0xf bank_mask:0xf
	v_mov_b32_dpp v175, v119 row_shr:1 row_mask:0xf bank_mask:0xf
	s_nop 1
	v_mov_b32_dpp v167, v127 row_shr:1 row_mask:0xf bank_mask:0xf
	v_mov_b32_dpp v172, v116 row_shr:1 row_mask:0xf bank_mask:0xf
	s_nop 1
	s_movk_i32 s10, 0x1000
	v_cmp_gt_i32_e64 s[46:47], s10, v190
	v_mov_b32_dpp v164, v124 row_shr:1 row_mask:0xf bank_mask:0xf
	v_rsq_f32_e32 v198, v191
	s_nop 0
	v_cmp_lt_i32_e32 vcc, 1, v199
	v_pk_mul_f32 v[96:97], v[96:97], v[198:199] op_sel_hi:[1,0]
	v_pk_mul_f32 v[94:95], v[94:95], v[198:199] op_sel_hi:[1,0]
	v_pk_mul_f32 v[92:93], v[92:93], v[198:199] op_sel_hi:[1,0]
	v_pk_mul_f32 v[90:91], v[90:91], v[198:199] op_sel_hi:[1,0]
	v_mov_b32_dpp v176, v120 row_shr:1 row_mask:0xf bank_mask:0xf
	v_mov_b32_dpp v168, v128 row_shr:1 row_mask:0xf bank_mask:0xf
	v_mov_b32_dpp v173, v117 row_shr:1 row_mask:0xf bank_mask:0xf
	v_mov_b32_dpp v165, v125 row_shr:1 row_mask:0xf bank_mask:0xf
	v_mov_b32_dpp v177, v121 row_shr:1 row_mask:0xf bank_mask:0xf
	v_mov_b32_dpp v169, v129 row_shr:1 row_mask:0xf bank_mask:0xf
	s_and_b64 s[24:25], vcc, s[46:47]
	v_ashrrev_i32_e32 v191, 31, v190
	s_and_saveexec_b64 s[10:11], s[24:25]
	s_cbranch_execz .LBB0_941
	s_waitcnt vmcnt(0)
	v_pk_fma_f32 v[174:175], v[146:147], v[174:175], v[158:159]
	v_pk_fma_f32 v[170:171], v[138:139], v[170:171], v[142:143]
	v_pk_fma_f32 v[174:175], v[150:151], v[166:167], v[174:175]
	v_pk_fma_f32 v[170:171], v[130:131], v[162:163], v[170:171]
	v_pk_fma_f32 v[174:175], v[90:91], v[154:155], v[174:175]
	v_pk_fma_f32 v[170:171], v[94:95], v[134:135], v[170:171]
	v_mul_f32_e32 v210, 0xbfb8aa3b, v174
	v_pk_mul_f32 v[170:171], v[170:171], v[174:175]
	v_mul_f32_e32 v174, 0xbfb8aa3b, v175
	v_exp_f32_e32 v174, v174
	v_pk_fma_f32 v[172:173], v[140:141], v[172:173], v[144:145]
	v_exp_f32_e32 v210, v210
	v_pk_fma_f32 v[172:173], v[132:133], v[164:165], v[172:173]
	v_add_f32_e32 v174, 1.0, v174
	v_rcp_f32_e32 v215, v174
	v_pk_fma_f32 v[174:175], v[148:149], v[176:177], v[160:161]
	v_pk_fma_f32 v[172:173], v[96:97], v[136:137], v[172:173]
	v_pk_fma_f32 v[174:175], v[152:153], v[168:169], v[174:175]
	v_add_f32_e32 v210, 1.0, v210
	v_pk_fma_f32 v[174:175], v[92:93], v[156:157], v[174:175]
	v_rcp_f32_e32 v214, v210
	v_mul_f32_e32 v176, 0xbfb8aa3b, v174
	v_pk_mul_f32 v[172:173], v[172:173], v[174:175]
	v_mul_f32_e32 v174, 0xbfb8aa3b, v175
	v_exp_f32_e32 v176, v176
	v_exp_f32_e32 v174, v174
	v_readlane_b32 s26, v251, 45
	v_readlane_b32 s27, v251, 46
	v_add_f32_e32 v176, 1.0, v176
	v_add_f32_e32 v174, 1.0, v174
	v_rcp_f32_e32 v176, v176
	v_rcp_f32_e32 v177, v174
	v_lshl_add_u64 v[174:175], s[0:1], 0, v[190:191]
	v_pk_mul_f32 v[170:171], v[170:171], v[214:215]
	v_pk_mul_f32 v[172:173], v[172:173], v[176:177]
	v_mov_b64_e32 v[176:177], s[26:27]
	v_mad_u64_u32 v[176:177], s[26:27], v174, s54, v[176:177]
	v_mad_i32_i24 v177, v175, s54, v177
	v_lshl_add_u64 v[174:175], v[192:193], 1, v[176:177]
	v_cvt_pk_bf16_f32 v170, v170, v171
	v_cvt_pk_bf16_f32 v171, v172, v173
	global_store_dwordx2 v[174:175], v[170:171], off
.LBB0_941:
	s_or_b64 exec, exec, s[10:11]
	v_add_f32_e32 v170, v208, v209
	v_fmamk_f32 v170, v170, 0x3a800000, v243
	s_nop 1
	s_movk_i32 s10, 0x1000
	v_rsq_f32_e32 v172, v170
	s_nop 0
	v_or_b32_e32 v170, 1, v199
	v_add_u32_e32 v170, s31, v170
	v_cmp_lt_i32_e32 vcc, 0, v199
	v_cmp_gt_i32_e64 s[46:47], s10, v170
	v_pk_mul_f32 v[84:85], v[84:85], v[172:173] op_sel_hi:[1,0]
	v_pk_mul_f32 v[82:83], v[82:83], v[172:173] op_sel_hi:[1,0]
	v_pk_mul_f32 v[80:81], v[80:81], v[172:173] op_sel_hi:[1,0]
	v_pk_mul_f32 v[78:79], v[78:79], v[172:173] op_sel_hi:[1,0]
	s_and_b64 s[26:27], vcc, s[46:47]
	v_ashrrev_i32_e32 v171, 31, v170
	s_and_saveexec_b64 s[10:11], s[26:27]
	s_cbranch_execz .LBB0_943
	s_waitcnt vmcnt(0)
	v_pk_fma_f32 v[166:167], v[146:147], v[166:167], v[158:159]
	v_pk_fma_f32 v[162:163], v[138:139], v[162:163], v[142:143]
	v_pk_fma_f32 v[166:167], v[90:91], v[150:151], v[166:167]
	v_pk_fma_f32 v[162:163], v[94:95], v[130:131], v[162:163]
	v_pk_fma_f32 v[166:167], v[78:79], v[154:155], v[166:167]
	v_pk_fma_f32 v[162:163], v[82:83], v[134:135], v[162:163]
	v_mul_f32_e32 v173, 0xbfb8aa3b, v166
	v_pk_mul_f32 v[162:163], v[162:163], v[166:167]
	v_mul_f32_e32 v166, 0xbfb8aa3b, v167
	v_exp_f32_e32 v166, v166
	v_pk_fma_f32 v[164:165], v[140:141], v[164:165], v[144:145]
	v_exp_f32_e32 v173, v173
	v_pk_fma_f32 v[164:165], v[96:97], v[132:133], v[164:165]
	v_add_f32_e32 v166, 1.0, v166
	v_rcp_f32_e32 v175, v166
	v_pk_fma_f32 v[166:167], v[148:149], v[168:169], v[160:161]
	v_pk_fma_f32 v[164:165], v[84:85], v[136:137], v[164:165]
	v_pk_fma_f32 v[166:167], v[92:93], v[152:153], v[166:167]
	v_add_f32_e32 v173, 1.0, v173
	v_pk_fma_f32 v[166:167], v[80:81], v[156:157], v[166:167]
	v_rcp_f32_e32 v174, v173
	v_mul_f32_e32 v168, 0xbfb8aa3b, v166
	v_pk_mul_f32 v[164:165], v[164:165], v[166:167]
	v_mul_f32_e32 v166, 0xbfb8aa3b, v167
	v_exp_f32_e32 v168, v168
	v_exp_f32_e32 v166, v166
	v_readlane_b32 s38, v251, 45
	v_readlane_b32 s39, v251, 46
	v_add_f32_e32 v168, 1.0, v168
	v_add_f32_e32 v166, 1.0, v166
	v_rcp_f32_e32 v168, v168
	v_rcp_f32_e32 v169, v166
	v_lshl_add_u64 v[166:167], s[0:1], 0, v[170:171]
	v_pk_mul_f32 v[162:163], v[162:163], v[174:175]
	v_pk_mul_f32 v[164:165], v[164:165], v[168:169]
	v_mov_b64_e32 v[168:169], s[38:39]
	v_mad_u64_u32 v[168:169], s[38:39], v166, s54, v[168:169]
	v_mad_i32_i24 v169, v167, s54, v169
	v_lshl_add_u64 v[166:167], v[192:193], 1, v[168:169]
	v_cvt_pk_bf16_f32 v162, v162, v163
	v_cvt_pk_bf16_f32 v163, v164, v165
	global_store_dwordx2 v[166:167], v[162:163], off

.LBB0_951:
	v_add_f32_e32 v114, v206, v207
	v_fmamk_f32 v114, v114, 0x3a800000, v243
	s_waitcnt lgkmcnt(3)
	v_mov_b32_dpp v90, v106 row_shr:1 row_mask:0xf bank_mask:0xf
	s_waitcnt lgkmcnt(2)
	v_mov_b32_dpp v78, v102 row_shr:1 row_mask:0xf bank_mask:0xf
	s_nop 1
	s_waitcnt lgkmcnt(1)
	v_mov_b32_dpp v94, v110 row_shr:1 row_mask:0xf bank_mask:0xf
	s_waitcnt lgkmcnt(0)
	v_mov_b32_dpp v82, v98 row_shr:1 row_mask:0xf bank_mask:0xf
	v_mov_b32_dpp v91, v107 row_shr:1 row_mask:0xf bank_mask:0xf
	s_nop 1
	v_mov_b32_dpp v79, v103 row_shr:1 row_mask:0xf bank_mask:0xf
	v_mov_b32_dpp v95, v111 row_shr:1 row_mask:0xf bank_mask:0xf
	s_nop 1
	v_mov_b32_dpp v83, v99 row_shr:1 row_mask:0xf bank_mask:0xf
	v_mov_b32_dpp v92, v108 row_shr:1 row_mask:0xf bank_mask:0xf
	s_nop 1
	v_mov_b32_dpp v80, v104 row_shr:1 row_mask:0xf bank_mask:0xf
	v_mov_b32_dpp v96, v112 row_shr:1 row_mask:0xf bank_mask:0xf
	s_nop 1
	v_mov_b32_dpp v84, v100 row_shr:1 row_mask:0xf bank_mask:0xf
	v_mov_b32_dpp v93, v109 row_shr:1 row_mask:0xf bank_mask:0xf
	v_mov_b32_dpp v81, v105 row_shr:1 row_mask:0xf bank_mask:0xf
	v_rsq_f32_e32 v122, v114
	s_nop 0
	v_add_u32_e32 v115, 0x80, v199
	v_add_u32_e32 v114, s31, v115
	v_cmp_lt_i32_e32 vcc, 1, v115
	v_cmp_gt_i32_e64 s[48:49], s15, v114
	v_pk_mul_f32 v[72:73], v[72:73], v[122:123] op_sel_hi:[1,0]
	v_pk_mul_f32 v[70:71], v[70:71], v[122:123] op_sel_hi:[1,0]
	v_pk_mul_f32 v[68:69], v[68:69], v[122:123] op_sel_hi:[1,0]
	v_pk_mul_f32 v[66:67], v[66:67], v[122:123] op_sel_hi:[1,0]
	v_mov_b32_dpp v97, v113 row_shr:1 row_mask:0xf bank_mask:0xf
	v_mov_b32_dpp v85, v101 row_shr:1 row_mask:0xf bank_mask:0xf
	s_and_b64 s[54:55], vcc, s[48:49]
	v_ashrrev_i32_e32 v115, 31, v114
	s_and_saveexec_b64 s[40:41], s[54:55]
	s_cbranch_execz .LBB0_953
	s_waitcnt vmcnt(0)
	v_pk_fma_f32 v[94:95], v[146:147], v[94:95], v[158:159]
	v_pk_fma_f32 v[90:91], v[138:139], v[90:91], v[142:143]
	v_pk_fma_f32 v[94:95], v[150:151], v[82:83], v[94:95]
	v_pk_fma_f32 v[90:91], v[130:131], v[78:79], v[90:91]
	v_pk_fma_f32 v[94:95], v[66:67], v[154:155], v[94:95]
	v_pk_fma_f32 v[90:91], v[70:71], v[134:135], v[90:91]
	v_mul_f32_e32 v116, 0xbfb8aa3b, v94
	v_pk_mul_f32 v[90:91], v[90:91], v[94:95]
	v_mul_f32_e32 v94, 0xbfb8aa3b, v95
	v_exp_f32_e32 v94, v94
	v_pk_fma_f32 v[92:93], v[140:141], v[92:93], v[144:145]
	v_exp_f32_e32 v116, v116
	v_pk_fma_f32 v[92:93], v[132:133], v[80:81], v[92:93]
	v_add_f32_e32 v94, 1.0, v94
	v_rcp_f32_e32 v117, v94
	v_pk_fma_f32 v[94:95], v[148:149], v[96:97], v[160:161]
	v_pk_fma_f32 v[92:93], v[72:73], v[136:137], v[92:93]
	v_pk_fma_f32 v[94:95], v[152:153], v[84:85], v[94:95]
	v_add_f32_e32 v116, 1.0, v116
	v_pk_fma_f32 v[94:95], v[68:69], v[156:157], v[94:95]
	v_rcp_f32_e32 v116, v116
	v_mul_f32_e32 v96, 0xbfb8aa3b, v94
	v_pk_mul_f32 v[92:93], v[92:93], v[94:95]
	v_mul_f32_e32 v94, 0xbfb8aa3b, v95
	v_exp_f32_e32 v96, v96
	v_exp_f32_e32 v94, v94
	v_readlane_b32 s48, v251, 45
	v_readlane_b32 s49, v251, 46
	v_add_f32_e32 v96, 1.0, v96
	v_add_f32_e32 v94, 1.0, v94
	v_rcp_f32_e32 v96, v96
	v_rcp_f32_e32 v97, v94
	v_lshl_add_u64 v[94:95], s[0:1], 0, v[114:115]
	s_movk_i32 s15, 0x1600
	v_pk_mul_f32 v[90:91], v[90:91], v[116:117]
	v_pk_mul_f32 v[92:93], v[92:93], v[96:97]
	v_mov_b64_e32 v[96:97], s[48:49]
	v_mad_u64_u32 v[96:97], s[48:49], v94, s15, v[96:97]
	v_mad_i32_i24 v97, v95, s15, v97
	v_lshl_add_u64 v[94:95], v[192:193], 1, v[96:97]
	v_cvt_pk_bf16_f32 v90, v90, v91
	v_cvt_pk_bf16_f32 v91, v92, v93
	global_store_dwordx2 v[94:95], v[90:91], off
.LBB0_953:
	s_or_b64 exec, exec, s[40:41]
	v_add_f32_e32 v90, v204, v205
	v_fmamk_f32 v90, v90, 0x3a800000, v243
	s_movk_i32 s15, 0x1000
	s_nop 0
	v_rsq_f32_e32 v124, v90
	s_nop 0
	v_add_u32_e32 v90, 0x81, v199
	v_add_u32_e32 v116, s31, v90
	v_cmp_lt_i32_e32 vcc, 1, v90
	v_cmp_gt_i32_e64 s[48:49], s15, v116
	v_pk_mul_f32 v[52:53], v[52:53], v[124:125] op_sel_hi:[1,0]
	v_pk_mul_f32 v[50:51], v[50:51], v[124:125] op_sel_hi:[1,0]
	v_pk_mul_f32 v[48:49], v[48:49], v[124:125] op_sel_hi:[1,0]
	v_pk_mul_f32 v[46:47], v[46:47], v[124:125] op_sel_hi:[1,0]
	s_and_b64 s[40:41], vcc, s[48:49]
	v_ashrrev_i32_e32 v117, 31, v116
	s_and_saveexec_b64 s[48:49], s[40:41]
	s_cbranch_execz .LBB0_955
	s_waitcnt vmcnt(0)
	v_pk_fma_f32 v[82:83], v[146:147], v[82:83], v[158:159]
	v_pk_fma_f32 v[78:79], v[138:139], v[78:79], v[142:143]
	v_pk_fma_f32 v[82:83], v[66:67], v[150:151], v[82:83]
	v_pk_fma_f32 v[78:79], v[70:71], v[130:131], v[78:79]
	v_pk_fma_f32 v[82:83], v[46:47], v[154:155], v[82:83]
	v_pk_fma_f32 v[78:79], v[50:51], v[134:135], v[78:79]
	v_mul_f32_e32 v90, 0xbfb8aa3b, v82
	v_pk_mul_f32 v[78:79], v[78:79], v[82:83]
	v_mul_f32_e32 v82, 0xbfb8aa3b, v83
	v_exp_f32_e32 v82, v82
	v_pk_fma_f32 v[80:81], v[140:141], v[80:81], v[144:145]
	v_exp_f32_e32 v90, v90
	v_pk_fma_f32 v[80:81], v[72:73], v[132:133], v[80:81]
	v_add_f32_e32 v82, 1.0, v82
	v_rcp_f32_e32 v91, v82
	v_pk_fma_f32 v[82:83], v[148:149], v[84:85], v[160:161]
	v_pk_fma_f32 v[80:81], v[52:53], v[136:137], v[80:81]
	v_pk_fma_f32 v[82:83], v[68:69], v[152:153], v[82:83]
	v_add_f32_e32 v90, 1.0, v90
	v_pk_fma_f32 v[82:83], v[48:49], v[156:157], v[82:83]
	v_rcp_f32_e32 v90, v90
	v_mul_f32_e32 v84, 0xbfb8aa3b, v82
	v_pk_mul_f32 v[80:81], v[80:81], v[82:83]
	v_mul_f32_e32 v82, 0xbfb8aa3b, v83
	v_exp_f32_e32 v84, v84
	v_exp_f32_e32 v82, v82
	v_readlane_b32 s68, v251, 45
	v_readlane_b32 s69, v251, 46
	v_add_f32_e32 v84, 1.0, v84
	v_add_f32_e32 v82, 1.0, v82
	v_rcp_f32_e32 v84, v84
	v_rcp_f32_e32 v85, v82
	v_lshl_add_u64 v[82:83], s[0:1], 0, v[116:117]
	s_movk_i32 s15, 0x1600
	v_pk_mul_f32 v[78:79], v[78:79], v[90:91]
	v_pk_mul_f32 v[80:81], v[80:81], v[84:85]
	v_mov_b64_e32 v[84:85], s[68:69]
	v_mad_u64_u32 v[84:85], s[94:95], v82, s15, v[84:85]
	v_mad_i32_i24 v85, v83, s15, v85
	v_lshl_add_u64 v[82:83], v[192:193], 1, v[84:85]
	v_cvt_pk_bf16_f32 v78, v78, v79
	v_cvt_pk_bf16_f32 v79, v80, v81
	global_store_dwordx2 v[82:83], v[78:79], off

.LBB0_1185:
	s_ashr_i32 s1, s0, 31
	s_lshl_b64 s[0:1], s[0:1], 8
	v_mov_b32_e32 v205, v188
	v_mov_b32_e32 v134, v1
	s_add_u32 s0, s0, s84
	s_addc_u32 s1, s1, s86
	v_ashrrev_i32_e32 v135, 31, v134
	v_lshlrev_b32_e32 v132, 2, v205
	v_lshl_add_u64 v[130:131], s[0:1], 0, v[134:135]
	v_ashrrev_i32_e32 v133, 31, v132
	v_lshlrev_b32_e32 v134, 2, v134
	v_lshl_add_u64 v[132:133], v[132:133], 2, s[78:79]
	v_lshl_add_u32 v134, v205, 6, v134
	v_lshlrev_b64 v[178:179], 6, v[130:131]
	v_xor_b32_e32 v192, 64, v134
	v_xor_b32_e32 v191, 0x80, v134
	v_lshl_add_u64 v[134:135], v[132:133], 0, v[178:179]
	global_load_dwordx4 v[134:137], v[134:135], off
	v_lshl_add_u64 v[180:181], v[130:131], 0, 16
	v_lshlrev_b64 v[176:177], 6, v[180:181]
	v_lshl_add_u64 v[174:175], v[130:131], 0, 32
	v_lshlrev_b64 v[172:173], 6, v[174:175]
	v_lshl_add_u64 v[170:171], v[130:131], 0, 48
	v_lshlrev_b64 v[168:169], 6, v[170:171]
	v_lshl_add_u64 v[166:167], v[130:131], 0, s[28:29]
	v_lshlrev_b64 v[164:165], 6, v[166:167]
	s_waitcnt vmcnt(0)
	v_add_f32_e32 v134, v134, v135
	v_add_f32_e32 v135, v136, v137
	v_add_f32_e32 v134, v134, v135
	ds_bpermute_b32 v135, v192, v134
	s_waitcnt lgkmcnt(0)
	v_add_f32_e32 v134, v134, v135
	ds_bpermute_b32 v135, v191, v134
	s_waitcnt lgkmcnt(0)
	v_add_f32_e32 v134, v134, v135
	v_fmamk_f32 v134, v134, 0x3a800000, v243
	s_nop 1
	s_mov_b64 s[0:1], 0x90
	v_lshl_add_u64 v[162:163], v[130:131], 0, s[0:1]
	v_lshlrev_b64 v[160:161], 6, v[162:163]
	v_rsq_f32_e32 v208, v134
	s_nop 0
	v_lshl_add_u64 v[134:135], v[132:133], 0, v[176:177]
	global_load_dwordx4 v[134:137], v[134:135], off
	s_mov_b64 s[0:1], 0xa0
	v_lshl_add_u64 v[158:159], v[130:131], 0, s[0:1]
	v_lshlrev_b64 v[156:157], 6, v[158:159]
	s_mov_b64 s[0:1], 0xb0
	v_lshl_add_u64 v[152:153], v[130:131], 0, s[0:1]
	v_lshlrev_b64 v[150:151], 6, v[152:153]
	s_lshl_b32 s0, s4, 8
	s_ashr_i32 s1, s0, 31
	s_or_b64 s[0:1], s[0:1], s[62:63]
	v_lshlrev_b64 v[130:131], 10, v[130:131]
	v_mul_f32_e32 v126, v126, v208
	v_mul_f32_e32 v127, v127, v208
	v_mul_f32_e32 v128, v128, v208
	v_mul_f32_e32 v129, v129, v208
	v_mul_f32_e32 v126, 0xbfb8aa3b, v126
	v_mul_f32_e32 v127, 0xbfb8aa3b, v127
	v_mul_f32_e32 v128, 0xbfb8aa3b, v128
	v_mul_f32_e32 v124, v124, v208
	v_mul_f32_e32 v129, 0xbfb8aa3b, v129
	v_mul_f32_e32 v125, v125, v208
	v_exp_f32_e32 v126, v126
	v_mul_f32_e32 v122, v122, v208
	v_exp_f32_e32 v127, v127
	v_mul_f32_e32 v123, v123, v208
	v_exp_f32_e32 v128, v128
	v_mul_f32_e32 v124, 0xbfb8aa3b, v124
	v_exp_f32_e32 v129, v129
	v_mul_f32_e32 v125, 0xbfb8aa3b, v125
	v_mul_f32_e32 v122, 0xbfb8aa3b, v122
	v_mul_f32_e32 v123, 0xbfb8aa3b, v123
	v_exp_f32_e32 v124, v124
	v_exp_f32_e32 v125, v125
	v_exp_f32_e32 v122, v122
	v_exp_f32_e32 v123, v123
	v_add_f32_e32 v126, 1.0, v126
	v_add_f32_e32 v127, 1.0, v127
	v_add_f32_e32 v128, 1.0, v128
	v_add_f32_e32 v129, 1.0, v129
	v_rcp_f32_e32 v126, v126
	v_rcp_f32_e32 v127, v127
	v_rcp_f32_e32 v128, v128
	v_add_f32_e32 v124, 1.0, v124
	v_rcp_f32_e32 v129, v129
	v_add_f32_e32 v125, 1.0, v125
	v_add_f32_e32 v122, 1.0, v122
	v_add_f32_e32 v123, 1.0, v123
	v_rcp_f32_e32 v124, v124
	v_rcp_f32_e32 v125, v125
	v_rcp_f32_e32 v122, v122
	v_rcp_f32_e32 v123, v123
	s_andn2_b64 vcc, exec, s[68:69]
	s_waitcnt vmcnt(0)
	v_add_f32_e32 v134, v134, v135
	v_add_f32_e32 v135, v136, v137
	v_add_f32_e32 v134, v134, v135
	ds_bpermute_b32 v135, v192, v134
	s_waitcnt lgkmcnt(0)
	v_add_f32_e32 v206, v134, v135
	v_lshl_add_u64 v[134:135], v[132:133], 0, v[172:173]
	global_load_dwordx4 v[134:137], v[134:135], off
	ds_bpermute_b32 v207, v191, v206
	s_waitcnt vmcnt(0)
	v_add_f32_e32 v134, v134, v135
	v_add_f32_e32 v135, v136, v137
	v_add_f32_e32 v134, v134, v135
	ds_bpermute_b32 v135, v192, v134
	s_waitcnt lgkmcnt(0)
	v_add_f32_e32 v203, v134, v135
	v_lshl_add_u64 v[134:135], v[132:133], 0, v[168:169]
	global_load_dwordx4 v[134:137], v[134:135], off
	ds_bpermute_b32 v204, v191, v203
	s_waitcnt vmcnt(0)
	v_add_f32_e32 v134, v134, v135
	v_add_f32_e32 v135, v136, v137
	v_add_f32_e32 v134, v134, v135
	ds_bpermute_b32 v135, v192, v134
	s_waitcnt lgkmcnt(0)
	v_add_f32_e32 v201, v134, v135
	v_lshl_add_u64 v[134:135], v[132:133], 0, v[164:165]
	global_load_dwordx4 v[134:137], v[134:135], off
	ds_bpermute_b32 v202, v191, v201
	s_waitcnt vmcnt(0)
	v_add_f32_e32 v134, v134, v135
	v_add_f32_e32 v135, v136, v137
	v_add_f32_e32 v134, v134, v135
	ds_bpermute_b32 v135, v192, v134
	s_waitcnt lgkmcnt(0)
	v_add_f32_e32 v199, v134, v135
	v_lshl_add_u64 v[134:135], v[132:133], 0, v[160:161]
	global_load_dwordx4 v[134:137], v[134:135], off
	ds_bpermute_b32 v200, v191, v199
	s_waitcnt vmcnt(0)
	v_add_f32_e32 v134, v134, v135
	v_add_f32_e32 v135, v136, v137
	v_add_f32_e32 v134, v134, v135
	ds_bpermute_b32 v135, v192, v134
	s_waitcnt lgkmcnt(0)
	v_add_f32_e32 v197, v134, v135
	v_lshl_add_u64 v[134:135], v[132:133], 0, v[156:157]
	global_load_dwordx4 v[134:137], v[134:135], off
	v_lshl_add_u64 v[132:133], v[132:133], 0, v[150:151]
	ds_bpermute_b32 v198, v191, v197
	s_waitcnt vmcnt(0)
	v_add_f32_e32 v134, v134, v135
	v_add_f32_e32 v135, v136, v137
	v_add_f32_e32 v134, v134, v135
	ds_bpermute_b32 v135, v192, v134
	s_waitcnt lgkmcnt(0)
	v_add_f32_e32 v195, v134, v135
	global_load_dwordx4 v[132:135], v[132:133], off
	ds_bpermute_b32 v196, v191, v195
	s_waitcnt vmcnt(0)
	v_add_f32_e32 v132, v132, v133
	v_add_f32_e32 v133, v134, v135
	v_add_f32_e32 v132, v132, v133
	ds_bpermute_b32 v133, v192, v132
	s_waitcnt lgkmcnt(0)
	v_add_f32_e32 v193, v132, v133
	v_lshlrev_b32_e32 v132, 3, v205
	v_ashrrev_i32_e32 v133, 31, v132
	v_lshl_add_u64 v[154:155], s[0:1], 0, v[132:133]
	v_lshl_add_u64 v[186:187], v[154:155], 0, v[130:131]
	v_lshlrev_b64 v[134:135], 1, v[186:187]
	v_lshl_add_u64 v[182:183], s[20:21], 0, v[134:135]
	v_lshl_add_u64 v[184:185], s[22:23], 0, v[134:135]
	global_load_dwordx4 v[130:133], v[182:183], off
	global_load_dwordx4 v[134:137], v[184:185], off
	ds_bpermute_b32 v194, v191, v193
	s_waitcnt vmcnt(1)
	v_lshlrev_b32_e32 v210, 16, v130
	v_and_b32_e32 v211, 0xffff0000, v130
	s_waitcnt vmcnt(0)
	v_lshlrev_b32_e32 v212, 16, v134
	v_and_b32_e32 v213, 0xffff0000, v134
	v_lshlrev_b32_e32 v130, 16, v131
	v_and_b32_e32 v131, 0xffff0000, v131
	v_lshlrev_b32_e32 v134, 16, v135
	v_and_b32_e32 v135, 0xffff0000, v135
	v_pk_fma_f32 v[126:127], v[126:127], v[210:211], v[212:213]
	v_lshlrev_b32_e32 v210, 16, v132
	v_and_b32_e32 v211, 0xffff0000, v132
	v_pk_fma_f32 v[128:129], v[128:129], v[130:131], v[134:135]
	v_lshlrev_b32_e32 v130, 16, v133
	v_and_b32_e32 v131, 0xffff0000, v133
	v_lshlrev_b32_e32 v132, 16, v137
	v_and_b32_e32 v133, 0xffff0000, v137
	v_lshlrev_b32_e32 v212, 16, v136
	v_and_b32_e32 v213, 0xffff0000, v136
	v_pk_fma_f32 v[124:125], v[124:125], v[130:131], v[132:133]
	v_cndmask_b32_e64 v130, 0, 1, s[68:69]
	v_pk_fma_f32 v[122:123], v[122:123], v[210:211], v[212:213]
	v_cmp_ne_u32_e64 s[42:43], 1, v130
	v_lshl_add_u64 v[134:135], v[186:187], 2, s[54:55]
	s_cbranch_vccnz .LBB0_1268
	global_store_dwordx4 v[134:135], v[126:129], off
	global_store_dwordx4 v[134:135], v[122:125], off offset:16
	s_cbranch_execnz .LBB0_1188

.LBB0_1195:
	v_add_f32_e32 v114, v206, v207
	v_fmamk_f32 v114, v114, 0x3a800000, v243
	s_waitcnt lgkmcnt(0)
	v_rsq_f32_e32 v128, v114
	s_nop 0
	v_lshlrev_b64 v[114:115], 10, v[180:181]
	v_lshl_add_u64 v[126:127], v[114:115], 0, v[154:155]
	v_lshlrev_b64 v[114:115], 1, v[126:127]
	v_lshl_add_u64 v[122:123], s[20:21], 0, v[114:115]
	v_lshl_add_u64 v[124:125], s[22:23], 0, v[114:115]
	global_load_dwordx4 v[118:121], v[122:123], off
	global_load_dwordx4 v[114:117], v[124:125], off
	v_mul_f32_e32 v110, v110, v128
	v_mul_f32_e32 v111, v111, v128
	v_mul_f32_e32 v112, v112, v128
	v_mul_f32_e32 v113, v113, v128
	v_mul_f32_e32 v110, 0xbfb8aa3b, v110
	v_mul_f32_e32 v106, v106, v128
	v_mul_f32_e32 v111, 0xbfb8aa3b, v111
	v_mul_f32_e32 v107, v107, v128
	v_mul_f32_e32 v112, 0xbfb8aa3b, v112
	v_mul_f32_e32 v108, v108, v128
	v_mul_f32_e32 v113, 0xbfb8aa3b, v113
	v_mul_f32_e32 v109, v109, v128
	v_exp_f32_e32 v110, v110
	v_mul_f32_e32 v106, 0xbfb8aa3b, v106
	v_exp_f32_e32 v111, v111
	v_mul_f32_e32 v107, 0xbfb8aa3b, v107
	v_exp_f32_e32 v112, v112
	v_mul_f32_e32 v108, 0xbfb8aa3b, v108
	v_exp_f32_e32 v113, v113
	v_mul_f32_e32 v109, 0xbfb8aa3b, v109
	v_exp_f32_e32 v106, v106
	v_exp_f32_e32 v107, v107
	v_exp_f32_e32 v108, v108
	v_exp_f32_e32 v109, v109
	v_add_f32_e32 v110, 1.0, v110
	v_add_f32_e32 v111, 1.0, v111
	v_add_f32_e32 v112, 1.0, v112
	v_add_f32_e32 v113, 1.0, v113
	v_rcp_f32_e32 v110, v110
	v_add_f32_e32 v106, 1.0, v106
	v_rcp_f32_e32 v111, v111
	v_add_f32_e32 v107, 1.0, v107
	v_rcp_f32_e32 v112, v112
	v_add_f32_e32 v108, 1.0, v108
	v_rcp_f32_e32 v113, v113
	v_add_f32_e32 v109, 1.0, v109
	v_rcp_f32_e32 v106, v106
	v_rcp_f32_e32 v107, v107
	v_rcp_f32_e32 v108, v108
	v_rcp_f32_e32 v109, v109
	s_and_b64 vcc, exec, s[42:43]
	s_waitcnt vmcnt(1)
	v_lshlrev_b32_e32 v130, 16, v118
	v_and_b32_e32 v131, 0xffff0000, v118
	s_waitcnt vmcnt(0)
	v_lshlrev_b32_e32 v132, 16, v114
	v_and_b32_e32 v133, 0xffff0000, v114
	v_lshlrev_b32_e32 v118, 16, v119
	v_and_b32_e32 v119, 0xffff0000, v119
	v_lshlrev_b32_e32 v114, 16, v115
	v_and_b32_e32 v115, 0xffff0000, v115
	v_pk_fma_f32 v[110:111], v[110:111], v[130:131], v[132:133]
	v_lshlrev_b32_e32 v130, 16, v120
	v_and_b32_e32 v131, 0xffff0000, v120
	v_lshlrev_b32_e32 v132, 16, v116
	v_and_b32_e32 v133, 0xffff0000, v116
	v_pk_fma_f32 v[112:113], v[112:113], v[118:119], v[114:115]
	v_lshlrev_b32_e32 v114, 16, v121
	v_and_b32_e32 v115, 0xffff0000, v121
	v_lshlrev_b32_e32 v116, 16, v117
	v_and_b32_e32 v117, 0xffff0000, v117
	v_pk_fma_f32 v[106:107], v[106:107], v[130:131], v[132:133]
	v_pk_fma_f32 v[108:109], v[108:109], v[114:115], v[116:117]
	v_lshl_add_u64 v[118:119], v[126:127], 2, s[54:55]
	s_cbranch_vccnz .LBB0_1270
	global_store_dwordx4 v[118:119], v[110:113], off
	global_store_dwordx4 v[118:119], v[106:109], off offset:16
	s_cbranch_execnz .LBB0_1198

.LBB0_1205:
	v_add_f32_e32 v98, v203, v204
	v_fmamk_f32 v98, v98, 0x3a800000, v243
	s_waitcnt lgkmcnt(0)
	v_rsq_f32_e32 v112, v98
	s_nop 0
	v_lshlrev_b64 v[98:99], 10, v[174:175]
	v_lshl_add_u64 v[110:111], v[98:99], 0, v[154:155]
	v_lshlrev_b64 v[98:99], 1, v[110:111]
	v_lshl_add_u64 v[106:107], s[20:21], 0, v[98:99]
	v_lshl_add_u64 v[108:109], s[22:23], 0, v[98:99]
	global_load_dwordx4 v[102:105], v[106:107], off
	global_load_dwordx4 v[98:101], v[108:109], off
	v_mul_f32_e32 v94, v94, v112
	v_mul_f32_e32 v95, v95, v112
	v_mul_f32_e32 v96, v96, v112
	v_mul_f32_e32 v97, v97, v112
	v_mul_f32_e32 v94, 0xbfb8aa3b, v94
	v_mul_f32_e32 v90, v90, v112
	v_mul_f32_e32 v95, 0xbfb8aa3b, v95
	v_mul_f32_e32 v91, v91, v112
	v_mul_f32_e32 v96, 0xbfb8aa3b, v96
	v_mul_f32_e32 v92, v92, v112
	v_mul_f32_e32 v97, 0xbfb8aa3b, v97
	v_mul_f32_e32 v93, v93, v112
	v_exp_f32_e32 v94, v94
	v_mul_f32_e32 v90, 0xbfb8aa3b, v90
	v_exp_f32_e32 v95, v95
	v_mul_f32_e32 v91, 0xbfb8aa3b, v91
	v_exp_f32_e32 v96, v96
	v_mul_f32_e32 v92, 0xbfb8aa3b, v92
	v_exp_f32_e32 v97, v97
	v_mul_f32_e32 v93, 0xbfb8aa3b, v93
	v_exp_f32_e32 v90, v90
	v_exp_f32_e32 v91, v91
	v_exp_f32_e32 v92, v92
	v_exp_f32_e32 v93, v93
	v_add_f32_e32 v94, 1.0, v94
	v_add_f32_e32 v95, 1.0, v95
	v_add_f32_e32 v96, 1.0, v96
	v_add_f32_e32 v97, 1.0, v97
	v_rcp_f32_e32 v94, v94
	v_add_f32_e32 v90, 1.0, v90
	v_rcp_f32_e32 v95, v95
	v_add_f32_e32 v91, 1.0, v91
	v_rcp_f32_e32 v96, v96
	v_add_f32_e32 v92, 1.0, v92
	v_rcp_f32_e32 v97, v97
	v_add_f32_e32 v93, 1.0, v93
	v_rcp_f32_e32 v90, v90
	v_rcp_f32_e32 v91, v91
	v_rcp_f32_e32 v92, v92
	v_rcp_f32_e32 v93, v93
	s_and_b64 vcc, exec, s[42:43]
	s_waitcnt vmcnt(1)
	v_lshlrev_b32_e32 v114, 16, v102
	v_and_b32_e32 v115, 0xffff0000, v102
	s_waitcnt vmcnt(0)
	v_lshlrev_b32_e32 v116, 16, v98
	v_and_b32_e32 v117, 0xffff0000, v98
	v_lshlrev_b32_e32 v102, 16, v103
	v_and_b32_e32 v103, 0xffff0000, v103
	v_lshlrev_b32_e32 v98, 16, v99
	v_and_b32_e32 v99, 0xffff0000, v99
	v_pk_fma_f32 v[94:95], v[94:95], v[114:115], v[116:117]
	v_lshlrev_b32_e32 v114, 16, v104
	v_and_b32_e32 v115, 0xffff0000, v104
	v_lshlrev_b32_e32 v116, 16, v100
	v_and_b32_e32 v117, 0xffff0000, v100
	v_pk_fma_f32 v[96:97], v[96:97], v[102:103], v[98:99]
	v_lshlrev_b32_e32 v98, 16, v105
	v_and_b32_e32 v99, 0xffff0000, v105
	v_lshlrev_b32_e32 v100, 16, v101
	v_and_b32_e32 v101, 0xffff0000, v101
	v_pk_fma_f32 v[90:91], v[90:91], v[114:115], v[116:117]
	v_pk_fma_f32 v[92:93], v[92:93], v[98:99], v[100:101]
	v_lshl_add_u64 v[102:103], v[110:111], 2, s[54:55]
	s_cbranch_vccnz .LBB0_1272
	global_store_dwordx4 v[102:103], v[94:97], off
	global_store_dwordx4 v[102:103], v[90:93], off offset:16
	s_cbranch_execnz .LBB0_1208

.LBB0_1215:
	v_add_f32_e32 v82, v201, v202
	v_fmamk_f32 v82, v82, 0x3a800000, v243
	s_waitcnt lgkmcnt(0)
	v_rsq_f32_e32 v96, v82
	s_nop 0
	v_lshlrev_b64 v[82:83], 10, v[170:171]
	v_lshl_add_u64 v[94:95], v[82:83], 0, v[154:155]
	v_lshlrev_b64 v[82:83], 1, v[94:95]
	v_lshl_add_u64 v[90:91], s[20:21], 0, v[82:83]
	v_lshl_add_u64 v[92:93], s[22:23], 0, v[82:83]
	global_load_dwordx4 v[86:89], v[90:91], off
	global_load_dwordx4 v[82:85], v[92:93], off
	v_mul_f32_e32 v78, v78, v96
	v_mul_f32_e32 v79, v79, v96
	v_mul_f32_e32 v80, v80, v96
	v_mul_f32_e32 v81, v81, v96
	v_mul_f32_e32 v78, 0xbfb8aa3b, v78
	v_mul_f32_e32 v74, v74, v96
	v_mul_f32_e32 v79, 0xbfb8aa3b, v79
	v_mul_f32_e32 v75, v75, v96
	v_mul_f32_e32 v80, 0xbfb8aa3b, v80
	v_mul_f32_e32 v76, v76, v96
	v_mul_f32_e32 v81, 0xbfb8aa3b, v81
	v_mul_f32_e32 v77, v77, v96
	v_exp_f32_e32 v78, v78
	v_mul_f32_e32 v74, 0xbfb8aa3b, v74
	v_exp_f32_e32 v79, v79
	v_mul_f32_e32 v75, 0xbfb8aa3b, v75
	v_exp_f32_e32 v80, v80
	v_mul_f32_e32 v76, 0xbfb8aa3b, v76
	v_exp_f32_e32 v81, v81
	v_mul_f32_e32 v77, 0xbfb8aa3b, v77
	v_exp_f32_e32 v74, v74
	v_exp_f32_e32 v75, v75
	v_exp_f32_e32 v76, v76
	v_exp_f32_e32 v77, v77
	v_add_f32_e32 v78, 1.0, v78
	v_add_f32_e32 v79, 1.0, v79
	v_add_f32_e32 v80, 1.0, v80
	v_add_f32_e32 v81, 1.0, v81
	v_rcp_f32_e32 v78, v78
	v_add_f32_e32 v74, 1.0, v74
	v_rcp_f32_e32 v79, v79
	v_add_f32_e32 v75, 1.0, v75
	v_rcp_f32_e32 v80, v80
	v_add_f32_e32 v76, 1.0, v76
	v_rcp_f32_e32 v81, v81
	v_add_f32_e32 v77, 1.0, v77
	v_rcp_f32_e32 v74, v74
	v_rcp_f32_e32 v75, v75
	v_rcp_f32_e32 v76, v76
	v_rcp_f32_e32 v77, v77
	s_and_b64 vcc, exec, s[42:43]
	s_waitcnt vmcnt(1)
	v_lshlrev_b32_e32 v98, 16, v86
	v_and_b32_e32 v99, 0xffff0000, v86
	s_waitcnt vmcnt(0)
	v_lshlrev_b32_e32 v100, 16, v82
	v_and_b32_e32 v101, 0xffff0000, v82
	v_lshlrev_b32_e32 v86, 16, v87
	v_and_b32_e32 v87, 0xffff0000, v87
	v_lshlrev_b32_e32 v82, 16, v83
	v_and_b32_e32 v83, 0xffff0000, v83
	v_pk_fma_f32 v[78:79], v[78:79], v[98:99], v[100:101]
	v_lshlrev_b32_e32 v98, 16, v88
	v_and_b32_e32 v99, 0xffff0000, v88
	v_lshlrev_b32_e32 v100, 16, v84
	v_and_b32_e32 v101, 0xffff0000, v84
	v_pk_fma_f32 v[80:81], v[80:81], v[86:87], v[82:83]
	v_lshlrev_b32_e32 v82, 16, v89
	v_and_b32_e32 v83, 0xffff0000, v89
	v_lshlrev_b32_e32 v84, 16, v85
	v_and_b32_e32 v85, 0xffff0000, v85
	v_pk_fma_f32 v[74:75], v[74:75], v[98:99], v[100:101]
	v_pk_fma_f32 v[76:77], v[76:77], v[82:83], v[84:85]
	v_lshl_add_u64 v[86:87], v[94:95], 2, s[54:55]
	s_cbranch_vccnz .LBB0_1274
	global_store_dwordx4 v[86:87], v[78:81], off
	global_store_dwordx4 v[86:87], v[74:77], off offset:16
	s_cbranch_execnz .LBB0_1218

.LBB0_1225:
	v_add_f32_e32 v66, v199, v200
	v_fmamk_f32 v66, v66, 0x3a800000, v243
	s_waitcnt lgkmcnt(0)
	v_rsq_f32_e32 v80, v66
	s_nop 0
	v_lshlrev_b64 v[66:67], 10, v[166:167]
	v_lshl_add_u64 v[78:79], v[66:67], 0, v[154:155]
	v_lshlrev_b64 v[66:67], 1, v[78:79]
	v_lshl_add_u64 v[74:75], s[20:21], 0, v[66:67]
	v_lshl_add_u64 v[76:77], s[22:23], 0, v[66:67]
	global_load_dwordx4 v[70:73], v[74:75], off
	global_load_dwordx4 v[66:69], v[76:77], off
	v_mul_f32_e32 v62, v62, v80
	v_mul_f32_e32 v63, v63, v80
	v_mul_f32_e32 v64, v64, v80
	v_mul_f32_e32 v65, v65, v80
	v_mul_f32_e32 v62, 0xbfb8aa3b, v62
	v_mul_f32_e32 v58, v58, v80
	v_mul_f32_e32 v63, 0xbfb8aa3b, v63
	v_mul_f32_e32 v59, v59, v80
	v_mul_f32_e32 v64, 0xbfb8aa3b, v64
	v_mul_f32_e32 v60, v60, v80
	v_mul_f32_e32 v65, 0xbfb8aa3b, v65
	v_mul_f32_e32 v61, v61, v80
	v_exp_f32_e32 v62, v62
	v_mul_f32_e32 v58, 0xbfb8aa3b, v58
	v_exp_f32_e32 v63, v63
	v_mul_f32_e32 v59, 0xbfb8aa3b, v59
	v_exp_f32_e32 v64, v64
	v_mul_f32_e32 v60, 0xbfb8aa3b, v60
	v_exp_f32_e32 v65, v65
	v_mul_f32_e32 v61, 0xbfb8aa3b, v61
	v_exp_f32_e32 v58, v58
	v_exp_f32_e32 v59, v59
	v_exp_f32_e32 v60, v60
	v_exp_f32_e32 v61, v61
	v_add_f32_e32 v62, 1.0, v62
	v_add_f32_e32 v63, 1.0, v63
	v_add_f32_e32 v64, 1.0, v64
	v_add_f32_e32 v65, 1.0, v65
	v_rcp_f32_e32 v62, v62
	v_add_f32_e32 v58, 1.0, v58
	v_rcp_f32_e32 v63, v63
	v_add_f32_e32 v59, 1.0, v59
	v_rcp_f32_e32 v64, v64
	v_add_f32_e32 v60, 1.0, v60
	v_rcp_f32_e32 v65, v65
	v_add_f32_e32 v61, 1.0, v61
	v_rcp_f32_e32 v58, v58
	v_rcp_f32_e32 v59, v59
	v_rcp_f32_e32 v60, v60
	v_rcp_f32_e32 v61, v61
	s_and_b64 vcc, exec, s[42:43]
	s_waitcnt vmcnt(1)
	v_lshlrev_b32_e32 v82, 16, v70
	v_and_b32_e32 v83, 0xffff0000, v70
	s_waitcnt vmcnt(0)
	v_lshlrev_b32_e32 v84, 16, v66
	v_and_b32_e32 v85, 0xffff0000, v66
	v_lshlrev_b32_e32 v70, 16, v71
	v_and_b32_e32 v71, 0xffff0000, v71
	v_lshlrev_b32_e32 v66, 16, v67
	v_and_b32_e32 v67, 0xffff0000, v67
	v_pk_fma_f32 v[62:63], v[62:63], v[82:83], v[84:85]
	v_lshlrev_b32_e32 v82, 16, v72
	v_and_b32_e32 v83, 0xffff0000, v72
	v_lshlrev_b32_e32 v84, 16, v68
	v_and_b32_e32 v85, 0xffff0000, v68
	v_pk_fma_f32 v[64:65], v[64:65], v[70:71], v[66:67]
	v_lshlrev_b32_e32 v66, 16, v73
	v_and_b32_e32 v67, 0xffff0000, v73
	v_lshlrev_b32_e32 v68, 16, v69
	v_and_b32_e32 v69, 0xffff0000, v69
	v_pk_fma_f32 v[58:59], v[58:59], v[82:83], v[84:85]
	v_pk_fma_f32 v[60:61], v[60:61], v[66:67], v[68:69]
	v_lshl_add_u64 v[70:71], v[78:79], 2, s[54:55]
	s_cbranch_vccnz .LBB0_1276
	global_store_dwordx4 v[70:71], v[62:65], off
	global_store_dwordx4 v[70:71], v[58:61], off offset:16
	s_cbranch_execnz .LBB0_1228

.LBB0_1235:
	v_add_f32_e32 v50, v197, v198
	v_fmamk_f32 v50, v50, 0x3a800000, v243
	s_waitcnt lgkmcnt(0)
	v_rsq_f32_e32 v64, v50
	s_nop 0
	v_lshlrev_b64 v[50:51], 10, v[162:163]
	v_lshl_add_u64 v[62:63], v[50:51], 0, v[154:155]
	v_lshlrev_b64 v[50:51], 1, v[62:63]
	v_lshl_add_u64 v[58:59], s[20:21], 0, v[50:51]
	v_lshl_add_u64 v[60:61], s[22:23], 0, v[50:51]
	global_load_dwordx4 v[54:57], v[58:59], off
	global_load_dwordx4 v[50:53], v[60:61], off
	v_mul_f32_e32 v46, v46, v64
	v_mul_f32_e32 v47, v47, v64
	v_mul_f32_e32 v48, v48, v64
	v_mul_f32_e32 v49, v49, v64
	v_mul_f32_e32 v46, 0xbfb8aa3b, v46
	v_mul_f32_e32 v42, v42, v64
	v_mul_f32_e32 v47, 0xbfb8aa3b, v47
	v_mul_f32_e32 v43, v43, v64
	v_mul_f32_e32 v48, 0xbfb8aa3b, v48
	v_mul_f32_e32 v44, v44, v64
	v_mul_f32_e32 v49, 0xbfb8aa3b, v49
	v_mul_f32_e32 v45, v45, v64
	v_exp_f32_e32 v46, v46
	v_mul_f32_e32 v42, 0xbfb8aa3b, v42
	v_exp_f32_e32 v47, v47
	v_mul_f32_e32 v43, 0xbfb8aa3b, v43
	v_exp_f32_e32 v48, v48
	v_mul_f32_e32 v44, 0xbfb8aa3b, v44
	v_exp_f32_e32 v49, v49
	v_mul_f32_e32 v45, 0xbfb8aa3b, v45
	v_exp_f32_e32 v42, v42
	v_exp_f32_e32 v43, v43
	v_exp_f32_e32 v44, v44
	v_exp_f32_e32 v45, v45
	v_add_f32_e32 v46, 1.0, v46
	v_add_f32_e32 v47, 1.0, v47
	v_add_f32_e32 v48, 1.0, v48
	v_add_f32_e32 v49, 1.0, v49
	v_rcp_f32_e32 v46, v46
	v_add_f32_e32 v42, 1.0, v42
	v_rcp_f32_e32 v47, v47
	v_add_f32_e32 v43, 1.0, v43
	v_rcp_f32_e32 v48, v48
	v_add_f32_e32 v44, 1.0, v44
	v_rcp_f32_e32 v49, v49
	v_add_f32_e32 v45, 1.0, v45
	v_rcp_f32_e32 v42, v42
	v_rcp_f32_e32 v43, v43
	v_rcp_f32_e32 v44, v44
	v_rcp_f32_e32 v45, v45
	s_and_b64 vcc, exec, s[42:43]
	s_waitcnt vmcnt(1)
	v_lshlrev_b32_e32 v66, 16, v54
	v_and_b32_e32 v67, 0xffff0000, v54
	s_waitcnt vmcnt(0)
	v_lshlrev_b32_e32 v68, 16, v50
	v_and_b32_e32 v69, 0xffff0000, v50
	v_lshlrev_b32_e32 v54, 16, v55
	v_and_b32_e32 v55, 0xffff0000, v55
	v_lshlrev_b32_e32 v50, 16, v51
	v_and_b32_e32 v51, 0xffff0000, v51
	v_pk_fma_f32 v[46:47], v[46:47], v[66:67], v[68:69]
	v_lshlrev_b32_e32 v66, 16, v56
	v_and_b32_e32 v67, 0xffff0000, v56
	v_lshlrev_b32_e32 v68, 16, v52
	v_and_b32_e32 v69, 0xffff0000, v52
	v_pk_fma_f32 v[48:49], v[48:49], v[54:55], v[50:51]
	v_lshlrev_b32_e32 v50, 16, v57
	v_and_b32_e32 v51, 0xffff0000, v57
	v_lshlrev_b32_e32 v52, 16, v53
	v_and_b32_e32 v53, 0xffff0000, v53
	v_pk_fma_f32 v[42:43], v[42:43], v[66:67], v[68:69]
	v_pk_fma_f32 v[44:45], v[44:45], v[50:51], v[52:53]
	v_lshl_add_u64 v[54:55], v[62:63], 2, s[54:55]
	s_cbranch_vccnz .LBB0_1278
	global_store_dwordx4 v[54:55], v[46:49], off
	global_store_dwordx4 v[54:55], v[42:45], off offset:16
	s_cbranch_execnz .LBB0_1238

.LBB0_1245:
	v_add_f32_e32 v34, v195, v196
	v_fmamk_f32 v34, v34, 0x3a800000, v243
	s_waitcnt lgkmcnt(0)
	v_rsq_f32_e32 v48, v34
	s_nop 0
	v_lshlrev_b64 v[34:35], 10, v[158:159]
	v_lshl_add_u64 v[46:47], v[34:35], 0, v[154:155]
	v_lshlrev_b64 v[34:35], 1, v[46:47]
	v_lshl_add_u64 v[42:43], s[20:21], 0, v[34:35]
	v_lshl_add_u64 v[44:45], s[22:23], 0, v[34:35]
	global_load_dwordx4 v[38:41], v[42:43], off
	global_load_dwordx4 v[34:37], v[44:45], off
	v_mul_f32_e32 v30, v30, v48
	v_mul_f32_e32 v31, v31, v48
	v_mul_f32_e32 v32, v32, v48
	v_mul_f32_e32 v33, v33, v48
	v_mul_f32_e32 v30, 0xbfb8aa3b, v30
	v_mul_f32_e32 v26, v26, v48
	v_mul_f32_e32 v31, 0xbfb8aa3b, v31
	v_mul_f32_e32 v27, v27, v48
	v_mul_f32_e32 v32, 0xbfb8aa3b, v32
	v_mul_f32_e32 v28, v28, v48
	v_mul_f32_e32 v33, 0xbfb8aa3b, v33
	v_mul_f32_e32 v29, v29, v48
	v_exp_f32_e32 v30, v30
	v_mul_f32_e32 v26, 0xbfb8aa3b, v26
	v_exp_f32_e32 v31, v31
	v_mul_f32_e32 v27, 0xbfb8aa3b, v27
	v_exp_f32_e32 v32, v32
	v_mul_f32_e32 v28, 0xbfb8aa3b, v28
	v_exp_f32_e32 v33, v33
	v_mul_f32_e32 v29, 0xbfb8aa3b, v29
	v_exp_f32_e32 v26, v26
	v_exp_f32_e32 v27, v27
	v_exp_f32_e32 v28, v28
	v_exp_f32_e32 v29, v29
	v_add_f32_e32 v30, 1.0, v30
	v_add_f32_e32 v31, 1.0, v31
	v_add_f32_e32 v32, 1.0, v32
	v_add_f32_e32 v33, 1.0, v33
	v_rcp_f32_e32 v30, v30
	v_add_f32_e32 v26, 1.0, v26
	v_rcp_f32_e32 v31, v31
	v_add_f32_e32 v27, 1.0, v27
	v_rcp_f32_e32 v32, v32
	v_add_f32_e32 v28, 1.0, v28
	v_rcp_f32_e32 v33, v33
	v_add_f32_e32 v29, 1.0, v29
	v_rcp_f32_e32 v26, v26
	v_rcp_f32_e32 v27, v27
	v_rcp_f32_e32 v28, v28
	v_rcp_f32_e32 v29, v29
	s_and_b64 vcc, exec, s[42:43]
	s_waitcnt vmcnt(1)
	v_lshlrev_b32_e32 v50, 16, v38
	v_and_b32_e32 v51, 0xffff0000, v38
	s_waitcnt vmcnt(0)
	v_lshlrev_b32_e32 v52, 16, v34
	v_and_b32_e32 v53, 0xffff0000, v34
	v_lshlrev_b32_e32 v38, 16, v39
	v_and_b32_e32 v39, 0xffff0000, v39
	v_lshlrev_b32_e32 v34, 16, v35
	v_and_b32_e32 v35, 0xffff0000, v35
	v_pk_fma_f32 v[30:31], v[30:31], v[50:51], v[52:53]
	v_lshlrev_b32_e32 v50, 16, v40
	v_and_b32_e32 v51, 0xffff0000, v40
	v_lshlrev_b32_e32 v52, 16, v36
	v_and_b32_e32 v53, 0xffff0000, v36
	v_pk_fma_f32 v[32:33], v[32:33], v[38:39], v[34:35]
	v_lshlrev_b32_e32 v34, 16, v41
	v_and_b32_e32 v35, 0xffff0000, v41
	v_lshlrev_b32_e32 v36, 16, v37
	v_and_b32_e32 v37, 0xffff0000, v37
	v_pk_fma_f32 v[26:27], v[26:27], v[50:51], v[52:53]
	v_pk_fma_f32 v[28:29], v[28:29], v[34:35], v[36:37]
	v_lshl_add_u64 v[38:39], v[46:47], 2, s[54:55]
	s_cbranch_vccnz .LBB0_1280
	global_store_dwordx4 v[38:39], v[30:33], off
	global_store_dwordx4 v[38:39], v[26:29], off offset:16
	s_cbranch_execnz .LBB0_1248

.LBB0_1255:
	v_add_f32_e32 v18, v193, v194
	v_fmamk_f32 v18, v18, 0x3a800000, v243
	s_waitcnt lgkmcnt(0)
	v_rsq_f32_e32 v32, v18
	s_nop 0
	v_lshlrev_b64 v[18:19], 10, v[152:153]
	v_lshl_add_u64 v[30:31], v[18:19], 0, v[154:155]
	v_lshlrev_b64 v[18:19], 1, v[30:31]
	v_lshl_add_u64 v[26:27], s[20:21], 0, v[18:19]
	v_lshl_add_u64 v[28:29], s[22:23], 0, v[18:19]
	global_load_dwordx4 v[22:25], v[26:27], off
	global_load_dwordx4 v[18:21], v[28:29], off
	v_mul_f32_e32 v14, v14, v32
	v_mul_f32_e32 v15, v15, v32
	v_mul_f32_e32 v16, v16, v32
	v_mul_f32_e32 v17, v17, v32
	v_mul_f32_e32 v14, 0xbfb8aa3b, v14
	v_mul_f32_e32 v10, v10, v32
	v_mul_f32_e32 v15, 0xbfb8aa3b, v15
	v_mul_f32_e32 v11, v11, v32
	v_mul_f32_e32 v16, 0xbfb8aa3b, v16
	v_mul_f32_e32 v12, v12, v32
	v_mul_f32_e32 v17, 0xbfb8aa3b, v17
	v_mul_f32_e32 v13, v13, v32
	v_exp_f32_e32 v14, v14
	v_mul_f32_e32 v10, 0xbfb8aa3b, v10
	v_exp_f32_e32 v15, v15
	v_mul_f32_e32 v11, 0xbfb8aa3b, v11
	v_exp_f32_e32 v16, v16
	v_mul_f32_e32 v12, 0xbfb8aa3b, v12
	v_exp_f32_e32 v17, v17
	v_mul_f32_e32 v13, 0xbfb8aa3b, v13
	v_exp_f32_e32 v10, v10
	v_exp_f32_e32 v11, v11
	v_exp_f32_e32 v12, v12
	v_exp_f32_e32 v13, v13
	v_add_f32_e32 v14, 1.0, v14
	v_add_f32_e32 v15, 1.0, v15
	v_add_f32_e32 v16, 1.0, v16
	v_add_f32_e32 v17, 1.0, v17
	v_rcp_f32_e32 v14, v14
	v_add_f32_e32 v10, 1.0, v10
	v_rcp_f32_e32 v15, v15
	v_add_f32_e32 v11, 1.0, v11
	v_rcp_f32_e32 v16, v16
	v_add_f32_e32 v12, 1.0, v12
	v_rcp_f32_e32 v17, v17
	v_add_f32_e32 v13, 1.0, v13
	v_rcp_f32_e32 v10, v10
	v_rcp_f32_e32 v11, v11
	v_rcp_f32_e32 v12, v12
	v_rcp_f32_e32 v13, v13
	s_and_b64 vcc, exec, s[42:43]
	s_waitcnt vmcnt(1)
	v_lshlrev_b32_e32 v34, 16, v22
	v_and_b32_e32 v35, 0xffff0000, v22
	s_waitcnt vmcnt(0)
	v_lshlrev_b32_e32 v36, 16, v18
	v_and_b32_e32 v37, 0xffff0000, v18
	v_lshlrev_b32_e32 v22, 16, v23
	v_and_b32_e32 v23, 0xffff0000, v23
	v_lshlrev_b32_e32 v18, 16, v19
	v_and_b32_e32 v19, 0xffff0000, v19
	v_pk_fma_f32 v[14:15], v[14:15], v[34:35], v[36:37]
	v_lshlrev_b32_e32 v34, 16, v24
	v_and_b32_e32 v35, 0xffff0000, v24
	v_lshlrev_b32_e32 v36, 16, v20
	v_and_b32_e32 v37, 0xffff0000, v20
	v_pk_fma_f32 v[16:17], v[16:17], v[22:23], v[18:19]
	v_lshlrev_b32_e32 v18, 16, v25
	v_and_b32_e32 v19, 0xffff0000, v25
	v_lshlrev_b32_e32 v20, 16, v21
	v_and_b32_e32 v21, 0xffff0000, v21
	v_pk_fma_f32 v[10:11], v[10:11], v[34:35], v[36:37]
	v_pk_fma_f32 v[12:13], v[12:13], v[18:19], v[20:21]
	v_lshl_add_u64 v[22:23], v[30:31], 2, s[54:55]
	s_cbranch_vccnz .LBB0_1282
	global_store_dwordx4 v[22:23], v[14:17], off
	global_store_dwordx4 v[22:23], v[10:13], off offset:16
	s_cbranch_execnz .LBB0_1258
